# barrier-slide by 1 MFMA: closing s_barrier of each K-loop compute segment moved before the last MFMA (hide barrier release latency)
# speedup vs baseline: 1.0177x; 1.0177x over previous
;     __device__ __forceinline__ const char* tile(const Unit& u, int t) const { return A + (size_t)u.pm * 2 * hstep() + (size_t)t * (BK * 2); }
;     __device__ __forceinline__ const char* tile(const Unit& u, int t) const { return U + (long)(t >> 2) * xoff + (size_t)u.pn * (1024 * 512) + (size_t)u.pm * 2 * hstep() + (size_t)(t & 3) * (BK * 2); }
; #define PG8_STAGE(bufoff, gbase, voff) do { _Pragma("unroll") for (int _i = 0; _i < 2; ++_i) \
;         __builtin_amdgcn_global_load_lds((const unsigned*)((const char*)(gbase) + (voff)[_i]), (PG8_LAS unsigned*)(lds + (bufoff) + ldsw + _i * 8192), 16, 0, 0); } while (0)
; #define PG8_LDA(dst, b, h) do { _Pragma("unroll") for (int m = 0; m < 4; ++m) _Pragma("unroll") for (int k = 0; k < 2; ++k) dst[m][k] = *(const PG8_LAS bf16x8*)(lds + PG8_SA(b, h) + aoff + m * 2048 + k * 1024); } while (0)
; #define PG8_LDB(dst, b, h) do { _Pragma("unroll") for (int n = 0; n < 2; ++n) _Pragma("unroll") for (int k = 0; k < 2; ++k) dst[n][k] = *(const PG8_LAS bf16x8*)(lds + PG8_SB(b, h) + boff + n * 2048 + k * 1024); } while (0)
; #define PG8_MMA(ai, bj, At, Bt) do { __builtin_amdgcn_s_setprio(1); _Pragma("unroll") for (int m = 0; m < 4; ++m) _Pragma("unroll") for (int n = 0; n < 2; ++n) _Pragma("unroll") for (int k = 0; k < 2; ++k) \
;         acc[ai][bj][m][n] = __builtin_amdgcn_mfma_f32_16x16x32_bf16(Bt[n][k], At[m][k], acc[ai][bj][m][n], 0, 0, 0); __builtin_amdgcn_s_setprio(0); } while (0)
; #define PG8_WAIT_V(n) asm volatile("s_waitcnt vmcnt(" #n ")" ::: "memory")
;     ...
;             const bool last = (t == nt - 2);
;             const char* a1 = AS.tile(cur, t + 1);
;             const char* a2 = last ? AS.tile(nu, 0) : AS.tile(cur, t + 2); const char* b2 = last ? nB : cB + (size_t)(t + 2) * kstep;
;             const char* a3 = last ? AS.tile(nu, 1) : AS.tile(cur, t + 3); const char* b3 = b2 + kstep;
;             PG8_LDB(B0, 0, 0); PG8_LDB(B1, 0, 1); PG8_SCHED; PG8_LDA(At, 0, 0); PG8_STAGE(PG8_SA(1, 1), a1 + hstepA, voffA);
;             PG8_WAIT_V(8); PG8_WAIT_L(0); PG8_BAR; PG8_MMA(0, 0, At, B0); PG8_MMA(0, 1, At, B1); PG8_BAR; PG8_SCHED;
;             PG8_LDA(At, 0, 1); PG8_STAGE(PG8_SB(0, 0), b2, voffB); PG8_STAGE(PG8_SB(0, 1), b2 + hstepB, voffB); PG8_STAGE(PG8_SA(0, 0), a2, voffA);
;             PG8_WAIT_V(8); PG8_WAIT_L(0); PG8_BAR; PG8_MMA(1, 0, At, B0); PG8_MMA(1, 1, At, B1); PG8_BAR; PG8_SCHED;
.Lpeel_380:
	s_add_u32 s28, s1, s2
	s_addc_u32 s29, s77, s3
	s_add_u32 s48, s28, 0x100
	s_addc_u32 s49, s29, 0
	s_add_u32 s46, s82, s2
	s_addc_u32 s47, s83, s3
	s_add_u32 s28, s28, 0x180
	s_addc_u32 s29, s29, 0
	s_add_i32 s85, 0, 0x10000
	s_add_i32 s88, 0, 0x14000
	v_add_u32_e32 v158, s85, v174
	v_add_u32_e32 v186, s88, v174
	ds_read_b128 v[132:135], v158
	ds_read_b128 v[136:139], v158 offset:1024
	ds_read_b128 v[140:143], v158 offset:2048
	ds_read_b128 v[158:161], v158 offset:3072
	ds_read_b128 v[162:165], v186
	ds_read_b128 v[166:169], v186 offset:1024
	ds_read_b128 v[182:185], v186 offset:2048
	ds_read_b128 v[186:189], v186 offset:3072
	s_cmpk_eq_i32 s2, 0x700
	s_cselect_b32 s29, s81, s29
	s_cselect_b32 s28, s80, s28
	s_cselect_b32 s47, s76, s47
	s_cselect_b32 s46, s75, s46
	s_cselect_b32 s49, s79, s49
	s_cselect_b32 s48, s78, s48
	v_lshl_add_u64 v[222:223], v[128:129], 0, s[2:3]
	s_add_i32 m0, s27, 0xc000
	ds_read_b128 v[190:193], v180
	ds_read_b128 v[194:197], v180 offset:1024
	ds_read_b128 v[198:201], v180 offset:2048
	ds_read_b128 v[204:207], v180 offset:3072
	ds_read_b128 v[218:221], v180 offset:4096
	ds_read_b128 v[238:241], v180 offset:5120
	ds_read_b128 v[242:245], v180 offset:6144
	ds_read_b128 v[246:249], v180 offset:7168
	global_load_lds_dwordx4 v[222:223], off
	v_lshl_add_u64 v[222:223], v[130:131], 0, s[2:3]
	s_add_i32 m0, s27, 0xe000
	s_nop 0
	global_load_lds_dwordx4 v[222:223], off
	s_waitcnt vmcnt(8)
	s_waitcnt lgkmcnt(0)
	s_barrier
	s_setprio 1
	s_waitcnt lgkmcnt(0)
	v_mfma_f32_16x16x32_bf16 v[124:127], v[132:135], v[190:193], 0
	v_mfma_f32_16x16x32_bf16 v[120:123], v[140:143], v[190:193], 0
	v_mfma_f32_16x16x32_bf16 v[108:111], v[132:135], v[198:201], 0
	v_mfma_f32_16x16x32_bf16 v[104:107], v[140:143], v[198:201], 0
	v_mfma_f32_16x16x32_bf16 v[92:95], v[132:135], v[218:221], 0
	v_mfma_f32_16x16x32_bf16 v[88:91], v[140:143], v[218:221], 0
	v_mfma_f32_16x16x32_bf16 v[76:79], v[132:135], v[242:245], 0
	v_mfma_f32_16x16x32_bf16 v[72:75], v[140:143], v[242:245], 0
	v_mfma_f32_16x16x32_bf16 v[124:127], v[136:139], v[194:197], v[124:127]
	v_mfma_f32_16x16x32_bf16 v[120:123], v[158:161], v[194:197], v[120:123]
	v_mfma_f32_16x16x32_bf16 v[108:111], v[136:139], v[204:207], v[108:111]
	v_mfma_f32_16x16x32_bf16 v[104:107], v[158:161], v[204:207], v[104:107]
	v_mfma_f32_16x16x32_bf16 v[92:95], v[136:139], v[238:241], v[92:95]
	v_mfma_f32_16x16x32_bf16 v[88:91], v[158:161], v[238:241], v[88:91]
	v_mfma_f32_16x16x32_bf16 v[76:79], v[136:139], v[246:249], v[76:79]
	v_mfma_f32_16x16x32_bf16 v[72:75], v[158:161], v[246:249], v[72:75]
	s_setprio 0
	s_setprio 1
	v_mfma_f32_16x16x32_bf16 v[116:119], v[162:165], v[190:193], 0
	v_mfma_f32_16x16x32_bf16 v[112:115], v[182:185], v[190:193], 0
	v_mfma_f32_16x16x32_bf16 v[100:103], v[162:165], v[198:201], 0
	v_mfma_f32_16x16x32_bf16 v[96:99], v[182:185], v[198:201], 0
	v_mfma_f32_16x16x32_bf16 v[84:87], v[162:165], v[218:221], 0
	v_mfma_f32_16x16x32_bf16 v[80:83], v[182:185], v[218:221], 0
	v_mfma_f32_16x16x32_bf16 v[68:71], v[162:165], v[242:245], 0
	v_mfma_f32_16x16x32_bf16 v[64:67], v[182:185], v[242:245], 0
	v_mfma_f32_16x16x32_bf16 v[116:119], v[166:169], v[194:197], v[116:119]
	v_mfma_f32_16x16x32_bf16 v[112:115], v[186:189], v[194:197], v[112:115]
	v_mfma_f32_16x16x32_bf16 v[100:103], v[166:169], v[204:207], v[100:103]
	v_mfma_f32_16x16x32_bf16 v[96:99], v[186:189], v[204:207], v[96:99]
	v_mfma_f32_16x16x32_bf16 v[84:87], v[166:169], v[238:241], v[84:87]
	v_mfma_f32_16x16x32_bf16 v[80:83], v[186:189], v[238:241], v[80:83]
	v_mfma_f32_16x16x32_bf16 v[68:71], v[166:169], v[246:249], v[68:71]
	s_barrier
	v_mfma_f32_16x16x32_bf16 v[64:67], v[186:189], v[246:249], v[64:67]
	s_setprio 0
	s_add_i32 s85, s85, s52
	v_lshl_add_u64 v[222:223], s[46:47], 0, v[146:147]
	s_mov_b32 m0, s85
	ds_read_b128 v[190:193], v180 offset:16384
	ds_read_b128 v[194:197], v180 offset:17408
	ds_read_b128 v[198:201], v180 offset:18432
	ds_read_b128 v[204:207], v180 offset:19456
	ds_read_b128 v[218:221], v180 offset:20480
	ds_read_b128 v[238:241], v180 offset:21504
	ds_read_b128 v[242:245], v180 offset:22528
	ds_read_b128 v[246:249], v180 offset:23552
	global_load_lds_dwordx4 v[222:223], off
	s_add_i32 m0, s85, 0x2000
	s_add_u32 s86, s46, 0x40000
	v_lshl_add_u64 v[224:225], s[46:47], 0, v[150:151]
	s_addc_u32 s87, s47, 0
	s_add_i32 s85, s88, s52
	global_load_lds_dwordx4 v[224:225], off
	v_lshl_add_u64 v[250:251], s[86:87], 0, v[146:147]
	s_mov_b32 m0, s85
	s_nop 0
	global_load_lds_dwordx4 v[250:251], off
	v_lshl_add_u64 v[250:251], s[86:87], 0, v[150:151]
	s_add_i32 m0, s85, 0x2000
	s_nop 0
	global_load_lds_dwordx4 v[250:251], off
	v_lshl_add_u64 v[250:251], s[48:49], 0, v[144:145]
	s_mov_b32 m0, s27
	s_nop 0
	global_load_lds_dwordx4 v[250:251], off
	v_lshl_add_u64 v[250:251], s[48:49], 0, v[148:149]
	s_mov_b32 m0, s57
	s_nop 0
	global_load_lds_dwordx4 v[250:251], off
	s_waitcnt vmcnt(8)
	s_waitcnt lgkmcnt(0)
	s_barrier
; #define PG8_STAGE(bufoff, gbase, voff) do { _Pragma("unroll") for (int _i = 0; _i < 2; ++_i) \
;         __builtin_amdgcn_global_load_lds((const unsigned*)((const char*)(gbase) + (voff)[_i]), (PG8_LAS unsigned*)(lds + (bufoff) + ldsw + _i * 8192), 16, 0, 0); } while (0)
; #define PG8_LDA(dst, b, h) do { _Pragma("unroll") for (int m = 0; m < 4; ++m) _Pragma("unroll") for (int k = 0; k < 2; ++k) dst[m][k] = *(const PG8_LAS bf16x8*)(lds + PG8_SA(b, h) + aoff + m * 2048 + k * 1024); } while (0)
; #define PG8_LDB(dst, b, h) do { _Pragma("unroll") for (int n = 0; n < 2; ++n) _Pragma("unroll") for (int k = 0; k < 2; ++k) dst[n][k] = *(const PG8_LAS bf16x8*)(lds + PG8_SB(b, h) + boff + n * 2048 + k * 1024); } while (0)
; #define PG8_MMA(ai, bj, At, Bt) do { __builtin_amdgcn_s_setprio(1); _Pragma("unroll") for (int m = 0; m < 4; ++m) _Pragma("unroll") for (int n = 0; n < 2; ++n) _Pragma("unroll") for (int k = 0; k < 2; ++k) \
;         acc[ai][bj][m][n] = __builtin_amdgcn_mfma_f32_16x16x32_bf16(Bt[n][k], At[m][k], acc[ai][bj][m][n], 0, 0, 0); __builtin_amdgcn_s_setprio(0); } while (0)
; #define PG8_WAIT_V(n) asm volatile("s_waitcnt vmcnt(" #n ")" ::: "memory")
; #define PG8_WAIT_L(n) asm volatile("s_waitcnt lgkmcnt(" #n ")" ::: "memory")
; #define PG8_BAR __builtin_amdgcn_s_barrier()
; #define PG8_SCHED __builtin_amdgcn_sched_barrier(0)
;     ...
;             PG8_WAIT_V(8); PG8_WAIT_L(0); PG8_BAR; PG8_MMA(0, 0, At, B0); PG8_MMA(0, 1, At, B1); PG8_BAR; PG8_SCHED;
;             PG8_LDA(At, 0, 1); PG8_STAGE(PG8_SB(0, 0), b2, voffB); PG8_STAGE(PG8_SB(0, 1), b2 + hstepB, voffB); PG8_STAGE(PG8_SA(0, 0), a2, voffA);
;             PG8_WAIT_V(8); PG8_WAIT_L(0); PG8_BAR; PG8_MMA(1, 0, At, B0); PG8_MMA(1, 1, At, B1); PG8_BAR; PG8_SCHED;
;             PG8_LDB(B0, 1, 0); PG8_LDB(B1, 1, 1); PG8_SCHED; PG8_LDA(At, 1, 0); PG8_STAGE(PG8_SA(0, 1), a2 + hstepA, voffA);
;             PG8_WAIT_V(8); PG8_WAIT_L(0); PG8_BAR; PG8_MMA(0, 0, At, B0); PG8_MMA(0, 1, At, B1); PG8_BAR; PG8_SCHED;
	s_setprio 1
	s_waitcnt lgkmcnt(0)
	v_mfma_f32_16x16x32_bf16 v[60:63], v[132:135], v[190:193], 0
	v_mfma_f32_16x16x32_bf16 v[56:59], v[140:143], v[190:193], 0
	v_mfma_f32_16x16x32_bf16 v[44:47], v[132:135], v[198:201], 0
	v_mfma_f32_16x16x32_bf16 v[40:43], v[140:143], v[198:201], 0
	v_mfma_f32_16x16x32_bf16 v[28:31], v[132:135], v[218:221], 0
	v_mfma_f32_16x16x32_bf16 v[24:27], v[140:143], v[218:221], 0
	v_mfma_f32_16x16x32_bf16 v[12:15], v[132:135], v[242:245], 0
	v_mfma_f32_16x16x32_bf16 v[8:11], v[140:143], v[242:245], 0
	v_mfma_f32_16x16x32_bf16 v[60:63], v[136:139], v[194:197], v[60:63]
	v_mfma_f32_16x16x32_bf16 v[56:59], v[158:161], v[194:197], v[56:59]
	v_mfma_f32_16x16x32_bf16 v[44:47], v[136:139], v[204:207], v[44:47]
	v_mfma_f32_16x16x32_bf16 v[40:43], v[158:161], v[204:207], v[40:43]
	v_mfma_f32_16x16x32_bf16 v[28:31], v[136:139], v[238:241], v[28:31]
	v_mfma_f32_16x16x32_bf16 v[24:27], v[158:161], v[238:241], v[24:27]
	v_mfma_f32_16x16x32_bf16 v[12:15], v[136:139], v[246:249], v[12:15]
	v_mfma_f32_16x16x32_bf16 v[8:11], v[158:161], v[246:249], v[8:11]
	s_setprio 0
	s_setprio 1
	v_mfma_f32_16x16x32_bf16 v[52:55], v[162:165], v[190:193], 0
	v_mfma_f32_16x16x32_bf16 v[48:51], v[182:185], v[190:193], 0
	v_mfma_f32_16x16x32_bf16 v[36:39], v[162:165], v[198:201], 0
	v_mfma_f32_16x16x32_bf16 v[32:35], v[182:185], v[198:201], 0
	v_mfma_f32_16x16x32_bf16 v[20:23], v[162:165], v[218:221], 0
	v_mfma_f32_16x16x32_bf16 v[16:19], v[182:185], v[218:221], 0
	v_mfma_f32_16x16x32_bf16 v[4:7], v[162:165], v[242:245], 0
	v_mfma_f32_16x16x32_bf16 v[0:3], v[182:185], v[242:245], 0
	v_mfma_f32_16x16x32_bf16 v[52:55], v[166:169], v[194:197], v[52:55]
	v_mfma_f32_16x16x32_bf16 v[48:51], v[186:189], v[194:197], v[48:51]
	v_mfma_f32_16x16x32_bf16 v[36:39], v[166:169], v[204:207], v[36:39]
	v_mfma_f32_16x16x32_bf16 v[32:35], v[186:189], v[204:207], v[32:35]
	v_mfma_f32_16x16x32_bf16 v[20:23], v[166:169], v[238:241], v[20:23]
	v_mfma_f32_16x16x32_bf16 v[16:19], v[186:189], v[238:241], v[16:19]
	v_mfma_f32_16x16x32_bf16 v[4:7], v[166:169], v[246:249], v[4:7]
	s_barrier
	v_mfma_f32_16x16x32_bf16 v[0:3], v[186:189], v[246:249], v[0:3]
	s_setprio 0
	s_add_i32 s85, 0, 0x18000
	s_add_i32 s86, 0, 0x1c000
	v_add_u32_e32 v158, s85, v174
	v_add_u32_e32 v186, s86, v174
	ds_read_b128 v[132:135], v158
	ds_read_b128 v[136:139], v158 offset:1024
	ds_read_b128 v[140:143], v158 offset:2048
	ds_read_b128 v[158:161], v158 offset:3072
	ds_read_b128 v[162:165], v186
	ds_read_b128 v[166:169], v186 offset:1024
	ds_read_b128 v[182:185], v186 offset:2048
	ds_read_b128 v[186:189], v186 offset:3072
	s_add_u32 s48, s48, 0x40000
	s_addc_u32 s49, s49, 0
	s_mov_b32 m0, s58
	v_lshl_add_u64 v[250:251], s[48:49], 0, v[144:145]
	ds_read_b128 v[190:193], v180 offset:32768
	ds_read_b128 v[194:197], v180 offset:33792
	ds_read_b128 v[198:201], v180 offset:34816
	ds_read_b128 v[204:207], v180 offset:35840
	ds_read_b128 v[218:221], v180 offset:36864
	ds_read_b128 v[238:241], v180 offset:37888
	ds_read_b128 v[242:245], v180 offset:38912
	ds_read_b128 v[246:249], v180 offset:39936
	global_load_lds_dwordx4 v[250:251], off
	v_lshl_add_u64 v[250:251], s[48:49], 0, v[148:149]
	s_mov_b32 m0, s59
	s_nop 0
	global_load_lds_dwordx4 v[250:251], off
	s_waitcnt vmcnt(8)
	s_waitcnt lgkmcnt(0)
	s_barrier
	s_setprio 1
	s_waitcnt lgkmcnt(0)
	v_mfma_f32_16x16x32_bf16 v[124:127], v[132:135], v[190:193], v[124:127]
	v_mfma_f32_16x16x32_bf16 v[120:123], v[140:143], v[190:193], v[120:123]
	v_mfma_f32_16x16x32_bf16 v[108:111], v[132:135], v[198:201], v[108:111]
	v_mfma_f32_16x16x32_bf16 v[104:107], v[140:143], v[198:201], v[104:107]
	v_mfma_f32_16x16x32_bf16 v[92:95], v[132:135], v[218:221], v[92:95]
	v_mfma_f32_16x16x32_bf16 v[88:91], v[140:143], v[218:221], v[88:91]
	v_mfma_f32_16x16x32_bf16 v[76:79], v[132:135], v[242:245], v[76:79]
	v_mfma_f32_16x16x32_bf16 v[72:75], v[140:143], v[242:245], v[72:75]
	v_mfma_f32_16x16x32_bf16 v[124:127], v[136:139], v[194:197], v[124:127]
	v_mfma_f32_16x16x32_bf16 v[120:123], v[158:161], v[194:197], v[120:123]
	v_mfma_f32_16x16x32_bf16 v[108:111], v[136:139], v[204:207], v[108:111]
	v_mfma_f32_16x16x32_bf16 v[104:107], v[158:161], v[204:207], v[104:107]
	v_mfma_f32_16x16x32_bf16 v[92:95], v[136:139], v[238:241], v[92:95]
	v_mfma_f32_16x16x32_bf16 v[88:91], v[158:161], v[238:241], v[88:91]
	v_mfma_f32_16x16x32_bf16 v[76:79], v[136:139], v[246:249], v[76:79]
	v_mfma_f32_16x16x32_bf16 v[72:75], v[158:161], v[246:249], v[72:75]
	s_setprio 0
	s_setprio 1
	v_mfma_f32_16x16x32_bf16 v[116:119], v[162:165], v[190:193], v[116:119]
	v_mfma_f32_16x16x32_bf16 v[112:115], v[182:185], v[190:193], v[112:115]
	v_mfma_f32_16x16x32_bf16 v[100:103], v[162:165], v[198:201], v[100:103]
	v_mfma_f32_16x16x32_bf16 v[96:99], v[182:185], v[198:201], v[96:99]
	v_mfma_f32_16x16x32_bf16 v[84:87], v[162:165], v[218:221], v[84:87]
	v_mfma_f32_16x16x32_bf16 v[80:83], v[182:185], v[218:221], v[80:83]
	v_mfma_f32_16x16x32_bf16 v[68:71], v[162:165], v[242:245], v[68:71]
	v_mfma_f32_16x16x32_bf16 v[64:67], v[182:185], v[242:245], v[64:67]
	v_mfma_f32_16x16x32_bf16 v[116:119], v[166:169], v[194:197], v[116:119]
	v_mfma_f32_16x16x32_bf16 v[112:115], v[186:189], v[194:197], v[112:115]
	v_mfma_f32_16x16x32_bf16 v[100:103], v[166:169], v[204:207], v[100:103]
	v_mfma_f32_16x16x32_bf16 v[96:99], v[186:189], v[204:207], v[96:99]
	v_mfma_f32_16x16x32_bf16 v[84:87], v[166:169], v[238:241], v[84:87]
	v_mfma_f32_16x16x32_bf16 v[80:83], v[186:189], v[238:241], v[80:83]
	v_mfma_f32_16x16x32_bf16 v[68:71], v[166:169], v[246:249], v[68:71]
	s_barrier
;     __device__ __forceinline__ const char* tile(const Unit& u, int t) const { return A + (size_t)u.pm * 2 * hstep() + (size_t)t * (BK * 2); }
;     __device__ __forceinline__ const char* tile(const Unit& u, int t) const { return U + (long)(t >> 2) * xoff + (size_t)u.pn * (1024 * 512) + (size_t)u.pm * 2 * hstep() + (size_t)(t & 3) * (BK * 2); }
; #define PG8_STAGE(bufoff, gbase, voff) do { _Pragma("unroll") for (int _i = 0; _i < 2; ++_i) \
;         __builtin_amdgcn_global_load_lds((const unsigned*)((const char*)(gbase) + (voff)[_i]), (PG8_LAS unsigned*)(lds + (bufoff) + ldsw + _i * 8192), 16, 0, 0); } while (0)
; #define PG8_LDA(dst, b, h) do { _Pragma("unroll") for (int m = 0; m < 4; ++m) _Pragma("unroll") for (int k = 0; k < 2; ++k) dst[m][k] = *(const PG8_LAS bf16x8*)(lds + PG8_SA(b, h) + aoff + m * 2048 + k * 1024); } while (0)
; #define PG8_WAIT_V(n) asm volatile("s_waitcnt vmcnt(" #n ")" ::: "memory")
; #define PG8_BAR __builtin_amdgcn_s_barrier()
;     ...
;         for (int t = 0; t < nt; t += 2) {
;             const bool last = (t == nt - 2);
;             const char* a1 = AS.tile(cur, t + 1);
;             const char* a2 = last ? AS.tile(nu, 0) : AS.tile(cur, t + 2); const char* b2 = last ? nB : cB + (size_t)(t + 2) * kstep;
;             const char* a3 = last ? AS.tile(nu, 1) : AS.tile(cur, t + 3); const char* b3 = b2 + kstep;
;             PG8_LDB(B0, 0, 0); PG8_LDB(B1, 0, 1); PG8_SCHED; PG8_LDA(At, 0, 0); PG8_STAGE(PG8_SA(1, 1), a1 + hstepA, voffA);
;             PG8_WAIT_V(8); PG8_WAIT_L(0); PG8_BAR; PG8_MMA(0, 0, At, B0); PG8_MMA(0, 1, At, B1); PG8_BAR; PG8_SCHED;
;             PG8_LDA(At, 0, 1); PG8_STAGE(PG8_SB(0, 0), b2, voffB); PG8_STAGE(PG8_SB(0, 1), b2 + hstepB, voffB); PG8_STAGE(PG8_SA(0, 0), a2, voffA);
;             PG8_WAIT_V(8); PG8_WAIT_L(0); PG8_BAR; PG8_MMA(1, 0, At, B0); PG8_MMA(1, 1, At, B1); PG8_BAR; PG8_SCHED;
;             PG8_LDB(B0, 1, 0); PG8_LDB(B1, 1, 1); PG8_SCHED; PG8_LDA(At, 1, 0); PG8_STAGE(PG8_SA(0, 1), a2 + hstepA, voffA);
;             PG8_WAIT_V(8); PG8_WAIT_L(0); PG8_BAR; PG8_MMA(0, 0, At, B0); PG8_MMA(0, 1, At, B1); PG8_BAR; PG8_SCHED;
;             PG8_LDA(At, 1, 1); PG8_STAGE(PG8_SB(1, 0), b3, voffB); PG8_STAGE(PG8_SB(1, 1), b3 + hstepB, voffB); PG8_STAGE(PG8_SA(1, 0), a3, voffA);
;             PG8_WAIT_V(8); PG8_WAIT_L(0); PG8_BAR; PG8_MMA(1, 0, At, B0); PG8_MMA(1, 1, At, B1); PG8_BAR; PG8_SCHED;
	v_mfma_f32_16x16x32_bf16 v[64:67], v[186:189], v[246:249], v[64:67]
	s_setprio 0
	s_add_i32 s48, s85, s52
	v_lshl_add_u64 v[222:223], v[222:223], 0, s[90:91]
	s_mov_b32 m0, s48
	ds_read_b128 v[190:193], v180 offset:49152
	ds_read_b128 v[194:197], v180 offset:50176
	ds_read_b128 v[198:201], v180 offset:51200
	ds_read_b128 v[204:207], v180 offset:52224
	ds_read_b128 v[218:221], v180 offset:53248
	ds_read_b128 v[238:241], v180 offset:54272
	ds_read_b128 v[242:245], v180 offset:55296
	ds_read_b128 v[246:249], v180 offset:56320
	global_load_lds_dwordx4 v[222:223], off
	s_add_i32 m0, s48, 0x2000
	s_add_u32 s46, s46, 0x40080
	v_lshl_add_u64 v[222:223], v[224:225], 0, s[90:91]
	s_addc_u32 s47, s47, 0
	s_add_i32 s48, s86, s52
	global_load_lds_dwordx4 v[222:223], off
	v_lshl_add_u64 v[222:223], s[46:47], 0, v[146:147]
	s_mov_b32 m0, s48
	s_nop 0
	global_load_lds_dwordx4 v[222:223], off
	v_lshl_add_u64 v[222:223], s[46:47], 0, v[150:151]
	s_add_i32 m0, s48, 0x2000
	s_nop 0
	global_load_lds_dwordx4 v[222:223], off
	v_lshl_add_u64 v[222:223], s[28:29], 0, v[144:145]
	s_mov_b32 m0, s60
	s_nop 0
	global_load_lds_dwordx4 v[222:223], off
	v_lshl_add_u64 v[222:223], s[28:29], 0, v[148:149]
	s_mov_b32 m0, s61
	s_nop 0
	global_load_lds_dwordx4 v[222:223], off
	s_waitcnt vmcnt(8)
	s_waitcnt lgkmcnt(0)
	s_barrier
	s_setprio 1
	s_waitcnt lgkmcnt(0)
	v_mfma_f32_16x16x32_bf16 v[60:63], v[132:135], v[190:193], v[60:63]
	v_mfma_f32_16x16x32_bf16 v[56:59], v[140:143], v[190:193], v[56:59]
	v_mfma_f32_16x16x32_bf16 v[44:47], v[132:135], v[198:201], v[44:47]
	v_mfma_f32_16x16x32_bf16 v[40:43], v[140:143], v[198:201], v[40:43]
	v_mfma_f32_16x16x32_bf16 v[28:31], v[132:135], v[218:221], v[28:31]
	v_mfma_f32_16x16x32_bf16 v[24:27], v[140:143], v[218:221], v[24:27]
	v_mfma_f32_16x16x32_bf16 v[12:15], v[132:135], v[242:245], v[12:15]
	v_mfma_f32_16x16x32_bf16 v[8:11], v[140:143], v[242:245], v[8:11]
	v_mfma_f32_16x16x32_bf16 v[60:63], v[136:139], v[194:197], v[60:63]
	v_mfma_f32_16x16x32_bf16 v[56:59], v[158:161], v[194:197], v[56:59]
	v_mfma_f32_16x16x32_bf16 v[44:47], v[136:139], v[204:207], v[44:47]
	v_mfma_f32_16x16x32_bf16 v[40:43], v[158:161], v[204:207], v[40:43]
	v_mfma_f32_16x16x32_bf16 v[28:31], v[136:139], v[238:241], v[28:31]
	v_mfma_f32_16x16x32_bf16 v[24:27], v[158:161], v[238:241], v[24:27]
	v_mfma_f32_16x16x32_bf16 v[12:15], v[136:139], v[246:249], v[12:15]
	v_mfma_f32_16x16x32_bf16 v[8:11], v[158:161], v[246:249], v[8:11]
	s_setprio 0
	s_setprio 1
	v_mfma_f32_16x16x32_bf16 v[52:55], v[162:165], v[190:193], v[52:55]
	v_mfma_f32_16x16x32_bf16 v[48:51], v[182:185], v[190:193], v[48:51]
	v_mfma_f32_16x16x32_bf16 v[36:39], v[162:165], v[198:201], v[36:39]
	v_mfma_f32_16x16x32_bf16 v[32:35], v[182:185], v[198:201], v[32:35]
	v_mfma_f32_16x16x32_bf16 v[20:23], v[162:165], v[218:221], v[20:23]
	v_mfma_f32_16x16x32_bf16 v[16:19], v[182:185], v[218:221], v[16:19]
	v_mfma_f32_16x16x32_bf16 v[4:7], v[162:165], v[242:245], v[4:7]
	v_mfma_f32_16x16x32_bf16 v[0:3], v[182:185], v[242:245], v[0:3]
	v_mfma_f32_16x16x32_bf16 v[52:55], v[166:169], v[194:197], v[52:55]
	v_mfma_f32_16x16x32_bf16 v[48:51], v[186:189], v[194:197], v[48:51]
	v_mfma_f32_16x16x32_bf16 v[36:39], v[166:169], v[204:207], v[36:39]
	v_mfma_f32_16x16x32_bf16 v[32:35], v[186:189], v[204:207], v[32:35]
	v_mfma_f32_16x16x32_bf16 v[20:23], v[166:169], v[238:241], v[20:23]
	v_mfma_f32_16x16x32_bf16 v[16:19], v[186:189], v[238:241], v[16:19]
	v_mfma_f32_16x16x32_bf16 v[4:7], v[166:169], v[246:249], v[4:7]
	s_barrier
	v_mfma_f32_16x16x32_bf16 v[0:3], v[186:189], v[246:249], v[0:3]
	s_setprio 0
	s_add_i32 s84, s84, 2
	s_add_u32 s2, s2, 0x100
	s_addc_u32 s3, s3, 0
	s_cmp_gt_u32 s84, 13
	s_cbranch_scc0 .LBB0_380
	s_branch .Lpeel_exit_380
.LBB0_380:
	s_add_u32 s28, s1, s2
	s_addc_u32 s29, s77, s3
	s_add_u32 s48, s28, 0x100
	s_addc_u32 s49, s29, 0
	s_add_u32 s46, s82, s2
	s_addc_u32 s47, s83, s3
	s_add_u32 s28, s28, 0x180
	s_addc_u32 s29, s29, 0
	s_add_i32 s85, 0, 0x10000
	s_add_i32 s88, 0, 0x14000
	v_add_u32_e32 v158, s85, v174
	v_add_u32_e32 v186, s88, v174
	ds_read_b128 v[132:135], v158
	ds_read_b128 v[136:139], v158 offset:1024
	ds_read_b128 v[140:143], v158 offset:2048
	ds_read_b128 v[158:161], v158 offset:3072
	ds_read_b128 v[162:165], v186
	ds_read_b128 v[166:169], v186 offset:1024
	ds_read_b128 v[182:185], v186 offset:2048
	ds_read_b128 v[186:189], v186 offset:3072
	s_cmpk_eq_i32 s2, 0x700
	s_cselect_b32 s29, s81, s29
	s_cselect_b32 s28, s80, s28
	s_cselect_b32 s47, s76, s47
	s_cselect_b32 s46, s75, s46
	s_cselect_b32 s49, s79, s49
	s_cselect_b32 s48, s78, s48
	v_lshl_add_u64 v[222:223], v[128:129], 0, s[2:3]
	s_add_i32 m0, s27, 0xc000
	ds_read_b128 v[190:193], v180
	ds_read_b128 v[194:197], v180 offset:1024
	ds_read_b128 v[198:201], v180 offset:2048
	ds_read_b128 v[204:207], v180 offset:3072
	ds_read_b128 v[218:221], v180 offset:4096
	ds_read_b128 v[238:241], v180 offset:5120
	ds_read_b128 v[242:245], v180 offset:6144
	ds_read_b128 v[246:249], v180 offset:7168
	global_load_lds_dwordx4 v[222:223], off
	v_lshl_add_u64 v[222:223], v[130:131], 0, s[2:3]
	s_add_i32 m0, s27, 0xe000
	s_nop 0
	global_load_lds_dwordx4 v[222:223], off
	s_waitcnt vmcnt(8)
	s_waitcnt lgkmcnt(0)
	s_barrier
; #define PG8_STAGE(bufoff, gbase, voff) do { _Pragma("unroll") for (int _i = 0; _i < 2; ++_i) \
;         __builtin_amdgcn_global_load_lds((const unsigned*)((const char*)(gbase) + (voff)[_i]), (PG8_LAS unsigned*)(lds + (bufoff) + ldsw + _i * 8192), 16, 0, 0); } while (0)
; #define PG8_LDA(dst, b, h) do { _Pragma("unroll") for (int m = 0; m < 4; ++m) _Pragma("unroll") for (int k = 0; k < 2; ++k) dst[m][k] = *(const PG8_LAS bf16x8*)(lds + PG8_SA(b, h) + aoff + m * 2048 + k * 1024); } while (0)
; #define PG8_LDB(dst, b, h) do { _Pragma("unroll") for (int n = 0; n < 2; ++n) _Pragma("unroll") for (int k = 0; k < 2; ++k) dst[n][k] = *(const PG8_LAS bf16x8*)(lds + PG8_SB(b, h) + boff + n * 2048 + k * 1024); } while (0)
; #define PG8_MMA(ai, bj, At, Bt) do { __builtin_amdgcn_s_setprio(1); _Pragma("unroll") for (int m = 0; m < 4; ++m) _Pragma("unroll") for (int n = 0; n < 2; ++n) _Pragma("unroll") for (int k = 0; k < 2; ++k) \
;         acc[ai][bj][m][n] = __builtin_amdgcn_mfma_f32_16x16x32_bf16(Bt[n][k], At[m][k], acc[ai][bj][m][n], 0, 0, 0); __builtin_amdgcn_s_setprio(0); } while (0)
; #define PG8_WAIT_V(n) asm volatile("s_waitcnt vmcnt(" #n ")" ::: "memory")
; #define PG8_WAIT_L(n) asm volatile("s_waitcnt lgkmcnt(" #n ")" ::: "memory")
; #define PG8_BAR __builtin_amdgcn_s_barrier()
; #define PG8_SCHED __builtin_amdgcn_sched_barrier(0)
;     ...
;             PG8_WAIT_V(8); PG8_WAIT_L(0); PG8_BAR; PG8_MMA(0, 0, At, B0); PG8_MMA(0, 1, At, B1); PG8_BAR; PG8_SCHED;
;             PG8_LDA(At, 0, 1); PG8_STAGE(PG8_SB(0, 0), b2, voffB); PG8_STAGE(PG8_SB(0, 1), b2 + hstepB, voffB); PG8_STAGE(PG8_SA(0, 0), a2, voffA);
;             PG8_WAIT_V(8); PG8_WAIT_L(0); PG8_BAR; PG8_MMA(1, 0, At, B0); PG8_MMA(1, 1, At, B1); PG8_BAR; PG8_SCHED;
;             PG8_LDB(B0, 1, 0); PG8_LDB(B1, 1, 1); PG8_SCHED; PG8_LDA(At, 1, 0); PG8_STAGE(PG8_SA(0, 1), a2 + hstepA, voffA);
;             PG8_WAIT_V(8); PG8_WAIT_L(0); PG8_BAR; PG8_MMA(0, 0, At, B0); PG8_MMA(0, 1, At, B1); PG8_BAR; PG8_SCHED;
	s_setprio 1
	s_waitcnt lgkmcnt(0)
	v_mfma_f32_16x16x32_bf16 v[124:127], v[132:135], v[190:193], v[124:127]
	v_mfma_f32_16x16x32_bf16 v[120:123], v[140:143], v[190:193], v[120:123]
	v_mfma_f32_16x16x32_bf16 v[108:111], v[132:135], v[198:201], v[108:111]
	v_mfma_f32_16x16x32_bf16 v[104:107], v[140:143], v[198:201], v[104:107]
	v_mfma_f32_16x16x32_bf16 v[92:95], v[132:135], v[218:221], v[92:95]
	v_mfma_f32_16x16x32_bf16 v[88:91], v[140:143], v[218:221], v[88:91]
	v_mfma_f32_16x16x32_bf16 v[76:79], v[132:135], v[242:245], v[76:79]
	v_mfma_f32_16x16x32_bf16 v[72:75], v[140:143], v[242:245], v[72:75]
	v_mfma_f32_16x16x32_bf16 v[124:127], v[136:139], v[194:197], v[124:127]
	v_mfma_f32_16x16x32_bf16 v[120:123], v[158:161], v[194:197], v[120:123]
	v_mfma_f32_16x16x32_bf16 v[108:111], v[136:139], v[204:207], v[108:111]
	v_mfma_f32_16x16x32_bf16 v[104:107], v[158:161], v[204:207], v[104:107]
	v_mfma_f32_16x16x32_bf16 v[92:95], v[136:139], v[238:241], v[92:95]
	v_mfma_f32_16x16x32_bf16 v[88:91], v[158:161], v[238:241], v[88:91]
	v_mfma_f32_16x16x32_bf16 v[76:79], v[136:139], v[246:249], v[76:79]
	v_mfma_f32_16x16x32_bf16 v[72:75], v[158:161], v[246:249], v[72:75]
	s_setprio 0
	s_setprio 1
	v_mfma_f32_16x16x32_bf16 v[116:119], v[162:165], v[190:193], v[116:119]
	v_mfma_f32_16x16x32_bf16 v[112:115], v[182:185], v[190:193], v[112:115]
	v_mfma_f32_16x16x32_bf16 v[100:103], v[162:165], v[198:201], v[100:103]
	v_mfma_f32_16x16x32_bf16 v[96:99], v[182:185], v[198:201], v[96:99]
	v_mfma_f32_16x16x32_bf16 v[84:87], v[162:165], v[218:221], v[84:87]
	v_mfma_f32_16x16x32_bf16 v[80:83], v[182:185], v[218:221], v[80:83]
	v_mfma_f32_16x16x32_bf16 v[68:71], v[162:165], v[242:245], v[68:71]
	v_mfma_f32_16x16x32_bf16 v[64:67], v[182:185], v[242:245], v[64:67]
	v_mfma_f32_16x16x32_bf16 v[116:119], v[166:169], v[194:197], v[116:119]
	v_mfma_f32_16x16x32_bf16 v[112:115], v[186:189], v[194:197], v[112:115]
	v_mfma_f32_16x16x32_bf16 v[100:103], v[166:169], v[204:207], v[100:103]
	v_mfma_f32_16x16x32_bf16 v[96:99], v[186:189], v[204:207], v[96:99]
	v_mfma_f32_16x16x32_bf16 v[84:87], v[166:169], v[238:241], v[84:87]
	v_mfma_f32_16x16x32_bf16 v[80:83], v[186:189], v[238:241], v[80:83]
	v_mfma_f32_16x16x32_bf16 v[68:71], v[166:169], v[246:249], v[68:71]
	s_barrier
	v_mfma_f32_16x16x32_bf16 v[64:67], v[186:189], v[246:249], v[64:67]
	s_setprio 0
	s_add_i32 s85, s85, s52
	v_lshl_add_u64 v[222:223], s[46:47], 0, v[146:147]
	s_mov_b32 m0, s85
	ds_read_b128 v[190:193], v180 offset:16384
	ds_read_b128 v[194:197], v180 offset:17408
	ds_read_b128 v[198:201], v180 offset:18432
	ds_read_b128 v[204:207], v180 offset:19456
	ds_read_b128 v[218:221], v180 offset:20480
	ds_read_b128 v[238:241], v180 offset:21504
	ds_read_b128 v[242:245], v180 offset:22528
	ds_read_b128 v[246:249], v180 offset:23552
	global_load_lds_dwordx4 v[222:223], off
	s_add_i32 m0, s85, 0x2000
	s_add_u32 s86, s46, 0x40000
	v_lshl_add_u64 v[224:225], s[46:47], 0, v[150:151]
	s_addc_u32 s87, s47, 0
	s_add_i32 s85, s88, s52
	global_load_lds_dwordx4 v[224:225], off
	v_lshl_add_u64 v[250:251], s[86:87], 0, v[146:147]
	s_mov_b32 m0, s85
	s_nop 0
	global_load_lds_dwordx4 v[250:251], off
	v_lshl_add_u64 v[250:251], s[86:87], 0, v[150:151]
	s_add_i32 m0, s85, 0x2000
	s_nop 0
	global_load_lds_dwordx4 v[250:251], off
	v_lshl_add_u64 v[250:251], s[48:49], 0, v[144:145]
	s_mov_b32 m0, s27
	s_nop 0
	global_load_lds_dwordx4 v[250:251], off
	v_lshl_add_u64 v[250:251], s[48:49], 0, v[148:149]
	s_mov_b32 m0, s57
	s_nop 0
	global_load_lds_dwordx4 v[250:251], off
	s_waitcnt vmcnt(8)
	s_waitcnt lgkmcnt(0)
	s_barrier
	s_setprio 1
	s_waitcnt lgkmcnt(0)
	v_mfma_f32_16x16x32_bf16 v[60:63], v[132:135], v[190:193], v[60:63]
	v_mfma_f32_16x16x32_bf16 v[56:59], v[140:143], v[190:193], v[56:59]
	v_mfma_f32_16x16x32_bf16 v[44:47], v[132:135], v[198:201], v[44:47]
	v_mfma_f32_16x16x32_bf16 v[40:43], v[140:143], v[198:201], v[40:43]
	v_mfma_f32_16x16x32_bf16 v[28:31], v[132:135], v[218:221], v[28:31]
	v_mfma_f32_16x16x32_bf16 v[24:27], v[140:143], v[218:221], v[24:27]
	v_mfma_f32_16x16x32_bf16 v[12:15], v[132:135], v[242:245], v[12:15]
	v_mfma_f32_16x16x32_bf16 v[8:11], v[140:143], v[242:245], v[8:11]
	v_mfma_f32_16x16x32_bf16 v[60:63], v[136:139], v[194:197], v[60:63]
	v_mfma_f32_16x16x32_bf16 v[56:59], v[158:161], v[194:197], v[56:59]
	v_mfma_f32_16x16x32_bf16 v[44:47], v[136:139], v[204:207], v[44:47]
	v_mfma_f32_16x16x32_bf16 v[40:43], v[158:161], v[204:207], v[40:43]
	v_mfma_f32_16x16x32_bf16 v[28:31], v[136:139], v[238:241], v[28:31]
	v_mfma_f32_16x16x32_bf16 v[24:27], v[158:161], v[238:241], v[24:27]
	v_mfma_f32_16x16x32_bf16 v[12:15], v[136:139], v[246:249], v[12:15]
	v_mfma_f32_16x16x32_bf16 v[8:11], v[158:161], v[246:249], v[8:11]
	s_setprio 0
	s_setprio 1
	v_mfma_f32_16x16x32_bf16 v[52:55], v[162:165], v[190:193], v[52:55]
	v_mfma_f32_16x16x32_bf16 v[48:51], v[182:185], v[190:193], v[48:51]
	v_mfma_f32_16x16x32_bf16 v[36:39], v[162:165], v[198:201], v[36:39]
	v_mfma_f32_16x16x32_bf16 v[32:35], v[182:185], v[198:201], v[32:35]
	v_mfma_f32_16x16x32_bf16 v[20:23], v[162:165], v[218:221], v[20:23]
	v_mfma_f32_16x16x32_bf16 v[16:19], v[182:185], v[218:221], v[16:19]
	v_mfma_f32_16x16x32_bf16 v[4:7], v[162:165], v[242:245], v[4:7]
	v_mfma_f32_16x16x32_bf16 v[0:3], v[182:185], v[242:245], v[0:3]
	v_mfma_f32_16x16x32_bf16 v[52:55], v[166:169], v[194:197], v[52:55]
	v_mfma_f32_16x16x32_bf16 v[48:51], v[186:189], v[194:197], v[48:51]
	v_mfma_f32_16x16x32_bf16 v[36:39], v[166:169], v[204:207], v[36:39]
	v_mfma_f32_16x16x32_bf16 v[32:35], v[186:189], v[204:207], v[32:35]
	v_mfma_f32_16x16x32_bf16 v[20:23], v[166:169], v[238:241], v[20:23]
	v_mfma_f32_16x16x32_bf16 v[16:19], v[186:189], v[238:241], v[16:19]
	v_mfma_f32_16x16x32_bf16 v[4:7], v[166:169], v[246:249], v[4:7]
	s_barrier
; #define PG8_STAGE(bufoff, gbase, voff) do { _Pragma("unroll") for (int _i = 0; _i < 2; ++_i) \
;         __builtin_amdgcn_global_load_lds((const unsigned*)((const char*)(gbase) + (voff)[_i]), (PG8_LAS unsigned*)(lds + (bufoff) + ldsw + _i * 8192), 16, 0, 0); } while (0)
; #define PG8_LDA(dst, b, h) do { _Pragma("unroll") for (int m = 0; m < 4; ++m) _Pragma("unroll") for (int k = 0; k < 2; ++k) dst[m][k] = *(const PG8_LAS bf16x8*)(lds + PG8_SA(b, h) + aoff + m * 2048 + k * 1024); } while (0)
; #define PG8_LDB(dst, b, h) do { _Pragma("unroll") for (int n = 0; n < 2; ++n) _Pragma("unroll") for (int k = 0; k < 2; ++k) dst[n][k] = *(const PG8_LAS bf16x8*)(lds + PG8_SB(b, h) + boff + n * 2048 + k * 1024); } while (0)
; #define PG8_MMA(ai, bj, At, Bt) do { __builtin_amdgcn_s_setprio(1); _Pragma("unroll") for (int m = 0; m < 4; ++m) _Pragma("unroll") for (int n = 0; n < 2; ++n) _Pragma("unroll") for (int k = 0; k < 2; ++k) \
;         acc[ai][bj][m][n] = __builtin_amdgcn_mfma_f32_16x16x32_bf16(Bt[n][k], At[m][k], acc[ai][bj][m][n], 0, 0, 0); __builtin_amdgcn_s_setprio(0); } while (0)
; #define PG8_WAIT_V(n) asm volatile("s_waitcnt vmcnt(" #n ")" ::: "memory")
; #define PG8_WAIT_L(n) asm volatile("s_waitcnt lgkmcnt(" #n ")" ::: "memory")
; #define PG8_BAR __builtin_amdgcn_s_barrier()
; #define PG8_SCHED __builtin_amdgcn_sched_barrier(0)
;     ...
;             PG8_WAIT_V(8); PG8_WAIT_L(0); PG8_BAR; PG8_MMA(1, 0, At, B0); PG8_MMA(1, 1, At, B1); PG8_BAR; PG8_SCHED;
;             PG8_LDB(B0, 1, 0); PG8_LDB(B1, 1, 1); PG8_SCHED; PG8_LDA(At, 1, 0); PG8_STAGE(PG8_SA(0, 1), a2 + hstepA, voffA);
;             PG8_WAIT_V(8); PG8_WAIT_L(0); PG8_BAR; PG8_MMA(0, 0, At, B0); PG8_MMA(0, 1, At, B1); PG8_BAR; PG8_SCHED;
	v_mfma_f32_16x16x32_bf16 v[0:3], v[186:189], v[246:249], v[0:3]
	s_setprio 0
	s_add_i32 s85, 0, 0x18000
	s_add_i32 s86, 0, 0x1c000
	v_add_u32_e32 v158, s85, v174
	v_add_u32_e32 v186, s86, v174
	ds_read_b128 v[132:135], v158
	ds_read_b128 v[136:139], v158 offset:1024
	ds_read_b128 v[140:143], v158 offset:2048
	ds_read_b128 v[158:161], v158 offset:3072
	ds_read_b128 v[162:165], v186
	ds_read_b128 v[166:169], v186 offset:1024
	ds_read_b128 v[182:185], v186 offset:2048
	ds_read_b128 v[186:189], v186 offset:3072
	s_add_u32 s48, s48, 0x40000
	s_addc_u32 s49, s49, 0
	s_mov_b32 m0, s58
	v_lshl_add_u64 v[250:251], s[48:49], 0, v[144:145]
	ds_read_b128 v[190:193], v180 offset:32768
	ds_read_b128 v[194:197], v180 offset:33792
	ds_read_b128 v[198:201], v180 offset:34816
	ds_read_b128 v[204:207], v180 offset:35840
	ds_read_b128 v[218:221], v180 offset:36864
	ds_read_b128 v[238:241], v180 offset:37888
	ds_read_b128 v[242:245], v180 offset:38912
	ds_read_b128 v[246:249], v180 offset:39936
	global_load_lds_dwordx4 v[250:251], off
	v_lshl_add_u64 v[250:251], s[48:49], 0, v[148:149]
	s_mov_b32 m0, s59
	s_nop 0
	global_load_lds_dwordx4 v[250:251], off
	s_waitcnt vmcnt(8)
	s_waitcnt lgkmcnt(0)
	s_barrier
	s_setprio 1
	s_waitcnt lgkmcnt(0)
	v_mfma_f32_16x16x32_bf16 v[124:127], v[132:135], v[190:193], v[124:127]
	v_mfma_f32_16x16x32_bf16 v[120:123], v[140:143], v[190:193], v[120:123]
	v_mfma_f32_16x16x32_bf16 v[108:111], v[132:135], v[198:201], v[108:111]
	v_mfma_f32_16x16x32_bf16 v[104:107], v[140:143], v[198:201], v[104:107]
	v_mfma_f32_16x16x32_bf16 v[92:95], v[132:135], v[218:221], v[92:95]
	v_mfma_f32_16x16x32_bf16 v[88:91], v[140:143], v[218:221], v[88:91]
	v_mfma_f32_16x16x32_bf16 v[76:79], v[132:135], v[242:245], v[76:79]
	v_mfma_f32_16x16x32_bf16 v[72:75], v[140:143], v[242:245], v[72:75]
	v_mfma_f32_16x16x32_bf16 v[124:127], v[136:139], v[194:197], v[124:127]
	v_mfma_f32_16x16x32_bf16 v[120:123], v[158:161], v[194:197], v[120:123]
	v_mfma_f32_16x16x32_bf16 v[108:111], v[136:139], v[204:207], v[108:111]
	v_mfma_f32_16x16x32_bf16 v[104:107], v[158:161], v[204:207], v[104:107]
	v_mfma_f32_16x16x32_bf16 v[92:95], v[136:139], v[238:241], v[92:95]
	v_mfma_f32_16x16x32_bf16 v[88:91], v[158:161], v[238:241], v[88:91]
	v_mfma_f32_16x16x32_bf16 v[76:79], v[136:139], v[246:249], v[76:79]
	v_mfma_f32_16x16x32_bf16 v[72:75], v[158:161], v[246:249], v[72:75]
	s_setprio 0
	s_setprio 1
	v_mfma_f32_16x16x32_bf16 v[116:119], v[162:165], v[190:193], v[116:119]
	v_mfma_f32_16x16x32_bf16 v[112:115], v[182:185], v[190:193], v[112:115]
	v_mfma_f32_16x16x32_bf16 v[100:103], v[162:165], v[198:201], v[100:103]
	v_mfma_f32_16x16x32_bf16 v[96:99], v[182:185], v[198:201], v[96:99]
	v_mfma_f32_16x16x32_bf16 v[84:87], v[162:165], v[218:221], v[84:87]
	v_mfma_f32_16x16x32_bf16 v[80:83], v[182:185], v[218:221], v[80:83]
	v_mfma_f32_16x16x32_bf16 v[68:71], v[162:165], v[242:245], v[68:71]
	v_mfma_f32_16x16x32_bf16 v[64:67], v[182:185], v[242:245], v[64:67]
	v_mfma_f32_16x16x32_bf16 v[116:119], v[166:169], v[194:197], v[116:119]
	v_mfma_f32_16x16x32_bf16 v[112:115], v[186:189], v[194:197], v[112:115]
	v_mfma_f32_16x16x32_bf16 v[100:103], v[166:169], v[204:207], v[100:103]
	v_mfma_f32_16x16x32_bf16 v[96:99], v[186:189], v[204:207], v[96:99]
	v_mfma_f32_16x16x32_bf16 v[84:87], v[166:169], v[238:241], v[84:87]
	v_mfma_f32_16x16x32_bf16 v[80:83], v[186:189], v[238:241], v[80:83]
	v_mfma_f32_16x16x32_bf16 v[68:71], v[166:169], v[246:249], v[68:71]
	s_barrier
; #define PG8_STAGE(bufoff, gbase, voff) do { _Pragma("unroll") for (int _i = 0; _i < 2; ++_i) \
;         __builtin_amdgcn_global_load_lds((const unsigned*)((const char*)(gbase) + (voff)[_i]), (PG8_LAS unsigned*)(lds + (bufoff) + ldsw + _i * 8192), 16, 0, 0); } while (0)
; #define PG8_LDA(dst, b, h) do { _Pragma("unroll") for (int m = 0; m < 4; ++m) _Pragma("unroll") for (int k = 0; k < 2; ++k) dst[m][k] = *(const PG8_LAS bf16x8*)(lds + PG8_SA(b, h) + aoff + m * 2048 + k * 1024); } while (0)
; #define PG8_MMA(ai, bj, At, Bt) do { __builtin_amdgcn_s_setprio(1); _Pragma("unroll") for (int m = 0; m < 4; ++m) _Pragma("unroll") for (int n = 0; n < 2; ++n) _Pragma("unroll") for (int k = 0; k < 2; ++k) \
;         acc[ai][bj][m][n] = __builtin_amdgcn_mfma_f32_16x16x32_bf16(Bt[n][k], At[m][k], acc[ai][bj][m][n], 0, 0, 0); __builtin_amdgcn_s_setprio(0); } while (0)
; #define PG8_WAIT_V(n) asm volatile("s_waitcnt vmcnt(" #n ")" ::: "memory")
; #define PG8_WAIT_L(n) asm volatile("s_waitcnt lgkmcnt(" #n ")" ::: "memory")
; #define PG8_BAR __builtin_amdgcn_s_barrier()
; #define PG8_SCHED __builtin_amdgcn_sched_barrier(0)
;     ...
;             PG8_WAIT_V(8); PG8_WAIT_L(0); PG8_BAR; PG8_MMA(0, 0, At, B0); PG8_MMA(0, 1, At, B1); PG8_BAR; PG8_SCHED;
;             PG8_LDA(At, 1, 1); PG8_STAGE(PG8_SB(1, 0), b3, voffB); PG8_STAGE(PG8_SB(1, 1), b3 + hstepB, voffB); PG8_STAGE(PG8_SA(1, 0), a3, voffA);
;             PG8_WAIT_V(8); PG8_WAIT_L(0); PG8_BAR; PG8_MMA(1, 0, At, B0); PG8_MMA(1, 1, At, B1); PG8_BAR; PG8_SCHED;
	v_mfma_f32_16x16x32_bf16 v[64:67], v[186:189], v[246:249], v[64:67]
	s_setprio 0
	s_add_i32 s48, s85, s52
	v_lshl_add_u64 v[222:223], v[222:223], 0, s[90:91]
	s_mov_b32 m0, s48
	ds_read_b128 v[190:193], v180 offset:49152
	ds_read_b128 v[194:197], v180 offset:50176
	ds_read_b128 v[198:201], v180 offset:51200
	ds_read_b128 v[204:207], v180 offset:52224
	ds_read_b128 v[218:221], v180 offset:53248
	ds_read_b128 v[238:241], v180 offset:54272
	ds_read_b128 v[242:245], v180 offset:55296
	ds_read_b128 v[246:249], v180 offset:56320
	global_load_lds_dwordx4 v[222:223], off
	s_add_i32 m0, s48, 0x2000
	s_add_u32 s46, s46, 0x40080
	v_lshl_add_u64 v[222:223], v[224:225], 0, s[90:91]
	s_addc_u32 s47, s47, 0
	s_add_i32 s48, s86, s52
	global_load_lds_dwordx4 v[222:223], off
	v_lshl_add_u64 v[222:223], s[46:47], 0, v[146:147]
	s_mov_b32 m0, s48
	s_nop 0
	global_load_lds_dwordx4 v[222:223], off
	v_lshl_add_u64 v[222:223], s[46:47], 0, v[150:151]
	s_add_i32 m0, s48, 0x2000
	s_nop 0
	global_load_lds_dwordx4 v[222:223], off
	v_lshl_add_u64 v[222:223], s[28:29], 0, v[144:145]
	s_mov_b32 m0, s60
	s_nop 0
	global_load_lds_dwordx4 v[222:223], off
	v_lshl_add_u64 v[222:223], s[28:29], 0, v[148:149]
	s_mov_b32 m0, s61
	s_nop 0
	global_load_lds_dwordx4 v[222:223], off
	s_waitcnt vmcnt(8)
	s_waitcnt lgkmcnt(0)
	s_barrier
	s_setprio 1
	s_waitcnt lgkmcnt(0)
	v_mfma_f32_16x16x32_bf16 v[60:63], v[132:135], v[190:193], v[60:63]
	v_mfma_f32_16x16x32_bf16 v[56:59], v[140:143], v[190:193], v[56:59]
	v_mfma_f32_16x16x32_bf16 v[44:47], v[132:135], v[198:201], v[44:47]
	v_mfma_f32_16x16x32_bf16 v[40:43], v[140:143], v[198:201], v[40:43]
	v_mfma_f32_16x16x32_bf16 v[28:31], v[132:135], v[218:221], v[28:31]
	v_mfma_f32_16x16x32_bf16 v[24:27], v[140:143], v[218:221], v[24:27]
	v_mfma_f32_16x16x32_bf16 v[12:15], v[132:135], v[242:245], v[12:15]
	v_mfma_f32_16x16x32_bf16 v[8:11], v[140:143], v[242:245], v[8:11]
	v_mfma_f32_16x16x32_bf16 v[60:63], v[136:139], v[194:197], v[60:63]
	v_mfma_f32_16x16x32_bf16 v[56:59], v[158:161], v[194:197], v[56:59]
	v_mfma_f32_16x16x32_bf16 v[44:47], v[136:139], v[204:207], v[44:47]
	v_mfma_f32_16x16x32_bf16 v[40:43], v[158:161], v[204:207], v[40:43]
	v_mfma_f32_16x16x32_bf16 v[28:31], v[136:139], v[238:241], v[28:31]
	v_mfma_f32_16x16x32_bf16 v[24:27], v[158:161], v[238:241], v[24:27]
	v_mfma_f32_16x16x32_bf16 v[12:15], v[136:139], v[246:249], v[12:15]
	v_mfma_f32_16x16x32_bf16 v[8:11], v[158:161], v[246:249], v[8:11]
	s_setprio 0
	s_setprio 1
	v_mfma_f32_16x16x32_bf16 v[52:55], v[162:165], v[190:193], v[52:55]
	v_mfma_f32_16x16x32_bf16 v[48:51], v[182:185], v[190:193], v[48:51]
	v_mfma_f32_16x16x32_bf16 v[36:39], v[162:165], v[198:201], v[36:39]
	v_mfma_f32_16x16x32_bf16 v[32:35], v[182:185], v[198:201], v[32:35]
	v_mfma_f32_16x16x32_bf16 v[20:23], v[162:165], v[218:221], v[20:23]
	v_mfma_f32_16x16x32_bf16 v[16:19], v[182:185], v[218:221], v[16:19]
	v_mfma_f32_16x16x32_bf16 v[4:7], v[162:165], v[242:245], v[4:7]
	v_mfma_f32_16x16x32_bf16 v[0:3], v[182:185], v[242:245], v[0:3]
	v_mfma_f32_16x16x32_bf16 v[52:55], v[166:169], v[194:197], v[52:55]
	v_mfma_f32_16x16x32_bf16 v[48:51], v[186:189], v[194:197], v[48:51]
	v_mfma_f32_16x16x32_bf16 v[36:39], v[166:169], v[204:207], v[36:39]
	v_mfma_f32_16x16x32_bf16 v[32:35], v[186:189], v[204:207], v[32:35]
	v_mfma_f32_16x16x32_bf16 v[20:23], v[166:169], v[238:241], v[20:23]
	v_mfma_f32_16x16x32_bf16 v[16:19], v[186:189], v[238:241], v[16:19]
	v_mfma_f32_16x16x32_bf16 v[4:7], v[166:169], v[246:249], v[4:7]
	s_barrier
	v_mfma_f32_16x16x32_bf16 v[0:3], v[186:189], v[246:249], v[0:3]
	s_setprio 0
	s_add_i32 s84, s84, 2
	s_add_u32 s2, s2, 0x100
	s_addc_u32 s3, s3, 0
	s_cmp_gt_u32 s84, 13
	s_cbranch_scc0 .LBB0_380

;     __device__ __forceinline__ const char* tile(const Unit& u, int t) const { return A + (size_t)u.pm * 2 * hstep() + (size_t)t * (BK * 2); }
;     __device__ __forceinline__ const char* tile(const Unit& u, int t) const { return U + (long)(t >> 2) * xoff + (size_t)u.pn * (1024 * 512) + (size_t)u.pm * 2 * hstep() + (size_t)(t & 3) * (BK * 2); }
; #define PG8_STAGE(bufoff, gbase, voff) do { _Pragma("unroll") for (int _i = 0; _i < 2; ++_i) \
;         __builtin_amdgcn_global_load_lds((const unsigned*)((const char*)(gbase) + (voff)[_i]), (PG8_LAS unsigned*)(lds + (bufoff) + ldsw + _i * 8192), 16, 0, 0); } while (0)
; #define PG8_LDA(dst, b, h) do { _Pragma("unroll") for (int m = 0; m < 4; ++m) _Pragma("unroll") for (int k = 0; k < 2; ++k) dst[m][k] = *(const PG8_LAS bf16x8*)(lds + PG8_SA(b, h) + aoff + m * 2048 + k * 1024); } while (0)
; #define PG8_LDB(dst, b, h) do { _Pragma("unroll") for (int n = 0; n < 2; ++n) _Pragma("unroll") for (int k = 0; k < 2; ++k) dst[n][k] = *(const PG8_LAS bf16x8*)(lds + PG8_SB(b, h) + boff + n * 2048 + k * 1024); } while (0)
; #define PG8_MMA(ai, bj, At, Bt) do { __builtin_amdgcn_s_setprio(1); _Pragma("unroll") for (int m = 0; m < 4; ++m) _Pragma("unroll") for (int n = 0; n < 2; ++n) _Pragma("unroll") for (int k = 0; k < 2; ++k) \
;         acc[ai][bj][m][n] = __builtin_amdgcn_mfma_f32_16x16x32_bf16(Bt[n][k], At[m][k], acc[ai][bj][m][n], 0, 0, 0); __builtin_amdgcn_s_setprio(0); } while (0)
; #define PG8_WAIT_V(n) asm volatile("s_waitcnt vmcnt(" #n ")" ::: "memory")
;     ...
;             const bool last = (t == nt - 2);
;             const char* a1 = AS.tile(cur, t + 1);
;             const char* a2 = last ? AS.tile(nu, 0) : AS.tile(cur, t + 2); const char* b2 = last ? nB : cB + (size_t)(t + 2) * kstep;
;             const char* a3 = last ? AS.tile(nu, 1) : AS.tile(cur, t + 3); const char* b3 = b2 + kstep;
;             PG8_LDB(B0, 0, 0); PG8_LDB(B1, 0, 1); PG8_SCHED; PG8_LDA(At, 0, 0); PG8_STAGE(PG8_SA(1, 1), a1 + hstepA, voffA);
;             PG8_WAIT_V(8); PG8_WAIT_L(0); PG8_BAR; PG8_MMA(0, 0, At, B0); PG8_MMA(0, 1, At, B1); PG8_BAR; PG8_SCHED;
;             PG8_LDA(At, 0, 1); PG8_STAGE(PG8_SB(0, 0), b2, voffB); PG8_STAGE(PG8_SB(0, 1), b2 + hstepB, voffB); PG8_STAGE(PG8_SA(0, 0), a2, voffA);
;             PG8_WAIT_V(8); PG8_WAIT_L(0); PG8_BAR; PG8_MMA(1, 0, At, B0); PG8_MMA(1, 1, At, B1); PG8_BAR; PG8_SCHED;
.Lpeel_451:
	s_add_u32 s20, s61, s18
	s_addc_u32 s21, s64, s19
	s_add_u32 s26, s20, 0x3600100
	s_addc_u32 s27, s21, 0
	s_add_u32 s24, s65, s18
	s_addc_u32 s25, s66, s19
	s_add_u32 s20, s20, 0x3600180
	s_addc_u32 s21, s21, 0
	s_add_i32 s68, 0, 0x10000
	s_add_i32 s70, 0, 0x14000
	v_add_u32_e32 v144, s68, v203
	v_add_u32_e32 v174, s70, v203
	ds_read_b128 v[132:135], v144
	ds_read_b128 v[136:139], v144 offset:1024
	ds_read_b128 v[140:143], v144 offset:2048
	ds_read_b128 v[144:147], v144 offset:3072
	ds_read_b128 v[148:151], v174
	ds_read_b128 v[152:155], v174 offset:1024
	ds_read_b128 v[170:173], v174 offset:2048
	ds_read_b128 v[174:177], v174 offset:3072
	s_cmpk_eq_i32 s18, 0x700
	s_cselect_b32 s21, s60, s21
	s_cselect_b32 s20, s59, s20
	s_cselect_b32 s25, s57, s25
	s_cselect_b32 s24, s56, s24
	s_cselect_b32 s27, s58, s27
	s_cselect_b32 s26, s3, s26
	v_lshl_add_u64 v[238:239], v[112:113], 0, s[18:19]
	s_add_i32 m0, s35, 0xc000
	ds_read_b128 v[178:181], v211
	ds_read_b128 v[182:185], v211 offset:1024
	ds_read_b128 v[186:189], v211 offset:2048
	ds_read_b128 v[190:193], v211 offset:3072
	ds_read_b128 v[194:197], v211 offset:4096
	ds_read_b128 v[198:201], v211 offset:5120
	ds_read_b128 v[218:221], v211 offset:6144
	ds_read_b128 v[222:225], v211 offset:7168
	global_load_lds_dwordx4 v[238:239], off
	v_lshl_add_u64 v[238:239], v[114:115], 0, s[18:19]
	s_add_i32 m0, s35, 0xe000
	s_nop 0
	global_load_lds_dwordx4 v[238:239], off
	s_waitcnt vmcnt(24)
	s_waitcnt lgkmcnt(0)
	s_barrier
	s_setprio 1
	s_waitcnt lgkmcnt(0)
	v_mfma_f32_16x16x32_bf16 v[120:123], v[132:135], v[178:181], 0
	v_mfma_f32_16x16x32_bf16 v[116:119], v[140:143], v[178:181], 0
	v_mfma_f32_16x16x32_bf16 v[108:111], v[132:135], v[186:189], 0
	v_mfma_f32_16x16x32_bf16 v[104:107], v[140:143], v[186:189], 0
	v_mfma_f32_16x16x32_bf16 v[92:95], v[132:135], v[194:197], 0
	v_mfma_f32_16x16x32_bf16 v[88:91], v[140:143], v[194:197], 0
	v_mfma_f32_16x16x32_bf16 v[76:79], v[132:135], v[218:221], 0
	v_mfma_f32_16x16x32_bf16 v[72:75], v[140:143], v[218:221], 0
	v_mfma_f32_16x16x32_bf16 v[120:123], v[136:139], v[182:185], v[120:123]
	v_mfma_f32_16x16x32_bf16 v[116:119], v[144:147], v[182:185], v[116:119]
	v_mfma_f32_16x16x32_bf16 v[108:111], v[136:139], v[190:193], v[108:111]
	v_mfma_f32_16x16x32_bf16 v[104:107], v[144:147], v[190:193], v[104:107]
	v_mfma_f32_16x16x32_bf16 v[92:95], v[136:139], v[198:201], v[92:95]
	v_mfma_f32_16x16x32_bf16 v[88:91], v[144:147], v[198:201], v[88:91]
	v_mfma_f32_16x16x32_bf16 v[76:79], v[136:139], v[222:225], v[76:79]
	v_mfma_f32_16x16x32_bf16 v[72:75], v[144:147], v[222:225], v[72:75]
	s_setprio 0
	s_setprio 1
	v_mfma_f32_16x16x32_bf16 v[128:131], v[148:151], v[178:181], 0
	v_mfma_f32_16x16x32_bf16 v[124:127], v[170:173], v[178:181], 0
	v_mfma_f32_16x16x32_bf16 v[100:103], v[148:151], v[186:189], 0
	v_mfma_f32_16x16x32_bf16 v[96:99], v[170:173], v[186:189], 0
	v_mfma_f32_16x16x32_bf16 v[84:87], v[148:151], v[194:197], 0
	v_mfma_f32_16x16x32_bf16 v[80:83], v[170:173], v[194:197], 0
	v_mfma_f32_16x16x32_bf16 v[68:71], v[148:151], v[218:221], 0
	v_mfma_f32_16x16x32_bf16 v[64:67], v[170:173], v[218:221], 0
	v_mfma_f32_16x16x32_bf16 v[128:131], v[152:155], v[182:185], v[128:131]
	v_mfma_f32_16x16x32_bf16 v[124:127], v[174:177], v[182:185], v[124:127]
	v_mfma_f32_16x16x32_bf16 v[100:103], v[152:155], v[190:193], v[100:103]
	v_mfma_f32_16x16x32_bf16 v[96:99], v[174:177], v[190:193], v[96:99]
	v_mfma_f32_16x16x32_bf16 v[84:87], v[152:155], v[198:201], v[84:87]
	v_mfma_f32_16x16x32_bf16 v[80:83], v[174:177], v[198:201], v[80:83]
	v_mfma_f32_16x16x32_bf16 v[68:71], v[152:155], v[222:225], v[68:71]
	s_barrier
	v_mfma_f32_16x16x32_bf16 v[64:67], v[174:177], v[222:225], v[64:67]
	s_setprio 0
	s_add_i32 s68, s68, s31
	v_lshl_add_u64 v[238:239], s[24:25], 0, v[208:209]
	s_mov_b32 m0, s68
	ds_read_b128 v[178:181], v211 offset:16384
	ds_read_b128 v[182:185], v211 offset:17408
	ds_read_b128 v[186:189], v211 offset:18432
	ds_read_b128 v[190:193], v211 offset:19456
	ds_read_b128 v[194:197], v211 offset:20480
	ds_read_b128 v[198:201], v211 offset:21504
	ds_read_b128 v[218:221], v211 offset:22528
	ds_read_b128 v[222:225], v211 offset:23552
	global_load_lds_dwordx4 v[238:239], off
	s_add_i32 m0, s68, 0x2000
	s_add_u32 s68, s24, 0x40000
	v_lshl_add_u64 v[240:241], s[24:25], 0, v[156:157]
	s_addc_u32 s69, s25, 0
	s_add_i32 s70, s70, s31
	global_load_lds_dwordx4 v[240:241], off
	v_lshl_add_u64 v[242:243], s[68:69], 0, v[208:209]
	s_mov_b32 m0, s70
	s_nop 0
	global_load_lds_dwordx4 v[242:243], off
	v_lshl_add_u64 v[242:243], s[68:69], 0, v[156:157]
	s_add_i32 m0, s70, 0x2000
	s_nop 0
	global_load_lds_dwordx4 v[242:243], off
	v_lshl_add_u64 v[242:243], s[26:27], 0, v[160:161]
	s_mov_b32 m0, s35
	s_nop 0
	global_load_lds_dwordx4 v[242:243], off
	v_lshl_add_u64 v[242:243], s[26:27], 0, v[158:159]
	s_mov_b32 m0, s44
	s_nop 0
	global_load_lds_dwordx4 v[242:243], off
	s_waitcnt vmcnt(8)
	s_waitcnt lgkmcnt(0)
	s_barrier
; #define PG8_STAGE(bufoff, gbase, voff) do { _Pragma("unroll") for (int _i = 0; _i < 2; ++_i) \
;         __builtin_amdgcn_global_load_lds((const unsigned*)((const char*)(gbase) + (voff)[_i]), (PG8_LAS unsigned*)(lds + (bufoff) + ldsw + _i * 8192), 16, 0, 0); } while (0)
; #define PG8_LDA(dst, b, h) do { _Pragma("unroll") for (int m = 0; m < 4; ++m) _Pragma("unroll") for (int k = 0; k < 2; ++k) dst[m][k] = *(const PG8_LAS bf16x8*)(lds + PG8_SA(b, h) + aoff + m * 2048 + k * 1024); } while (0)
; #define PG8_LDB(dst, b, h) do { _Pragma("unroll") for (int n = 0; n < 2; ++n) _Pragma("unroll") for (int k = 0; k < 2; ++k) dst[n][k] = *(const PG8_LAS bf16x8*)(lds + PG8_SB(b, h) + boff + n * 2048 + k * 1024); } while (0)
; #define PG8_MMA(ai, bj, At, Bt) do { __builtin_amdgcn_s_setprio(1); _Pragma("unroll") for (int m = 0; m < 4; ++m) _Pragma("unroll") for (int n = 0; n < 2; ++n) _Pragma("unroll") for (int k = 0; k < 2; ++k) \
;         acc[ai][bj][m][n] = __builtin_amdgcn_mfma_f32_16x16x32_bf16(Bt[n][k], At[m][k], acc[ai][bj][m][n], 0, 0, 0); __builtin_amdgcn_s_setprio(0); } while (0)
; #define PG8_WAIT_V(n) asm volatile("s_waitcnt vmcnt(" #n ")" ::: "memory")
; #define PG8_WAIT_L(n) asm volatile("s_waitcnt lgkmcnt(" #n ")" ::: "memory")
; #define PG8_BAR __builtin_amdgcn_s_barrier()
; #define PG8_SCHED __builtin_amdgcn_sched_barrier(0)
;     ...
;             PG8_WAIT_V(8); PG8_WAIT_L(0); PG8_BAR; PG8_MMA(0, 0, At, B0); PG8_MMA(0, 1, At, B1); PG8_BAR; PG8_SCHED;
;             PG8_LDA(At, 0, 1); PG8_STAGE(PG8_SB(0, 0), b2, voffB); PG8_STAGE(PG8_SB(0, 1), b2 + hstepB, voffB); PG8_STAGE(PG8_SA(0, 0), a2, voffA);
;             PG8_WAIT_V(8); PG8_WAIT_L(0); PG8_BAR; PG8_MMA(1, 0, At, B0); PG8_MMA(1, 1, At, B1); PG8_BAR; PG8_SCHED;
;             PG8_LDB(B0, 1, 0); PG8_LDB(B1, 1, 1); PG8_SCHED; PG8_LDA(At, 1, 0); PG8_STAGE(PG8_SA(0, 1), a2 + hstepA, voffA);
;             PG8_WAIT_V(8); PG8_WAIT_L(0); PG8_BAR; PG8_MMA(0, 0, At, B0); PG8_MMA(0, 1, At, B1); PG8_BAR; PG8_SCHED;
	s_setprio 1
	s_waitcnt lgkmcnt(0)
	v_mfma_f32_16x16x32_bf16 v[60:63], v[132:135], v[178:181], 0
	v_mfma_f32_16x16x32_bf16 v[56:59], v[140:143], v[178:181], 0
	v_mfma_f32_16x16x32_bf16 v[44:47], v[132:135], v[186:189], 0
	v_mfma_f32_16x16x32_bf16 v[40:43], v[140:143], v[186:189], 0
	v_mfma_f32_16x16x32_bf16 v[28:31], v[132:135], v[194:197], 0
	v_mfma_f32_16x16x32_bf16 v[24:27], v[140:143], v[194:197], 0
	v_mfma_f32_16x16x32_bf16 v[12:15], v[132:135], v[218:221], 0
	v_mfma_f32_16x16x32_bf16 v[8:11], v[140:143], v[218:221], 0
	v_mfma_f32_16x16x32_bf16 v[60:63], v[136:139], v[182:185], v[60:63]
	v_mfma_f32_16x16x32_bf16 v[56:59], v[144:147], v[182:185], v[56:59]
	v_mfma_f32_16x16x32_bf16 v[44:47], v[136:139], v[190:193], v[44:47]
	v_mfma_f32_16x16x32_bf16 v[40:43], v[144:147], v[190:193], v[40:43]
	v_mfma_f32_16x16x32_bf16 v[28:31], v[136:139], v[198:201], v[28:31]
	v_mfma_f32_16x16x32_bf16 v[24:27], v[144:147], v[198:201], v[24:27]
	v_mfma_f32_16x16x32_bf16 v[12:15], v[136:139], v[222:225], v[12:15]
	v_mfma_f32_16x16x32_bf16 v[8:11], v[144:147], v[222:225], v[8:11]
	s_setprio 0
	s_setprio 1
	v_mfma_f32_16x16x32_bf16 v[52:55], v[148:151], v[178:181], 0
	v_mfma_f32_16x16x32_bf16 v[48:51], v[170:173], v[178:181], 0
	v_mfma_f32_16x16x32_bf16 v[36:39], v[148:151], v[186:189], 0
	v_mfma_f32_16x16x32_bf16 v[32:35], v[170:173], v[186:189], 0
	v_mfma_f32_16x16x32_bf16 v[20:23], v[148:151], v[194:197], 0
	v_mfma_f32_16x16x32_bf16 v[16:19], v[170:173], v[194:197], 0
	v_mfma_f32_16x16x32_bf16 v[4:7], v[148:151], v[218:221], 0
	v_mfma_f32_16x16x32_bf16 v[0:3], v[170:173], v[218:221], 0
	v_mfma_f32_16x16x32_bf16 v[52:55], v[152:155], v[182:185], v[52:55]
	v_mfma_f32_16x16x32_bf16 v[48:51], v[174:177], v[182:185], v[48:51]
	v_mfma_f32_16x16x32_bf16 v[36:39], v[152:155], v[190:193], v[36:39]
	v_mfma_f32_16x16x32_bf16 v[32:35], v[174:177], v[190:193], v[32:35]
	v_mfma_f32_16x16x32_bf16 v[20:23], v[152:155], v[198:201], v[20:23]
	v_mfma_f32_16x16x32_bf16 v[16:19], v[174:177], v[198:201], v[16:19]
	v_mfma_f32_16x16x32_bf16 v[4:7], v[152:155], v[222:225], v[4:7]
	s_barrier
	v_mfma_f32_16x16x32_bf16 v[0:3], v[174:177], v[222:225], v[0:3]
	s_setprio 0
	s_add_i32 s68, 0, 0x18000
	s_add_i32 s69, 0, 0x1c000
	v_add_u32_e32 v144, s68, v203
	v_add_u32_e32 v174, s69, v203
	ds_read_b128 v[132:135], v144
	ds_read_b128 v[136:139], v144 offset:1024
	ds_read_b128 v[140:143], v144 offset:2048
	ds_read_b128 v[144:147], v144 offset:3072
	ds_read_b128 v[148:151], v174
	ds_read_b128 v[152:155], v174 offset:1024
	ds_read_b128 v[170:173], v174 offset:2048
	ds_read_b128 v[174:177], v174 offset:3072
	s_add_u32 s26, s26, 0x40000
	s_addc_u32 s27, s27, 0
	s_mov_b32 m0, s45
	v_lshl_add_u64 v[242:243], s[26:27], 0, v[160:161]
	ds_read_b128 v[178:181], v211 offset:32768
	ds_read_b128 v[182:185], v211 offset:33792
	ds_read_b128 v[186:189], v211 offset:34816
	ds_read_b128 v[190:193], v211 offset:35840
	ds_read_b128 v[194:197], v211 offset:36864
	ds_read_b128 v[198:201], v211 offset:37888
	ds_read_b128 v[218:221], v211 offset:38912
	ds_read_b128 v[222:225], v211 offset:39936
	global_load_lds_dwordx4 v[242:243], off
	v_lshl_add_u64 v[242:243], s[26:27], 0, v[158:159]
	s_mov_b32 m0, s46
	s_nop 0
	global_load_lds_dwordx4 v[242:243], off
	s_waitcnt vmcnt(8)
	s_waitcnt lgkmcnt(0)
	s_barrier
	s_setprio 1
	s_waitcnt lgkmcnt(0)
	v_mfma_f32_16x16x32_bf16 v[120:123], v[132:135], v[178:181], v[120:123]
	v_mfma_f32_16x16x32_bf16 v[116:119], v[140:143], v[178:181], v[116:119]
	v_mfma_f32_16x16x32_bf16 v[108:111], v[132:135], v[186:189], v[108:111]
	v_mfma_f32_16x16x32_bf16 v[104:107], v[140:143], v[186:189], v[104:107]
	v_mfma_f32_16x16x32_bf16 v[92:95], v[132:135], v[194:197], v[92:95]
	v_mfma_f32_16x16x32_bf16 v[88:91], v[140:143], v[194:197], v[88:91]
	v_mfma_f32_16x16x32_bf16 v[76:79], v[132:135], v[218:221], v[76:79]
	v_mfma_f32_16x16x32_bf16 v[72:75], v[140:143], v[218:221], v[72:75]
	v_mfma_f32_16x16x32_bf16 v[120:123], v[136:139], v[182:185], v[120:123]
	v_mfma_f32_16x16x32_bf16 v[116:119], v[144:147], v[182:185], v[116:119]
	v_mfma_f32_16x16x32_bf16 v[108:111], v[136:139], v[190:193], v[108:111]
	v_mfma_f32_16x16x32_bf16 v[104:107], v[144:147], v[190:193], v[104:107]
	v_mfma_f32_16x16x32_bf16 v[92:95], v[136:139], v[198:201], v[92:95]
	v_mfma_f32_16x16x32_bf16 v[88:91], v[144:147], v[198:201], v[88:91]
	v_mfma_f32_16x16x32_bf16 v[76:79], v[136:139], v[222:225], v[76:79]
	v_mfma_f32_16x16x32_bf16 v[72:75], v[144:147], v[222:225], v[72:75]
	s_setprio 0
	s_setprio 1
	v_mfma_f32_16x16x32_bf16 v[128:131], v[148:151], v[178:181], v[128:131]
	v_mfma_f32_16x16x32_bf16 v[124:127], v[170:173], v[178:181], v[124:127]
	v_mfma_f32_16x16x32_bf16 v[100:103], v[148:151], v[186:189], v[100:103]
	v_mfma_f32_16x16x32_bf16 v[96:99], v[170:173], v[186:189], v[96:99]
	v_mfma_f32_16x16x32_bf16 v[84:87], v[148:151], v[194:197], v[84:87]
	v_mfma_f32_16x16x32_bf16 v[80:83], v[170:173], v[194:197], v[80:83]
	v_mfma_f32_16x16x32_bf16 v[68:71], v[148:151], v[218:221], v[68:71]
	v_mfma_f32_16x16x32_bf16 v[64:67], v[170:173], v[218:221], v[64:67]
	v_mfma_f32_16x16x32_bf16 v[128:131], v[152:155], v[182:185], v[128:131]
	v_mfma_f32_16x16x32_bf16 v[124:127], v[174:177], v[182:185], v[124:127]
	v_mfma_f32_16x16x32_bf16 v[100:103], v[152:155], v[190:193], v[100:103]
	v_mfma_f32_16x16x32_bf16 v[96:99], v[174:177], v[190:193], v[96:99]
	v_mfma_f32_16x16x32_bf16 v[84:87], v[152:155], v[198:201], v[84:87]
	v_mfma_f32_16x16x32_bf16 v[80:83], v[174:177], v[198:201], v[80:83]
	v_mfma_f32_16x16x32_bf16 v[68:71], v[152:155], v[222:225], v[68:71]
	s_barrier
;     __device__ __forceinline__ const char* tile(const Unit& u, int t) const { return A + (size_t)u.pm * 2 * hstep() + (size_t)t * (BK * 2); }
;     __device__ __forceinline__ const char* tile(const Unit& u, int t) const { return U + (long)(t >> 2) * xoff + (size_t)u.pn * (1024 * 512) + (size_t)u.pm * 2 * hstep() + (size_t)(t & 3) * (BK * 2); }
; #define PG8_STAGE(bufoff, gbase, voff) do { _Pragma("unroll") for (int _i = 0; _i < 2; ++_i) \
;         __builtin_amdgcn_global_load_lds((const unsigned*)((const char*)(gbase) + (voff)[_i]), (PG8_LAS unsigned*)(lds + (bufoff) + ldsw + _i * 8192), 16, 0, 0); } while (0)
; #define PG8_LDA(dst, b, h) do { _Pragma("unroll") for (int m = 0; m < 4; ++m) _Pragma("unroll") for (int k = 0; k < 2; ++k) dst[m][k] = *(const PG8_LAS bf16x8*)(lds + PG8_SA(b, h) + aoff + m * 2048 + k * 1024); } while (0)
; #define PG8_WAIT_V(n) asm volatile("s_waitcnt vmcnt(" #n ")" ::: "memory")
; #define PG8_BAR __builtin_amdgcn_s_barrier()
;     ...
;         for (int t = 0; t < nt; t += 2) {
;             const bool last = (t == nt - 2);
;             const char* a1 = AS.tile(cur, t + 1);
;             const char* a2 = last ? AS.tile(nu, 0) : AS.tile(cur, t + 2); const char* b2 = last ? nB : cB + (size_t)(t + 2) * kstep;
;             const char* a3 = last ? AS.tile(nu, 1) : AS.tile(cur, t + 3); const char* b3 = b2 + kstep;
;             PG8_LDB(B0, 0, 0); PG8_LDB(B1, 0, 1); PG8_SCHED; PG8_LDA(At, 0, 0); PG8_STAGE(PG8_SA(1, 1), a1 + hstepA, voffA);
;             PG8_WAIT_V(8); PG8_WAIT_L(0); PG8_BAR; PG8_MMA(0, 0, At, B0); PG8_MMA(0, 1, At, B1); PG8_BAR; PG8_SCHED;
;             PG8_LDA(At, 0, 1); PG8_STAGE(PG8_SB(0, 0), b2, voffB); PG8_STAGE(PG8_SB(0, 1), b2 + hstepB, voffB); PG8_STAGE(PG8_SA(0, 0), a2, voffA);
;             PG8_WAIT_V(8); PG8_WAIT_L(0); PG8_BAR; PG8_MMA(1, 0, At, B0); PG8_MMA(1, 1, At, B1); PG8_BAR; PG8_SCHED;
;             PG8_LDB(B0, 1, 0); PG8_LDB(B1, 1, 1); PG8_SCHED; PG8_LDA(At, 1, 0); PG8_STAGE(PG8_SA(0, 1), a2 + hstepA, voffA);
;             PG8_WAIT_V(8); PG8_WAIT_L(0); PG8_BAR; PG8_MMA(0, 0, At, B0); PG8_MMA(0, 1, At, B1); PG8_BAR; PG8_SCHED;
;             PG8_LDA(At, 1, 1); PG8_STAGE(PG8_SB(1, 0), b3, voffB); PG8_STAGE(PG8_SB(1, 1), b3 + hstepB, voffB); PG8_STAGE(PG8_SA(1, 0), a3, voffA);
;             PG8_WAIT_V(8); PG8_WAIT_L(0); PG8_BAR; PG8_MMA(1, 0, At, B0); PG8_MMA(1, 1, At, B1); PG8_BAR; PG8_SCHED;
	v_mfma_f32_16x16x32_bf16 v[64:67], v[174:177], v[222:225], v[64:67]
	s_setprio 0
	s_add_i32 s26, s68, s31
	v_lshl_add_u64 v[238:239], v[238:239], 0, s[72:73]
	s_mov_b32 m0, s26
	ds_read_b128 v[178:181], v211 offset:49152
	ds_read_b128 v[182:185], v211 offset:50176
	ds_read_b128 v[186:189], v211 offset:51200
	ds_read_b128 v[190:193], v211 offset:52224
	ds_read_b128 v[194:197], v211 offset:53248
	ds_read_b128 v[198:201], v211 offset:54272
	ds_read_b128 v[218:221], v211 offset:55296
	ds_read_b128 v[222:225], v211 offset:56320
	global_load_lds_dwordx4 v[238:239], off
	s_add_i32 m0, s26, 0x2000
	s_add_u32 s24, s24, 0x40080
	v_lshl_add_u64 v[238:239], v[240:241], 0, s[72:73]
	s_addc_u32 s25, s25, 0
	s_add_i32 s26, s69, s31
	global_load_lds_dwordx4 v[238:239], off
	v_lshl_add_u64 v[238:239], s[24:25], 0, v[208:209]
	s_mov_b32 m0, s26
	s_nop 0
	global_load_lds_dwordx4 v[238:239], off
	v_lshl_add_u64 v[238:239], s[24:25], 0, v[156:157]
	s_add_i32 m0, s26, 0x2000
	s_nop 0
	global_load_lds_dwordx4 v[238:239], off
	v_lshl_add_u64 v[238:239], s[20:21], 0, v[160:161]
	s_mov_b32 m0, s47
	s_nop 0
	global_load_lds_dwordx4 v[238:239], off
	v_lshl_add_u64 v[238:239], s[20:21], 0, v[158:159]
	s_mov_b32 m0, s48
	s_nop 0
	global_load_lds_dwordx4 v[238:239], off
	s_waitcnt vmcnt(8)
	s_waitcnt lgkmcnt(0)
	s_barrier
	s_setprio 1
	s_waitcnt lgkmcnt(0)
	v_mfma_f32_16x16x32_bf16 v[60:63], v[132:135], v[178:181], v[60:63]
	v_mfma_f32_16x16x32_bf16 v[56:59], v[140:143], v[178:181], v[56:59]
	v_mfma_f32_16x16x32_bf16 v[44:47], v[132:135], v[186:189], v[44:47]
	v_mfma_f32_16x16x32_bf16 v[40:43], v[140:143], v[186:189], v[40:43]
	v_mfma_f32_16x16x32_bf16 v[28:31], v[132:135], v[194:197], v[28:31]
	v_mfma_f32_16x16x32_bf16 v[24:27], v[140:143], v[194:197], v[24:27]
	v_mfma_f32_16x16x32_bf16 v[12:15], v[132:135], v[218:221], v[12:15]
	v_mfma_f32_16x16x32_bf16 v[8:11], v[140:143], v[218:221], v[8:11]
	v_mfma_f32_16x16x32_bf16 v[60:63], v[136:139], v[182:185], v[60:63]
	v_mfma_f32_16x16x32_bf16 v[56:59], v[144:147], v[182:185], v[56:59]
	v_mfma_f32_16x16x32_bf16 v[44:47], v[136:139], v[190:193], v[44:47]
	v_mfma_f32_16x16x32_bf16 v[40:43], v[144:147], v[190:193], v[40:43]
	v_mfma_f32_16x16x32_bf16 v[28:31], v[136:139], v[198:201], v[28:31]
	v_mfma_f32_16x16x32_bf16 v[24:27], v[144:147], v[198:201], v[24:27]
	v_mfma_f32_16x16x32_bf16 v[12:15], v[136:139], v[222:225], v[12:15]
	v_mfma_f32_16x16x32_bf16 v[8:11], v[144:147], v[222:225], v[8:11]
	s_setprio 0
	s_setprio 1
	v_mfma_f32_16x16x32_bf16 v[52:55], v[148:151], v[178:181], v[52:55]
	v_mfma_f32_16x16x32_bf16 v[48:51], v[170:173], v[178:181], v[48:51]
	v_mfma_f32_16x16x32_bf16 v[36:39], v[148:151], v[186:189], v[36:39]
	v_mfma_f32_16x16x32_bf16 v[32:35], v[170:173], v[186:189], v[32:35]
	v_mfma_f32_16x16x32_bf16 v[20:23], v[148:151], v[194:197], v[20:23]
	v_mfma_f32_16x16x32_bf16 v[16:19], v[170:173], v[194:197], v[16:19]
	v_mfma_f32_16x16x32_bf16 v[4:7], v[148:151], v[218:221], v[4:7]
	v_mfma_f32_16x16x32_bf16 v[0:3], v[170:173], v[218:221], v[0:3]
	v_mfma_f32_16x16x32_bf16 v[52:55], v[152:155], v[182:185], v[52:55]
	v_mfma_f32_16x16x32_bf16 v[48:51], v[174:177], v[182:185], v[48:51]
	v_mfma_f32_16x16x32_bf16 v[36:39], v[152:155], v[190:193], v[36:39]
	v_mfma_f32_16x16x32_bf16 v[32:35], v[174:177], v[190:193], v[32:35]
	v_mfma_f32_16x16x32_bf16 v[20:23], v[152:155], v[198:201], v[20:23]
	v_mfma_f32_16x16x32_bf16 v[16:19], v[174:177], v[198:201], v[16:19]
	v_mfma_f32_16x16x32_bf16 v[4:7], v[152:155], v[222:225], v[4:7]
	s_barrier
	v_mfma_f32_16x16x32_bf16 v[0:3], v[174:177], v[222:225], v[0:3]
	s_setprio 0
	s_add_i32 s67, s67, 2
	s_add_u32 s18, s18, 0x100
	s_addc_u32 s19, s19, 0
	s_cmp_gt_u32 s67, 13
	s_cbranch_scc0 .LBB0_451
	s_branch .Lpeel_exit_451
.LBB0_451:
	s_add_u32 s20, s61, s18
	s_addc_u32 s21, s64, s19
	s_add_u32 s26, s20, 0x3600100
	s_addc_u32 s27, s21, 0
	s_add_u32 s24, s65, s18
	s_addc_u32 s25, s66, s19
	s_add_u32 s20, s20, 0x3600180
	s_addc_u32 s21, s21, 0
	s_add_i32 s68, 0, 0x10000
	s_add_i32 s70, 0, 0x14000
	v_add_u32_e32 v144, s68, v203
	v_add_u32_e32 v174, s70, v203
	ds_read_b128 v[132:135], v144
	ds_read_b128 v[136:139], v144 offset:1024
	ds_read_b128 v[140:143], v144 offset:2048
	ds_read_b128 v[144:147], v144 offset:3072
	ds_read_b128 v[148:151], v174
	ds_read_b128 v[152:155], v174 offset:1024
	ds_read_b128 v[170:173], v174 offset:2048
	ds_read_b128 v[174:177], v174 offset:3072
	s_cmpk_eq_i32 s18, 0x700
	s_cselect_b32 s21, s60, s21
	s_cselect_b32 s20, s59, s20
	s_cselect_b32 s25, s57, s25
	s_cselect_b32 s24, s56, s24
	s_cselect_b32 s27, s58, s27
	s_cselect_b32 s26, s3, s26
	v_lshl_add_u64 v[238:239], v[112:113], 0, s[18:19]
	s_add_i32 m0, s35, 0xc000
	ds_read_b128 v[178:181], v211
	ds_read_b128 v[182:185], v211 offset:1024
	ds_read_b128 v[186:189], v211 offset:2048
	ds_read_b128 v[190:193], v211 offset:3072
	ds_read_b128 v[194:197], v211 offset:4096
	ds_read_b128 v[198:201], v211 offset:5120
	ds_read_b128 v[218:221], v211 offset:6144
	ds_read_b128 v[222:225], v211 offset:7168
	global_load_lds_dwordx4 v[238:239], off
	v_lshl_add_u64 v[238:239], v[114:115], 0, s[18:19]
	s_add_i32 m0, s35, 0xe000
	s_nop 0
	global_load_lds_dwordx4 v[238:239], off
	s_waitcnt vmcnt(8)
	s_waitcnt lgkmcnt(0)
	s_barrier
; #define PG8_STAGE(bufoff, gbase, voff) do { _Pragma("unroll") for (int _i = 0; _i < 2; ++_i) \
;         __builtin_amdgcn_global_load_lds((const unsigned*)((const char*)(gbase) + (voff)[_i]), (PG8_LAS unsigned*)(lds + (bufoff) + ldsw + _i * 8192), 16, 0, 0); } while (0)
; #define PG8_LDA(dst, b, h) do { _Pragma("unroll") for (int m = 0; m < 4; ++m) _Pragma("unroll") for (int k = 0; k < 2; ++k) dst[m][k] = *(const PG8_LAS bf16x8*)(lds + PG8_SA(b, h) + aoff + m * 2048 + k * 1024); } while (0)
; #define PG8_LDB(dst, b, h) do { _Pragma("unroll") for (int n = 0; n < 2; ++n) _Pragma("unroll") for (int k = 0; k < 2; ++k) dst[n][k] = *(const PG8_LAS bf16x8*)(lds + PG8_SB(b, h) + boff + n * 2048 + k * 1024); } while (0)
; #define PG8_MMA(ai, bj, At, Bt) do { __builtin_amdgcn_s_setprio(1); _Pragma("unroll") for (int m = 0; m < 4; ++m) _Pragma("unroll") for (int n = 0; n < 2; ++n) _Pragma("unroll") for (int k = 0; k < 2; ++k) \
;         acc[ai][bj][m][n] = __builtin_amdgcn_mfma_f32_16x16x32_bf16(Bt[n][k], At[m][k], acc[ai][bj][m][n], 0, 0, 0); __builtin_amdgcn_s_setprio(0); } while (0)
; #define PG8_WAIT_V(n) asm volatile("s_waitcnt vmcnt(" #n ")" ::: "memory")
; #define PG8_WAIT_L(n) asm volatile("s_waitcnt lgkmcnt(" #n ")" ::: "memory")
; #define PG8_BAR __builtin_amdgcn_s_barrier()
; #define PG8_SCHED __builtin_amdgcn_sched_barrier(0)
;     ...
;             PG8_WAIT_V(8); PG8_WAIT_L(0); PG8_BAR; PG8_MMA(0, 0, At, B0); PG8_MMA(0, 1, At, B1); PG8_BAR; PG8_SCHED;
;             PG8_LDA(At, 0, 1); PG8_STAGE(PG8_SB(0, 0), b2, voffB); PG8_STAGE(PG8_SB(0, 1), b2 + hstepB, voffB); PG8_STAGE(PG8_SA(0, 0), a2, voffA);
;             PG8_WAIT_V(8); PG8_WAIT_L(0); PG8_BAR; PG8_MMA(1, 0, At, B0); PG8_MMA(1, 1, At, B1); PG8_BAR; PG8_SCHED;
;             PG8_LDB(B0, 1, 0); PG8_LDB(B1, 1, 1); PG8_SCHED; PG8_LDA(At, 1, 0); PG8_STAGE(PG8_SA(0, 1), a2 + hstepA, voffA);
;             PG8_WAIT_V(8); PG8_WAIT_L(0); PG8_BAR; PG8_MMA(0, 0, At, B0); PG8_MMA(0, 1, At, B1); PG8_BAR; PG8_SCHED;
	s_setprio 1
	s_waitcnt lgkmcnt(0)
	v_mfma_f32_16x16x32_bf16 v[120:123], v[132:135], v[178:181], v[120:123]
	v_mfma_f32_16x16x32_bf16 v[116:119], v[140:143], v[178:181], v[116:119]
	v_mfma_f32_16x16x32_bf16 v[108:111], v[132:135], v[186:189], v[108:111]
	v_mfma_f32_16x16x32_bf16 v[104:107], v[140:143], v[186:189], v[104:107]
	v_mfma_f32_16x16x32_bf16 v[92:95], v[132:135], v[194:197], v[92:95]
	v_mfma_f32_16x16x32_bf16 v[88:91], v[140:143], v[194:197], v[88:91]
	v_mfma_f32_16x16x32_bf16 v[76:79], v[132:135], v[218:221], v[76:79]
	v_mfma_f32_16x16x32_bf16 v[72:75], v[140:143], v[218:221], v[72:75]
	v_mfma_f32_16x16x32_bf16 v[120:123], v[136:139], v[182:185], v[120:123]
	v_mfma_f32_16x16x32_bf16 v[116:119], v[144:147], v[182:185], v[116:119]
	v_mfma_f32_16x16x32_bf16 v[108:111], v[136:139], v[190:193], v[108:111]
	v_mfma_f32_16x16x32_bf16 v[104:107], v[144:147], v[190:193], v[104:107]
	v_mfma_f32_16x16x32_bf16 v[92:95], v[136:139], v[198:201], v[92:95]
	v_mfma_f32_16x16x32_bf16 v[88:91], v[144:147], v[198:201], v[88:91]
	v_mfma_f32_16x16x32_bf16 v[76:79], v[136:139], v[222:225], v[76:79]
	v_mfma_f32_16x16x32_bf16 v[72:75], v[144:147], v[222:225], v[72:75]
	s_setprio 0
	s_setprio 1
	v_mfma_f32_16x16x32_bf16 v[128:131], v[148:151], v[178:181], v[128:131]
	v_mfma_f32_16x16x32_bf16 v[124:127], v[170:173], v[178:181], v[124:127]
	v_mfma_f32_16x16x32_bf16 v[100:103], v[148:151], v[186:189], v[100:103]
	v_mfma_f32_16x16x32_bf16 v[96:99], v[170:173], v[186:189], v[96:99]
	v_mfma_f32_16x16x32_bf16 v[84:87], v[148:151], v[194:197], v[84:87]
	v_mfma_f32_16x16x32_bf16 v[80:83], v[170:173], v[194:197], v[80:83]
	v_mfma_f32_16x16x32_bf16 v[68:71], v[148:151], v[218:221], v[68:71]
	v_mfma_f32_16x16x32_bf16 v[64:67], v[170:173], v[218:221], v[64:67]
	v_mfma_f32_16x16x32_bf16 v[128:131], v[152:155], v[182:185], v[128:131]
	v_mfma_f32_16x16x32_bf16 v[124:127], v[174:177], v[182:185], v[124:127]
	v_mfma_f32_16x16x32_bf16 v[100:103], v[152:155], v[190:193], v[100:103]
	v_mfma_f32_16x16x32_bf16 v[96:99], v[174:177], v[190:193], v[96:99]
	v_mfma_f32_16x16x32_bf16 v[84:87], v[152:155], v[198:201], v[84:87]
	v_mfma_f32_16x16x32_bf16 v[80:83], v[174:177], v[198:201], v[80:83]
	v_mfma_f32_16x16x32_bf16 v[68:71], v[152:155], v[222:225], v[68:71]
	s_barrier
	v_mfma_f32_16x16x32_bf16 v[64:67], v[174:177], v[222:225], v[64:67]
	s_setprio 0
	s_add_i32 s68, s68, s31
	v_lshl_add_u64 v[238:239], s[24:25], 0, v[208:209]
	s_mov_b32 m0, s68
	ds_read_b128 v[178:181], v211 offset:16384
	ds_read_b128 v[182:185], v211 offset:17408
	ds_read_b128 v[186:189], v211 offset:18432
	ds_read_b128 v[190:193], v211 offset:19456
	ds_read_b128 v[194:197], v211 offset:20480
	ds_read_b128 v[198:201], v211 offset:21504
	ds_read_b128 v[218:221], v211 offset:22528
	ds_read_b128 v[222:225], v211 offset:23552
	global_load_lds_dwordx4 v[238:239], off
	s_add_i32 m0, s68, 0x2000
	s_add_u32 s68, s24, 0x40000
	v_lshl_add_u64 v[240:241], s[24:25], 0, v[156:157]
	s_addc_u32 s69, s25, 0
	s_add_i32 s70, s70, s31
	global_load_lds_dwordx4 v[240:241], off
	v_lshl_add_u64 v[242:243], s[68:69], 0, v[208:209]
	s_mov_b32 m0, s70
	s_nop 0
	global_load_lds_dwordx4 v[242:243], off
	v_lshl_add_u64 v[242:243], s[68:69], 0, v[156:157]
	s_add_i32 m0, s70, 0x2000
	s_nop 0
	global_load_lds_dwordx4 v[242:243], off
	v_lshl_add_u64 v[242:243], s[26:27], 0, v[160:161]
	s_mov_b32 m0, s35
	s_nop 0
	global_load_lds_dwordx4 v[242:243], off
	v_lshl_add_u64 v[242:243], s[26:27], 0, v[158:159]
	s_mov_b32 m0, s44
	s_nop 0
	global_load_lds_dwordx4 v[242:243], off
	s_waitcnt vmcnt(8)
	s_waitcnt lgkmcnt(0)
	s_barrier
	s_setprio 1
	s_waitcnt lgkmcnt(0)
	v_mfma_f32_16x16x32_bf16 v[60:63], v[132:135], v[178:181], v[60:63]
	v_mfma_f32_16x16x32_bf16 v[56:59], v[140:143], v[178:181], v[56:59]
	v_mfma_f32_16x16x32_bf16 v[44:47], v[132:135], v[186:189], v[44:47]
	v_mfma_f32_16x16x32_bf16 v[40:43], v[140:143], v[186:189], v[40:43]
	v_mfma_f32_16x16x32_bf16 v[28:31], v[132:135], v[194:197], v[28:31]
	v_mfma_f32_16x16x32_bf16 v[24:27], v[140:143], v[194:197], v[24:27]
	v_mfma_f32_16x16x32_bf16 v[12:15], v[132:135], v[218:221], v[12:15]
	v_mfma_f32_16x16x32_bf16 v[8:11], v[140:143], v[218:221], v[8:11]
	v_mfma_f32_16x16x32_bf16 v[60:63], v[136:139], v[182:185], v[60:63]
	v_mfma_f32_16x16x32_bf16 v[56:59], v[144:147], v[182:185], v[56:59]
	v_mfma_f32_16x16x32_bf16 v[44:47], v[136:139], v[190:193], v[44:47]
	v_mfma_f32_16x16x32_bf16 v[40:43], v[144:147], v[190:193], v[40:43]
	v_mfma_f32_16x16x32_bf16 v[28:31], v[136:139], v[198:201], v[28:31]
	v_mfma_f32_16x16x32_bf16 v[24:27], v[144:147], v[198:201], v[24:27]
	v_mfma_f32_16x16x32_bf16 v[12:15], v[136:139], v[222:225], v[12:15]
	v_mfma_f32_16x16x32_bf16 v[8:11], v[144:147], v[222:225], v[8:11]
	s_setprio 0
	s_setprio 1
	v_mfma_f32_16x16x32_bf16 v[52:55], v[148:151], v[178:181], v[52:55]
	v_mfma_f32_16x16x32_bf16 v[48:51], v[170:173], v[178:181], v[48:51]
	v_mfma_f32_16x16x32_bf16 v[36:39], v[148:151], v[186:189], v[36:39]
	v_mfma_f32_16x16x32_bf16 v[32:35], v[170:173], v[186:189], v[32:35]
	v_mfma_f32_16x16x32_bf16 v[20:23], v[148:151], v[194:197], v[20:23]
	v_mfma_f32_16x16x32_bf16 v[16:19], v[170:173], v[194:197], v[16:19]
	v_mfma_f32_16x16x32_bf16 v[4:7], v[148:151], v[218:221], v[4:7]
	v_mfma_f32_16x16x32_bf16 v[0:3], v[170:173], v[218:221], v[0:3]
	v_mfma_f32_16x16x32_bf16 v[52:55], v[152:155], v[182:185], v[52:55]
	v_mfma_f32_16x16x32_bf16 v[48:51], v[174:177], v[182:185], v[48:51]
	v_mfma_f32_16x16x32_bf16 v[36:39], v[152:155], v[190:193], v[36:39]
	v_mfma_f32_16x16x32_bf16 v[32:35], v[174:177], v[190:193], v[32:35]
	v_mfma_f32_16x16x32_bf16 v[20:23], v[152:155], v[198:201], v[20:23]
	v_mfma_f32_16x16x32_bf16 v[16:19], v[174:177], v[198:201], v[16:19]
	v_mfma_f32_16x16x32_bf16 v[4:7], v[152:155], v[222:225], v[4:7]
	s_barrier
; #define PG8_STAGE(bufoff, gbase, voff) do { _Pragma("unroll") for (int _i = 0; _i < 2; ++_i) \
;         __builtin_amdgcn_global_load_lds((const unsigned*)((const char*)(gbase) + (voff)[_i]), (PG8_LAS unsigned*)(lds + (bufoff) + ldsw + _i * 8192), 16, 0, 0); } while (0)
; #define PG8_LDA(dst, b, h) do { _Pragma("unroll") for (int m = 0; m < 4; ++m) _Pragma("unroll") for (int k = 0; k < 2; ++k) dst[m][k] = *(const PG8_LAS bf16x8*)(lds + PG8_SA(b, h) + aoff + m * 2048 + k * 1024); } while (0)
; #define PG8_LDB(dst, b, h) do { _Pragma("unroll") for (int n = 0; n < 2; ++n) _Pragma("unroll") for (int k = 0; k < 2; ++k) dst[n][k] = *(const PG8_LAS bf16x8*)(lds + PG8_SB(b, h) + boff + n * 2048 + k * 1024); } while (0)
; #define PG8_MMA(ai, bj, At, Bt) do { __builtin_amdgcn_s_setprio(1); _Pragma("unroll") for (int m = 0; m < 4; ++m) _Pragma("unroll") for (int n = 0; n < 2; ++n) _Pragma("unroll") for (int k = 0; k < 2; ++k) \
;         acc[ai][bj][m][n] = __builtin_amdgcn_mfma_f32_16x16x32_bf16(Bt[n][k], At[m][k], acc[ai][bj][m][n], 0, 0, 0); __builtin_amdgcn_s_setprio(0); } while (0)
; #define PG8_WAIT_V(n) asm volatile("s_waitcnt vmcnt(" #n ")" ::: "memory")
; #define PG8_WAIT_L(n) asm volatile("s_waitcnt lgkmcnt(" #n ")" ::: "memory")
; #define PG8_BAR __builtin_amdgcn_s_barrier()
; #define PG8_SCHED __builtin_amdgcn_sched_barrier(0)
;     ...
;             PG8_WAIT_V(8); PG8_WAIT_L(0); PG8_BAR; PG8_MMA(1, 0, At, B0); PG8_MMA(1, 1, At, B1); PG8_BAR; PG8_SCHED;
;             PG8_LDB(B0, 1, 0); PG8_LDB(B1, 1, 1); PG8_SCHED; PG8_LDA(At, 1, 0); PG8_STAGE(PG8_SA(0, 1), a2 + hstepA, voffA);
;             PG8_WAIT_V(8); PG8_WAIT_L(0); PG8_BAR; PG8_MMA(0, 0, At, B0); PG8_MMA(0, 1, At, B1); PG8_BAR; PG8_SCHED;
	v_mfma_f32_16x16x32_bf16 v[0:3], v[174:177], v[222:225], v[0:3]
	s_setprio 0
	s_add_i32 s68, 0, 0x18000
	s_add_i32 s69, 0, 0x1c000
	v_add_u32_e32 v144, s68, v203
	v_add_u32_e32 v174, s69, v203
	ds_read_b128 v[132:135], v144
	ds_read_b128 v[136:139], v144 offset:1024
	ds_read_b128 v[140:143], v144 offset:2048
	ds_read_b128 v[144:147], v144 offset:3072
	ds_read_b128 v[148:151], v174
	ds_read_b128 v[152:155], v174 offset:1024
	ds_read_b128 v[170:173], v174 offset:2048
	ds_read_b128 v[174:177], v174 offset:3072
	s_add_u32 s26, s26, 0x40000
	s_addc_u32 s27, s27, 0
	s_mov_b32 m0, s45
	v_lshl_add_u64 v[242:243], s[26:27], 0, v[160:161]
	ds_read_b128 v[178:181], v211 offset:32768
	ds_read_b128 v[182:185], v211 offset:33792
	ds_read_b128 v[186:189], v211 offset:34816
	ds_read_b128 v[190:193], v211 offset:35840
	ds_read_b128 v[194:197], v211 offset:36864
	ds_read_b128 v[198:201], v211 offset:37888
	ds_read_b128 v[218:221], v211 offset:38912
	ds_read_b128 v[222:225], v211 offset:39936
	global_load_lds_dwordx4 v[242:243], off
	v_lshl_add_u64 v[242:243], s[26:27], 0, v[158:159]
	s_mov_b32 m0, s46
	s_nop 0
	global_load_lds_dwordx4 v[242:243], off
	s_waitcnt vmcnt(8)
	s_waitcnt lgkmcnt(0)
	s_barrier
	s_setprio 1
	s_waitcnt lgkmcnt(0)
	v_mfma_f32_16x16x32_bf16 v[120:123], v[132:135], v[178:181], v[120:123]
	v_mfma_f32_16x16x32_bf16 v[116:119], v[140:143], v[178:181], v[116:119]
	v_mfma_f32_16x16x32_bf16 v[108:111], v[132:135], v[186:189], v[108:111]
	v_mfma_f32_16x16x32_bf16 v[104:107], v[140:143], v[186:189], v[104:107]
	v_mfma_f32_16x16x32_bf16 v[92:95], v[132:135], v[194:197], v[92:95]
	v_mfma_f32_16x16x32_bf16 v[88:91], v[140:143], v[194:197], v[88:91]
	v_mfma_f32_16x16x32_bf16 v[76:79], v[132:135], v[218:221], v[76:79]
	v_mfma_f32_16x16x32_bf16 v[72:75], v[140:143], v[218:221], v[72:75]
	v_mfma_f32_16x16x32_bf16 v[120:123], v[136:139], v[182:185], v[120:123]
	v_mfma_f32_16x16x32_bf16 v[116:119], v[144:147], v[182:185], v[116:119]
	v_mfma_f32_16x16x32_bf16 v[108:111], v[136:139], v[190:193], v[108:111]
	v_mfma_f32_16x16x32_bf16 v[104:107], v[144:147], v[190:193], v[104:107]
	v_mfma_f32_16x16x32_bf16 v[92:95], v[136:139], v[198:201], v[92:95]
	v_mfma_f32_16x16x32_bf16 v[88:91], v[144:147], v[198:201], v[88:91]
	v_mfma_f32_16x16x32_bf16 v[76:79], v[136:139], v[222:225], v[76:79]
	v_mfma_f32_16x16x32_bf16 v[72:75], v[144:147], v[222:225], v[72:75]
	s_setprio 0
	s_setprio 1
	v_mfma_f32_16x16x32_bf16 v[128:131], v[148:151], v[178:181], v[128:131]
	v_mfma_f32_16x16x32_bf16 v[124:127], v[170:173], v[178:181], v[124:127]
	v_mfma_f32_16x16x32_bf16 v[100:103], v[148:151], v[186:189], v[100:103]
	v_mfma_f32_16x16x32_bf16 v[96:99], v[170:173], v[186:189], v[96:99]
	v_mfma_f32_16x16x32_bf16 v[84:87], v[148:151], v[194:197], v[84:87]
	v_mfma_f32_16x16x32_bf16 v[80:83], v[170:173], v[194:197], v[80:83]
	v_mfma_f32_16x16x32_bf16 v[68:71], v[148:151], v[218:221], v[68:71]
	v_mfma_f32_16x16x32_bf16 v[64:67], v[170:173], v[218:221], v[64:67]
	v_mfma_f32_16x16x32_bf16 v[128:131], v[152:155], v[182:185], v[128:131]
	v_mfma_f32_16x16x32_bf16 v[124:127], v[174:177], v[182:185], v[124:127]
	v_mfma_f32_16x16x32_bf16 v[100:103], v[152:155], v[190:193], v[100:103]
	v_mfma_f32_16x16x32_bf16 v[96:99], v[174:177], v[190:193], v[96:99]
	v_mfma_f32_16x16x32_bf16 v[84:87], v[152:155], v[198:201], v[84:87]
	v_mfma_f32_16x16x32_bf16 v[80:83], v[174:177], v[198:201], v[80:83]
	v_mfma_f32_16x16x32_bf16 v[68:71], v[152:155], v[222:225], v[68:71]
	s_barrier
; #define PG8_STAGE(bufoff, gbase, voff) do { _Pragma("unroll") for (int _i = 0; _i < 2; ++_i) \
;         __builtin_amdgcn_global_load_lds((const unsigned*)((const char*)(gbase) + (voff)[_i]), (PG8_LAS unsigned*)(lds + (bufoff) + ldsw + _i * 8192), 16, 0, 0); } while (0)
; #define PG8_LDA(dst, b, h) do { _Pragma("unroll") for (int m = 0; m < 4; ++m) _Pragma("unroll") for (int k = 0; k < 2; ++k) dst[m][k] = *(const PG8_LAS bf16x8*)(lds + PG8_SA(b, h) + aoff + m * 2048 + k * 1024); } while (0)
; #define PG8_MMA(ai, bj, At, Bt) do { __builtin_amdgcn_s_setprio(1); _Pragma("unroll") for (int m = 0; m < 4; ++m) _Pragma("unroll") for (int n = 0; n < 2; ++n) _Pragma("unroll") for (int k = 0; k < 2; ++k) \
;         acc[ai][bj][m][n] = __builtin_amdgcn_mfma_f32_16x16x32_bf16(Bt[n][k], At[m][k], acc[ai][bj][m][n], 0, 0, 0); __builtin_amdgcn_s_setprio(0); } while (0)
; #define PG8_WAIT_V(n) asm volatile("s_waitcnt vmcnt(" #n ")" ::: "memory")
; #define PG8_WAIT_L(n) asm volatile("s_waitcnt lgkmcnt(" #n ")" ::: "memory")
; #define PG8_BAR __builtin_amdgcn_s_barrier()
; #define PG8_SCHED __builtin_amdgcn_sched_barrier(0)
;     ...
;             PG8_WAIT_V(8); PG8_WAIT_L(0); PG8_BAR; PG8_MMA(0, 0, At, B0); PG8_MMA(0, 1, At, B1); PG8_BAR; PG8_SCHED;
;             PG8_LDA(At, 1, 1); PG8_STAGE(PG8_SB(1, 0), b3, voffB); PG8_STAGE(PG8_SB(1, 1), b3 + hstepB, voffB); PG8_STAGE(PG8_SA(1, 0), a3, voffA);
;             PG8_WAIT_V(8); PG8_WAIT_L(0); PG8_BAR; PG8_MMA(1, 0, At, B0); PG8_MMA(1, 1, At, B1); PG8_BAR; PG8_SCHED;
	v_mfma_f32_16x16x32_bf16 v[64:67], v[174:177], v[222:225], v[64:67]
	s_setprio 0
	s_add_i32 s26, s68, s31
	v_lshl_add_u64 v[238:239], v[238:239], 0, s[72:73]
	s_mov_b32 m0, s26
	ds_read_b128 v[178:181], v211 offset:49152
	ds_read_b128 v[182:185], v211 offset:50176
	ds_read_b128 v[186:189], v211 offset:51200
	ds_read_b128 v[190:193], v211 offset:52224
	ds_read_b128 v[194:197], v211 offset:53248
	ds_read_b128 v[198:201], v211 offset:54272
	ds_read_b128 v[218:221], v211 offset:55296
	ds_read_b128 v[222:225], v211 offset:56320
	global_load_lds_dwordx4 v[238:239], off
	s_add_i32 m0, s26, 0x2000
	s_add_u32 s24, s24, 0x40080
	v_lshl_add_u64 v[238:239], v[240:241], 0, s[72:73]
	s_addc_u32 s25, s25, 0
	s_add_i32 s26, s69, s31
	global_load_lds_dwordx4 v[238:239], off
	v_lshl_add_u64 v[238:239], s[24:25], 0, v[208:209]
	s_mov_b32 m0, s26
	s_nop 0
	global_load_lds_dwordx4 v[238:239], off
	v_lshl_add_u64 v[238:239], s[24:25], 0, v[156:157]
	s_add_i32 m0, s26, 0x2000
	s_nop 0
	global_load_lds_dwordx4 v[238:239], off
	v_lshl_add_u64 v[238:239], s[20:21], 0, v[160:161]
	s_mov_b32 m0, s47
	s_nop 0
	global_load_lds_dwordx4 v[238:239], off
	v_lshl_add_u64 v[238:239], s[20:21], 0, v[158:159]
	s_mov_b32 m0, s48
	s_nop 0
	global_load_lds_dwordx4 v[238:239], off
	s_waitcnt vmcnt(8)
	s_waitcnt lgkmcnt(0)
	s_barrier
	s_setprio 1
	s_waitcnt lgkmcnt(0)
	v_mfma_f32_16x16x32_bf16 v[60:63], v[132:135], v[178:181], v[60:63]
	v_mfma_f32_16x16x32_bf16 v[56:59], v[140:143], v[178:181], v[56:59]
	v_mfma_f32_16x16x32_bf16 v[44:47], v[132:135], v[186:189], v[44:47]
	v_mfma_f32_16x16x32_bf16 v[40:43], v[140:143], v[186:189], v[40:43]
	v_mfma_f32_16x16x32_bf16 v[28:31], v[132:135], v[194:197], v[28:31]
	v_mfma_f32_16x16x32_bf16 v[24:27], v[140:143], v[194:197], v[24:27]
	v_mfma_f32_16x16x32_bf16 v[12:15], v[132:135], v[218:221], v[12:15]
	v_mfma_f32_16x16x32_bf16 v[8:11], v[140:143], v[218:221], v[8:11]
	v_mfma_f32_16x16x32_bf16 v[60:63], v[136:139], v[182:185], v[60:63]
	v_mfma_f32_16x16x32_bf16 v[56:59], v[144:147], v[182:185], v[56:59]
	v_mfma_f32_16x16x32_bf16 v[44:47], v[136:139], v[190:193], v[44:47]
	v_mfma_f32_16x16x32_bf16 v[40:43], v[144:147], v[190:193], v[40:43]
	v_mfma_f32_16x16x32_bf16 v[28:31], v[136:139], v[198:201], v[28:31]
	v_mfma_f32_16x16x32_bf16 v[24:27], v[144:147], v[198:201], v[24:27]
	v_mfma_f32_16x16x32_bf16 v[12:15], v[136:139], v[222:225], v[12:15]
	v_mfma_f32_16x16x32_bf16 v[8:11], v[144:147], v[222:225], v[8:11]
	s_setprio 0
	s_setprio 1
	v_mfma_f32_16x16x32_bf16 v[52:55], v[148:151], v[178:181], v[52:55]
	v_mfma_f32_16x16x32_bf16 v[48:51], v[170:173], v[178:181], v[48:51]
	v_mfma_f32_16x16x32_bf16 v[36:39], v[148:151], v[186:189], v[36:39]
	v_mfma_f32_16x16x32_bf16 v[32:35], v[170:173], v[186:189], v[32:35]
	v_mfma_f32_16x16x32_bf16 v[20:23], v[148:151], v[194:197], v[20:23]
	v_mfma_f32_16x16x32_bf16 v[16:19], v[170:173], v[194:197], v[16:19]
	v_mfma_f32_16x16x32_bf16 v[4:7], v[148:151], v[218:221], v[4:7]
	v_mfma_f32_16x16x32_bf16 v[0:3], v[170:173], v[218:221], v[0:3]
	v_mfma_f32_16x16x32_bf16 v[52:55], v[152:155], v[182:185], v[52:55]
	v_mfma_f32_16x16x32_bf16 v[48:51], v[174:177], v[182:185], v[48:51]
	v_mfma_f32_16x16x32_bf16 v[36:39], v[152:155], v[190:193], v[36:39]
	v_mfma_f32_16x16x32_bf16 v[32:35], v[174:177], v[190:193], v[32:35]
	v_mfma_f32_16x16x32_bf16 v[20:23], v[152:155], v[198:201], v[20:23]
	v_mfma_f32_16x16x32_bf16 v[16:19], v[174:177], v[198:201], v[16:19]
	v_mfma_f32_16x16x32_bf16 v[4:7], v[152:155], v[222:225], v[4:7]
	s_barrier
	v_mfma_f32_16x16x32_bf16 v[0:3], v[174:177], v[222:225], v[0:3]
	s_setprio 0
	s_add_i32 s67, s67, 2
	s_add_u32 s18, s18, 0x100
	s_addc_u32 s19, s19, 0
	s_cmp_gt_u32 s67, 13
	s_cbranch_scc0 .LBB0_451

;     __device__ __forceinline__ const char* tile(const Unit& u, int t) const { return A + (size_t)u.pm * 2 * hstep() + (size_t)t * (BK * 2); }
;     __device__ __forceinline__ const char* tile(const Unit& u, int t) const { return U + (long)(t >> 2) * xoff + (size_t)u.pn * (1024 * 512) + (size_t)u.pm * 2 * hstep() + (size_t)(t & 3) * (BK * 2); }
; #define PG8_STAGE(bufoff, gbase, voff) do { _Pragma("unroll") for (int _i = 0; _i < 2; ++_i) \
;         __builtin_amdgcn_global_load_lds((const unsigned*)((const char*)(gbase) + (voff)[_i]), (PG8_LAS unsigned*)(lds + (bufoff) + ldsw + _i * 8192), 16, 0, 0); } while (0)
; #define PG8_LDA(dst, b, h) do { _Pragma("unroll") for (int m = 0; m < 4; ++m) _Pragma("unroll") for (int k = 0; k < 2; ++k) dst[m][k] = *(const PG8_LAS bf16x8*)(lds + PG8_SA(b, h) + aoff + m * 2048 + k * 1024); } while (0)
; #define PG8_LDB(dst, b, h) do { _Pragma("unroll") for (int n = 0; n < 2; ++n) _Pragma("unroll") for (int k = 0; k < 2; ++k) dst[n][k] = *(const PG8_LAS bf16x8*)(lds + PG8_SB(b, h) + boff + n * 2048 + k * 1024); } while (0)
; #define PG8_MMA(ai, bj, At, Bt) do { __builtin_amdgcn_s_setprio(1); _Pragma("unroll") for (int m = 0; m < 4; ++m) _Pragma("unroll") for (int n = 0; n < 2; ++n) _Pragma("unroll") for (int k = 0; k < 2; ++k) \
;         acc[ai][bj][m][n] = __builtin_amdgcn_mfma_f32_16x16x32_bf16(Bt[n][k], At[m][k], acc[ai][bj][m][n], 0, 0, 0); __builtin_amdgcn_s_setprio(0); } while (0)
; #define PG8_WAIT_V(n) asm volatile("s_waitcnt vmcnt(" #n ")" ::: "memory")
;     ...
;             const bool last = (t == nt - 2);
;             const char* a1 = AS.tile(cur, t + 1);
;             const char* a2 = last ? AS.tile(nu, 0) : AS.tile(cur, t + 2); const char* b2 = last ? nB : cB + (size_t)(t + 2) * kstep;
;             const char* a3 = last ? AS.tile(nu, 1) : AS.tile(cur, t + 3); const char* b3 = b2 + kstep;
;             PG8_LDB(B0, 0, 0); PG8_LDB(B1, 0, 1); PG8_SCHED; PG8_LDA(At, 0, 0); PG8_STAGE(PG8_SA(1, 1), a1 + hstepA, voffA);
;             PG8_WAIT_V(8); PG8_WAIT_L(0); PG8_BAR; PG8_MMA(0, 0, At, B0); PG8_MMA(0, 1, At, B1); PG8_BAR; PG8_SCHED;
;             PG8_LDA(At, 0, 1); PG8_STAGE(PG8_SB(0, 0), b2, voffB); PG8_STAGE(PG8_SB(0, 1), b2 + hstepB, voffB); PG8_STAGE(PG8_SA(0, 0), a2, voffA);
;             PG8_WAIT_V(8); PG8_WAIT_L(0); PG8_BAR; PG8_MMA(1, 0, At, B0); PG8_MMA(1, 1, At, B1); PG8_BAR; PG8_SCHED;
.Lpeel_504:
	s_add_u32 s14, s52, s12
	s_addc_u32 s15, s53, s13
	s_add_u32 s18, s14, 0x400100
	s_addc_u32 s19, s15, 0
	s_add_u32 s16, s54, s12
	s_addc_u32 s17, s55, s13
	s_add_u32 s14, s14, 0x400180
	s_addc_u32 s15, s15, 0
	s_add_i32 s57, 0, 0x10000
	s_add_i32 s60, 0, 0x14000
	v_add_u32_e32 v146, s57, v149
	ds_read_b128 v[156:159], v146
	ds_read_b128 v[160:163], v146 offset:1024
	ds_read_b128 v[164:167], v146 offset:2048
	ds_read_b128 v[168:171], v146 offset:3072
	v_add_u32_e32 v146, s60, v149
	ds_read_b128 v[172:175], v146
	ds_read_b128 v[176:179], v146 offset:1024
	ds_read_b128 v[180:183], v146 offset:2048
	ds_read_b128 v[184:187], v146 offset:3072
	s_cmpk_eq_i32 s12, 0x700
	s_cselect_b32 s15, s51, s15
	s_cselect_b32 s14, s50, s14
	s_cselect_b32 s17, s48, s17
	s_cselect_b32 s16, s47, s16
	s_cselect_b32 s19, s49, s19
	s_cselect_b32 s18, s11, s18
	v_lshl_add_u64 v[146:147], v[142:143], 0, s[12:13]
	s_add_i32 m0, s26, 0xc000
	ds_read_b128 v[188:191], v152
	ds_read_b128 v[192:195], v152 offset:1024
	ds_read_b128 v[196:199], v152 offset:2048
	ds_read_b128 v[200:203], v152 offset:3072
	ds_read_b128 v[204:207], v152 offset:4096
	ds_read_b128 v[218:221], v152 offset:5120
	ds_read_b128 v[222:225], v152 offset:6144
	ds_read_b128 v[238:241], v152 offset:7168
	global_load_lds_dwordx4 v[146:147], off
	v_lshl_add_u64 v[146:147], v[144:145], 0, s[12:13]
	s_add_i32 m0, s26, 0xe000
	s_nop 0
	global_load_lds_dwordx4 v[146:147], off
	s_waitcnt vmcnt(24)
	s_waitcnt lgkmcnt(0)
	s_barrier
	s_setprio 1
	s_waitcnt lgkmcnt(0)
	v_mfma_f32_16x16x32_bf16 v[124:127], v[156:159], v[188:191], 0
	v_mfma_f32_16x16x32_bf16 v[120:123], v[164:167], v[188:191], 0
	v_mfma_f32_16x16x32_bf16 v[108:111], v[156:159], v[196:199], 0
	v_mfma_f32_16x16x32_bf16 v[104:107], v[164:167], v[196:199], 0
	v_mfma_f32_16x16x32_bf16 v[92:95], v[156:159], v[204:207], 0
	v_mfma_f32_16x16x32_bf16 v[88:91], v[164:167], v[204:207], 0
	v_mfma_f32_16x16x32_bf16 v[76:79], v[156:159], v[222:225], 0
	v_mfma_f32_16x16x32_bf16 v[72:75], v[164:167], v[222:225], 0
	v_mfma_f32_16x16x32_bf16 v[124:127], v[160:163], v[192:195], v[124:127]
	v_mfma_f32_16x16x32_bf16 v[120:123], v[168:171], v[192:195], v[120:123]
	v_mfma_f32_16x16x32_bf16 v[108:111], v[160:163], v[200:203], v[108:111]
	v_mfma_f32_16x16x32_bf16 v[104:107], v[168:171], v[200:203], v[104:107]
	v_mfma_f32_16x16x32_bf16 v[92:95], v[160:163], v[218:221], v[92:95]
	v_mfma_f32_16x16x32_bf16 v[88:91], v[168:171], v[218:221], v[88:91]
	v_mfma_f32_16x16x32_bf16 v[76:79], v[160:163], v[238:241], v[76:79]
	v_mfma_f32_16x16x32_bf16 v[72:75], v[168:171], v[238:241], v[72:75]
	s_setprio 0
	s_setprio 1
	v_mfma_f32_16x16x32_bf16 v[116:119], v[172:175], v[188:191], 0
	v_mfma_f32_16x16x32_bf16 v[112:115], v[180:183], v[188:191], 0
	v_mfma_f32_16x16x32_bf16 v[100:103], v[172:175], v[196:199], 0
	v_mfma_f32_16x16x32_bf16 v[96:99], v[180:183], v[196:199], 0
	v_mfma_f32_16x16x32_bf16 v[84:87], v[172:175], v[204:207], 0
	v_mfma_f32_16x16x32_bf16 v[80:83], v[180:183], v[204:207], 0
	v_mfma_f32_16x16x32_bf16 v[68:71], v[172:175], v[222:225], 0
	v_mfma_f32_16x16x32_bf16 v[64:67], v[180:183], v[222:225], 0
	v_mfma_f32_16x16x32_bf16 v[116:119], v[176:179], v[192:195], v[116:119]
	v_mfma_f32_16x16x32_bf16 v[112:115], v[184:187], v[192:195], v[112:115]
	v_mfma_f32_16x16x32_bf16 v[100:103], v[176:179], v[200:203], v[100:103]
	v_mfma_f32_16x16x32_bf16 v[96:99], v[184:187], v[200:203], v[96:99]
	v_mfma_f32_16x16x32_bf16 v[84:87], v[176:179], v[218:221], v[84:87]
	v_mfma_f32_16x16x32_bf16 v[80:83], v[184:187], v[218:221], v[80:83]
	v_mfma_f32_16x16x32_bf16 v[68:71], v[176:179], v[238:241], v[68:71]
	s_barrier
	v_mfma_f32_16x16x32_bf16 v[64:67], v[184:187], v[238:241], v[64:67]
	s_setprio 0
	s_add_i32 s57, s57, s25
	v_lshl_add_u64 v[146:147], s[16:17], 0, v[208:209]
	s_mov_b32 m0, s57
	ds_read_b128 v[188:191], v152 offset:16384
	ds_read_b128 v[192:195], v152 offset:17408
	ds_read_b128 v[196:199], v152 offset:18432
	ds_read_b128 v[200:203], v152 offset:19456
	ds_read_b128 v[204:207], v152 offset:20480
	ds_read_b128 v[218:221], v152 offset:21504
	ds_read_b128 v[222:225], v152 offset:22528
	ds_read_b128 v[238:241], v152 offset:23552
	global_load_lds_dwordx4 v[146:147], off
	s_add_i32 m0, s57, 0x2000
	s_add_u32 s58, s16, 0x40000
	v_lshl_add_u64 v[242:243], s[16:17], 0, v[128:129]
	s_addc_u32 s59, s17, 0
	s_add_i32 s57, s60, s25
	global_load_lds_dwordx4 v[242:243], off
	v_lshl_add_u64 v[244:245], s[58:59], 0, v[208:209]
	s_mov_b32 m0, s57
	s_nop 0
	global_load_lds_dwordx4 v[244:245], off
	v_lshl_add_u64 v[244:245], s[58:59], 0, v[128:129]
	s_add_i32 m0, s57, 0x2000
	s_nop 0
	global_load_lds_dwordx4 v[244:245], off
	v_lshl_add_u64 v[244:245], s[18:19], 0, v[132:133]
	s_mov_b32 m0, s26
	s_nop 0
	global_load_lds_dwordx4 v[244:245], off
	v_lshl_add_u64 v[244:245], s[18:19], 0, v[130:131]
	s_mov_b32 m0, s27
	s_nop 0
	global_load_lds_dwordx4 v[244:245], off
	s_waitcnt vmcnt(8)
	s_waitcnt lgkmcnt(0)
	s_barrier
; #define PG8_STAGE(bufoff, gbase, voff) do { _Pragma("unroll") for (int _i = 0; _i < 2; ++_i) \
;         __builtin_amdgcn_global_load_lds((const unsigned*)((const char*)(gbase) + (voff)[_i]), (PG8_LAS unsigned*)(lds + (bufoff) + ldsw + _i * 8192), 16, 0, 0); } while (0)
; #define PG8_LDA(dst, b, h) do { _Pragma("unroll") for (int m = 0; m < 4; ++m) _Pragma("unroll") for (int k = 0; k < 2; ++k) dst[m][k] = *(const PG8_LAS bf16x8*)(lds + PG8_SA(b, h) + aoff + m * 2048 + k * 1024); } while (0)
; #define PG8_LDB(dst, b, h) do { _Pragma("unroll") for (int n = 0; n < 2; ++n) _Pragma("unroll") for (int k = 0; k < 2; ++k) dst[n][k] = *(const PG8_LAS bf16x8*)(lds + PG8_SB(b, h) + boff + n * 2048 + k * 1024); } while (0)
; #define PG8_MMA(ai, bj, At, Bt) do { __builtin_amdgcn_s_setprio(1); _Pragma("unroll") for (int m = 0; m < 4; ++m) _Pragma("unroll") for (int n = 0; n < 2; ++n) _Pragma("unroll") for (int k = 0; k < 2; ++k) \
;         acc[ai][bj][m][n] = __builtin_amdgcn_mfma_f32_16x16x32_bf16(Bt[n][k], At[m][k], acc[ai][bj][m][n], 0, 0, 0); __builtin_amdgcn_s_setprio(0); } while (0)
; #define PG8_WAIT_V(n) asm volatile("s_waitcnt vmcnt(" #n ")" ::: "memory")
; #define PG8_WAIT_L(n) asm volatile("s_waitcnt lgkmcnt(" #n ")" ::: "memory")
; #define PG8_BAR __builtin_amdgcn_s_barrier()
; #define PG8_SCHED __builtin_amdgcn_sched_barrier(0)
;     ...
;             PG8_WAIT_V(8); PG8_WAIT_L(0); PG8_BAR; PG8_MMA(0, 0, At, B0); PG8_MMA(0, 1, At, B1); PG8_BAR; PG8_SCHED;
;             PG8_LDA(At, 0, 1); PG8_STAGE(PG8_SB(0, 0), b2, voffB); PG8_STAGE(PG8_SB(0, 1), b2 + hstepB, voffB); PG8_STAGE(PG8_SA(0, 0), a2, voffA);
;             PG8_WAIT_V(8); PG8_WAIT_L(0); PG8_BAR; PG8_MMA(1, 0, At, B0); PG8_MMA(1, 1, At, B1); PG8_BAR; PG8_SCHED;
;             PG8_LDB(B0, 1, 0); PG8_LDB(B1, 1, 1); PG8_SCHED; PG8_LDA(At, 1, 0); PG8_STAGE(PG8_SA(0, 1), a2 + hstepA, voffA);
;             PG8_WAIT_V(8); PG8_WAIT_L(0); PG8_BAR; PG8_MMA(0, 0, At, B0); PG8_MMA(0, 1, At, B1); PG8_BAR; PG8_SCHED;
	s_setprio 1
	s_waitcnt lgkmcnt(0)
	v_mfma_f32_16x16x32_bf16 v[60:63], v[156:159], v[188:191], 0
	v_mfma_f32_16x16x32_bf16 v[56:59], v[164:167], v[188:191], 0
	v_mfma_f32_16x16x32_bf16 v[44:47], v[156:159], v[196:199], 0
	v_mfma_f32_16x16x32_bf16 v[40:43], v[164:167], v[196:199], 0
	v_mfma_f32_16x16x32_bf16 v[28:31], v[156:159], v[204:207], 0
	v_mfma_f32_16x16x32_bf16 v[24:27], v[164:167], v[204:207], 0
	v_mfma_f32_16x16x32_bf16 v[12:15], v[156:159], v[222:225], 0
	v_mfma_f32_16x16x32_bf16 v[8:11], v[164:167], v[222:225], 0
	v_mfma_f32_16x16x32_bf16 v[60:63], v[160:163], v[192:195], v[60:63]
	v_mfma_f32_16x16x32_bf16 v[56:59], v[168:171], v[192:195], v[56:59]
	v_mfma_f32_16x16x32_bf16 v[44:47], v[160:163], v[200:203], v[44:47]
	v_mfma_f32_16x16x32_bf16 v[40:43], v[168:171], v[200:203], v[40:43]
	v_mfma_f32_16x16x32_bf16 v[28:31], v[160:163], v[218:221], v[28:31]
	v_mfma_f32_16x16x32_bf16 v[24:27], v[168:171], v[218:221], v[24:27]
	v_mfma_f32_16x16x32_bf16 v[12:15], v[160:163], v[238:241], v[12:15]
	v_mfma_f32_16x16x32_bf16 v[8:11], v[168:171], v[238:241], v[8:11]
	s_setprio 0
	s_setprio 1
	v_mfma_f32_16x16x32_bf16 v[52:55], v[172:175], v[188:191], 0
	v_mfma_f32_16x16x32_bf16 v[48:51], v[180:183], v[188:191], 0
	v_mfma_f32_16x16x32_bf16 v[36:39], v[172:175], v[196:199], 0
	v_mfma_f32_16x16x32_bf16 v[32:35], v[180:183], v[196:199], 0
	v_mfma_f32_16x16x32_bf16 v[20:23], v[172:175], v[204:207], 0
	v_mfma_f32_16x16x32_bf16 v[16:19], v[180:183], v[204:207], 0
	v_mfma_f32_16x16x32_bf16 v[4:7], v[172:175], v[222:225], 0
	v_mfma_f32_16x16x32_bf16 v[0:3], v[180:183], v[222:225], 0
	v_mfma_f32_16x16x32_bf16 v[52:55], v[176:179], v[192:195], v[52:55]
	v_mfma_f32_16x16x32_bf16 v[48:51], v[184:187], v[192:195], v[48:51]
	v_mfma_f32_16x16x32_bf16 v[36:39], v[176:179], v[200:203], v[36:39]
	v_mfma_f32_16x16x32_bf16 v[32:35], v[184:187], v[200:203], v[32:35]
	v_mfma_f32_16x16x32_bf16 v[20:23], v[176:179], v[218:221], v[20:23]
	v_mfma_f32_16x16x32_bf16 v[16:19], v[184:187], v[218:221], v[16:19]
	v_mfma_f32_16x16x32_bf16 v[4:7], v[176:179], v[238:241], v[4:7]
	s_barrier
	v_mfma_f32_16x16x32_bf16 v[0:3], v[184:187], v[238:241], v[0:3]
	s_setprio 0
	s_add_i32 s57, 0, 0x18000
	v_add_u32_e32 v155, s57, v149
	s_add_i32 s58, 0, 0x1c000
	ds_read_b128 v[156:159], v155
	ds_read_b128 v[160:163], v155 offset:1024
	ds_read_b128 v[164:167], v155 offset:2048
	ds_read_b128 v[168:171], v155 offset:3072
	v_add_u32_e32 v155, s58, v149
	ds_read_b128 v[172:175], v155
	ds_read_b128 v[176:179], v155 offset:1024
	ds_read_b128 v[180:183], v155 offset:2048
	ds_read_b128 v[184:187], v155 offset:3072
	s_add_u32 s18, s18, 0x40000
	s_addc_u32 s19, s19, 0
	s_mov_b32 m0, s28
	v_lshl_add_u64 v[244:245], s[18:19], 0, v[132:133]
	ds_read_b128 v[188:191], v152 offset:32768
	ds_read_b128 v[192:195], v152 offset:33792
	ds_read_b128 v[196:199], v152 offset:34816
	ds_read_b128 v[200:203], v152 offset:35840
	ds_read_b128 v[204:207], v152 offset:36864
	ds_read_b128 v[218:221], v152 offset:37888
	ds_read_b128 v[222:225], v152 offset:38912
	ds_read_b128 v[238:241], v152 offset:39936
	global_load_lds_dwordx4 v[244:245], off
	v_lshl_add_u64 v[244:245], s[18:19], 0, v[130:131]
	s_mov_b32 m0, s29
	s_nop 0
	global_load_lds_dwordx4 v[244:245], off
	s_waitcnt vmcnt(8)
	s_waitcnt lgkmcnt(0)
	s_barrier
	s_setprio 1
	s_waitcnt lgkmcnt(0)
	v_mfma_f32_16x16x32_bf16 v[124:127], v[156:159], v[188:191], v[124:127]
	v_mfma_f32_16x16x32_bf16 v[120:123], v[164:167], v[188:191], v[120:123]
	v_mfma_f32_16x16x32_bf16 v[108:111], v[156:159], v[196:199], v[108:111]
	v_mfma_f32_16x16x32_bf16 v[104:107], v[164:167], v[196:199], v[104:107]
	v_mfma_f32_16x16x32_bf16 v[92:95], v[156:159], v[204:207], v[92:95]
	v_mfma_f32_16x16x32_bf16 v[88:91], v[164:167], v[204:207], v[88:91]
	v_mfma_f32_16x16x32_bf16 v[76:79], v[156:159], v[222:225], v[76:79]
	v_mfma_f32_16x16x32_bf16 v[72:75], v[164:167], v[222:225], v[72:75]
	v_mfma_f32_16x16x32_bf16 v[124:127], v[160:163], v[192:195], v[124:127]
	v_mfma_f32_16x16x32_bf16 v[120:123], v[168:171], v[192:195], v[120:123]
	v_mfma_f32_16x16x32_bf16 v[108:111], v[160:163], v[200:203], v[108:111]
	v_mfma_f32_16x16x32_bf16 v[104:107], v[168:171], v[200:203], v[104:107]
	v_mfma_f32_16x16x32_bf16 v[92:95], v[160:163], v[218:221], v[92:95]
	v_mfma_f32_16x16x32_bf16 v[88:91], v[168:171], v[218:221], v[88:91]
	v_mfma_f32_16x16x32_bf16 v[76:79], v[160:163], v[238:241], v[76:79]
	v_mfma_f32_16x16x32_bf16 v[72:75], v[168:171], v[238:241], v[72:75]
	s_setprio 0
	s_setprio 1
	v_mfma_f32_16x16x32_bf16 v[116:119], v[172:175], v[188:191], v[116:119]
	v_mfma_f32_16x16x32_bf16 v[112:115], v[180:183], v[188:191], v[112:115]
	v_mfma_f32_16x16x32_bf16 v[100:103], v[172:175], v[196:199], v[100:103]
	v_mfma_f32_16x16x32_bf16 v[96:99], v[180:183], v[196:199], v[96:99]
	v_mfma_f32_16x16x32_bf16 v[84:87], v[172:175], v[204:207], v[84:87]
	v_mfma_f32_16x16x32_bf16 v[80:83], v[180:183], v[204:207], v[80:83]
	v_mfma_f32_16x16x32_bf16 v[68:71], v[172:175], v[222:225], v[68:71]
	v_mfma_f32_16x16x32_bf16 v[64:67], v[180:183], v[222:225], v[64:67]
	v_mfma_f32_16x16x32_bf16 v[116:119], v[176:179], v[192:195], v[116:119]
	v_mfma_f32_16x16x32_bf16 v[112:115], v[184:187], v[192:195], v[112:115]
	v_mfma_f32_16x16x32_bf16 v[100:103], v[176:179], v[200:203], v[100:103]
	v_mfma_f32_16x16x32_bf16 v[96:99], v[184:187], v[200:203], v[96:99]
	v_mfma_f32_16x16x32_bf16 v[84:87], v[176:179], v[218:221], v[84:87]
	v_mfma_f32_16x16x32_bf16 v[80:83], v[184:187], v[218:221], v[80:83]
	v_mfma_f32_16x16x32_bf16 v[68:71], v[176:179], v[238:241], v[68:71]
	s_barrier
;     __device__ __forceinline__ const char* tile(const Unit& u, int t) const { return A + (size_t)u.pm * 2 * hstep() + (size_t)t * (BK * 2); }
;     __device__ __forceinline__ const char* tile(const Unit& u, int t) const { return U + (long)(t >> 2) * xoff + (size_t)u.pn * (1024 * 512) + (size_t)u.pm * 2 * hstep() + (size_t)(t & 3) * (BK * 2); }
; #define PG8_STAGE(bufoff, gbase, voff) do { _Pragma("unroll") for (int _i = 0; _i < 2; ++_i) \
;         __builtin_amdgcn_global_load_lds((const unsigned*)((const char*)(gbase) + (voff)[_i]), (PG8_LAS unsigned*)(lds + (bufoff) + ldsw + _i * 8192), 16, 0, 0); } while (0)
; #define PG8_LDA(dst, b, h) do { _Pragma("unroll") for (int m = 0; m < 4; ++m) _Pragma("unroll") for (int k = 0; k < 2; ++k) dst[m][k] = *(const PG8_LAS bf16x8*)(lds + PG8_SA(b, h) + aoff + m * 2048 + k * 1024); } while (0)
; #define PG8_WAIT_V(n) asm volatile("s_waitcnt vmcnt(" #n ")" ::: "memory")
; #define PG8_BAR __builtin_amdgcn_s_barrier()
;     ...
;         for (int t = 0; t < nt; t += 2) {
;             const bool last = (t == nt - 2);
;             const char* a1 = AS.tile(cur, t + 1);
;             const char* a2 = last ? AS.tile(nu, 0) : AS.tile(cur, t + 2); const char* b2 = last ? nB : cB + (size_t)(t + 2) * kstep;
;             const char* a3 = last ? AS.tile(nu, 1) : AS.tile(cur, t + 3); const char* b3 = b2 + kstep;
;             PG8_LDB(B0, 0, 0); PG8_LDB(B1, 0, 1); PG8_SCHED; PG8_LDA(At, 0, 0); PG8_STAGE(PG8_SA(1, 1), a1 + hstepA, voffA);
;             PG8_WAIT_V(8); PG8_WAIT_L(0); PG8_BAR; PG8_MMA(0, 0, At, B0); PG8_MMA(0, 1, At, B1); PG8_BAR; PG8_SCHED;
;             PG8_LDA(At, 0, 1); PG8_STAGE(PG8_SB(0, 0), b2, voffB); PG8_STAGE(PG8_SB(0, 1), b2 + hstepB, voffB); PG8_STAGE(PG8_SA(0, 0), a2, voffA);
;             PG8_WAIT_V(8); PG8_WAIT_L(0); PG8_BAR; PG8_MMA(1, 0, At, B0); PG8_MMA(1, 1, At, B1); PG8_BAR; PG8_SCHED;
;             PG8_LDB(B0, 1, 0); PG8_LDB(B1, 1, 1); PG8_SCHED; PG8_LDA(At, 1, 0); PG8_STAGE(PG8_SA(0, 1), a2 + hstepA, voffA);
;             PG8_WAIT_V(8); PG8_WAIT_L(0); PG8_BAR; PG8_MMA(0, 0, At, B0); PG8_MMA(0, 1, At, B1); PG8_BAR; PG8_SCHED;
;             PG8_LDA(At, 1, 1); PG8_STAGE(PG8_SB(1, 0), b3, voffB); PG8_STAGE(PG8_SB(1, 1), b3 + hstepB, voffB); PG8_STAGE(PG8_SA(1, 0), a3, voffA);
;             PG8_WAIT_V(8); PG8_WAIT_L(0); PG8_BAR; PG8_MMA(1, 0, At, B0); PG8_MMA(1, 1, At, B1); PG8_BAR; PG8_SCHED;
	v_mfma_f32_16x16x32_bf16 v[64:67], v[184:187], v[238:241], v[64:67]
	s_setprio 0
	s_add_i32 s18, s57, s25
	v_lshl_add_u64 v[146:147], v[146:147], 0, s[64:65]
	s_mov_b32 m0, s18
	ds_read_b128 v[188:191], v152 offset:49152
	ds_read_b128 v[192:195], v152 offset:50176
	ds_read_b128 v[196:199], v152 offset:51200
	ds_read_b128 v[200:203], v152 offset:52224
	ds_read_b128 v[204:207], v152 offset:53248
	ds_read_b128 v[218:221], v152 offset:54272
	ds_read_b128 v[222:225], v152 offset:55296
	ds_read_b128 v[238:241], v152 offset:56320
	global_load_lds_dwordx4 v[146:147], off
	s_add_i32 m0, s18, 0x2000
	s_add_u32 s16, s16, 0x40080
	v_lshl_add_u64 v[146:147], v[242:243], 0, s[64:65]
	s_addc_u32 s17, s17, 0
	s_add_i32 s18, s58, s25
	global_load_lds_dwordx4 v[146:147], off
	v_lshl_add_u64 v[146:147], s[16:17], 0, v[208:209]
	s_mov_b32 m0, s18
	s_nop 0
	global_load_lds_dwordx4 v[146:147], off
	v_lshl_add_u64 v[146:147], s[16:17], 0, v[128:129]
	s_add_i32 m0, s18, 0x2000
	s_nop 0
	global_load_lds_dwordx4 v[146:147], off
	v_lshl_add_u64 v[146:147], s[14:15], 0, v[132:133]
	s_mov_b32 m0, s30
	s_nop 0
	global_load_lds_dwordx4 v[146:147], off
	v_lshl_add_u64 v[146:147], s[14:15], 0, v[130:131]
	s_mov_b32 m0, s31
	s_nop 0
	global_load_lds_dwordx4 v[146:147], off
	s_waitcnt vmcnt(8)
	s_waitcnt lgkmcnt(0)
	s_barrier
	s_setprio 1
	s_waitcnt lgkmcnt(0)
	v_mfma_f32_16x16x32_bf16 v[60:63], v[156:159], v[188:191], v[60:63]
	v_mfma_f32_16x16x32_bf16 v[56:59], v[164:167], v[188:191], v[56:59]
	v_mfma_f32_16x16x32_bf16 v[44:47], v[156:159], v[196:199], v[44:47]
	v_mfma_f32_16x16x32_bf16 v[40:43], v[164:167], v[196:199], v[40:43]
	v_mfma_f32_16x16x32_bf16 v[28:31], v[156:159], v[204:207], v[28:31]
	v_mfma_f32_16x16x32_bf16 v[24:27], v[164:167], v[204:207], v[24:27]
	v_mfma_f32_16x16x32_bf16 v[12:15], v[156:159], v[222:225], v[12:15]
	v_mfma_f32_16x16x32_bf16 v[8:11], v[164:167], v[222:225], v[8:11]
	v_mfma_f32_16x16x32_bf16 v[60:63], v[160:163], v[192:195], v[60:63]
	v_mfma_f32_16x16x32_bf16 v[56:59], v[168:171], v[192:195], v[56:59]
	v_mfma_f32_16x16x32_bf16 v[44:47], v[160:163], v[200:203], v[44:47]
	v_mfma_f32_16x16x32_bf16 v[40:43], v[168:171], v[200:203], v[40:43]
	v_mfma_f32_16x16x32_bf16 v[28:31], v[160:163], v[218:221], v[28:31]
	v_mfma_f32_16x16x32_bf16 v[24:27], v[168:171], v[218:221], v[24:27]
	v_mfma_f32_16x16x32_bf16 v[12:15], v[160:163], v[238:241], v[12:15]
	v_mfma_f32_16x16x32_bf16 v[8:11], v[168:171], v[238:241], v[8:11]
	s_setprio 0
	s_setprio 1
	v_mfma_f32_16x16x32_bf16 v[52:55], v[172:175], v[188:191], v[52:55]
	v_mfma_f32_16x16x32_bf16 v[48:51], v[180:183], v[188:191], v[48:51]
	v_mfma_f32_16x16x32_bf16 v[36:39], v[172:175], v[196:199], v[36:39]
	v_mfma_f32_16x16x32_bf16 v[32:35], v[180:183], v[196:199], v[32:35]
	v_mfma_f32_16x16x32_bf16 v[20:23], v[172:175], v[204:207], v[20:23]
	v_mfma_f32_16x16x32_bf16 v[16:19], v[180:183], v[204:207], v[16:19]
	v_mfma_f32_16x16x32_bf16 v[4:7], v[172:175], v[222:225], v[4:7]
	v_mfma_f32_16x16x32_bf16 v[0:3], v[180:183], v[222:225], v[0:3]
	v_mfma_f32_16x16x32_bf16 v[52:55], v[176:179], v[192:195], v[52:55]
	v_mfma_f32_16x16x32_bf16 v[48:51], v[184:187], v[192:195], v[48:51]
	v_mfma_f32_16x16x32_bf16 v[36:39], v[176:179], v[200:203], v[36:39]
	v_mfma_f32_16x16x32_bf16 v[32:35], v[184:187], v[200:203], v[32:35]
	v_mfma_f32_16x16x32_bf16 v[20:23], v[176:179], v[218:221], v[20:23]
	v_mfma_f32_16x16x32_bf16 v[16:19], v[184:187], v[218:221], v[16:19]
	v_mfma_f32_16x16x32_bf16 v[4:7], v[176:179], v[238:241], v[4:7]
	s_barrier
	v_mfma_f32_16x16x32_bf16 v[0:3], v[184:187], v[238:241], v[0:3]
	s_setprio 0
	s_add_i32 s56, s56, 2
	s_add_u32 s12, s12, 0x100
	s_addc_u32 s13, s13, 0
	s_cmp_gt_u32 s56, 13
	s_cbranch_scc0 .LBB0_504
	s_branch .Lpeel_exit_504
.LBB0_504:
	s_add_u32 s14, s52, s12
	s_addc_u32 s15, s53, s13
	s_add_u32 s18, s14, 0x400100
	s_addc_u32 s19, s15, 0
	s_add_u32 s16, s54, s12
	s_addc_u32 s17, s55, s13
	s_add_u32 s14, s14, 0x400180
	s_addc_u32 s15, s15, 0
	s_add_i32 s57, 0, 0x10000
	s_add_i32 s60, 0, 0x14000
	v_add_u32_e32 v146, s57, v149
	ds_read_b128 v[156:159], v146
	ds_read_b128 v[160:163], v146 offset:1024
	ds_read_b128 v[164:167], v146 offset:2048
	ds_read_b128 v[168:171], v146 offset:3072
	v_add_u32_e32 v146, s60, v149
	ds_read_b128 v[172:175], v146
	ds_read_b128 v[176:179], v146 offset:1024
	ds_read_b128 v[180:183], v146 offset:2048
	ds_read_b128 v[184:187], v146 offset:3072
	s_cmpk_eq_i32 s12, 0x700
	s_cselect_b32 s15, s51, s15
	s_cselect_b32 s14, s50, s14
	s_cselect_b32 s17, s48, s17
	s_cselect_b32 s16, s47, s16
	s_cselect_b32 s19, s49, s19
	s_cselect_b32 s18, s11, s18
	v_lshl_add_u64 v[146:147], v[142:143], 0, s[12:13]
	s_add_i32 m0, s26, 0xc000
	ds_read_b128 v[188:191], v152
	ds_read_b128 v[192:195], v152 offset:1024
	ds_read_b128 v[196:199], v152 offset:2048
	ds_read_b128 v[200:203], v152 offset:3072
	ds_read_b128 v[204:207], v152 offset:4096
	ds_read_b128 v[218:221], v152 offset:5120
	ds_read_b128 v[222:225], v152 offset:6144
	ds_read_b128 v[238:241], v152 offset:7168
	global_load_lds_dwordx4 v[146:147], off
	v_lshl_add_u64 v[146:147], v[144:145], 0, s[12:13]
	s_add_i32 m0, s26, 0xe000
	s_nop 0
	global_load_lds_dwordx4 v[146:147], off
	s_waitcnt vmcnt(8)
	s_waitcnt lgkmcnt(0)
	s_barrier
; #define PG8_STAGE(bufoff, gbase, voff) do { _Pragma("unroll") for (int _i = 0; _i < 2; ++_i) \
;         __builtin_amdgcn_global_load_lds((const unsigned*)((const char*)(gbase) + (voff)[_i]), (PG8_LAS unsigned*)(lds + (bufoff) + ldsw + _i * 8192), 16, 0, 0); } while (0)
; #define PG8_LDA(dst, b, h) do { _Pragma("unroll") for (int m = 0; m < 4; ++m) _Pragma("unroll") for (int k = 0; k < 2; ++k) dst[m][k] = *(const PG8_LAS bf16x8*)(lds + PG8_SA(b, h) + aoff + m * 2048 + k * 1024); } while (0)
; #define PG8_LDB(dst, b, h) do { _Pragma("unroll") for (int n = 0; n < 2; ++n) _Pragma("unroll") for (int k = 0; k < 2; ++k) dst[n][k] = *(const PG8_LAS bf16x8*)(lds + PG8_SB(b, h) + boff + n * 2048 + k * 1024); } while (0)
; #define PG8_MMA(ai, bj, At, Bt) do { __builtin_amdgcn_s_setprio(1); _Pragma("unroll") for (int m = 0; m < 4; ++m) _Pragma("unroll") for (int n = 0; n < 2; ++n) _Pragma("unroll") for (int k = 0; k < 2; ++k) \
;         acc[ai][bj][m][n] = __builtin_amdgcn_mfma_f32_16x16x32_bf16(Bt[n][k], At[m][k], acc[ai][bj][m][n], 0, 0, 0); __builtin_amdgcn_s_setprio(0); } while (0)
; #define PG8_WAIT_V(n) asm volatile("s_waitcnt vmcnt(" #n ")" ::: "memory")
; #define PG8_WAIT_L(n) asm volatile("s_waitcnt lgkmcnt(" #n ")" ::: "memory")
; #define PG8_BAR __builtin_amdgcn_s_barrier()
; #define PG8_SCHED __builtin_amdgcn_sched_barrier(0)
;     ...
;             PG8_WAIT_V(8); PG8_WAIT_L(0); PG8_BAR; PG8_MMA(0, 0, At, B0); PG8_MMA(0, 1, At, B1); PG8_BAR; PG8_SCHED;
;             PG8_LDA(At, 0, 1); PG8_STAGE(PG8_SB(0, 0), b2, voffB); PG8_STAGE(PG8_SB(0, 1), b2 + hstepB, voffB); PG8_STAGE(PG8_SA(0, 0), a2, voffA);
;             PG8_WAIT_V(8); PG8_WAIT_L(0); PG8_BAR; PG8_MMA(1, 0, At, B0); PG8_MMA(1, 1, At, B1); PG8_BAR; PG8_SCHED;
;             PG8_LDB(B0, 1, 0); PG8_LDB(B1, 1, 1); PG8_SCHED; PG8_LDA(At, 1, 0); PG8_STAGE(PG8_SA(0, 1), a2 + hstepA, voffA);
;             PG8_WAIT_V(8); PG8_WAIT_L(0); PG8_BAR; PG8_MMA(0, 0, At, B0); PG8_MMA(0, 1, At, B1); PG8_BAR; PG8_SCHED;
	s_setprio 1
	s_waitcnt lgkmcnt(0)
	v_mfma_f32_16x16x32_bf16 v[124:127], v[156:159], v[188:191], v[124:127]
	v_mfma_f32_16x16x32_bf16 v[120:123], v[164:167], v[188:191], v[120:123]
	v_mfma_f32_16x16x32_bf16 v[108:111], v[156:159], v[196:199], v[108:111]
	v_mfma_f32_16x16x32_bf16 v[104:107], v[164:167], v[196:199], v[104:107]
	v_mfma_f32_16x16x32_bf16 v[92:95], v[156:159], v[204:207], v[92:95]
	v_mfma_f32_16x16x32_bf16 v[88:91], v[164:167], v[204:207], v[88:91]
	v_mfma_f32_16x16x32_bf16 v[76:79], v[156:159], v[222:225], v[76:79]
	v_mfma_f32_16x16x32_bf16 v[72:75], v[164:167], v[222:225], v[72:75]
	v_mfma_f32_16x16x32_bf16 v[124:127], v[160:163], v[192:195], v[124:127]
	v_mfma_f32_16x16x32_bf16 v[120:123], v[168:171], v[192:195], v[120:123]
	v_mfma_f32_16x16x32_bf16 v[108:111], v[160:163], v[200:203], v[108:111]
	v_mfma_f32_16x16x32_bf16 v[104:107], v[168:171], v[200:203], v[104:107]
	v_mfma_f32_16x16x32_bf16 v[92:95], v[160:163], v[218:221], v[92:95]
	v_mfma_f32_16x16x32_bf16 v[88:91], v[168:171], v[218:221], v[88:91]
	v_mfma_f32_16x16x32_bf16 v[76:79], v[160:163], v[238:241], v[76:79]
	v_mfma_f32_16x16x32_bf16 v[72:75], v[168:171], v[238:241], v[72:75]
	s_setprio 0
	s_setprio 1
	v_mfma_f32_16x16x32_bf16 v[116:119], v[172:175], v[188:191], v[116:119]
	v_mfma_f32_16x16x32_bf16 v[112:115], v[180:183], v[188:191], v[112:115]
	v_mfma_f32_16x16x32_bf16 v[100:103], v[172:175], v[196:199], v[100:103]
	v_mfma_f32_16x16x32_bf16 v[96:99], v[180:183], v[196:199], v[96:99]
	v_mfma_f32_16x16x32_bf16 v[84:87], v[172:175], v[204:207], v[84:87]
	v_mfma_f32_16x16x32_bf16 v[80:83], v[180:183], v[204:207], v[80:83]
	v_mfma_f32_16x16x32_bf16 v[68:71], v[172:175], v[222:225], v[68:71]
	v_mfma_f32_16x16x32_bf16 v[64:67], v[180:183], v[222:225], v[64:67]
	v_mfma_f32_16x16x32_bf16 v[116:119], v[176:179], v[192:195], v[116:119]
	v_mfma_f32_16x16x32_bf16 v[112:115], v[184:187], v[192:195], v[112:115]
	v_mfma_f32_16x16x32_bf16 v[100:103], v[176:179], v[200:203], v[100:103]
	v_mfma_f32_16x16x32_bf16 v[96:99], v[184:187], v[200:203], v[96:99]
	v_mfma_f32_16x16x32_bf16 v[84:87], v[176:179], v[218:221], v[84:87]
	v_mfma_f32_16x16x32_bf16 v[80:83], v[184:187], v[218:221], v[80:83]
	v_mfma_f32_16x16x32_bf16 v[68:71], v[176:179], v[238:241], v[68:71]
	s_barrier
	v_mfma_f32_16x16x32_bf16 v[64:67], v[184:187], v[238:241], v[64:67]
	s_setprio 0
	s_add_i32 s57, s57, s25
	v_lshl_add_u64 v[146:147], s[16:17], 0, v[208:209]
	s_mov_b32 m0, s57
	ds_read_b128 v[188:191], v152 offset:16384
	ds_read_b128 v[192:195], v152 offset:17408
	ds_read_b128 v[196:199], v152 offset:18432
	ds_read_b128 v[200:203], v152 offset:19456
	ds_read_b128 v[204:207], v152 offset:20480
	ds_read_b128 v[218:221], v152 offset:21504
	ds_read_b128 v[222:225], v152 offset:22528
	ds_read_b128 v[238:241], v152 offset:23552
	global_load_lds_dwordx4 v[146:147], off
	s_add_i32 m0, s57, 0x2000
	s_add_u32 s58, s16, 0x40000
	v_lshl_add_u64 v[242:243], s[16:17], 0, v[128:129]
	s_addc_u32 s59, s17, 0
	s_add_i32 s57, s60, s25
	global_load_lds_dwordx4 v[242:243], off
	v_lshl_add_u64 v[244:245], s[58:59], 0, v[208:209]
	s_mov_b32 m0, s57
	s_nop 0
	global_load_lds_dwordx4 v[244:245], off
	v_lshl_add_u64 v[244:245], s[58:59], 0, v[128:129]
	s_add_i32 m0, s57, 0x2000
	s_nop 0
	global_load_lds_dwordx4 v[244:245], off
	v_lshl_add_u64 v[244:245], s[18:19], 0, v[132:133]
	s_mov_b32 m0, s26
	s_nop 0
	global_load_lds_dwordx4 v[244:245], off
	v_lshl_add_u64 v[244:245], s[18:19], 0, v[130:131]
	s_mov_b32 m0, s27
	s_nop 0
	global_load_lds_dwordx4 v[244:245], off
	s_waitcnt vmcnt(8)
	s_waitcnt lgkmcnt(0)
	s_barrier
	s_setprio 1
	s_waitcnt lgkmcnt(0)
	v_mfma_f32_16x16x32_bf16 v[60:63], v[156:159], v[188:191], v[60:63]
	v_mfma_f32_16x16x32_bf16 v[56:59], v[164:167], v[188:191], v[56:59]
	v_mfma_f32_16x16x32_bf16 v[44:47], v[156:159], v[196:199], v[44:47]
	v_mfma_f32_16x16x32_bf16 v[40:43], v[164:167], v[196:199], v[40:43]
	v_mfma_f32_16x16x32_bf16 v[28:31], v[156:159], v[204:207], v[28:31]
	v_mfma_f32_16x16x32_bf16 v[24:27], v[164:167], v[204:207], v[24:27]
	v_mfma_f32_16x16x32_bf16 v[12:15], v[156:159], v[222:225], v[12:15]
	v_mfma_f32_16x16x32_bf16 v[8:11], v[164:167], v[222:225], v[8:11]
	v_mfma_f32_16x16x32_bf16 v[60:63], v[160:163], v[192:195], v[60:63]
	v_mfma_f32_16x16x32_bf16 v[56:59], v[168:171], v[192:195], v[56:59]
	v_mfma_f32_16x16x32_bf16 v[44:47], v[160:163], v[200:203], v[44:47]
	v_mfma_f32_16x16x32_bf16 v[40:43], v[168:171], v[200:203], v[40:43]
	v_mfma_f32_16x16x32_bf16 v[28:31], v[160:163], v[218:221], v[28:31]
	v_mfma_f32_16x16x32_bf16 v[24:27], v[168:171], v[218:221], v[24:27]
	v_mfma_f32_16x16x32_bf16 v[12:15], v[160:163], v[238:241], v[12:15]
	v_mfma_f32_16x16x32_bf16 v[8:11], v[168:171], v[238:241], v[8:11]
	s_setprio 0
	s_setprio 1
	v_mfma_f32_16x16x32_bf16 v[52:55], v[172:175], v[188:191], v[52:55]
	v_mfma_f32_16x16x32_bf16 v[48:51], v[180:183], v[188:191], v[48:51]
	v_mfma_f32_16x16x32_bf16 v[36:39], v[172:175], v[196:199], v[36:39]
	v_mfma_f32_16x16x32_bf16 v[32:35], v[180:183], v[196:199], v[32:35]
	v_mfma_f32_16x16x32_bf16 v[20:23], v[172:175], v[204:207], v[20:23]
	v_mfma_f32_16x16x32_bf16 v[16:19], v[180:183], v[204:207], v[16:19]
	v_mfma_f32_16x16x32_bf16 v[4:7], v[172:175], v[222:225], v[4:7]
	v_mfma_f32_16x16x32_bf16 v[0:3], v[180:183], v[222:225], v[0:3]
	v_mfma_f32_16x16x32_bf16 v[52:55], v[176:179], v[192:195], v[52:55]
	v_mfma_f32_16x16x32_bf16 v[48:51], v[184:187], v[192:195], v[48:51]
	v_mfma_f32_16x16x32_bf16 v[36:39], v[176:179], v[200:203], v[36:39]
	v_mfma_f32_16x16x32_bf16 v[32:35], v[184:187], v[200:203], v[32:35]
	v_mfma_f32_16x16x32_bf16 v[20:23], v[176:179], v[218:221], v[20:23]
	v_mfma_f32_16x16x32_bf16 v[16:19], v[184:187], v[218:221], v[16:19]
	v_mfma_f32_16x16x32_bf16 v[4:7], v[176:179], v[238:241], v[4:7]
	s_barrier
; #define PG8_STAGE(bufoff, gbase, voff) do { _Pragma("unroll") for (int _i = 0; _i < 2; ++_i) \
;         __builtin_amdgcn_global_load_lds((const unsigned*)((const char*)(gbase) + (voff)[_i]), (PG8_LAS unsigned*)(lds + (bufoff) + ldsw + _i * 8192), 16, 0, 0); } while (0)
; #define PG8_LDA(dst, b, h) do { _Pragma("unroll") for (int m = 0; m < 4; ++m) _Pragma("unroll") for (int k = 0; k < 2; ++k) dst[m][k] = *(const PG8_LAS bf16x8*)(lds + PG8_SA(b, h) + aoff + m * 2048 + k * 1024); } while (0)
; #define PG8_LDB(dst, b, h) do { _Pragma("unroll") for (int n = 0; n < 2; ++n) _Pragma("unroll") for (int k = 0; k < 2; ++k) dst[n][k] = *(const PG8_LAS bf16x8*)(lds + PG8_SB(b, h) + boff + n * 2048 + k * 1024); } while (0)
; #define PG8_MMA(ai, bj, At, Bt) do { __builtin_amdgcn_s_setprio(1); _Pragma("unroll") for (int m = 0; m < 4; ++m) _Pragma("unroll") for (int n = 0; n < 2; ++n) _Pragma("unroll") for (int k = 0; k < 2; ++k) \
;         acc[ai][bj][m][n] = __builtin_amdgcn_mfma_f32_16x16x32_bf16(Bt[n][k], At[m][k], acc[ai][bj][m][n], 0, 0, 0); __builtin_amdgcn_s_setprio(0); } while (0)
; #define PG8_WAIT_V(n) asm volatile("s_waitcnt vmcnt(" #n ")" ::: "memory")
; #define PG8_WAIT_L(n) asm volatile("s_waitcnt lgkmcnt(" #n ")" ::: "memory")
; #define PG8_BAR __builtin_amdgcn_s_barrier()
; #define PG8_SCHED __builtin_amdgcn_sched_barrier(0)
;     ...
;             PG8_WAIT_V(8); PG8_WAIT_L(0); PG8_BAR; PG8_MMA(1, 0, At, B0); PG8_MMA(1, 1, At, B1); PG8_BAR; PG8_SCHED;
;             PG8_LDB(B0, 1, 0); PG8_LDB(B1, 1, 1); PG8_SCHED; PG8_LDA(At, 1, 0); PG8_STAGE(PG8_SA(0, 1), a2 + hstepA, voffA);
;             PG8_WAIT_V(8); PG8_WAIT_L(0); PG8_BAR; PG8_MMA(0, 0, At, B0); PG8_MMA(0, 1, At, B1); PG8_BAR; PG8_SCHED;
	v_mfma_f32_16x16x32_bf16 v[0:3], v[184:187], v[238:241], v[0:3]
	s_setprio 0
	s_add_i32 s57, 0, 0x18000
	v_add_u32_e32 v155, s57, v149
	s_add_i32 s58, 0, 0x1c000
	ds_read_b128 v[156:159], v155
	ds_read_b128 v[160:163], v155 offset:1024
	ds_read_b128 v[164:167], v155 offset:2048
	ds_read_b128 v[168:171], v155 offset:3072
	v_add_u32_e32 v155, s58, v149
	ds_read_b128 v[172:175], v155
	ds_read_b128 v[176:179], v155 offset:1024
	ds_read_b128 v[180:183], v155 offset:2048
	ds_read_b128 v[184:187], v155 offset:3072
	s_add_u32 s18, s18, 0x40000
	s_addc_u32 s19, s19, 0
	s_mov_b32 m0, s28
	v_lshl_add_u64 v[244:245], s[18:19], 0, v[132:133]
	ds_read_b128 v[188:191], v152 offset:32768
	ds_read_b128 v[192:195], v152 offset:33792
	ds_read_b128 v[196:199], v152 offset:34816
	ds_read_b128 v[200:203], v152 offset:35840
	ds_read_b128 v[204:207], v152 offset:36864
	ds_read_b128 v[218:221], v152 offset:37888
	ds_read_b128 v[222:225], v152 offset:38912
	ds_read_b128 v[238:241], v152 offset:39936
	global_load_lds_dwordx4 v[244:245], off
	v_lshl_add_u64 v[244:245], s[18:19], 0, v[130:131]
	s_mov_b32 m0, s29
	s_nop 0
	global_load_lds_dwordx4 v[244:245], off
	s_waitcnt vmcnt(8)
	s_waitcnt lgkmcnt(0)
	s_barrier
	s_setprio 1
	s_waitcnt lgkmcnt(0)
	v_mfma_f32_16x16x32_bf16 v[124:127], v[156:159], v[188:191], v[124:127]
	v_mfma_f32_16x16x32_bf16 v[120:123], v[164:167], v[188:191], v[120:123]
	v_mfma_f32_16x16x32_bf16 v[108:111], v[156:159], v[196:199], v[108:111]
	v_mfma_f32_16x16x32_bf16 v[104:107], v[164:167], v[196:199], v[104:107]
	v_mfma_f32_16x16x32_bf16 v[92:95], v[156:159], v[204:207], v[92:95]
	v_mfma_f32_16x16x32_bf16 v[88:91], v[164:167], v[204:207], v[88:91]
	v_mfma_f32_16x16x32_bf16 v[76:79], v[156:159], v[222:225], v[76:79]
	v_mfma_f32_16x16x32_bf16 v[72:75], v[164:167], v[222:225], v[72:75]
	v_mfma_f32_16x16x32_bf16 v[124:127], v[160:163], v[192:195], v[124:127]
	v_mfma_f32_16x16x32_bf16 v[120:123], v[168:171], v[192:195], v[120:123]
	v_mfma_f32_16x16x32_bf16 v[108:111], v[160:163], v[200:203], v[108:111]
	v_mfma_f32_16x16x32_bf16 v[104:107], v[168:171], v[200:203], v[104:107]
	v_mfma_f32_16x16x32_bf16 v[92:95], v[160:163], v[218:221], v[92:95]
	v_mfma_f32_16x16x32_bf16 v[88:91], v[168:171], v[218:221], v[88:91]
	v_mfma_f32_16x16x32_bf16 v[76:79], v[160:163], v[238:241], v[76:79]
	v_mfma_f32_16x16x32_bf16 v[72:75], v[168:171], v[238:241], v[72:75]
	s_setprio 0
	s_setprio 1
	v_mfma_f32_16x16x32_bf16 v[116:119], v[172:175], v[188:191], v[116:119]
	v_mfma_f32_16x16x32_bf16 v[112:115], v[180:183], v[188:191], v[112:115]
	v_mfma_f32_16x16x32_bf16 v[100:103], v[172:175], v[196:199], v[100:103]
	v_mfma_f32_16x16x32_bf16 v[96:99], v[180:183], v[196:199], v[96:99]
	v_mfma_f32_16x16x32_bf16 v[84:87], v[172:175], v[204:207], v[84:87]
	v_mfma_f32_16x16x32_bf16 v[80:83], v[180:183], v[204:207], v[80:83]
	v_mfma_f32_16x16x32_bf16 v[68:71], v[172:175], v[222:225], v[68:71]
	v_mfma_f32_16x16x32_bf16 v[64:67], v[180:183], v[222:225], v[64:67]
	v_mfma_f32_16x16x32_bf16 v[116:119], v[176:179], v[192:195], v[116:119]
	v_mfma_f32_16x16x32_bf16 v[112:115], v[184:187], v[192:195], v[112:115]
	v_mfma_f32_16x16x32_bf16 v[100:103], v[176:179], v[200:203], v[100:103]
	v_mfma_f32_16x16x32_bf16 v[96:99], v[184:187], v[200:203], v[96:99]
	v_mfma_f32_16x16x32_bf16 v[84:87], v[176:179], v[218:221], v[84:87]
	v_mfma_f32_16x16x32_bf16 v[80:83], v[184:187], v[218:221], v[80:83]
	v_mfma_f32_16x16x32_bf16 v[68:71], v[176:179], v[238:241], v[68:71]
	s_barrier
; #define PG8_STAGE(bufoff, gbase, voff) do { _Pragma("unroll") for (int _i = 0; _i < 2; ++_i) \
;         __builtin_amdgcn_global_load_lds((const unsigned*)((const char*)(gbase) + (voff)[_i]), (PG8_LAS unsigned*)(lds + (bufoff) + ldsw + _i * 8192), 16, 0, 0); } while (0)
; #define PG8_LDA(dst, b, h) do { _Pragma("unroll") for (int m = 0; m < 4; ++m) _Pragma("unroll") for (int k = 0; k < 2; ++k) dst[m][k] = *(const PG8_LAS bf16x8*)(lds + PG8_SA(b, h) + aoff + m * 2048 + k * 1024); } while (0)
; #define PG8_MMA(ai, bj, At, Bt) do { __builtin_amdgcn_s_setprio(1); _Pragma("unroll") for (int m = 0; m < 4; ++m) _Pragma("unroll") for (int n = 0; n < 2; ++n) _Pragma("unroll") for (int k = 0; k < 2; ++k) \
;         acc[ai][bj][m][n] = __builtin_amdgcn_mfma_f32_16x16x32_bf16(Bt[n][k], At[m][k], acc[ai][bj][m][n], 0, 0, 0); __builtin_amdgcn_s_setprio(0); } while (0)
; #define PG8_WAIT_V(n) asm volatile("s_waitcnt vmcnt(" #n ")" ::: "memory")
; #define PG8_WAIT_L(n) asm volatile("s_waitcnt lgkmcnt(" #n ")" ::: "memory")
; #define PG8_BAR __builtin_amdgcn_s_barrier()
; #define PG8_SCHED __builtin_amdgcn_sched_barrier(0)
;     ...
;             PG8_WAIT_V(8); PG8_WAIT_L(0); PG8_BAR; PG8_MMA(0, 0, At, B0); PG8_MMA(0, 1, At, B1); PG8_BAR; PG8_SCHED;
;             PG8_LDA(At, 1, 1); PG8_STAGE(PG8_SB(1, 0), b3, voffB); PG8_STAGE(PG8_SB(1, 1), b3 + hstepB, voffB); PG8_STAGE(PG8_SA(1, 0), a3, voffA);
;             PG8_WAIT_V(8); PG8_WAIT_L(0); PG8_BAR; PG8_MMA(1, 0, At, B0); PG8_MMA(1, 1, At, B1); PG8_BAR; PG8_SCHED;
	v_mfma_f32_16x16x32_bf16 v[64:67], v[184:187], v[238:241], v[64:67]
	s_setprio 0
	s_add_i32 s18, s57, s25
	v_lshl_add_u64 v[146:147], v[146:147], 0, s[64:65]
	s_mov_b32 m0, s18
	ds_read_b128 v[188:191], v152 offset:49152
	ds_read_b128 v[192:195], v152 offset:50176
	ds_read_b128 v[196:199], v152 offset:51200
	ds_read_b128 v[200:203], v152 offset:52224
	ds_read_b128 v[204:207], v152 offset:53248
	ds_read_b128 v[218:221], v152 offset:54272
	ds_read_b128 v[222:225], v152 offset:55296
	ds_read_b128 v[238:241], v152 offset:56320
	global_load_lds_dwordx4 v[146:147], off
	s_add_i32 m0, s18, 0x2000
	s_add_u32 s16, s16, 0x40080
	v_lshl_add_u64 v[146:147], v[242:243], 0, s[64:65]
	s_addc_u32 s17, s17, 0
	s_add_i32 s18, s58, s25
	global_load_lds_dwordx4 v[146:147], off
	v_lshl_add_u64 v[146:147], s[16:17], 0, v[208:209]
	s_mov_b32 m0, s18
	s_nop 0
	global_load_lds_dwordx4 v[146:147], off
	v_lshl_add_u64 v[146:147], s[16:17], 0, v[128:129]
	s_add_i32 m0, s18, 0x2000
	s_nop 0
	global_load_lds_dwordx4 v[146:147], off
	v_lshl_add_u64 v[146:147], s[14:15], 0, v[132:133]
	s_mov_b32 m0, s30
	s_nop 0
	global_load_lds_dwordx4 v[146:147], off
	v_lshl_add_u64 v[146:147], s[14:15], 0, v[130:131]
	s_mov_b32 m0, s31
	s_nop 0
	global_load_lds_dwordx4 v[146:147], off
	s_waitcnt vmcnt(8)
	s_waitcnt lgkmcnt(0)
	s_barrier
	s_setprio 1
	s_waitcnt lgkmcnt(0)
	v_mfma_f32_16x16x32_bf16 v[60:63], v[156:159], v[188:191], v[60:63]
	v_mfma_f32_16x16x32_bf16 v[56:59], v[164:167], v[188:191], v[56:59]
	v_mfma_f32_16x16x32_bf16 v[44:47], v[156:159], v[196:199], v[44:47]
	v_mfma_f32_16x16x32_bf16 v[40:43], v[164:167], v[196:199], v[40:43]
	v_mfma_f32_16x16x32_bf16 v[28:31], v[156:159], v[204:207], v[28:31]
	v_mfma_f32_16x16x32_bf16 v[24:27], v[164:167], v[204:207], v[24:27]
	v_mfma_f32_16x16x32_bf16 v[12:15], v[156:159], v[222:225], v[12:15]
	v_mfma_f32_16x16x32_bf16 v[8:11], v[164:167], v[222:225], v[8:11]
	v_mfma_f32_16x16x32_bf16 v[60:63], v[160:163], v[192:195], v[60:63]
	v_mfma_f32_16x16x32_bf16 v[56:59], v[168:171], v[192:195], v[56:59]
	v_mfma_f32_16x16x32_bf16 v[44:47], v[160:163], v[200:203], v[44:47]
	v_mfma_f32_16x16x32_bf16 v[40:43], v[168:171], v[200:203], v[40:43]
	v_mfma_f32_16x16x32_bf16 v[28:31], v[160:163], v[218:221], v[28:31]
	v_mfma_f32_16x16x32_bf16 v[24:27], v[168:171], v[218:221], v[24:27]
	v_mfma_f32_16x16x32_bf16 v[12:15], v[160:163], v[238:241], v[12:15]
	v_mfma_f32_16x16x32_bf16 v[8:11], v[168:171], v[238:241], v[8:11]
	s_setprio 0
	s_setprio 1
	v_mfma_f32_16x16x32_bf16 v[52:55], v[172:175], v[188:191], v[52:55]
	v_mfma_f32_16x16x32_bf16 v[48:51], v[180:183], v[188:191], v[48:51]
	v_mfma_f32_16x16x32_bf16 v[36:39], v[172:175], v[196:199], v[36:39]
	v_mfma_f32_16x16x32_bf16 v[32:35], v[180:183], v[196:199], v[32:35]
	v_mfma_f32_16x16x32_bf16 v[20:23], v[172:175], v[204:207], v[20:23]
	v_mfma_f32_16x16x32_bf16 v[16:19], v[180:183], v[204:207], v[16:19]
	v_mfma_f32_16x16x32_bf16 v[4:7], v[172:175], v[222:225], v[4:7]
	v_mfma_f32_16x16x32_bf16 v[0:3], v[180:183], v[222:225], v[0:3]
	v_mfma_f32_16x16x32_bf16 v[52:55], v[176:179], v[192:195], v[52:55]
	v_mfma_f32_16x16x32_bf16 v[48:51], v[184:187], v[192:195], v[48:51]
	v_mfma_f32_16x16x32_bf16 v[36:39], v[176:179], v[200:203], v[36:39]
	v_mfma_f32_16x16x32_bf16 v[32:35], v[184:187], v[200:203], v[32:35]
	v_mfma_f32_16x16x32_bf16 v[20:23], v[176:179], v[218:221], v[20:23]
	v_mfma_f32_16x16x32_bf16 v[16:19], v[184:187], v[218:221], v[16:19]
	v_mfma_f32_16x16x32_bf16 v[4:7], v[176:179], v[238:241], v[4:7]
	s_barrier
	v_mfma_f32_16x16x32_bf16 v[0:3], v[184:187], v[238:241], v[0:3]
	s_setprio 0
	s_add_i32 s56, s56, 2
	s_add_u32 s12, s12, 0x100
	s_addc_u32 s13, s13, 0
	s_cmp_gt_u32 s56, 13
	s_cbranch_scc0 .LBB0_504

;     __device__ __forceinline__ const char* tile(const Unit& u, int t) const { return A + (size_t)u.pm * 2 * hstep() + (size_t)t * (BK * 2); }
;     __device__ __forceinline__ const char* tile(const Unit& u, int t) const { return U + (long)(t >> 2) * xoff + (size_t)u.pn * (1024 * 512) + (size_t)u.pm * 2 * hstep() + (size_t)(t & 3) * (BK * 2); }
; #define PG8_STAGE(bufoff, gbase, voff) do { _Pragma("unroll") for (int _i = 0; _i < 2; ++_i) \
;         __builtin_amdgcn_global_load_lds((const unsigned*)((const char*)(gbase) + (voff)[_i]), (PG8_LAS unsigned*)(lds + (bufoff) + ldsw + _i * 8192), 16, 0, 0); } while (0)
; #define PG8_LDA(dst, b, h) do { _Pragma("unroll") for (int m = 0; m < 4; ++m) _Pragma("unroll") for (int k = 0; k < 2; ++k) dst[m][k] = *(const PG8_LAS bf16x8*)(lds + PG8_SA(b, h) + aoff + m * 2048 + k * 1024); } while (0)
; #define PG8_LDB(dst, b, h) do { _Pragma("unroll") for (int n = 0; n < 2; ++n) _Pragma("unroll") for (int k = 0; k < 2; ++k) dst[n][k] = *(const PG8_LAS bf16x8*)(lds + PG8_SB(b, h) + boff + n * 2048 + k * 1024); } while (0)
; #define PG8_MMA(ai, bj, At, Bt) do { __builtin_amdgcn_s_setprio(1); _Pragma("unroll") for (int m = 0; m < 4; ++m) _Pragma("unroll") for (int n = 0; n < 2; ++n) _Pragma("unroll") for (int k = 0; k < 2; ++k) \
;         acc[ai][bj][m][n] = __builtin_amdgcn_mfma_f32_16x16x32_bf16(Bt[n][k], At[m][k], acc[ai][bj][m][n], 0, 0, 0); __builtin_amdgcn_s_setprio(0); } while (0)
; #define PG8_WAIT_V(n) asm volatile("s_waitcnt vmcnt(" #n ")" ::: "memory")
;     ...
;             const bool last = (t == nt - 2);
;             const char* a1 = AS.tile(cur, t + 1);
;             const char* a2 = last ? AS.tile(nu, 0) : AS.tile(cur, t + 2); const char* b2 = last ? nB : cB + (size_t)(t + 2) * kstep;
;             const char* a3 = last ? AS.tile(nu, 1) : AS.tile(cur, t + 3); const char* b3 = b2 + kstep;
;             PG8_LDB(B0, 0, 0); PG8_LDB(B1, 0, 1); PG8_SCHED; PG8_LDA(At, 0, 0); PG8_STAGE(PG8_SA(1, 1), a1 + hstepA, voffA);
;             PG8_WAIT_V(8); PG8_WAIT_L(0); PG8_BAR; PG8_MMA(0, 0, At, B0); PG8_MMA(0, 1, At, B1); PG8_BAR; PG8_SCHED;
;             PG8_LDA(At, 0, 1); PG8_STAGE(PG8_SB(0, 0), b2, voffB); PG8_STAGE(PG8_SB(0, 1), b2 + hstepB, voffB); PG8_STAGE(PG8_SA(0, 0), a2, voffA);
;             PG8_WAIT_V(8); PG8_WAIT_L(0); PG8_BAR; PG8_MMA(1, 0, At, B0); PG8_MMA(1, 1, At, B1); PG8_BAR; PG8_SCHED;
.Lpeel_534:
	s_add_i32 s68, s2, 2
	s_add_u32 s3, s82, s64
	s_addc_u32 s20, s83, s65
	s_add_u32 s69, s3, 0x100
	s_addc_u32 s21, s20, 0
	s_add_u32 s70, s82, s66
	s_addc_u32 s71, s83, s67
	s_add_u32 s72, s3, 0x180
	s_addc_u32 s3, s20, 0
	s_add_i32 s73, 0, 0x10000
	s_add_i32 s74, 0, 0x14000
	v_add_u32_e32 v108, s73, v212
	v_add_u32_e32 v152, s74, v212
	ds_read_b128 v[76:79], v108
	ds_read_b128 v[88:91], v108 offset:1024
	ds_read_b128 v[100:103], v108 offset:2048
	ds_read_b128 v[108:111], v108 offset:3072
	ds_read_b128 v[124:127], v152
	ds_read_b128 v[128:131], v152 offset:1024
	ds_read_b128 v[144:147], v152 offset:2048
	ds_read_b128 v[152:155], v152 offset:3072
	s_cmp_eq_u32 s51, s2
	s_cselect_b32 s2, s60, s72
	s_cselect_b32 s3, s61, s3
	s_cselect_b32 s71, s41, s71
	s_cselect_b32 s70, s40, s70
	s_cselect_b32 s21, s59, s21
	s_cselect_b32 s20, s1, s69
	v_lshl_add_u64 v[222:223], s[82:83], 0, v[64:65]
	s_add_i32 m0, s35, 0xc000
	ds_read_b128 v[156:159], v241
	ds_read_b128 v[168:171], v241 offset:1024
	ds_read_b128 v[172:175], v241 offset:2048
	ds_read_b128 v[176:179], v241 offset:3072
	ds_read_b128 v[180:183], v241 offset:4096
	ds_read_b128 v[184:187], v241 offset:5120
	ds_read_b128 v[188:191], v241 offset:6144
	ds_read_b128 v[218:221], v241 offset:7168
	global_load_lds_dwordx4 v[222:223], off
	v_lshl_add_u64 v[222:223], s[82:83], 0, v[66:67]
	s_add_i32 m0, s35, 0xe000
	s_nop 0
	global_load_lds_dwordx4 v[222:223], off
	s_waitcnt vmcnt(8)
	s_waitcnt lgkmcnt(0)
	s_barrier
	s_setprio 1
	s_waitcnt lgkmcnt(0)
	v_mfma_f32_16x16x32_bf16 v[164:167], v[76:79], v[156:159], 0
	v_mfma_f32_16x16x32_bf16 v[160:163], v[100:103], v[156:159], 0
	v_mfma_f32_16x16x32_bf16 v[136:139], v[76:79], v[172:175], 0
	v_mfma_f32_16x16x32_bf16 v[132:135], v[100:103], v[172:175], 0
	v_mfma_f32_16x16x32_bf16 v[112:115], v[76:79], v[180:183], 0
	v_mfma_f32_16x16x32_bf16 v[104:107], v[100:103], v[180:183], 0
	v_mfma_f32_16x16x32_bf16 v[84:87], v[76:79], v[188:191], 0
	v_mfma_f32_16x16x32_bf16 v[80:83], v[100:103], v[188:191], 0
	v_mfma_f32_16x16x32_bf16 v[164:167], v[88:91], v[168:171], v[164:167]
	v_mfma_f32_16x16x32_bf16 v[160:163], v[108:111], v[168:171], v[160:163]
	v_mfma_f32_16x16x32_bf16 v[136:139], v[88:91], v[176:179], v[136:139]
	v_mfma_f32_16x16x32_bf16 v[132:135], v[108:111], v[176:179], v[132:135]
	v_mfma_f32_16x16x32_bf16 v[112:115], v[88:91], v[184:187], v[112:115]
	v_mfma_f32_16x16x32_bf16 v[104:107], v[108:111], v[184:187], v[104:107]
	v_mfma_f32_16x16x32_bf16 v[84:87], v[88:91], v[218:221], v[84:87]
	v_mfma_f32_16x16x32_bf16 v[80:83], v[108:111], v[218:221], v[80:83]
	s_setprio 0
	s_setprio 1
	v_mfma_f32_16x16x32_bf16 v[148:151], v[124:127], v[156:159], 0
	v_mfma_f32_16x16x32_bf16 v[140:143], v[144:147], v[156:159], 0
	v_mfma_f32_16x16x32_bf16 v[120:123], v[124:127], v[172:175], 0
	v_mfma_f32_16x16x32_bf16 v[116:119], v[144:147], v[172:175], 0
	v_mfma_f32_16x16x32_bf16 v[96:99], v[124:127], v[180:183], 0
	v_mfma_f32_16x16x32_bf16 v[92:95], v[144:147], v[180:183], 0
	v_mfma_f32_16x16x32_bf16 v[72:75], v[124:127], v[188:191], 0
	v_mfma_f32_16x16x32_bf16 v[68:71], v[144:147], v[188:191], 0
	v_mfma_f32_16x16x32_bf16 v[148:151], v[128:131], v[168:171], v[148:151]
	v_mfma_f32_16x16x32_bf16 v[140:143], v[152:155], v[168:171], v[140:143]
	v_mfma_f32_16x16x32_bf16 v[120:123], v[128:131], v[176:179], v[120:123]
	v_mfma_f32_16x16x32_bf16 v[116:119], v[152:155], v[176:179], v[116:119]
	v_mfma_f32_16x16x32_bf16 v[96:99], v[128:131], v[184:187], v[96:99]
	v_mfma_f32_16x16x32_bf16 v[92:95], v[152:155], v[184:187], v[92:95]
	v_mfma_f32_16x16x32_bf16 v[72:75], v[128:131], v[218:221], v[72:75]
	s_barrier
	v_mfma_f32_16x16x32_bf16 v[68:71], v[152:155], v[218:221], v[68:71]
	s_setprio 0
	s_add_i32 s69, s73, s25
	v_lshl_add_u64 v[222:223], s[70:71], 0, v[196:197]
	s_mov_b32 m0, s69
	ds_read_b128 v[156:159], v241 offset:16384
	ds_read_b128 v[168:171], v241 offset:17408
	ds_read_b128 v[172:175], v241 offset:18432
	ds_read_b128 v[176:179], v241 offset:19456
	ds_read_b128 v[180:183], v241 offset:20480
	ds_read_b128 v[184:187], v241 offset:21504
	ds_read_b128 v[188:191], v241 offset:22528
	ds_read_b128 v[218:221], v241 offset:23552
	global_load_lds_dwordx4 v[222:223], off
	s_add_i32 m0, s69, 0x2000
	v_lshl_add_u64 v[224:225], s[70:71], 0, v[192:193]
	s_add_u32 s70, s70, s24
	s_addc_u32 s71, s71, 0
	s_add_i32 s69, s74, s25
	global_load_lds_dwordx4 v[224:225], off
	v_lshl_add_u64 v[244:245], s[70:71], 0, v[196:197]
	s_mov_b32 m0, s69
	v_lshl_add_u64 v[246:247], s[70:71], 0, v[192:193]
	global_load_lds_dwordx4 v[244:245], off
	s_add_i32 m0, s69, 0x2000
	v_lshl_add_u64 v[248:249], s[20:21], 0, v[198:199]
	global_load_lds_dwordx4 v[246:247], off
	s_mov_b32 m0, s35
	s_nop 0
	global_load_lds_dwordx4 v[248:249], off
	v_lshl_add_u64 v[248:249], s[20:21], 0, v[194:195]
	s_mov_b32 m0, s44
	s_nop 0
	global_load_lds_dwordx4 v[248:249], off
	s_waitcnt vmcnt(8)
	s_waitcnt lgkmcnt(0)
	s_barrier
; #define PG8_STAGE(bufoff, gbase, voff) do { _Pragma("unroll") for (int _i = 0; _i < 2; ++_i) \
;         __builtin_amdgcn_global_load_lds((const unsigned*)((const char*)(gbase) + (voff)[_i]), (PG8_LAS unsigned*)(lds + (bufoff) + ldsw + _i * 8192), 16, 0, 0); } while (0)
; #define PG8_LDA(dst, b, h) do { _Pragma("unroll") for (int m = 0; m < 4; ++m) _Pragma("unroll") for (int k = 0; k < 2; ++k) dst[m][k] = *(const PG8_LAS bf16x8*)(lds + PG8_SA(b, h) + aoff + m * 2048 + k * 1024); } while (0)
; #define PG8_LDB(dst, b, h) do { _Pragma("unroll") for (int n = 0; n < 2; ++n) _Pragma("unroll") for (int k = 0; k < 2; ++k) dst[n][k] = *(const PG8_LAS bf16x8*)(lds + PG8_SB(b, h) + boff + n * 2048 + k * 1024); } while (0)
; #define PG8_MMA(ai, bj, At, Bt) do { __builtin_amdgcn_s_setprio(1); _Pragma("unroll") for (int m = 0; m < 4; ++m) _Pragma("unroll") for (int n = 0; n < 2; ++n) _Pragma("unroll") for (int k = 0; k < 2; ++k) \
;         acc[ai][bj][m][n] = __builtin_amdgcn_mfma_f32_16x16x32_bf16(Bt[n][k], At[m][k], acc[ai][bj][m][n], 0, 0, 0); __builtin_amdgcn_s_setprio(0); } while (0)
; #define PG8_WAIT_V(n) asm volatile("s_waitcnt vmcnt(" #n ")" ::: "memory")
; #define PG8_WAIT_L(n) asm volatile("s_waitcnt lgkmcnt(" #n ")" ::: "memory")
; #define PG8_BAR __builtin_amdgcn_s_barrier()
; #define PG8_SCHED __builtin_amdgcn_sched_barrier(0)
;     ...
;             PG8_WAIT_V(8); PG8_WAIT_L(0); PG8_BAR; PG8_MMA(0, 0, At, B0); PG8_MMA(0, 1, At, B1); PG8_BAR; PG8_SCHED;
;             PG8_LDA(At, 0, 1); PG8_STAGE(PG8_SB(0, 0), b2, voffB); PG8_STAGE(PG8_SB(0, 1), b2 + hstepB, voffB); PG8_STAGE(PG8_SA(0, 0), a2, voffA);
;             PG8_WAIT_V(8); PG8_WAIT_L(0); PG8_BAR; PG8_MMA(1, 0, At, B0); PG8_MMA(1, 1, At, B1); PG8_BAR; PG8_SCHED;
;             PG8_LDB(B0, 1, 0); PG8_LDB(B1, 1, 1); PG8_SCHED; PG8_LDA(At, 1, 0); PG8_STAGE(PG8_SA(0, 1), a2 + hstepA, voffA);
;             PG8_WAIT_V(8); PG8_WAIT_L(0); PG8_BAR; PG8_MMA(0, 0, At, B0); PG8_MMA(0, 1, At, B1); PG8_BAR; PG8_SCHED;
	s_setprio 1
	s_waitcnt lgkmcnt(0)
	v_mfma_f32_16x16x32_bf16 v[60:63], v[76:79], v[156:159], 0
	v_mfma_f32_16x16x32_bf16 v[56:59], v[100:103], v[156:159], 0
	v_mfma_f32_16x16x32_bf16 v[44:47], v[76:79], v[172:175], 0
	v_mfma_f32_16x16x32_bf16 v[40:43], v[100:103], v[172:175], 0
	v_mfma_f32_16x16x32_bf16 v[28:31], v[76:79], v[180:183], 0
	v_mfma_f32_16x16x32_bf16 v[24:27], v[100:103], v[180:183], 0
	v_mfma_f32_16x16x32_bf16 v[12:15], v[76:79], v[188:191], 0
	v_mfma_f32_16x16x32_bf16 v[8:11], v[100:103], v[188:191], 0
	v_mfma_f32_16x16x32_bf16 v[60:63], v[88:91], v[168:171], v[60:63]
	v_mfma_f32_16x16x32_bf16 v[56:59], v[108:111], v[168:171], v[56:59]
	v_mfma_f32_16x16x32_bf16 v[44:47], v[88:91], v[176:179], v[44:47]
	v_mfma_f32_16x16x32_bf16 v[40:43], v[108:111], v[176:179], v[40:43]
	v_mfma_f32_16x16x32_bf16 v[28:31], v[88:91], v[184:187], v[28:31]
	v_mfma_f32_16x16x32_bf16 v[24:27], v[108:111], v[184:187], v[24:27]
	v_mfma_f32_16x16x32_bf16 v[12:15], v[88:91], v[218:221], v[12:15]
	v_mfma_f32_16x16x32_bf16 v[8:11], v[108:111], v[218:221], v[8:11]
	s_setprio 0
	s_setprio 1
	v_mfma_f32_16x16x32_bf16 v[52:55], v[124:127], v[156:159], 0
	v_mfma_f32_16x16x32_bf16 v[48:51], v[144:147], v[156:159], 0
	v_mfma_f32_16x16x32_bf16 v[36:39], v[124:127], v[172:175], 0
	v_mfma_f32_16x16x32_bf16 v[32:35], v[144:147], v[172:175], 0
	v_mfma_f32_16x16x32_bf16 v[20:23], v[124:127], v[180:183], 0
	v_mfma_f32_16x16x32_bf16 v[16:19], v[144:147], v[180:183], 0
	v_mfma_f32_16x16x32_bf16 v[4:7], v[124:127], v[188:191], 0
	v_mfma_f32_16x16x32_bf16 v[0:3], v[144:147], v[188:191], 0
	v_mfma_f32_16x16x32_bf16 v[52:55], v[128:131], v[168:171], v[52:55]
	v_mfma_f32_16x16x32_bf16 v[48:51], v[152:155], v[168:171], v[48:51]
	v_mfma_f32_16x16x32_bf16 v[36:39], v[128:131], v[176:179], v[36:39]
	v_mfma_f32_16x16x32_bf16 v[32:35], v[152:155], v[176:179], v[32:35]
	v_mfma_f32_16x16x32_bf16 v[20:23], v[128:131], v[184:187], v[20:23]
	v_mfma_f32_16x16x32_bf16 v[16:19], v[152:155], v[184:187], v[16:19]
	v_mfma_f32_16x16x32_bf16 v[4:7], v[128:131], v[218:221], v[4:7]
	s_barrier
	v_mfma_f32_16x16x32_bf16 v[0:3], v[152:155], v[218:221], v[0:3]
	s_setprio 0
	s_add_i32 s69, 0, 0x18000
	s_add_i32 s70, 0, 0x1c000
	v_add_u32_e32 v108, s69, v212
	v_add_u32_e32 v152, s70, v212
	ds_read_b128 v[76:79], v108
	ds_read_b128 v[88:91], v108 offset:1024
	ds_read_b128 v[100:103], v108 offset:2048
	ds_read_b128 v[108:111], v108 offset:3072
	ds_read_b128 v[124:127], v152
	ds_read_b128 v[128:131], v152 offset:1024
	ds_read_b128 v[144:147], v152 offset:2048
	ds_read_b128 v[152:155], v152 offset:3072
	s_add_u32 s20, s20, s24
	s_addc_u32 s21, s21, 0
	s_mov_b32 m0, s45
	v_lshl_add_u64 v[248:249], s[20:21], 0, v[198:199]
	ds_read_b128 v[156:159], v241 offset:32768
	ds_read_b128 v[168:171], v241 offset:33792
	ds_read_b128 v[172:175], v241 offset:34816
	ds_read_b128 v[176:179], v241 offset:35840
	ds_read_b128 v[180:183], v241 offset:36864
	ds_read_b128 v[184:187], v241 offset:37888
	ds_read_b128 v[188:191], v241 offset:38912
	ds_read_b128 v[218:221], v241 offset:39936
	global_load_lds_dwordx4 v[248:249], off
	v_lshl_add_u64 v[248:249], s[20:21], 0, v[194:195]
	s_mov_b32 m0, s46
	s_nop 0
	global_load_lds_dwordx4 v[248:249], off
	s_waitcnt vmcnt(8)
	s_waitcnt lgkmcnt(0)
	s_barrier
	s_setprio 1
	s_waitcnt lgkmcnt(0)
	v_mfma_f32_16x16x32_bf16 v[164:167], v[76:79], v[156:159], v[164:167]
	v_mfma_f32_16x16x32_bf16 v[160:163], v[100:103], v[156:159], v[160:163]
	v_mfma_f32_16x16x32_bf16 v[136:139], v[76:79], v[172:175], v[136:139]
	v_mfma_f32_16x16x32_bf16 v[132:135], v[100:103], v[172:175], v[132:135]
	v_mfma_f32_16x16x32_bf16 v[112:115], v[76:79], v[180:183], v[112:115]
	v_mfma_f32_16x16x32_bf16 v[104:107], v[100:103], v[180:183], v[104:107]
	v_mfma_f32_16x16x32_bf16 v[84:87], v[76:79], v[188:191], v[84:87]
	v_mfma_f32_16x16x32_bf16 v[80:83], v[100:103], v[188:191], v[80:83]
	v_mfma_f32_16x16x32_bf16 v[164:167], v[88:91], v[168:171], v[164:167]
	v_mfma_f32_16x16x32_bf16 v[160:163], v[108:111], v[168:171], v[160:163]
	v_mfma_f32_16x16x32_bf16 v[136:139], v[88:91], v[176:179], v[136:139]
	v_mfma_f32_16x16x32_bf16 v[132:135], v[108:111], v[176:179], v[132:135]
	v_mfma_f32_16x16x32_bf16 v[112:115], v[88:91], v[184:187], v[112:115]
	v_mfma_f32_16x16x32_bf16 v[104:107], v[108:111], v[184:187], v[104:107]
	v_mfma_f32_16x16x32_bf16 v[84:87], v[88:91], v[218:221], v[84:87]
	v_mfma_f32_16x16x32_bf16 v[80:83], v[108:111], v[218:221], v[80:83]
	s_setprio 0
	s_setprio 1
	v_mfma_f32_16x16x32_bf16 v[148:151], v[124:127], v[156:159], v[148:151]
	v_mfma_f32_16x16x32_bf16 v[140:143], v[144:147], v[156:159], v[140:143]
	v_mfma_f32_16x16x32_bf16 v[120:123], v[124:127], v[172:175], v[120:123]
	v_mfma_f32_16x16x32_bf16 v[116:119], v[144:147], v[172:175], v[116:119]
	v_mfma_f32_16x16x32_bf16 v[96:99], v[124:127], v[180:183], v[96:99]
	v_mfma_f32_16x16x32_bf16 v[92:95], v[144:147], v[180:183], v[92:95]
	v_mfma_f32_16x16x32_bf16 v[72:75], v[124:127], v[188:191], v[72:75]
	v_mfma_f32_16x16x32_bf16 v[68:71], v[144:147], v[188:191], v[68:71]
	v_mfma_f32_16x16x32_bf16 v[148:151], v[128:131], v[168:171], v[148:151]
	v_mfma_f32_16x16x32_bf16 v[140:143], v[152:155], v[168:171], v[140:143]
	v_mfma_f32_16x16x32_bf16 v[120:123], v[128:131], v[176:179], v[120:123]
	v_mfma_f32_16x16x32_bf16 v[116:119], v[152:155], v[176:179], v[116:119]
	v_mfma_f32_16x16x32_bf16 v[96:99], v[128:131], v[184:187], v[96:99]
	v_mfma_f32_16x16x32_bf16 v[92:95], v[152:155], v[184:187], v[92:95]
	v_mfma_f32_16x16x32_bf16 v[72:75], v[128:131], v[218:221], v[72:75]
	s_barrier
;     __device__ __forceinline__ const char* tile(const Unit& u, int t) const { return A + (size_t)u.pm * 2 * hstep() + (size_t)t * (BK * 2); }
;     __device__ __forceinline__ const char* tile(const Unit& u, int t) const { return U + (long)(t >> 2) * xoff + (size_t)u.pn * (1024 * 512) + (size_t)u.pm * 2 * hstep() + (size_t)(t & 3) * (BK * 2); }
; #define PG8_STAGE(bufoff, gbase, voff) do { _Pragma("unroll") for (int _i = 0; _i < 2; ++_i) \
;         __builtin_amdgcn_global_load_lds((const unsigned*)((const char*)(gbase) + (voff)[_i]), (PG8_LAS unsigned*)(lds + (bufoff) + ldsw + _i * 8192), 16, 0, 0); } while (0)
; #define PG8_LDA(dst, b, h) do { _Pragma("unroll") for (int m = 0; m < 4; ++m) _Pragma("unroll") for (int k = 0; k < 2; ++k) dst[m][k] = *(const PG8_LAS bf16x8*)(lds + PG8_SA(b, h) + aoff + m * 2048 + k * 1024); } while (0)
; #define PG8_WAIT_V(n) asm volatile("s_waitcnt vmcnt(" #n ")" ::: "memory")
; #define PG8_BAR __builtin_amdgcn_s_barrier()
;     ...
;         for (int t = 0; t < nt; t += 2) {
;             const bool last = (t == nt - 2);
;             const char* a1 = AS.tile(cur, t + 1);
;             const char* a2 = last ? AS.tile(nu, 0) : AS.tile(cur, t + 2); const char* b2 = last ? nB : cB + (size_t)(t + 2) * kstep;
;             const char* a3 = last ? AS.tile(nu, 1) : AS.tile(cur, t + 3); const char* b3 = b2 + kstep;
;             PG8_LDB(B0, 0, 0); PG8_LDB(B1, 0, 1); PG8_SCHED; PG8_LDA(At, 0, 0); PG8_STAGE(PG8_SA(1, 1), a1 + hstepA, voffA);
;             PG8_WAIT_V(8); PG8_WAIT_L(0); PG8_BAR; PG8_MMA(0, 0, At, B0); PG8_MMA(0, 1, At, B1); PG8_BAR; PG8_SCHED;
;             PG8_LDA(At, 0, 1); PG8_STAGE(PG8_SB(0, 0), b2, voffB); PG8_STAGE(PG8_SB(0, 1), b2 + hstepB, voffB); PG8_STAGE(PG8_SA(0, 0), a2, voffA);
;             PG8_WAIT_V(8); PG8_WAIT_L(0); PG8_BAR; PG8_MMA(1, 0, At, B0); PG8_MMA(1, 1, At, B1); PG8_BAR; PG8_SCHED;
;             PG8_LDB(B0, 1, 0); PG8_LDB(B1, 1, 1); PG8_SCHED; PG8_LDA(At, 1, 0); PG8_STAGE(PG8_SA(0, 1), a2 + hstepA, voffA);
;             PG8_WAIT_V(8); PG8_WAIT_L(0); PG8_BAR; PG8_MMA(0, 0, At, B0); PG8_MMA(0, 1, At, B1); PG8_BAR; PG8_SCHED;
;             PG8_LDA(At, 1, 1); PG8_STAGE(PG8_SB(1, 0), b3, voffB); PG8_STAGE(PG8_SB(1, 1), b3 + hstepB, voffB); PG8_STAGE(PG8_SA(1, 0), a3, voffA);
;             PG8_WAIT_V(8); PG8_WAIT_L(0); PG8_BAR; PG8_MMA(1, 0, At, B0); PG8_MMA(1, 1, At, B1); PG8_BAR; PG8_SCHED;
	v_mfma_f32_16x16x32_bf16 v[68:71], v[152:155], v[218:221], v[68:71]
	s_setprio 0
	s_add_i32 s20, s69, s25
	v_lshl_add_u64 v[222:223], v[222:223], 0, s[76:77]
	s_mov_b32 m0, s20
	ds_read_b128 v[156:159], v241 offset:49152
	ds_read_b128 v[168:171], v241 offset:50176
	ds_read_b128 v[172:175], v241 offset:51200
	ds_read_b128 v[176:179], v241 offset:52224
	ds_read_b128 v[180:183], v241 offset:53248
	ds_read_b128 v[184:187], v241 offset:54272
	ds_read_b128 v[188:191], v241 offset:55296
	ds_read_b128 v[218:221], v241 offset:56320
	global_load_lds_dwordx4 v[222:223], off
	v_lshl_add_u64 v[222:223], v[224:225], 0, s[76:77]
	s_add_i32 m0, s20, 0x2000
	s_add_i32 s20, s70, s25
	global_load_lds_dwordx4 v[222:223], off
	v_lshl_add_u64 v[222:223], v[244:245], 0, s[76:77]
	s_mov_b32 m0, s20
	s_nop 0
	global_load_lds_dwordx4 v[222:223], off
	v_lshl_add_u64 v[222:223], v[246:247], 0, s[76:77]
	s_add_i32 m0, s20, 0x2000
	s_nop 0
	global_load_lds_dwordx4 v[222:223], off
	v_lshl_add_u64 v[222:223], s[2:3], 0, v[198:199]
	s_mov_b32 m0, s47
	s_nop 0
	global_load_lds_dwordx4 v[222:223], off
	v_lshl_add_u64 v[222:223], s[2:3], 0, v[194:195]
	s_mov_b32 m0, s48
	s_nop 0
	global_load_lds_dwordx4 v[222:223], off
	s_waitcnt vmcnt(8)
	s_waitcnt lgkmcnt(0)
	s_barrier
	s_setprio 1
	s_waitcnt lgkmcnt(0)
	v_mfma_f32_16x16x32_bf16 v[60:63], v[76:79], v[156:159], v[60:63]
	v_mfma_f32_16x16x32_bf16 v[56:59], v[100:103], v[156:159], v[56:59]
	v_mfma_f32_16x16x32_bf16 v[44:47], v[76:79], v[172:175], v[44:47]
	v_mfma_f32_16x16x32_bf16 v[40:43], v[100:103], v[172:175], v[40:43]
	v_mfma_f32_16x16x32_bf16 v[28:31], v[76:79], v[180:183], v[28:31]
	v_mfma_f32_16x16x32_bf16 v[24:27], v[100:103], v[180:183], v[24:27]
	v_mfma_f32_16x16x32_bf16 v[12:15], v[76:79], v[188:191], v[12:15]
	v_mfma_f32_16x16x32_bf16 v[8:11], v[100:103], v[188:191], v[8:11]
	v_mfma_f32_16x16x32_bf16 v[60:63], v[88:91], v[168:171], v[60:63]
	v_mfma_f32_16x16x32_bf16 v[56:59], v[108:111], v[168:171], v[56:59]
	v_mfma_f32_16x16x32_bf16 v[44:47], v[88:91], v[176:179], v[44:47]
	v_mfma_f32_16x16x32_bf16 v[40:43], v[108:111], v[176:179], v[40:43]
	v_mfma_f32_16x16x32_bf16 v[28:31], v[88:91], v[184:187], v[28:31]
	v_mfma_f32_16x16x32_bf16 v[24:27], v[108:111], v[184:187], v[24:27]
	v_mfma_f32_16x16x32_bf16 v[12:15], v[88:91], v[218:221], v[12:15]
	v_mfma_f32_16x16x32_bf16 v[8:11], v[108:111], v[218:221], v[8:11]
	s_setprio 0
	s_setprio 1
	v_mfma_f32_16x16x32_bf16 v[52:55], v[124:127], v[156:159], v[52:55]
	v_mfma_f32_16x16x32_bf16 v[48:51], v[144:147], v[156:159], v[48:51]
	v_mfma_f32_16x16x32_bf16 v[36:39], v[124:127], v[172:175], v[36:39]
	v_mfma_f32_16x16x32_bf16 v[32:35], v[144:147], v[172:175], v[32:35]
	v_mfma_f32_16x16x32_bf16 v[20:23], v[124:127], v[180:183], v[20:23]
	v_mfma_f32_16x16x32_bf16 v[16:19], v[144:147], v[180:183], v[16:19]
	v_mfma_f32_16x16x32_bf16 v[4:7], v[124:127], v[188:191], v[4:7]
	v_mfma_f32_16x16x32_bf16 v[0:3], v[144:147], v[188:191], v[0:3]
	v_mfma_f32_16x16x32_bf16 v[52:55], v[128:131], v[168:171], v[52:55]
	v_mfma_f32_16x16x32_bf16 v[48:51], v[152:155], v[168:171], v[48:51]
	v_mfma_f32_16x16x32_bf16 v[36:39], v[128:131], v[176:179], v[36:39]
	v_mfma_f32_16x16x32_bf16 v[32:35], v[152:155], v[176:179], v[32:35]
	v_mfma_f32_16x16x32_bf16 v[20:23], v[128:131], v[184:187], v[20:23]
	v_mfma_f32_16x16x32_bf16 v[16:19], v[152:155], v[184:187], v[16:19]
	v_mfma_f32_16x16x32_bf16 v[4:7], v[128:131], v[218:221], v[4:7]
	s_barrier
	v_mfma_f32_16x16x32_bf16 v[0:3], v[152:155], v[218:221], v[0:3]
	s_setprio 0
	s_add_u32 s64, s64, 0x100
	s_addc_u32 s65, s65, 0
	s_add_u32 s66, s66, 0x100
	s_addc_u32 s67, s67, 0
	v_lshl_add_u64 v[64:65], v[64:65], 0, s[78:79]
	v_lshl_add_u64 v[66:67], v[66:67], 0, s[78:79]
	s_cmp_ge_u32 s68, s50
	s_mov_b32 s2, s68
	s_cbranch_scc0 .LBB0_534
	s_branch .Lpeel_exit_534
.LBB0_534:
	s_add_i32 s68, s2, 2
	s_add_u32 s3, s82, s64
	s_addc_u32 s20, s83, s65
	s_add_u32 s69, s3, 0x100
	s_addc_u32 s21, s20, 0
	s_add_u32 s70, s82, s66
	s_addc_u32 s71, s83, s67
	s_add_u32 s72, s3, 0x180
	s_addc_u32 s3, s20, 0
	s_add_i32 s73, 0, 0x10000
	s_add_i32 s74, 0, 0x14000
	v_add_u32_e32 v108, s73, v212
	v_add_u32_e32 v152, s74, v212
	ds_read_b128 v[76:79], v108
	ds_read_b128 v[88:91], v108 offset:1024
	ds_read_b128 v[100:103], v108 offset:2048
	ds_read_b128 v[108:111], v108 offset:3072
	ds_read_b128 v[124:127], v152
	ds_read_b128 v[128:131], v152 offset:1024
	ds_read_b128 v[144:147], v152 offset:2048
	ds_read_b128 v[152:155], v152 offset:3072
	s_cmp_eq_u32 s51, s2
	s_cselect_b32 s2, s60, s72
	s_cselect_b32 s3, s61, s3
	s_cselect_b32 s71, s41, s71
	s_cselect_b32 s70, s40, s70
	s_cselect_b32 s21, s59, s21
	s_cselect_b32 s20, s1, s69
	v_lshl_add_u64 v[222:223], s[82:83], 0, v[64:65]
	s_add_i32 m0, s35, 0xc000
	ds_read_b128 v[156:159], v241
	ds_read_b128 v[168:171], v241 offset:1024
	ds_read_b128 v[172:175], v241 offset:2048
	ds_read_b128 v[176:179], v241 offset:3072
	ds_read_b128 v[180:183], v241 offset:4096
	ds_read_b128 v[184:187], v241 offset:5120
	ds_read_b128 v[188:191], v241 offset:6144
	ds_read_b128 v[218:221], v241 offset:7168
	global_load_lds_dwordx4 v[222:223], off
	v_lshl_add_u64 v[222:223], s[82:83], 0, v[66:67]
	s_add_i32 m0, s35, 0xe000
	s_nop 0
	global_load_lds_dwordx4 v[222:223], off
	s_waitcnt vmcnt(8)
	s_waitcnt lgkmcnt(0)
	s_barrier
; #define PG8_STAGE(bufoff, gbase, voff) do { _Pragma("unroll") for (int _i = 0; _i < 2; ++_i) \
;         __builtin_amdgcn_global_load_lds((const unsigned*)((const char*)(gbase) + (voff)[_i]), (PG8_LAS unsigned*)(lds + (bufoff) + ldsw + _i * 8192), 16, 0, 0); } while (0)
; #define PG8_LDA(dst, b, h) do { _Pragma("unroll") for (int m = 0; m < 4; ++m) _Pragma("unroll") for (int k = 0; k < 2; ++k) dst[m][k] = *(const PG8_LAS bf16x8*)(lds + PG8_SA(b, h) + aoff + m * 2048 + k * 1024); } while (0)
; #define PG8_LDB(dst, b, h) do { _Pragma("unroll") for (int n = 0; n < 2; ++n) _Pragma("unroll") for (int k = 0; k < 2; ++k) dst[n][k] = *(const PG8_LAS bf16x8*)(lds + PG8_SB(b, h) + boff + n * 2048 + k * 1024); } while (0)
; #define PG8_MMA(ai, bj, At, Bt) do { __builtin_amdgcn_s_setprio(1); _Pragma("unroll") for (int m = 0; m < 4; ++m) _Pragma("unroll") for (int n = 0; n < 2; ++n) _Pragma("unroll") for (int k = 0; k < 2; ++k) \
;         acc[ai][bj][m][n] = __builtin_amdgcn_mfma_f32_16x16x32_bf16(Bt[n][k], At[m][k], acc[ai][bj][m][n], 0, 0, 0); __builtin_amdgcn_s_setprio(0); } while (0)
; #define PG8_WAIT_V(n) asm volatile("s_waitcnt vmcnt(" #n ")" ::: "memory")
; #define PG8_WAIT_L(n) asm volatile("s_waitcnt lgkmcnt(" #n ")" ::: "memory")
; #define PG8_BAR __builtin_amdgcn_s_barrier()
; #define PG8_SCHED __builtin_amdgcn_sched_barrier(0)
;     ...
;             PG8_LDB(B0, 0, 0); PG8_LDB(B1, 0, 1); PG8_SCHED; PG8_LDA(At, 0, 0); PG8_STAGE(PG8_SA(1, 1), a1 + hstepA, voffA);
;             PG8_WAIT_V(8); PG8_WAIT_L(0); PG8_BAR; PG8_MMA(0, 0, At, B0); PG8_MMA(0, 1, At, B1); PG8_BAR; PG8_SCHED;
;             PG8_LDA(At, 0, 1); PG8_STAGE(PG8_SB(0, 0), b2, voffB); PG8_STAGE(PG8_SB(0, 1), b2 + hstepB, voffB); PG8_STAGE(PG8_SA(0, 0), a2, voffA);
;             PG8_WAIT_V(8); PG8_WAIT_L(0); PG8_BAR; PG8_MMA(1, 0, At, B0); PG8_MMA(1, 1, At, B1); PG8_BAR; PG8_SCHED;
;             PG8_LDB(B0, 1, 0); PG8_LDB(B1, 1, 1); PG8_SCHED; PG8_LDA(At, 1, 0); PG8_STAGE(PG8_SA(0, 1), a2 + hstepA, voffA);
;             PG8_WAIT_V(8); PG8_WAIT_L(0); PG8_BAR; PG8_MMA(0, 0, At, B0); PG8_MMA(0, 1, At, B1); PG8_BAR; PG8_SCHED;
;             PG8_LDA(At, 1, 1); PG8_STAGE(PG8_SB(1, 0), b3, voffB); PG8_STAGE(PG8_SB(1, 1), b3 + hstepB, voffB); PG8_STAGE(PG8_SA(1, 0), a3, voffA);
;             PG8_WAIT_V(8); PG8_WAIT_L(0); PG8_BAR; PG8_MMA(1, 0, At, B0); PG8_MMA(1, 1, At, B1); PG8_BAR; PG8_SCHED;
	s_setprio 1
	s_waitcnt lgkmcnt(0)
	v_mfma_f32_16x16x32_bf16 v[164:167], v[76:79], v[156:159], v[164:167]
	v_mfma_f32_16x16x32_bf16 v[160:163], v[100:103], v[156:159], v[160:163]
	v_mfma_f32_16x16x32_bf16 v[136:139], v[76:79], v[172:175], v[136:139]
	v_mfma_f32_16x16x32_bf16 v[132:135], v[100:103], v[172:175], v[132:135]
	v_mfma_f32_16x16x32_bf16 v[112:115], v[76:79], v[180:183], v[112:115]
	v_mfma_f32_16x16x32_bf16 v[104:107], v[100:103], v[180:183], v[104:107]
	v_mfma_f32_16x16x32_bf16 v[84:87], v[76:79], v[188:191], v[84:87]
	v_mfma_f32_16x16x32_bf16 v[80:83], v[100:103], v[188:191], v[80:83]
	v_mfma_f32_16x16x32_bf16 v[164:167], v[88:91], v[168:171], v[164:167]
	v_mfma_f32_16x16x32_bf16 v[160:163], v[108:111], v[168:171], v[160:163]
	v_mfma_f32_16x16x32_bf16 v[136:139], v[88:91], v[176:179], v[136:139]
	v_mfma_f32_16x16x32_bf16 v[132:135], v[108:111], v[176:179], v[132:135]
	v_mfma_f32_16x16x32_bf16 v[112:115], v[88:91], v[184:187], v[112:115]
	v_mfma_f32_16x16x32_bf16 v[104:107], v[108:111], v[184:187], v[104:107]
	v_mfma_f32_16x16x32_bf16 v[84:87], v[88:91], v[218:221], v[84:87]
	v_mfma_f32_16x16x32_bf16 v[80:83], v[108:111], v[218:221], v[80:83]
	s_setprio 0
	s_setprio 1
	v_mfma_f32_16x16x32_bf16 v[148:151], v[124:127], v[156:159], v[148:151]
	v_mfma_f32_16x16x32_bf16 v[140:143], v[144:147], v[156:159], v[140:143]
	v_mfma_f32_16x16x32_bf16 v[120:123], v[124:127], v[172:175], v[120:123]
	v_mfma_f32_16x16x32_bf16 v[116:119], v[144:147], v[172:175], v[116:119]
	v_mfma_f32_16x16x32_bf16 v[96:99], v[124:127], v[180:183], v[96:99]
	v_mfma_f32_16x16x32_bf16 v[92:95], v[144:147], v[180:183], v[92:95]
	v_mfma_f32_16x16x32_bf16 v[72:75], v[124:127], v[188:191], v[72:75]
	v_mfma_f32_16x16x32_bf16 v[68:71], v[144:147], v[188:191], v[68:71]
	v_mfma_f32_16x16x32_bf16 v[148:151], v[128:131], v[168:171], v[148:151]
	v_mfma_f32_16x16x32_bf16 v[140:143], v[152:155], v[168:171], v[140:143]
	v_mfma_f32_16x16x32_bf16 v[120:123], v[128:131], v[176:179], v[120:123]
	v_mfma_f32_16x16x32_bf16 v[116:119], v[152:155], v[176:179], v[116:119]
	v_mfma_f32_16x16x32_bf16 v[96:99], v[128:131], v[184:187], v[96:99]
	v_mfma_f32_16x16x32_bf16 v[92:95], v[152:155], v[184:187], v[92:95]
	v_mfma_f32_16x16x32_bf16 v[72:75], v[128:131], v[218:221], v[72:75]
	s_barrier
	v_mfma_f32_16x16x32_bf16 v[68:71], v[152:155], v[218:221], v[68:71]
	s_setprio 0
	s_add_i32 s69, s73, s25
	v_lshl_add_u64 v[222:223], s[70:71], 0, v[196:197]
	s_mov_b32 m0, s69
	ds_read_b128 v[156:159], v241 offset:16384
	ds_read_b128 v[168:171], v241 offset:17408
	ds_read_b128 v[172:175], v241 offset:18432
	ds_read_b128 v[176:179], v241 offset:19456
	ds_read_b128 v[180:183], v241 offset:20480
	ds_read_b128 v[184:187], v241 offset:21504
	ds_read_b128 v[188:191], v241 offset:22528
	ds_read_b128 v[218:221], v241 offset:23552
	global_load_lds_dwordx4 v[222:223], off
	s_add_i32 m0, s69, 0x2000
	v_lshl_add_u64 v[224:225], s[70:71], 0, v[192:193]
	s_add_u32 s70, s70, s24
	s_addc_u32 s71, s71, 0
	s_add_i32 s69, s74, s25
	global_load_lds_dwordx4 v[224:225], off
	v_lshl_add_u64 v[244:245], s[70:71], 0, v[196:197]
	s_mov_b32 m0, s69
	v_lshl_add_u64 v[246:247], s[70:71], 0, v[192:193]
	global_load_lds_dwordx4 v[244:245], off
	s_add_i32 m0, s69, 0x2000
	v_lshl_add_u64 v[248:249], s[20:21], 0, v[198:199]
	global_load_lds_dwordx4 v[246:247], off
	s_mov_b32 m0, s35
	s_nop 0
	global_load_lds_dwordx4 v[248:249], off
	v_lshl_add_u64 v[248:249], s[20:21], 0, v[194:195]
	s_mov_b32 m0, s44
	s_nop 0
	global_load_lds_dwordx4 v[248:249], off
	s_waitcnt vmcnt(8)
	s_waitcnt lgkmcnt(0)
	s_barrier
	s_setprio 1
	s_waitcnt lgkmcnt(0)
	v_mfma_f32_16x16x32_bf16 v[60:63], v[76:79], v[156:159], v[60:63]
	v_mfma_f32_16x16x32_bf16 v[56:59], v[100:103], v[156:159], v[56:59]
	v_mfma_f32_16x16x32_bf16 v[44:47], v[76:79], v[172:175], v[44:47]
	v_mfma_f32_16x16x32_bf16 v[40:43], v[100:103], v[172:175], v[40:43]
	v_mfma_f32_16x16x32_bf16 v[28:31], v[76:79], v[180:183], v[28:31]
	v_mfma_f32_16x16x32_bf16 v[24:27], v[100:103], v[180:183], v[24:27]
	v_mfma_f32_16x16x32_bf16 v[12:15], v[76:79], v[188:191], v[12:15]
	v_mfma_f32_16x16x32_bf16 v[8:11], v[100:103], v[188:191], v[8:11]
	v_mfma_f32_16x16x32_bf16 v[60:63], v[88:91], v[168:171], v[60:63]
	v_mfma_f32_16x16x32_bf16 v[56:59], v[108:111], v[168:171], v[56:59]
	v_mfma_f32_16x16x32_bf16 v[44:47], v[88:91], v[176:179], v[44:47]
	v_mfma_f32_16x16x32_bf16 v[40:43], v[108:111], v[176:179], v[40:43]
	v_mfma_f32_16x16x32_bf16 v[28:31], v[88:91], v[184:187], v[28:31]
	v_mfma_f32_16x16x32_bf16 v[24:27], v[108:111], v[184:187], v[24:27]
	v_mfma_f32_16x16x32_bf16 v[12:15], v[88:91], v[218:221], v[12:15]
	v_mfma_f32_16x16x32_bf16 v[8:11], v[108:111], v[218:221], v[8:11]
	s_setprio 0
	s_setprio 1
	v_mfma_f32_16x16x32_bf16 v[52:55], v[124:127], v[156:159], v[52:55]
	v_mfma_f32_16x16x32_bf16 v[48:51], v[144:147], v[156:159], v[48:51]
	v_mfma_f32_16x16x32_bf16 v[36:39], v[124:127], v[172:175], v[36:39]
	v_mfma_f32_16x16x32_bf16 v[32:35], v[144:147], v[172:175], v[32:35]
	v_mfma_f32_16x16x32_bf16 v[20:23], v[124:127], v[180:183], v[20:23]
	v_mfma_f32_16x16x32_bf16 v[16:19], v[144:147], v[180:183], v[16:19]
	v_mfma_f32_16x16x32_bf16 v[4:7], v[124:127], v[188:191], v[4:7]
	v_mfma_f32_16x16x32_bf16 v[0:3], v[144:147], v[188:191], v[0:3]
	v_mfma_f32_16x16x32_bf16 v[52:55], v[128:131], v[168:171], v[52:55]
	v_mfma_f32_16x16x32_bf16 v[48:51], v[152:155], v[168:171], v[48:51]
	v_mfma_f32_16x16x32_bf16 v[36:39], v[128:131], v[176:179], v[36:39]
	v_mfma_f32_16x16x32_bf16 v[32:35], v[152:155], v[176:179], v[32:35]
	v_mfma_f32_16x16x32_bf16 v[20:23], v[128:131], v[184:187], v[20:23]
	v_mfma_f32_16x16x32_bf16 v[16:19], v[152:155], v[184:187], v[16:19]
	v_mfma_f32_16x16x32_bf16 v[4:7], v[128:131], v[218:221], v[4:7]
	s_barrier
; #define PG8_STAGE(bufoff, gbase, voff) do { _Pragma("unroll") for (int _i = 0; _i < 2; ++_i) \
;         __builtin_amdgcn_global_load_lds((const unsigned*)((const char*)(gbase) + (voff)[_i]), (PG8_LAS unsigned*)(lds + (bufoff) + ldsw + _i * 8192), 16, 0, 0); } while (0)
; #define PG8_LDA(dst, b, h) do { _Pragma("unroll") for (int m = 0; m < 4; ++m) _Pragma("unroll") for (int k = 0; k < 2; ++k) dst[m][k] = *(const PG8_LAS bf16x8*)(lds + PG8_SA(b, h) + aoff + m * 2048 + k * 1024); } while (0)
; #define PG8_LDB(dst, b, h) do { _Pragma("unroll") for (int n = 0; n < 2; ++n) _Pragma("unroll") for (int k = 0; k < 2; ++k) dst[n][k] = *(const PG8_LAS bf16x8*)(lds + PG8_SB(b, h) + boff + n * 2048 + k * 1024); } while (0)
; #define PG8_MMA(ai, bj, At, Bt) do { __builtin_amdgcn_s_setprio(1); _Pragma("unroll") for (int m = 0; m < 4; ++m) _Pragma("unroll") for (int n = 0; n < 2; ++n) _Pragma("unroll") for (int k = 0; k < 2; ++k) \
;         acc[ai][bj][m][n] = __builtin_amdgcn_mfma_f32_16x16x32_bf16(Bt[n][k], At[m][k], acc[ai][bj][m][n], 0, 0, 0); __builtin_amdgcn_s_setprio(0); } while (0)
; #define PG8_WAIT_V(n) asm volatile("s_waitcnt vmcnt(" #n ")" ::: "memory")
; #define PG8_WAIT_L(n) asm volatile("s_waitcnt lgkmcnt(" #n ")" ::: "memory")
; #define PG8_BAR __builtin_amdgcn_s_barrier()
; #define PG8_SCHED __builtin_amdgcn_sched_barrier(0)
;     ...
;             PG8_LDB(B0, 0, 0); PG8_LDB(B1, 0, 1); PG8_SCHED; PG8_LDA(At, 0, 0); PG8_STAGE(PG8_SA(1, 1), a1 + hstepA, voffA);
;             PG8_WAIT_V(8); PG8_WAIT_L(0); PG8_BAR; PG8_MMA(0, 0, At, B0); PG8_MMA(0, 1, At, B1); PG8_BAR; PG8_SCHED;
;             PG8_LDA(At, 0, 1); PG8_STAGE(PG8_SB(0, 0), b2, voffB); PG8_STAGE(PG8_SB(0, 1), b2 + hstepB, voffB); PG8_STAGE(PG8_SA(0, 0), a2, voffA);
;             PG8_WAIT_V(8); PG8_WAIT_L(0); PG8_BAR; PG8_MMA(1, 0, At, B0); PG8_MMA(1, 1, At, B1); PG8_BAR; PG8_SCHED;
;             PG8_LDB(B0, 1, 0); PG8_LDB(B1, 1, 1); PG8_SCHED; PG8_LDA(At, 1, 0); PG8_STAGE(PG8_SA(0, 1), a2 + hstepA, voffA);
;             PG8_WAIT_V(8); PG8_WAIT_L(0); PG8_BAR; PG8_MMA(0, 0, At, B0); PG8_MMA(0, 1, At, B1); PG8_BAR; PG8_SCHED;
;             PG8_LDA(At, 1, 1); PG8_STAGE(PG8_SB(1, 0), b3, voffB); PG8_STAGE(PG8_SB(1, 1), b3 + hstepB, voffB); PG8_STAGE(PG8_SA(1, 0), a3, voffA);
;             PG8_WAIT_V(8); PG8_WAIT_L(0); PG8_BAR; PG8_MMA(1, 0, At, B0); PG8_MMA(1, 1, At, B1); PG8_BAR; PG8_SCHED;
	v_mfma_f32_16x16x32_bf16 v[0:3], v[152:155], v[218:221], v[0:3]
	s_setprio 0
	s_add_i32 s69, 0, 0x18000
	s_add_i32 s70, 0, 0x1c000
	v_add_u32_e32 v108, s69, v212
	v_add_u32_e32 v152, s70, v212
	ds_read_b128 v[76:79], v108
	ds_read_b128 v[88:91], v108 offset:1024
	ds_read_b128 v[100:103], v108 offset:2048
	ds_read_b128 v[108:111], v108 offset:3072
	ds_read_b128 v[124:127], v152
	ds_read_b128 v[128:131], v152 offset:1024
	ds_read_b128 v[144:147], v152 offset:2048
	ds_read_b128 v[152:155], v152 offset:3072
	s_add_u32 s20, s20, s24
	s_addc_u32 s21, s21, 0
	s_mov_b32 m0, s45
	v_lshl_add_u64 v[248:249], s[20:21], 0, v[198:199]
	ds_read_b128 v[156:159], v241 offset:32768
	ds_read_b128 v[168:171], v241 offset:33792
	ds_read_b128 v[172:175], v241 offset:34816
	ds_read_b128 v[176:179], v241 offset:35840
	ds_read_b128 v[180:183], v241 offset:36864
	ds_read_b128 v[184:187], v241 offset:37888
	ds_read_b128 v[188:191], v241 offset:38912
	ds_read_b128 v[218:221], v241 offset:39936
	global_load_lds_dwordx4 v[248:249], off
	v_lshl_add_u64 v[248:249], s[20:21], 0, v[194:195]
	s_mov_b32 m0, s46
	s_nop 0
	global_load_lds_dwordx4 v[248:249], off
	s_waitcnt vmcnt(8)
	s_waitcnt lgkmcnt(0)
	s_barrier
	s_setprio 1
	s_waitcnt lgkmcnt(0)
	v_mfma_f32_16x16x32_bf16 v[164:167], v[76:79], v[156:159], v[164:167]
	v_mfma_f32_16x16x32_bf16 v[160:163], v[100:103], v[156:159], v[160:163]
	v_mfma_f32_16x16x32_bf16 v[136:139], v[76:79], v[172:175], v[136:139]
	v_mfma_f32_16x16x32_bf16 v[132:135], v[100:103], v[172:175], v[132:135]
	v_mfma_f32_16x16x32_bf16 v[112:115], v[76:79], v[180:183], v[112:115]
	v_mfma_f32_16x16x32_bf16 v[104:107], v[100:103], v[180:183], v[104:107]
	v_mfma_f32_16x16x32_bf16 v[84:87], v[76:79], v[188:191], v[84:87]
	v_mfma_f32_16x16x32_bf16 v[80:83], v[100:103], v[188:191], v[80:83]
	v_mfma_f32_16x16x32_bf16 v[164:167], v[88:91], v[168:171], v[164:167]
	v_mfma_f32_16x16x32_bf16 v[160:163], v[108:111], v[168:171], v[160:163]
	v_mfma_f32_16x16x32_bf16 v[136:139], v[88:91], v[176:179], v[136:139]
	v_mfma_f32_16x16x32_bf16 v[132:135], v[108:111], v[176:179], v[132:135]
	v_mfma_f32_16x16x32_bf16 v[112:115], v[88:91], v[184:187], v[112:115]
	v_mfma_f32_16x16x32_bf16 v[104:107], v[108:111], v[184:187], v[104:107]
	v_mfma_f32_16x16x32_bf16 v[84:87], v[88:91], v[218:221], v[84:87]
	v_mfma_f32_16x16x32_bf16 v[80:83], v[108:111], v[218:221], v[80:83]
	s_setprio 0
	s_setprio 1
	v_mfma_f32_16x16x32_bf16 v[148:151], v[124:127], v[156:159], v[148:151]
	v_mfma_f32_16x16x32_bf16 v[140:143], v[144:147], v[156:159], v[140:143]
	v_mfma_f32_16x16x32_bf16 v[120:123], v[124:127], v[172:175], v[120:123]
	v_mfma_f32_16x16x32_bf16 v[116:119], v[144:147], v[172:175], v[116:119]
	v_mfma_f32_16x16x32_bf16 v[96:99], v[124:127], v[180:183], v[96:99]
	v_mfma_f32_16x16x32_bf16 v[92:95], v[144:147], v[180:183], v[92:95]
	v_mfma_f32_16x16x32_bf16 v[72:75], v[124:127], v[188:191], v[72:75]
	v_mfma_f32_16x16x32_bf16 v[68:71], v[144:147], v[188:191], v[68:71]
	v_mfma_f32_16x16x32_bf16 v[148:151], v[128:131], v[168:171], v[148:151]
	v_mfma_f32_16x16x32_bf16 v[140:143], v[152:155], v[168:171], v[140:143]
	v_mfma_f32_16x16x32_bf16 v[120:123], v[128:131], v[176:179], v[120:123]
	v_mfma_f32_16x16x32_bf16 v[116:119], v[152:155], v[176:179], v[116:119]
	v_mfma_f32_16x16x32_bf16 v[96:99], v[128:131], v[184:187], v[96:99]
	v_mfma_f32_16x16x32_bf16 v[92:95], v[152:155], v[184:187], v[92:95]
	v_mfma_f32_16x16x32_bf16 v[72:75], v[128:131], v[218:221], v[72:75]
	s_barrier
; #define PG8_STAGE(bufoff, gbase, voff) do { _Pragma("unroll") for (int _i = 0; _i < 2; ++_i) \
;         __builtin_amdgcn_global_load_lds((const unsigned*)((const char*)(gbase) + (voff)[_i]), (PG8_LAS unsigned*)(lds + (bufoff) + ldsw + _i * 8192), 16, 0, 0); } while (0)
; #define PG8_LDA(dst, b, h) do { _Pragma("unroll") for (int m = 0; m < 4; ++m) _Pragma("unroll") for (int k = 0; k < 2; ++k) dst[m][k] = *(const PG8_LAS bf16x8*)(lds + PG8_SA(b, h) + aoff + m * 2048 + k * 1024); } while (0)
; #define PG8_LDB(dst, b, h) do { _Pragma("unroll") for (int n = 0; n < 2; ++n) _Pragma("unroll") for (int k = 0; k < 2; ++k) dst[n][k] = *(const PG8_LAS bf16x8*)(lds + PG8_SB(b, h) + boff + n * 2048 + k * 1024); } while (0)
; #define PG8_MMA(ai, bj, At, Bt) do { __builtin_amdgcn_s_setprio(1); _Pragma("unroll") for (int m = 0; m < 4; ++m) _Pragma("unroll") for (int n = 0; n < 2; ++n) _Pragma("unroll") for (int k = 0; k < 2; ++k) \
;         acc[ai][bj][m][n] = __builtin_amdgcn_mfma_f32_16x16x32_bf16(Bt[n][k], At[m][k], acc[ai][bj][m][n], 0, 0, 0); __builtin_amdgcn_s_setprio(0); } while (0)
; #define PG8_WAIT_V(n) asm volatile("s_waitcnt vmcnt(" #n ")" ::: "memory")
; #define PG8_WAIT_L(n) asm volatile("s_waitcnt lgkmcnt(" #n ")" ::: "memory")
; #define PG8_BAR __builtin_amdgcn_s_barrier()
; #define PG8_SCHED __builtin_amdgcn_sched_barrier(0)
;     ...
;             PG8_LDB(B0, 0, 0); PG8_LDB(B1, 0, 1); PG8_SCHED; PG8_LDA(At, 0, 0); PG8_STAGE(PG8_SA(1, 1), a1 + hstepA, voffA);
;             PG8_WAIT_V(8); PG8_WAIT_L(0); PG8_BAR; PG8_MMA(0, 0, At, B0); PG8_MMA(0, 1, At, B1); PG8_BAR; PG8_SCHED;
;             PG8_LDA(At, 0, 1); PG8_STAGE(PG8_SB(0, 0), b2, voffB); PG8_STAGE(PG8_SB(0, 1), b2 + hstepB, voffB); PG8_STAGE(PG8_SA(0, 0), a2, voffA);
;             PG8_WAIT_V(8); PG8_WAIT_L(0); PG8_BAR; PG8_MMA(1, 0, At, B0); PG8_MMA(1, 1, At, B1); PG8_BAR; PG8_SCHED;
;             PG8_LDB(B0, 1, 0); PG8_LDB(B1, 1, 1); PG8_SCHED; PG8_LDA(At, 1, 0); PG8_STAGE(PG8_SA(0, 1), a2 + hstepA, voffA);
;             PG8_WAIT_V(8); PG8_WAIT_L(0); PG8_BAR; PG8_MMA(0, 0, At, B0); PG8_MMA(0, 1, At, B1); PG8_BAR; PG8_SCHED;
;             PG8_LDA(At, 1, 1); PG8_STAGE(PG8_SB(1, 0), b3, voffB); PG8_STAGE(PG8_SB(1, 1), b3 + hstepB, voffB); PG8_STAGE(PG8_SA(1, 0), a3, voffA);
;             PG8_WAIT_V(8); PG8_WAIT_L(0); PG8_BAR; PG8_MMA(1, 0, At, B0); PG8_MMA(1, 1, At, B1); PG8_BAR; PG8_SCHED;
	v_mfma_f32_16x16x32_bf16 v[68:71], v[152:155], v[218:221], v[68:71]
	s_setprio 0
	s_add_i32 s20, s69, s25
	v_lshl_add_u64 v[222:223], v[222:223], 0, s[76:77]
	s_mov_b32 m0, s20
	ds_read_b128 v[156:159], v241 offset:49152
	ds_read_b128 v[168:171], v241 offset:50176
	ds_read_b128 v[172:175], v241 offset:51200
	ds_read_b128 v[176:179], v241 offset:52224
	ds_read_b128 v[180:183], v241 offset:53248
	ds_read_b128 v[184:187], v241 offset:54272
	ds_read_b128 v[188:191], v241 offset:55296
	ds_read_b128 v[218:221], v241 offset:56320
	global_load_lds_dwordx4 v[222:223], off
	v_lshl_add_u64 v[222:223], v[224:225], 0, s[76:77]
	s_add_i32 m0, s20, 0x2000
	s_add_i32 s20, s70, s25
	global_load_lds_dwordx4 v[222:223], off
	v_lshl_add_u64 v[222:223], v[244:245], 0, s[76:77]
	s_mov_b32 m0, s20
	s_nop 0
	global_load_lds_dwordx4 v[222:223], off
	v_lshl_add_u64 v[222:223], v[246:247], 0, s[76:77]
	s_add_i32 m0, s20, 0x2000
	s_nop 0
	global_load_lds_dwordx4 v[222:223], off
	v_lshl_add_u64 v[222:223], s[2:3], 0, v[198:199]
	s_mov_b32 m0, s47
	s_nop 0
	global_load_lds_dwordx4 v[222:223], off
	v_lshl_add_u64 v[222:223], s[2:3], 0, v[194:195]
	s_mov_b32 m0, s48
	s_nop 0
	global_load_lds_dwordx4 v[222:223], off
	s_waitcnt vmcnt(8)
	s_waitcnt lgkmcnt(0)
	s_barrier
	s_setprio 1
	s_waitcnt lgkmcnt(0)
	v_mfma_f32_16x16x32_bf16 v[60:63], v[76:79], v[156:159], v[60:63]
	v_mfma_f32_16x16x32_bf16 v[56:59], v[100:103], v[156:159], v[56:59]
	v_mfma_f32_16x16x32_bf16 v[44:47], v[76:79], v[172:175], v[44:47]
	v_mfma_f32_16x16x32_bf16 v[40:43], v[100:103], v[172:175], v[40:43]
	v_mfma_f32_16x16x32_bf16 v[28:31], v[76:79], v[180:183], v[28:31]
	v_mfma_f32_16x16x32_bf16 v[24:27], v[100:103], v[180:183], v[24:27]
	v_mfma_f32_16x16x32_bf16 v[12:15], v[76:79], v[188:191], v[12:15]
	v_mfma_f32_16x16x32_bf16 v[8:11], v[100:103], v[188:191], v[8:11]
	v_mfma_f32_16x16x32_bf16 v[60:63], v[88:91], v[168:171], v[60:63]
	v_mfma_f32_16x16x32_bf16 v[56:59], v[108:111], v[168:171], v[56:59]
	v_mfma_f32_16x16x32_bf16 v[44:47], v[88:91], v[176:179], v[44:47]
	v_mfma_f32_16x16x32_bf16 v[40:43], v[108:111], v[176:179], v[40:43]
	v_mfma_f32_16x16x32_bf16 v[28:31], v[88:91], v[184:187], v[28:31]
	v_mfma_f32_16x16x32_bf16 v[24:27], v[108:111], v[184:187], v[24:27]
	v_mfma_f32_16x16x32_bf16 v[12:15], v[88:91], v[218:221], v[12:15]
	v_mfma_f32_16x16x32_bf16 v[8:11], v[108:111], v[218:221], v[8:11]
	s_setprio 0
	s_setprio 1
	v_mfma_f32_16x16x32_bf16 v[52:55], v[124:127], v[156:159], v[52:55]
	v_mfma_f32_16x16x32_bf16 v[48:51], v[144:147], v[156:159], v[48:51]
	v_mfma_f32_16x16x32_bf16 v[36:39], v[124:127], v[172:175], v[36:39]
	v_mfma_f32_16x16x32_bf16 v[32:35], v[144:147], v[172:175], v[32:35]
	v_mfma_f32_16x16x32_bf16 v[20:23], v[124:127], v[180:183], v[20:23]
	v_mfma_f32_16x16x32_bf16 v[16:19], v[144:147], v[180:183], v[16:19]
	v_mfma_f32_16x16x32_bf16 v[4:7], v[124:127], v[188:191], v[4:7]
	v_mfma_f32_16x16x32_bf16 v[0:3], v[144:147], v[188:191], v[0:3]
	v_mfma_f32_16x16x32_bf16 v[52:55], v[128:131], v[168:171], v[52:55]
	v_mfma_f32_16x16x32_bf16 v[48:51], v[152:155], v[168:171], v[48:51]
	v_mfma_f32_16x16x32_bf16 v[36:39], v[128:131], v[176:179], v[36:39]
	v_mfma_f32_16x16x32_bf16 v[32:35], v[152:155], v[176:179], v[32:35]
	v_mfma_f32_16x16x32_bf16 v[20:23], v[128:131], v[184:187], v[20:23]
	v_mfma_f32_16x16x32_bf16 v[16:19], v[152:155], v[184:187], v[16:19]
	v_mfma_f32_16x16x32_bf16 v[4:7], v[128:131], v[218:221], v[4:7]
	s_barrier
	v_mfma_f32_16x16x32_bf16 v[0:3], v[152:155], v[218:221], v[0:3]
	s_setprio 0
	s_add_u32 s64, s64, 0x100
	s_addc_u32 s65, s65, 0
	s_add_u32 s66, s66, 0x100
	s_addc_u32 s67, s67, 0
	v_lshl_add_u64 v[64:65], v[64:65], 0, s[78:79]
	v_lshl_add_u64 v[66:67], v[66:67], 0, s[78:79]
	s_cmp_ge_u32 s68, s50
	s_mov_b32 s2, s68
	s_cbranch_scc0 .LBB0_534

; #define PG8_STAGE(bufoff, gbase, voff) do { _Pragma("unroll") for (int _i = 0; _i < 2; ++_i) \
;         __builtin_amdgcn_global_load_lds((const unsigned*)((const char*)(gbase) + (voff)[_i]), (PG8_LAS unsigned*)(lds + (bufoff) + ldsw + _i * 8192), 16, 0, 0); } while (0)
; #define PG8_LDA(dst, b, h) do { _Pragma("unroll") for (int m = 0; m < 4; ++m) _Pragma("unroll") for (int k = 0; k < 2; ++k) dst[m][k] = *(const PG8_LAS bf16x8*)(lds + PG8_SA(b, h) + aoff + m * 2048 + k * 1024); } while (0)
; #define PG8_LDB(dst, b, h) do { _Pragma("unroll") for (int n = 0; n < 2; ++n) _Pragma("unroll") for (int k = 0; k < 2; ++k) dst[n][k] = *(const PG8_LAS bf16x8*)(lds + PG8_SB(b, h) + boff + n * 2048 + k * 1024); } while (0)
; #define PG8_MMA(ai, bj, At, Bt) do { __builtin_amdgcn_s_setprio(1); _Pragma("unroll") for (int m = 0; m < 4; ++m) _Pragma("unroll") for (int n = 0; n < 2; ++n) _Pragma("unroll") for (int k = 0; k < 2; ++k) \
;         acc[ai][bj][m][n] = __builtin_amdgcn_mfma_f32_16x16x32_bf16(Bt[n][k], At[m][k], acc[ai][bj][m][n], 0, 0, 0); __builtin_amdgcn_s_setprio(0); } while (0)
; #define PG8_WAIT_V(n) asm volatile("s_waitcnt vmcnt(" #n ")" ::: "memory")
; #define PG8_WAIT_L(n) asm volatile("s_waitcnt lgkmcnt(" #n ")" ::: "memory")
; #define PG8_BAR __builtin_amdgcn_s_barrier()
; #define PG8_SCHED __builtin_amdgcn_sched_barrier(0)
;     ...
;             PG8_LDB(B0, 0, 0); PG8_LDB(B1, 0, 1); PG8_SCHED; PG8_LDA(At, 0, 0); PG8_STAGE(PG8_SA(1, 1), a1 + hstepA, voffA);
;             PG8_WAIT_V(8); PG8_WAIT_L(0); PG8_BAR; PG8_MMA(0, 0, At, B0); PG8_MMA(0, 1, At, B1); PG8_BAR; PG8_SCHED;
;             PG8_LDA(At, 0, 1); PG8_STAGE(PG8_SB(0, 0), b2, voffB); PG8_STAGE(PG8_SB(0, 1), b2 + hstepB, voffB); PG8_STAGE(PG8_SA(0, 0), a2, voffA);
;             PG8_WAIT_V(8); PG8_WAIT_L(0); PG8_BAR; PG8_MMA(1, 0, At, B0); PG8_MMA(1, 1, At, B1); PG8_BAR; PG8_SCHED;
;             PG8_LDB(B0, 1, 0); PG8_LDB(B1, 1, 1); PG8_SCHED; PG8_LDA(At, 1, 0); PG8_STAGE(PG8_SA(0, 1), a2 + hstepA, voffA);
;             PG8_WAIT_V(8); PG8_WAIT_L(0); PG8_BAR; PG8_MMA(0, 0, At, B0); PG8_MMA(0, 1, At, B1); PG8_BAR; PG8_SCHED;
;             PG8_LDA(At, 1, 1); PG8_STAGE(PG8_SB(1, 0), b3, voffB); PG8_STAGE(PG8_SB(1, 1), b3 + hstepB, voffB); PG8_STAGE(PG8_SA(1, 0), a3, voffA);
;             PG8_WAIT_V(8); PG8_WAIT_L(0); PG8_BAR; PG8_MMA(1, 0, At, B0); PG8_MMA(1, 1, At, B1); PG8_BAR; PG8_SCHED;
.Lpeel_702:
	s_add_u32 s20, s40, s2
	s_addc_u32 s21, s41, s3
	s_add_u32 s26, s20, 0x400100
	s_addc_u32 s27, s21, 0
	s_add_u32 s24, s42, s2
	s_addc_u32 s25, s43, s3
	s_add_u32 s20, s20, 0x400180
	s_addc_u32 s21, s21, 0
	s_add_i32 s63, 0, 0x10000
	s_add_i32 s66, 0, 0x14000
	v_add_u32_e32 v156, s63, v185
	v_add_u32_e32 v172, s66, v185
	ds_read_b128 v[132:135], v156
	ds_read_b128 v[136:139], v156 offset:1024
	ds_read_b128 v[140:143], v156 offset:2048
	ds_read_b128 v[156:159], v156 offset:3072
	ds_read_b128 v[160:163], v172
	ds_read_b128 v[164:167], v172 offset:1024
	ds_read_b128 v[168:171], v172 offset:2048
	ds_read_b128 v[172:175], v172 offset:3072
	s_cmpk_eq_i32 s2, 0x700
	s_cselect_b32 s21, s31, s21
	s_cselect_b32 s20, s30, s20
	s_cselect_b32 s25, s28, s25
	s_cselect_b32 s24, s1, s24
	s_cselect_b32 s27, s29, s27
	s_cselect_b32 s26, s19, s26
	v_lshl_add_u64 v[238:239], v[128:129], 0, s[2:3]
	s_add_i32 m0, s49, 0xc000
	ds_read_b128 v[176:179], v190
	ds_read_b128 v[180:183], v190 offset:1024
	ds_read_b128 v[192:195], v190 offset:2048
	ds_read_b128 v[196:199], v190 offset:3072
	ds_read_b128 v[200:203], v190 offset:4096
	ds_read_b128 v[204:207], v190 offset:5120
	ds_read_b128 v[218:221], v190 offset:6144
	ds_read_b128 v[222:225], v190 offset:7168
	global_load_lds_dwordx4 v[238:239], off
	v_lshl_add_u64 v[238:239], v[130:131], 0, s[2:3]
	s_add_i32 m0, s49, 0xe000
	s_nop 0
	global_load_lds_dwordx4 v[238:239], off
	s_waitcnt vmcnt(24)
	s_waitcnt lgkmcnt(0)
	s_barrier
	s_setprio 1
	s_waitcnt lgkmcnt(0)
	v_mfma_f32_16x16x32_bf16 v[124:127], v[132:135], v[176:179], 0
	v_mfma_f32_16x16x32_bf16 v[120:123], v[140:143], v[176:179], 0
	v_mfma_f32_16x16x32_bf16 v[112:115], v[132:135], v[192:195], 0
	v_mfma_f32_16x16x32_bf16 v[104:107], v[140:143], v[192:195], 0
	v_mfma_f32_16x16x32_bf16 v[96:99], v[132:135], v[200:203], 0
	v_mfma_f32_16x16x32_bf16 v[88:91], v[140:143], v[200:203], 0
	v_mfma_f32_16x16x32_bf16 v[80:83], v[132:135], v[218:221], 0
	v_mfma_f32_16x16x32_bf16 v[72:75], v[140:143], v[218:221], 0
	v_mfma_f32_16x16x32_bf16 v[124:127], v[136:139], v[180:183], v[124:127]
	v_mfma_f32_16x16x32_bf16 v[120:123], v[156:159], v[180:183], v[120:123]
	v_mfma_f32_16x16x32_bf16 v[112:115], v[136:139], v[196:199], v[112:115]
	v_mfma_f32_16x16x32_bf16 v[104:107], v[156:159], v[196:199], v[104:107]
	v_mfma_f32_16x16x32_bf16 v[96:99], v[136:139], v[204:207], v[96:99]
	v_mfma_f32_16x16x32_bf16 v[88:91], v[156:159], v[204:207], v[88:91]
	v_mfma_f32_16x16x32_bf16 v[80:83], v[136:139], v[222:225], v[80:83]
	v_mfma_f32_16x16x32_bf16 v[72:75], v[156:159], v[222:225], v[72:75]
	s_setprio 0
	s_setprio 1
	v_mfma_f32_16x16x32_bf16 v[116:119], v[160:163], v[176:179], 0
	v_mfma_f32_16x16x32_bf16 v[108:111], v[168:171], v[176:179], 0
	v_mfma_f32_16x16x32_bf16 v[100:103], v[160:163], v[192:195], 0
	v_mfma_f32_16x16x32_bf16 v[92:95], v[168:171], v[192:195], 0
	v_mfma_f32_16x16x32_bf16 v[84:87], v[160:163], v[200:203], 0
	v_mfma_f32_16x16x32_bf16 v[76:79], v[168:171], v[200:203], 0
	v_mfma_f32_16x16x32_bf16 v[68:71], v[160:163], v[218:221], 0
	v_mfma_f32_16x16x32_bf16 v[64:67], v[168:171], v[218:221], 0
	v_mfma_f32_16x16x32_bf16 v[116:119], v[164:167], v[180:183], v[116:119]
	v_mfma_f32_16x16x32_bf16 v[108:111], v[172:175], v[180:183], v[108:111]
	v_mfma_f32_16x16x32_bf16 v[100:103], v[164:167], v[196:199], v[100:103]
	v_mfma_f32_16x16x32_bf16 v[92:95], v[172:175], v[196:199], v[92:95]
	v_mfma_f32_16x16x32_bf16 v[84:87], v[164:167], v[204:207], v[84:87]
	v_mfma_f32_16x16x32_bf16 v[76:79], v[172:175], v[204:207], v[76:79]
	v_mfma_f32_16x16x32_bf16 v[68:71], v[164:167], v[222:225], v[68:71]
	s_barrier
	v_mfma_f32_16x16x32_bf16 v[64:67], v[172:175], v[222:225], v[64:67]
	s_setprio 0
	s_add_i32 s63, s63, s48
	v_lshl_add_u64 v[238:239], s[24:25], 0, v[148:149]
	s_mov_b32 m0, s63
	ds_read_b128 v[176:179], v190 offset:16384
	ds_read_b128 v[180:183], v190 offset:17408
	ds_read_b128 v[192:195], v190 offset:18432
	ds_read_b128 v[196:199], v190 offset:19456
	ds_read_b128 v[200:203], v190 offset:20480
	ds_read_b128 v[204:207], v190 offset:21504
	ds_read_b128 v[218:221], v190 offset:22528
	ds_read_b128 v[222:225], v190 offset:23552
	global_load_lds_dwordx4 v[238:239], off
	s_add_i32 m0, s63, 0x2000
	s_add_u32 s64, s24, 0x40000
	v_lshl_add_u64 v[240:241], s[24:25], 0, v[144:145]
	s_addc_u32 s65, s25, 0
	s_add_i32 s63, s66, s48
	global_load_lds_dwordx4 v[240:241], off
	v_lshl_add_u64 v[242:243], s[64:65], 0, v[148:149]
	s_mov_b32 m0, s63
	s_nop 0
	global_load_lds_dwordx4 v[242:243], off
	v_lshl_add_u64 v[242:243], s[64:65], 0, v[144:145]
	s_add_i32 m0, s63, 0x2000
	s_nop 0
	global_load_lds_dwordx4 v[242:243], off
	v_lshl_add_u64 v[242:243], s[26:27], 0, v[150:151]
	s_mov_b32 m0, s49
	s_nop 0
	global_load_lds_dwordx4 v[242:243], off
	v_lshl_add_u64 v[242:243], s[26:27], 0, v[146:147]
	s_mov_b32 m0, s50
	s_nop 0
	global_load_lds_dwordx4 v[242:243], off
	s_waitcnt vmcnt(8)
	s_waitcnt lgkmcnt(0)
	s_barrier
; #define PG8_STAGE(bufoff, gbase, voff) do { _Pragma("unroll") for (int _i = 0; _i < 2; ++_i) \
;         __builtin_amdgcn_global_load_lds((const unsigned*)((const char*)(gbase) + (voff)[_i]), (PG8_LAS unsigned*)(lds + (bufoff) + ldsw + _i * 8192), 16, 0, 0); } while (0)
; #define PG8_LDA(dst, b, h) do { _Pragma("unroll") for (int m = 0; m < 4; ++m) _Pragma("unroll") for (int k = 0; k < 2; ++k) dst[m][k] = *(const PG8_LAS bf16x8*)(lds + PG8_SA(b, h) + aoff + m * 2048 + k * 1024); } while (0)
; #define PG8_LDB(dst, b, h) do { _Pragma("unroll") for (int n = 0; n < 2; ++n) _Pragma("unroll") for (int k = 0; k < 2; ++k) dst[n][k] = *(const PG8_LAS bf16x8*)(lds + PG8_SB(b, h) + boff + n * 2048 + k * 1024); } while (0)
; #define PG8_MMA(ai, bj, At, Bt) do { __builtin_amdgcn_s_setprio(1); _Pragma("unroll") for (int m = 0; m < 4; ++m) _Pragma("unroll") for (int n = 0; n < 2; ++n) _Pragma("unroll") for (int k = 0; k < 2; ++k) \
;         acc[ai][bj][m][n] = __builtin_amdgcn_mfma_f32_16x16x32_bf16(Bt[n][k], At[m][k], acc[ai][bj][m][n], 0, 0, 0); __builtin_amdgcn_s_setprio(0); } while (0)
; #define PG8_WAIT_V(n) asm volatile("s_waitcnt vmcnt(" #n ")" ::: "memory")
; #define PG8_WAIT_L(n) asm volatile("s_waitcnt lgkmcnt(" #n ")" ::: "memory")
; #define PG8_BAR __builtin_amdgcn_s_barrier()
; #define PG8_SCHED __builtin_amdgcn_sched_barrier(0)
;     ...
;             PG8_LDB(B0, 0, 0); PG8_LDB(B1, 0, 1); PG8_SCHED; PG8_LDA(At, 0, 0); PG8_STAGE(PG8_SA(1, 1), a1 + hstepA, voffA);
;             PG8_WAIT_V(8); PG8_WAIT_L(0); PG8_BAR; PG8_MMA(0, 0, At, B0); PG8_MMA(0, 1, At, B1); PG8_BAR; PG8_SCHED;
;             PG8_LDA(At, 0, 1); PG8_STAGE(PG8_SB(0, 0), b2, voffB); PG8_STAGE(PG8_SB(0, 1), b2 + hstepB, voffB); PG8_STAGE(PG8_SA(0, 0), a2, voffA);
;             PG8_WAIT_V(8); PG8_WAIT_L(0); PG8_BAR; PG8_MMA(1, 0, At, B0); PG8_MMA(1, 1, At, B1); PG8_BAR; PG8_SCHED;
;             PG8_LDB(B0, 1, 0); PG8_LDB(B1, 1, 1); PG8_SCHED; PG8_LDA(At, 1, 0); PG8_STAGE(PG8_SA(0, 1), a2 + hstepA, voffA);
;             PG8_WAIT_V(8); PG8_WAIT_L(0); PG8_BAR; PG8_MMA(0, 0, At, B0); PG8_MMA(0, 1, At, B1); PG8_BAR; PG8_SCHED;
;             PG8_LDA(At, 1, 1); PG8_STAGE(PG8_SB(1, 0), b3, voffB); PG8_STAGE(PG8_SB(1, 1), b3 + hstepB, voffB); PG8_STAGE(PG8_SA(1, 0), a3, voffA);
;             PG8_WAIT_V(8); PG8_WAIT_L(0); PG8_BAR; PG8_MMA(1, 0, At, B0); PG8_MMA(1, 1, At, B1); PG8_BAR; PG8_SCHED;
	s_setprio 1
	s_waitcnt lgkmcnt(0)
	v_mfma_f32_16x16x32_bf16 v[60:63], v[132:135], v[176:179], 0
	v_mfma_f32_16x16x32_bf16 v[56:59], v[140:143], v[176:179], 0
	v_mfma_f32_16x16x32_bf16 v[48:51], v[132:135], v[192:195], 0
	v_mfma_f32_16x16x32_bf16 v[40:43], v[140:143], v[192:195], 0
	v_mfma_f32_16x16x32_bf16 v[32:35], v[132:135], v[200:203], 0
	v_mfma_f32_16x16x32_bf16 v[24:27], v[140:143], v[200:203], 0
	v_mfma_f32_16x16x32_bf16 v[16:19], v[132:135], v[218:221], 0
	v_mfma_f32_16x16x32_bf16 v[8:11], v[140:143], v[218:221], 0
	v_mfma_f32_16x16x32_bf16 v[60:63], v[136:139], v[180:183], v[60:63]
	v_mfma_f32_16x16x32_bf16 v[56:59], v[156:159], v[180:183], v[56:59]
	v_mfma_f32_16x16x32_bf16 v[48:51], v[136:139], v[196:199], v[48:51]
	v_mfma_f32_16x16x32_bf16 v[40:43], v[156:159], v[196:199], v[40:43]
	v_mfma_f32_16x16x32_bf16 v[32:35], v[136:139], v[204:207], v[32:35]
	v_mfma_f32_16x16x32_bf16 v[24:27], v[156:159], v[204:207], v[24:27]
	v_mfma_f32_16x16x32_bf16 v[16:19], v[136:139], v[222:225], v[16:19]
	v_mfma_f32_16x16x32_bf16 v[8:11], v[156:159], v[222:225], v[8:11]
	s_setprio 0
	s_setprio 1
	v_mfma_f32_16x16x32_bf16 v[52:55], v[160:163], v[176:179], 0
	v_mfma_f32_16x16x32_bf16 v[44:47], v[168:171], v[176:179], 0
	v_mfma_f32_16x16x32_bf16 v[36:39], v[160:163], v[192:195], 0
	v_mfma_f32_16x16x32_bf16 v[28:31], v[168:171], v[192:195], 0
	v_mfma_f32_16x16x32_bf16 v[20:23], v[160:163], v[200:203], 0
	v_mfma_f32_16x16x32_bf16 v[12:15], v[168:171], v[200:203], 0
	v_mfma_f32_16x16x32_bf16 v[4:7], v[160:163], v[218:221], 0
	v_mfma_f32_16x16x32_bf16 v[0:3], v[168:171], v[218:221], 0
	v_mfma_f32_16x16x32_bf16 v[52:55], v[164:167], v[180:183], v[52:55]
	v_mfma_f32_16x16x32_bf16 v[44:47], v[172:175], v[180:183], v[44:47]
	v_mfma_f32_16x16x32_bf16 v[36:39], v[164:167], v[196:199], v[36:39]
	v_mfma_f32_16x16x32_bf16 v[28:31], v[172:175], v[196:199], v[28:31]
	v_mfma_f32_16x16x32_bf16 v[20:23], v[164:167], v[204:207], v[20:23]
	v_mfma_f32_16x16x32_bf16 v[12:15], v[172:175], v[204:207], v[12:15]
	v_mfma_f32_16x16x32_bf16 v[4:7], v[164:167], v[222:225], v[4:7]
	s_barrier
	v_mfma_f32_16x16x32_bf16 v[0:3], v[172:175], v[222:225], v[0:3]
	s_setprio 0
	s_add_i32 s63, 0, 0x18000
	s_add_i32 s64, 0, 0x1c000
	v_add_u32_e32 v156, s63, v185
	v_add_u32_e32 v172, s64, v185
	ds_read_b128 v[132:135], v156
	ds_read_b128 v[136:139], v156 offset:1024
	ds_read_b128 v[140:143], v156 offset:2048
	ds_read_b128 v[156:159], v156 offset:3072
	ds_read_b128 v[160:163], v172
	ds_read_b128 v[164:167], v172 offset:1024
	ds_read_b128 v[168:171], v172 offset:2048
	ds_read_b128 v[172:175], v172 offset:3072
	s_add_u32 s26, s26, 0x40000
	s_addc_u32 s27, s27, 0
	s_mov_b32 m0, s51
	v_lshl_add_u64 v[242:243], s[26:27], 0, v[150:151]
	ds_read_b128 v[176:179], v190 offset:32768
	ds_read_b128 v[180:183], v190 offset:33792
	ds_read_b128 v[192:195], v190 offset:34816
	ds_read_b128 v[196:199], v190 offset:35840
	ds_read_b128 v[200:203], v190 offset:36864
	ds_read_b128 v[204:207], v190 offset:37888
	ds_read_b128 v[218:221], v190 offset:38912
	ds_read_b128 v[222:225], v190 offset:39936
	global_load_lds_dwordx4 v[242:243], off
	v_lshl_add_u64 v[242:243], s[26:27], 0, v[146:147]
	s_mov_b32 m0, s52
	s_nop 0
	global_load_lds_dwordx4 v[242:243], off
	s_waitcnt vmcnt(8)
	s_waitcnt lgkmcnt(0)
	s_barrier
	s_setprio 1
	s_waitcnt lgkmcnt(0)
	v_mfma_f32_16x16x32_bf16 v[124:127], v[132:135], v[176:179], v[124:127]
	v_mfma_f32_16x16x32_bf16 v[120:123], v[140:143], v[176:179], v[120:123]
	v_mfma_f32_16x16x32_bf16 v[112:115], v[132:135], v[192:195], v[112:115]
	v_mfma_f32_16x16x32_bf16 v[104:107], v[140:143], v[192:195], v[104:107]
	v_mfma_f32_16x16x32_bf16 v[96:99], v[132:135], v[200:203], v[96:99]
	v_mfma_f32_16x16x32_bf16 v[88:91], v[140:143], v[200:203], v[88:91]
	v_mfma_f32_16x16x32_bf16 v[80:83], v[132:135], v[218:221], v[80:83]
	v_mfma_f32_16x16x32_bf16 v[72:75], v[140:143], v[218:221], v[72:75]
	v_mfma_f32_16x16x32_bf16 v[124:127], v[136:139], v[180:183], v[124:127]
	v_mfma_f32_16x16x32_bf16 v[120:123], v[156:159], v[180:183], v[120:123]
	v_mfma_f32_16x16x32_bf16 v[112:115], v[136:139], v[196:199], v[112:115]
	v_mfma_f32_16x16x32_bf16 v[104:107], v[156:159], v[196:199], v[104:107]
	v_mfma_f32_16x16x32_bf16 v[96:99], v[136:139], v[204:207], v[96:99]
	v_mfma_f32_16x16x32_bf16 v[88:91], v[156:159], v[204:207], v[88:91]
	v_mfma_f32_16x16x32_bf16 v[80:83], v[136:139], v[222:225], v[80:83]
	v_mfma_f32_16x16x32_bf16 v[72:75], v[156:159], v[222:225], v[72:75]
	s_setprio 0
	s_setprio 1
	v_mfma_f32_16x16x32_bf16 v[116:119], v[160:163], v[176:179], v[116:119]
	v_mfma_f32_16x16x32_bf16 v[108:111], v[168:171], v[176:179], v[108:111]
	v_mfma_f32_16x16x32_bf16 v[100:103], v[160:163], v[192:195], v[100:103]
	v_mfma_f32_16x16x32_bf16 v[92:95], v[168:171], v[192:195], v[92:95]
	v_mfma_f32_16x16x32_bf16 v[84:87], v[160:163], v[200:203], v[84:87]
	v_mfma_f32_16x16x32_bf16 v[76:79], v[168:171], v[200:203], v[76:79]
	v_mfma_f32_16x16x32_bf16 v[68:71], v[160:163], v[218:221], v[68:71]
	v_mfma_f32_16x16x32_bf16 v[64:67], v[168:171], v[218:221], v[64:67]
	v_mfma_f32_16x16x32_bf16 v[116:119], v[164:167], v[180:183], v[116:119]
	v_mfma_f32_16x16x32_bf16 v[108:111], v[172:175], v[180:183], v[108:111]
	v_mfma_f32_16x16x32_bf16 v[100:103], v[164:167], v[196:199], v[100:103]
	v_mfma_f32_16x16x32_bf16 v[92:95], v[172:175], v[196:199], v[92:95]
	v_mfma_f32_16x16x32_bf16 v[84:87], v[164:167], v[204:207], v[84:87]
	v_mfma_f32_16x16x32_bf16 v[76:79], v[172:175], v[204:207], v[76:79]
	v_mfma_f32_16x16x32_bf16 v[68:71], v[164:167], v[222:225], v[68:71]
	s_barrier
; #define PG8_STAGE(bufoff, gbase, voff) do { _Pragma("unroll") for (int _i = 0; _i < 2; ++_i) \
;         __builtin_amdgcn_global_load_lds((const unsigned*)((const char*)(gbase) + (voff)[_i]), (PG8_LAS unsigned*)(lds + (bufoff) + ldsw + _i * 8192), 16, 0, 0); } while (0)
; #define PG8_LDA(dst, b, h) do { _Pragma("unroll") for (int m = 0; m < 4; ++m) _Pragma("unroll") for (int k = 0; k < 2; ++k) dst[m][k] = *(const PG8_LAS bf16x8*)(lds + PG8_SA(b, h) + aoff + m * 2048 + k * 1024); } while (0)
; #define PG8_LDB(dst, b, h) do { _Pragma("unroll") for (int n = 0; n < 2; ++n) _Pragma("unroll") for (int k = 0; k < 2; ++k) dst[n][k] = *(const PG8_LAS bf16x8*)(lds + PG8_SB(b, h) + boff + n * 2048 + k * 1024); } while (0)
; #define PG8_MMA(ai, bj, At, Bt) do { __builtin_amdgcn_s_setprio(1); _Pragma("unroll") for (int m = 0; m < 4; ++m) _Pragma("unroll") for (int n = 0; n < 2; ++n) _Pragma("unroll") for (int k = 0; k < 2; ++k) \
;         acc[ai][bj][m][n] = __builtin_amdgcn_mfma_f32_16x16x32_bf16(Bt[n][k], At[m][k], acc[ai][bj][m][n], 0, 0, 0); __builtin_amdgcn_s_setprio(0); } while (0)
; #define PG8_WAIT_V(n) asm volatile("s_waitcnt vmcnt(" #n ")" ::: "memory")
; #define PG8_WAIT_L(n) asm volatile("s_waitcnt lgkmcnt(" #n ")" ::: "memory")
; #define PG8_BAR __builtin_amdgcn_s_barrier()
; #define PG8_SCHED __builtin_amdgcn_sched_barrier(0)
;     ...
;             PG8_LDB(B0, 0, 0); PG8_LDB(B1, 0, 1); PG8_SCHED; PG8_LDA(At, 0, 0); PG8_STAGE(PG8_SA(1, 1), a1 + hstepA, voffA);
;             PG8_WAIT_V(8); PG8_WAIT_L(0); PG8_BAR; PG8_MMA(0, 0, At, B0); PG8_MMA(0, 1, At, B1); PG8_BAR; PG8_SCHED;
;             PG8_LDA(At, 0, 1); PG8_STAGE(PG8_SB(0, 0), b2, voffB); PG8_STAGE(PG8_SB(0, 1), b2 + hstepB, voffB); PG8_STAGE(PG8_SA(0, 0), a2, voffA);
;             PG8_WAIT_V(8); PG8_WAIT_L(0); PG8_BAR; PG8_MMA(1, 0, At, B0); PG8_MMA(1, 1, At, B1); PG8_BAR; PG8_SCHED;
;             PG8_LDB(B0, 1, 0); PG8_LDB(B1, 1, 1); PG8_SCHED; PG8_LDA(At, 1, 0); PG8_STAGE(PG8_SA(0, 1), a2 + hstepA, voffA);
;             PG8_WAIT_V(8); PG8_WAIT_L(0); PG8_BAR; PG8_MMA(0, 0, At, B0); PG8_MMA(0, 1, At, B1); PG8_BAR; PG8_SCHED;
;             PG8_LDA(At, 1, 1); PG8_STAGE(PG8_SB(1, 0), b3, voffB); PG8_STAGE(PG8_SB(1, 1), b3 + hstepB, voffB); PG8_STAGE(PG8_SA(1, 0), a3, voffA);
;             PG8_WAIT_V(8); PG8_WAIT_L(0); PG8_BAR; PG8_MMA(1, 0, At, B0); PG8_MMA(1, 1, At, B1); PG8_BAR; PG8_SCHED;
	v_mfma_f32_16x16x32_bf16 v[64:67], v[172:175], v[222:225], v[64:67]
	s_setprio 0
	s_add_i32 s26, s63, s48
	v_lshl_add_u64 v[238:239], v[238:239], 0, s[68:69]
	s_mov_b32 m0, s26
	ds_read_b128 v[176:179], v190 offset:49152
	ds_read_b128 v[180:183], v190 offset:50176
	ds_read_b128 v[192:195], v190 offset:51200
	ds_read_b128 v[196:199], v190 offset:52224
	ds_read_b128 v[200:203], v190 offset:53248
	ds_read_b128 v[204:207], v190 offset:54272
	ds_read_b128 v[218:221], v190 offset:55296
	ds_read_b128 v[222:225], v190 offset:56320
	global_load_lds_dwordx4 v[238:239], off
	s_add_i32 m0, s26, 0x2000
	s_add_u32 s24, s24, 0x40080
	v_lshl_add_u64 v[238:239], v[240:241], 0, s[68:69]
	s_addc_u32 s25, s25, 0
	s_add_i32 s26, s64, s48
	global_load_lds_dwordx4 v[238:239], off
	v_lshl_add_u64 v[238:239], s[24:25], 0, v[148:149]
	s_mov_b32 m0, s26
	s_nop 0
	global_load_lds_dwordx4 v[238:239], off
	v_lshl_add_u64 v[238:239], s[24:25], 0, v[144:145]
	s_add_i32 m0, s26, 0x2000
	s_nop 0
	global_load_lds_dwordx4 v[238:239], off
	v_lshl_add_u64 v[238:239], s[20:21], 0, v[150:151]
	s_mov_b32 m0, s53
	s_nop 0
	global_load_lds_dwordx4 v[238:239], off
	v_lshl_add_u64 v[238:239], s[20:21], 0, v[146:147]
	s_mov_b32 m0, s54
	s_nop 0
	global_load_lds_dwordx4 v[238:239], off
	s_waitcnt vmcnt(8)
	s_waitcnt lgkmcnt(0)
	s_barrier
	s_setprio 1
	s_waitcnt lgkmcnt(0)
	v_mfma_f32_16x16x32_bf16 v[60:63], v[132:135], v[176:179], v[60:63]
	v_mfma_f32_16x16x32_bf16 v[56:59], v[140:143], v[176:179], v[56:59]
	v_mfma_f32_16x16x32_bf16 v[48:51], v[132:135], v[192:195], v[48:51]
	v_mfma_f32_16x16x32_bf16 v[40:43], v[140:143], v[192:195], v[40:43]
	v_mfma_f32_16x16x32_bf16 v[32:35], v[132:135], v[200:203], v[32:35]
	v_mfma_f32_16x16x32_bf16 v[24:27], v[140:143], v[200:203], v[24:27]
	v_mfma_f32_16x16x32_bf16 v[16:19], v[132:135], v[218:221], v[16:19]
	v_mfma_f32_16x16x32_bf16 v[8:11], v[140:143], v[218:221], v[8:11]
	v_mfma_f32_16x16x32_bf16 v[60:63], v[136:139], v[180:183], v[60:63]
	v_mfma_f32_16x16x32_bf16 v[56:59], v[156:159], v[180:183], v[56:59]
	v_mfma_f32_16x16x32_bf16 v[48:51], v[136:139], v[196:199], v[48:51]
	v_mfma_f32_16x16x32_bf16 v[40:43], v[156:159], v[196:199], v[40:43]
	v_mfma_f32_16x16x32_bf16 v[32:35], v[136:139], v[204:207], v[32:35]
	v_mfma_f32_16x16x32_bf16 v[24:27], v[156:159], v[204:207], v[24:27]
	v_mfma_f32_16x16x32_bf16 v[16:19], v[136:139], v[222:225], v[16:19]
	v_mfma_f32_16x16x32_bf16 v[8:11], v[156:159], v[222:225], v[8:11]
	s_setprio 0
	s_setprio 1
	v_mfma_f32_16x16x32_bf16 v[52:55], v[160:163], v[176:179], v[52:55]
	v_mfma_f32_16x16x32_bf16 v[44:47], v[168:171], v[176:179], v[44:47]
	v_mfma_f32_16x16x32_bf16 v[36:39], v[160:163], v[192:195], v[36:39]
	v_mfma_f32_16x16x32_bf16 v[28:31], v[168:171], v[192:195], v[28:31]
	v_mfma_f32_16x16x32_bf16 v[20:23], v[160:163], v[200:203], v[20:23]
	v_mfma_f32_16x16x32_bf16 v[12:15], v[168:171], v[200:203], v[12:15]
	v_mfma_f32_16x16x32_bf16 v[4:7], v[160:163], v[218:221], v[4:7]
	v_mfma_f32_16x16x32_bf16 v[0:3], v[168:171], v[218:221], v[0:3]
	v_mfma_f32_16x16x32_bf16 v[52:55], v[164:167], v[180:183], v[52:55]
	v_mfma_f32_16x16x32_bf16 v[44:47], v[172:175], v[180:183], v[44:47]
	v_mfma_f32_16x16x32_bf16 v[36:39], v[164:167], v[196:199], v[36:39]
	v_mfma_f32_16x16x32_bf16 v[28:31], v[172:175], v[196:199], v[28:31]
	v_mfma_f32_16x16x32_bf16 v[20:23], v[164:167], v[204:207], v[20:23]
	v_mfma_f32_16x16x32_bf16 v[12:15], v[172:175], v[204:207], v[12:15]
	v_mfma_f32_16x16x32_bf16 v[4:7], v[164:167], v[222:225], v[4:7]
	s_barrier
	v_mfma_f32_16x16x32_bf16 v[0:3], v[172:175], v[222:225], v[0:3]
	s_setprio 0
	s_add_i32 s62, s62, 2
	s_add_u32 s2, s2, 0x100
	s_addc_u32 s3, s3, 0
	s_cmp_gt_u32 s62, 13
	s_cbranch_scc0 .LBB0_702
	s_branch .Lpeel_exit_702
.LBB0_702:
	s_add_u32 s20, s40, s2
	s_addc_u32 s21, s41, s3
	s_add_u32 s26, s20, 0x400100
	s_addc_u32 s27, s21, 0
	s_add_u32 s24, s42, s2
	s_addc_u32 s25, s43, s3
	s_add_u32 s20, s20, 0x400180
	s_addc_u32 s21, s21, 0
	s_add_i32 s63, 0, 0x10000
	s_add_i32 s66, 0, 0x14000
	v_add_u32_e32 v156, s63, v185
	v_add_u32_e32 v172, s66, v185
	ds_read_b128 v[132:135], v156
	ds_read_b128 v[136:139], v156 offset:1024
	ds_read_b128 v[140:143], v156 offset:2048
	ds_read_b128 v[156:159], v156 offset:3072
	ds_read_b128 v[160:163], v172
	ds_read_b128 v[164:167], v172 offset:1024
	ds_read_b128 v[168:171], v172 offset:2048
	ds_read_b128 v[172:175], v172 offset:3072
	s_cmpk_eq_i32 s2, 0x700
	s_cselect_b32 s21, s31, s21
	s_cselect_b32 s20, s30, s20
	s_cselect_b32 s25, s28, s25
	s_cselect_b32 s24, s1, s24
	s_cselect_b32 s27, s29, s27
	s_cselect_b32 s26, s19, s26
	v_lshl_add_u64 v[238:239], v[128:129], 0, s[2:3]
	s_add_i32 m0, s49, 0xc000
	ds_read_b128 v[176:179], v190
	ds_read_b128 v[180:183], v190 offset:1024
	ds_read_b128 v[192:195], v190 offset:2048
	ds_read_b128 v[196:199], v190 offset:3072
	ds_read_b128 v[200:203], v190 offset:4096
	ds_read_b128 v[204:207], v190 offset:5120
	ds_read_b128 v[218:221], v190 offset:6144
	ds_read_b128 v[222:225], v190 offset:7168
	global_load_lds_dwordx4 v[238:239], off
	v_lshl_add_u64 v[238:239], v[130:131], 0, s[2:3]
	s_add_i32 m0, s49, 0xe000
	s_nop 0
	global_load_lds_dwordx4 v[238:239], off
	s_waitcnt vmcnt(8)
	s_waitcnt lgkmcnt(0)
	s_barrier
; #define PG8_STAGE(bufoff, gbase, voff) do { _Pragma("unroll") for (int _i = 0; _i < 2; ++_i) \
;         __builtin_amdgcn_global_load_lds((const unsigned*)((const char*)(gbase) + (voff)[_i]), (PG8_LAS unsigned*)(lds + (bufoff) + ldsw + _i * 8192), 16, 0, 0); } while (0)
; #define PG8_LDA(dst, b, h) do { _Pragma("unroll") for (int m = 0; m < 4; ++m) _Pragma("unroll") for (int k = 0; k < 2; ++k) dst[m][k] = *(const PG8_LAS bf16x8*)(lds + PG8_SA(b, h) + aoff + m * 2048 + k * 1024); } while (0)
; #define PG8_LDB(dst, b, h) do { _Pragma("unroll") for (int n = 0; n < 2; ++n) _Pragma("unroll") for (int k = 0; k < 2; ++k) dst[n][k] = *(const PG8_LAS bf16x8*)(lds + PG8_SB(b, h) + boff + n * 2048 + k * 1024); } while (0)
; #define PG8_MMA(ai, bj, At, Bt) do { __builtin_amdgcn_s_setprio(1); _Pragma("unroll") for (int m = 0; m < 4; ++m) _Pragma("unroll") for (int n = 0; n < 2; ++n) _Pragma("unroll") for (int k = 0; k < 2; ++k) \
;         acc[ai][bj][m][n] = __builtin_amdgcn_mfma_f32_16x16x32_bf16(Bt[n][k], At[m][k], acc[ai][bj][m][n], 0, 0, 0); __builtin_amdgcn_s_setprio(0); } while (0)
; #define PG8_WAIT_V(n) asm volatile("s_waitcnt vmcnt(" #n ")" ::: "memory")
; #define PG8_WAIT_L(n) asm volatile("s_waitcnt lgkmcnt(" #n ")" ::: "memory")
; #define PG8_BAR __builtin_amdgcn_s_barrier()
; #define PG8_SCHED __builtin_amdgcn_sched_barrier(0)
;     ...
;             PG8_LDB(B0, 0, 0); PG8_LDB(B1, 0, 1); PG8_SCHED; PG8_LDA(At, 0, 0); PG8_STAGE(PG8_SA(1, 1), a1 + hstepA, voffA);
;             PG8_WAIT_V(8); PG8_WAIT_L(0); PG8_BAR; PG8_MMA(0, 0, At, B0); PG8_MMA(0, 1, At, B1); PG8_BAR; PG8_SCHED;
;             PG8_LDA(At, 0, 1); PG8_STAGE(PG8_SB(0, 0), b2, voffB); PG8_STAGE(PG8_SB(0, 1), b2 + hstepB, voffB); PG8_STAGE(PG8_SA(0, 0), a2, voffA);
;             PG8_WAIT_V(8); PG8_WAIT_L(0); PG8_BAR; PG8_MMA(1, 0, At, B0); PG8_MMA(1, 1, At, B1); PG8_BAR; PG8_SCHED;
;             PG8_LDB(B0, 1, 0); PG8_LDB(B1, 1, 1); PG8_SCHED; PG8_LDA(At, 1, 0); PG8_STAGE(PG8_SA(0, 1), a2 + hstepA, voffA);
;             PG8_WAIT_V(8); PG8_WAIT_L(0); PG8_BAR; PG8_MMA(0, 0, At, B0); PG8_MMA(0, 1, At, B1); PG8_BAR; PG8_SCHED;
;             PG8_LDA(At, 1, 1); PG8_STAGE(PG8_SB(1, 0), b3, voffB); PG8_STAGE(PG8_SB(1, 1), b3 + hstepB, voffB); PG8_STAGE(PG8_SA(1, 0), a3, voffA);
;             PG8_WAIT_V(8); PG8_WAIT_L(0); PG8_BAR; PG8_MMA(1, 0, At, B0); PG8_MMA(1, 1, At, B1); PG8_BAR; PG8_SCHED;
	s_setprio 1
	s_waitcnt lgkmcnt(0)
	v_mfma_f32_16x16x32_bf16 v[124:127], v[132:135], v[176:179], v[124:127]
	v_mfma_f32_16x16x32_bf16 v[120:123], v[140:143], v[176:179], v[120:123]
	v_mfma_f32_16x16x32_bf16 v[112:115], v[132:135], v[192:195], v[112:115]
	v_mfma_f32_16x16x32_bf16 v[104:107], v[140:143], v[192:195], v[104:107]
	v_mfma_f32_16x16x32_bf16 v[96:99], v[132:135], v[200:203], v[96:99]
	v_mfma_f32_16x16x32_bf16 v[88:91], v[140:143], v[200:203], v[88:91]
	v_mfma_f32_16x16x32_bf16 v[80:83], v[132:135], v[218:221], v[80:83]
	v_mfma_f32_16x16x32_bf16 v[72:75], v[140:143], v[218:221], v[72:75]
	v_mfma_f32_16x16x32_bf16 v[124:127], v[136:139], v[180:183], v[124:127]
	v_mfma_f32_16x16x32_bf16 v[120:123], v[156:159], v[180:183], v[120:123]
	v_mfma_f32_16x16x32_bf16 v[112:115], v[136:139], v[196:199], v[112:115]
	v_mfma_f32_16x16x32_bf16 v[104:107], v[156:159], v[196:199], v[104:107]
	v_mfma_f32_16x16x32_bf16 v[96:99], v[136:139], v[204:207], v[96:99]
	v_mfma_f32_16x16x32_bf16 v[88:91], v[156:159], v[204:207], v[88:91]
	v_mfma_f32_16x16x32_bf16 v[80:83], v[136:139], v[222:225], v[80:83]
	v_mfma_f32_16x16x32_bf16 v[72:75], v[156:159], v[222:225], v[72:75]
	s_setprio 0
	s_setprio 1
	v_mfma_f32_16x16x32_bf16 v[116:119], v[160:163], v[176:179], v[116:119]
	v_mfma_f32_16x16x32_bf16 v[108:111], v[168:171], v[176:179], v[108:111]
	v_mfma_f32_16x16x32_bf16 v[100:103], v[160:163], v[192:195], v[100:103]
	v_mfma_f32_16x16x32_bf16 v[92:95], v[168:171], v[192:195], v[92:95]
	v_mfma_f32_16x16x32_bf16 v[84:87], v[160:163], v[200:203], v[84:87]
	v_mfma_f32_16x16x32_bf16 v[76:79], v[168:171], v[200:203], v[76:79]
	v_mfma_f32_16x16x32_bf16 v[68:71], v[160:163], v[218:221], v[68:71]
	v_mfma_f32_16x16x32_bf16 v[64:67], v[168:171], v[218:221], v[64:67]
	v_mfma_f32_16x16x32_bf16 v[116:119], v[164:167], v[180:183], v[116:119]
	v_mfma_f32_16x16x32_bf16 v[108:111], v[172:175], v[180:183], v[108:111]
	v_mfma_f32_16x16x32_bf16 v[100:103], v[164:167], v[196:199], v[100:103]
	v_mfma_f32_16x16x32_bf16 v[92:95], v[172:175], v[196:199], v[92:95]
	v_mfma_f32_16x16x32_bf16 v[84:87], v[164:167], v[204:207], v[84:87]
	v_mfma_f32_16x16x32_bf16 v[76:79], v[172:175], v[204:207], v[76:79]
	v_mfma_f32_16x16x32_bf16 v[68:71], v[164:167], v[222:225], v[68:71]
	s_barrier
	v_mfma_f32_16x16x32_bf16 v[64:67], v[172:175], v[222:225], v[64:67]
	s_setprio 0
	s_add_i32 s63, s63, s48
	v_lshl_add_u64 v[238:239], s[24:25], 0, v[148:149]
	s_mov_b32 m0, s63
	ds_read_b128 v[176:179], v190 offset:16384
	ds_read_b128 v[180:183], v190 offset:17408
	ds_read_b128 v[192:195], v190 offset:18432
	ds_read_b128 v[196:199], v190 offset:19456
	ds_read_b128 v[200:203], v190 offset:20480
	ds_read_b128 v[204:207], v190 offset:21504
	ds_read_b128 v[218:221], v190 offset:22528
	ds_read_b128 v[222:225], v190 offset:23552
	global_load_lds_dwordx4 v[238:239], off
	s_add_i32 m0, s63, 0x2000
	s_add_u32 s64, s24, 0x40000
	v_lshl_add_u64 v[240:241], s[24:25], 0, v[144:145]
	s_addc_u32 s65, s25, 0
	s_add_i32 s63, s66, s48
	global_load_lds_dwordx4 v[240:241], off
	v_lshl_add_u64 v[242:243], s[64:65], 0, v[148:149]
	s_mov_b32 m0, s63
	s_nop 0
	global_load_lds_dwordx4 v[242:243], off
	v_lshl_add_u64 v[242:243], s[64:65], 0, v[144:145]
	s_add_i32 m0, s63, 0x2000
	s_nop 0
	global_load_lds_dwordx4 v[242:243], off
	v_lshl_add_u64 v[242:243], s[26:27], 0, v[150:151]
	s_mov_b32 m0, s49
	s_nop 0
	global_load_lds_dwordx4 v[242:243], off
	v_lshl_add_u64 v[242:243], s[26:27], 0, v[146:147]
	s_mov_b32 m0, s50
	s_nop 0
	global_load_lds_dwordx4 v[242:243], off
	s_waitcnt vmcnt(8)
	s_waitcnt lgkmcnt(0)
	s_barrier
	s_setprio 1
	s_waitcnt lgkmcnt(0)
	v_mfma_f32_16x16x32_bf16 v[60:63], v[132:135], v[176:179], v[60:63]
	v_mfma_f32_16x16x32_bf16 v[56:59], v[140:143], v[176:179], v[56:59]
	v_mfma_f32_16x16x32_bf16 v[48:51], v[132:135], v[192:195], v[48:51]
	v_mfma_f32_16x16x32_bf16 v[40:43], v[140:143], v[192:195], v[40:43]
	v_mfma_f32_16x16x32_bf16 v[32:35], v[132:135], v[200:203], v[32:35]
	v_mfma_f32_16x16x32_bf16 v[24:27], v[140:143], v[200:203], v[24:27]
	v_mfma_f32_16x16x32_bf16 v[16:19], v[132:135], v[218:221], v[16:19]
	v_mfma_f32_16x16x32_bf16 v[8:11], v[140:143], v[218:221], v[8:11]
	v_mfma_f32_16x16x32_bf16 v[60:63], v[136:139], v[180:183], v[60:63]
	v_mfma_f32_16x16x32_bf16 v[56:59], v[156:159], v[180:183], v[56:59]
	v_mfma_f32_16x16x32_bf16 v[48:51], v[136:139], v[196:199], v[48:51]
	v_mfma_f32_16x16x32_bf16 v[40:43], v[156:159], v[196:199], v[40:43]
	v_mfma_f32_16x16x32_bf16 v[32:35], v[136:139], v[204:207], v[32:35]
	v_mfma_f32_16x16x32_bf16 v[24:27], v[156:159], v[204:207], v[24:27]
	v_mfma_f32_16x16x32_bf16 v[16:19], v[136:139], v[222:225], v[16:19]
	v_mfma_f32_16x16x32_bf16 v[8:11], v[156:159], v[222:225], v[8:11]
	s_setprio 0
	s_setprio 1
	v_mfma_f32_16x16x32_bf16 v[52:55], v[160:163], v[176:179], v[52:55]
	v_mfma_f32_16x16x32_bf16 v[44:47], v[168:171], v[176:179], v[44:47]
	v_mfma_f32_16x16x32_bf16 v[36:39], v[160:163], v[192:195], v[36:39]
	v_mfma_f32_16x16x32_bf16 v[28:31], v[168:171], v[192:195], v[28:31]
	v_mfma_f32_16x16x32_bf16 v[20:23], v[160:163], v[200:203], v[20:23]
	v_mfma_f32_16x16x32_bf16 v[12:15], v[168:171], v[200:203], v[12:15]
	v_mfma_f32_16x16x32_bf16 v[4:7], v[160:163], v[218:221], v[4:7]
	v_mfma_f32_16x16x32_bf16 v[0:3], v[168:171], v[218:221], v[0:3]
	v_mfma_f32_16x16x32_bf16 v[52:55], v[164:167], v[180:183], v[52:55]
	v_mfma_f32_16x16x32_bf16 v[44:47], v[172:175], v[180:183], v[44:47]
	v_mfma_f32_16x16x32_bf16 v[36:39], v[164:167], v[196:199], v[36:39]
	v_mfma_f32_16x16x32_bf16 v[28:31], v[172:175], v[196:199], v[28:31]
	v_mfma_f32_16x16x32_bf16 v[20:23], v[164:167], v[204:207], v[20:23]
	v_mfma_f32_16x16x32_bf16 v[12:15], v[172:175], v[204:207], v[12:15]
	v_mfma_f32_16x16x32_bf16 v[4:7], v[164:167], v[222:225], v[4:7]
	s_barrier
; #define PG8_STAGE(bufoff, gbase, voff) do { _Pragma("unroll") for (int _i = 0; _i < 2; ++_i) \
;         __builtin_amdgcn_global_load_lds((const unsigned*)((const char*)(gbase) + (voff)[_i]), (PG8_LAS unsigned*)(lds + (bufoff) + ldsw + _i * 8192), 16, 0, 0); } while (0)
; #define PG8_LDA(dst, b, h) do { _Pragma("unroll") for (int m = 0; m < 4; ++m) _Pragma("unroll") for (int k = 0; k < 2; ++k) dst[m][k] = *(const PG8_LAS bf16x8*)(lds + PG8_SA(b, h) + aoff + m * 2048 + k * 1024); } while (0)
; #define PG8_LDB(dst, b, h) do { _Pragma("unroll") for (int n = 0; n < 2; ++n) _Pragma("unroll") for (int k = 0; k < 2; ++k) dst[n][k] = *(const PG8_LAS bf16x8*)(lds + PG8_SB(b, h) + boff + n * 2048 + k * 1024); } while (0)
; #define PG8_MMA(ai, bj, At, Bt) do { __builtin_amdgcn_s_setprio(1); _Pragma("unroll") for (int m = 0; m < 4; ++m) _Pragma("unroll") for (int n = 0; n < 2; ++n) _Pragma("unroll") for (int k = 0; k < 2; ++k) \
;         acc[ai][bj][m][n] = __builtin_amdgcn_mfma_f32_16x16x32_bf16(Bt[n][k], At[m][k], acc[ai][bj][m][n], 0, 0, 0); __builtin_amdgcn_s_setprio(0); } while (0)
; #define PG8_WAIT_V(n) asm volatile("s_waitcnt vmcnt(" #n ")" ::: "memory")
; #define PG8_WAIT_L(n) asm volatile("s_waitcnt lgkmcnt(" #n ")" ::: "memory")
; #define PG8_BAR __builtin_amdgcn_s_barrier()
; #define PG8_SCHED __builtin_amdgcn_sched_barrier(0)
;     ...
;             PG8_LDB(B0, 0, 0); PG8_LDB(B1, 0, 1); PG8_SCHED; PG8_LDA(At, 0, 0); PG8_STAGE(PG8_SA(1, 1), a1 + hstepA, voffA);
;             PG8_WAIT_V(8); PG8_WAIT_L(0); PG8_BAR; PG8_MMA(0, 0, At, B0); PG8_MMA(0, 1, At, B1); PG8_BAR; PG8_SCHED;
;             PG8_LDA(At, 0, 1); PG8_STAGE(PG8_SB(0, 0), b2, voffB); PG8_STAGE(PG8_SB(0, 1), b2 + hstepB, voffB); PG8_STAGE(PG8_SA(0, 0), a2, voffA);
;             PG8_WAIT_V(8); PG8_WAIT_L(0); PG8_BAR; PG8_MMA(1, 0, At, B0); PG8_MMA(1, 1, At, B1); PG8_BAR; PG8_SCHED;
;             PG8_LDB(B0, 1, 0); PG8_LDB(B1, 1, 1); PG8_SCHED; PG8_LDA(At, 1, 0); PG8_STAGE(PG8_SA(0, 1), a2 + hstepA, voffA);
;             PG8_WAIT_V(8); PG8_WAIT_L(0); PG8_BAR; PG8_MMA(0, 0, At, B0); PG8_MMA(0, 1, At, B1); PG8_BAR; PG8_SCHED;
;             PG8_LDA(At, 1, 1); PG8_STAGE(PG8_SB(1, 0), b3, voffB); PG8_STAGE(PG8_SB(1, 1), b3 + hstepB, voffB); PG8_STAGE(PG8_SA(1, 0), a3, voffA);
;             PG8_WAIT_V(8); PG8_WAIT_L(0); PG8_BAR; PG8_MMA(1, 0, At, B0); PG8_MMA(1, 1, At, B1); PG8_BAR; PG8_SCHED;
	v_mfma_f32_16x16x32_bf16 v[0:3], v[172:175], v[222:225], v[0:3]
	s_setprio 0
	s_add_i32 s63, 0, 0x18000
	s_add_i32 s64, 0, 0x1c000
	v_add_u32_e32 v156, s63, v185
	v_add_u32_e32 v172, s64, v185
	ds_read_b128 v[132:135], v156
	ds_read_b128 v[136:139], v156 offset:1024
	ds_read_b128 v[140:143], v156 offset:2048
	ds_read_b128 v[156:159], v156 offset:3072
	ds_read_b128 v[160:163], v172
	ds_read_b128 v[164:167], v172 offset:1024
	ds_read_b128 v[168:171], v172 offset:2048
	ds_read_b128 v[172:175], v172 offset:3072
	s_add_u32 s26, s26, 0x40000
	s_addc_u32 s27, s27, 0
	s_mov_b32 m0, s51
	v_lshl_add_u64 v[242:243], s[26:27], 0, v[150:151]
	ds_read_b128 v[176:179], v190 offset:32768
	ds_read_b128 v[180:183], v190 offset:33792
	ds_read_b128 v[192:195], v190 offset:34816
	ds_read_b128 v[196:199], v190 offset:35840
	ds_read_b128 v[200:203], v190 offset:36864
	ds_read_b128 v[204:207], v190 offset:37888
	ds_read_b128 v[218:221], v190 offset:38912
	ds_read_b128 v[222:225], v190 offset:39936
	global_load_lds_dwordx4 v[242:243], off
	v_lshl_add_u64 v[242:243], s[26:27], 0, v[146:147]
	s_mov_b32 m0, s52
	s_nop 0
	global_load_lds_dwordx4 v[242:243], off
	s_waitcnt vmcnt(8)
	s_waitcnt lgkmcnt(0)
	s_barrier
	s_setprio 1
	s_waitcnt lgkmcnt(0)
	v_mfma_f32_16x16x32_bf16 v[124:127], v[132:135], v[176:179], v[124:127]
	v_mfma_f32_16x16x32_bf16 v[120:123], v[140:143], v[176:179], v[120:123]
	v_mfma_f32_16x16x32_bf16 v[112:115], v[132:135], v[192:195], v[112:115]
	v_mfma_f32_16x16x32_bf16 v[104:107], v[140:143], v[192:195], v[104:107]
	v_mfma_f32_16x16x32_bf16 v[96:99], v[132:135], v[200:203], v[96:99]
	v_mfma_f32_16x16x32_bf16 v[88:91], v[140:143], v[200:203], v[88:91]
	v_mfma_f32_16x16x32_bf16 v[80:83], v[132:135], v[218:221], v[80:83]
	v_mfma_f32_16x16x32_bf16 v[72:75], v[140:143], v[218:221], v[72:75]
	v_mfma_f32_16x16x32_bf16 v[124:127], v[136:139], v[180:183], v[124:127]
	v_mfma_f32_16x16x32_bf16 v[120:123], v[156:159], v[180:183], v[120:123]
	v_mfma_f32_16x16x32_bf16 v[112:115], v[136:139], v[196:199], v[112:115]
	v_mfma_f32_16x16x32_bf16 v[104:107], v[156:159], v[196:199], v[104:107]
	v_mfma_f32_16x16x32_bf16 v[96:99], v[136:139], v[204:207], v[96:99]
	v_mfma_f32_16x16x32_bf16 v[88:91], v[156:159], v[204:207], v[88:91]
	v_mfma_f32_16x16x32_bf16 v[80:83], v[136:139], v[222:225], v[80:83]
	v_mfma_f32_16x16x32_bf16 v[72:75], v[156:159], v[222:225], v[72:75]
	s_setprio 0
	s_setprio 1
	v_mfma_f32_16x16x32_bf16 v[116:119], v[160:163], v[176:179], v[116:119]
	v_mfma_f32_16x16x32_bf16 v[108:111], v[168:171], v[176:179], v[108:111]
	v_mfma_f32_16x16x32_bf16 v[100:103], v[160:163], v[192:195], v[100:103]
	v_mfma_f32_16x16x32_bf16 v[92:95], v[168:171], v[192:195], v[92:95]
	v_mfma_f32_16x16x32_bf16 v[84:87], v[160:163], v[200:203], v[84:87]
	v_mfma_f32_16x16x32_bf16 v[76:79], v[168:171], v[200:203], v[76:79]
	v_mfma_f32_16x16x32_bf16 v[68:71], v[160:163], v[218:221], v[68:71]
	v_mfma_f32_16x16x32_bf16 v[64:67], v[168:171], v[218:221], v[64:67]
	v_mfma_f32_16x16x32_bf16 v[116:119], v[164:167], v[180:183], v[116:119]
	v_mfma_f32_16x16x32_bf16 v[108:111], v[172:175], v[180:183], v[108:111]
	v_mfma_f32_16x16x32_bf16 v[100:103], v[164:167], v[196:199], v[100:103]
	v_mfma_f32_16x16x32_bf16 v[92:95], v[172:175], v[196:199], v[92:95]
	v_mfma_f32_16x16x32_bf16 v[84:87], v[164:167], v[204:207], v[84:87]
	v_mfma_f32_16x16x32_bf16 v[76:79], v[172:175], v[204:207], v[76:79]
	v_mfma_f32_16x16x32_bf16 v[68:71], v[164:167], v[222:225], v[68:71]
	s_barrier
; #define PG8_STAGE(bufoff, gbase, voff) do { _Pragma("unroll") for (int _i = 0; _i < 2; ++_i) \
;         __builtin_amdgcn_global_load_lds((const unsigned*)((const char*)(gbase) + (voff)[_i]), (PG8_LAS unsigned*)(lds + (bufoff) + ldsw + _i * 8192), 16, 0, 0); } while (0)
; #define PG8_LDA(dst, b, h) do { _Pragma("unroll") for (int m = 0; m < 4; ++m) _Pragma("unroll") for (int k = 0; k < 2; ++k) dst[m][k] = *(const PG8_LAS bf16x8*)(lds + PG8_SA(b, h) + aoff + m * 2048 + k * 1024); } while (0)
; #define PG8_LDB(dst, b, h) do { _Pragma("unroll") for (int n = 0; n < 2; ++n) _Pragma("unroll") for (int k = 0; k < 2; ++k) dst[n][k] = *(const PG8_LAS bf16x8*)(lds + PG8_SB(b, h) + boff + n * 2048 + k * 1024); } while (0)
; #define PG8_MMA(ai, bj, At, Bt) do { __builtin_amdgcn_s_setprio(1); _Pragma("unroll") for (int m = 0; m < 4; ++m) _Pragma("unroll") for (int n = 0; n < 2; ++n) _Pragma("unroll") for (int k = 0; k < 2; ++k) \
;         acc[ai][bj][m][n] = __builtin_amdgcn_mfma_f32_16x16x32_bf16(Bt[n][k], At[m][k], acc[ai][bj][m][n], 0, 0, 0); __builtin_amdgcn_s_setprio(0); } while (0)
; #define PG8_WAIT_V(n) asm volatile("s_waitcnt vmcnt(" #n ")" ::: "memory")
; #define PG8_WAIT_L(n) asm volatile("s_waitcnt lgkmcnt(" #n ")" ::: "memory")
; #define PG8_BAR __builtin_amdgcn_s_barrier()
; #define PG8_SCHED __builtin_amdgcn_sched_barrier(0)
;     ...
;             PG8_LDB(B0, 0, 0); PG8_LDB(B1, 0, 1); PG8_SCHED; PG8_LDA(At, 0, 0); PG8_STAGE(PG8_SA(1, 1), a1 + hstepA, voffA);
;             PG8_WAIT_V(8); PG8_WAIT_L(0); PG8_BAR; PG8_MMA(0, 0, At, B0); PG8_MMA(0, 1, At, B1); PG8_BAR; PG8_SCHED;
;             PG8_LDA(At, 0, 1); PG8_STAGE(PG8_SB(0, 0), b2, voffB); PG8_STAGE(PG8_SB(0, 1), b2 + hstepB, voffB); PG8_STAGE(PG8_SA(0, 0), a2, voffA);
;             PG8_WAIT_V(8); PG8_WAIT_L(0); PG8_BAR; PG8_MMA(1, 0, At, B0); PG8_MMA(1, 1, At, B1); PG8_BAR; PG8_SCHED;
;             PG8_LDB(B0, 1, 0); PG8_LDB(B1, 1, 1); PG8_SCHED; PG8_LDA(At, 1, 0); PG8_STAGE(PG8_SA(0, 1), a2 + hstepA, voffA);
;             PG8_WAIT_V(8); PG8_WAIT_L(0); PG8_BAR; PG8_MMA(0, 0, At, B0); PG8_MMA(0, 1, At, B1); PG8_BAR; PG8_SCHED;
;             PG8_LDA(At, 1, 1); PG8_STAGE(PG8_SB(1, 0), b3, voffB); PG8_STAGE(PG8_SB(1, 1), b3 + hstepB, voffB); PG8_STAGE(PG8_SA(1, 0), a3, voffA);
;             PG8_WAIT_V(8); PG8_WAIT_L(0); PG8_BAR; PG8_MMA(1, 0, At, B0); PG8_MMA(1, 1, At, B1); PG8_BAR; PG8_SCHED;
	v_mfma_f32_16x16x32_bf16 v[64:67], v[172:175], v[222:225], v[64:67]
	s_setprio 0
	s_add_i32 s26, s63, s48
	v_lshl_add_u64 v[238:239], v[238:239], 0, s[68:69]
	s_mov_b32 m0, s26
	ds_read_b128 v[176:179], v190 offset:49152
	ds_read_b128 v[180:183], v190 offset:50176
	ds_read_b128 v[192:195], v190 offset:51200
	ds_read_b128 v[196:199], v190 offset:52224
	ds_read_b128 v[200:203], v190 offset:53248
	ds_read_b128 v[204:207], v190 offset:54272
	ds_read_b128 v[218:221], v190 offset:55296
	ds_read_b128 v[222:225], v190 offset:56320
	global_load_lds_dwordx4 v[238:239], off
	s_add_i32 m0, s26, 0x2000
	s_add_u32 s24, s24, 0x40080
	v_lshl_add_u64 v[238:239], v[240:241], 0, s[68:69]
	s_addc_u32 s25, s25, 0
	s_add_i32 s26, s64, s48
	global_load_lds_dwordx4 v[238:239], off
	v_lshl_add_u64 v[238:239], s[24:25], 0, v[148:149]
	s_mov_b32 m0, s26
	s_nop 0
	global_load_lds_dwordx4 v[238:239], off
	v_lshl_add_u64 v[238:239], s[24:25], 0, v[144:145]
	s_add_i32 m0, s26, 0x2000
	s_nop 0
	global_load_lds_dwordx4 v[238:239], off
	v_lshl_add_u64 v[238:239], s[20:21], 0, v[150:151]
	s_mov_b32 m0, s53
	s_nop 0
	global_load_lds_dwordx4 v[238:239], off
	v_lshl_add_u64 v[238:239], s[20:21], 0, v[146:147]
	s_mov_b32 m0, s54
	s_nop 0
	global_load_lds_dwordx4 v[238:239], off
	s_waitcnt vmcnt(8)
	s_waitcnt lgkmcnt(0)
	s_barrier
	s_setprio 1
	s_waitcnt lgkmcnt(0)
	v_mfma_f32_16x16x32_bf16 v[60:63], v[132:135], v[176:179], v[60:63]
	v_mfma_f32_16x16x32_bf16 v[56:59], v[140:143], v[176:179], v[56:59]
	v_mfma_f32_16x16x32_bf16 v[48:51], v[132:135], v[192:195], v[48:51]
	v_mfma_f32_16x16x32_bf16 v[40:43], v[140:143], v[192:195], v[40:43]
	v_mfma_f32_16x16x32_bf16 v[32:35], v[132:135], v[200:203], v[32:35]
	v_mfma_f32_16x16x32_bf16 v[24:27], v[140:143], v[200:203], v[24:27]
	v_mfma_f32_16x16x32_bf16 v[16:19], v[132:135], v[218:221], v[16:19]
	v_mfma_f32_16x16x32_bf16 v[8:11], v[140:143], v[218:221], v[8:11]
	v_mfma_f32_16x16x32_bf16 v[60:63], v[136:139], v[180:183], v[60:63]
	v_mfma_f32_16x16x32_bf16 v[56:59], v[156:159], v[180:183], v[56:59]
	v_mfma_f32_16x16x32_bf16 v[48:51], v[136:139], v[196:199], v[48:51]
	v_mfma_f32_16x16x32_bf16 v[40:43], v[156:159], v[196:199], v[40:43]
	v_mfma_f32_16x16x32_bf16 v[32:35], v[136:139], v[204:207], v[32:35]
	v_mfma_f32_16x16x32_bf16 v[24:27], v[156:159], v[204:207], v[24:27]
	v_mfma_f32_16x16x32_bf16 v[16:19], v[136:139], v[222:225], v[16:19]
	v_mfma_f32_16x16x32_bf16 v[8:11], v[156:159], v[222:225], v[8:11]
	s_setprio 0
	s_setprio 1
	v_mfma_f32_16x16x32_bf16 v[52:55], v[160:163], v[176:179], v[52:55]
	v_mfma_f32_16x16x32_bf16 v[44:47], v[168:171], v[176:179], v[44:47]
	v_mfma_f32_16x16x32_bf16 v[36:39], v[160:163], v[192:195], v[36:39]
	v_mfma_f32_16x16x32_bf16 v[28:31], v[168:171], v[192:195], v[28:31]
	v_mfma_f32_16x16x32_bf16 v[20:23], v[160:163], v[200:203], v[20:23]
	v_mfma_f32_16x16x32_bf16 v[12:15], v[168:171], v[200:203], v[12:15]
	v_mfma_f32_16x16x32_bf16 v[4:7], v[160:163], v[218:221], v[4:7]
	v_mfma_f32_16x16x32_bf16 v[0:3], v[168:171], v[218:221], v[0:3]
	v_mfma_f32_16x16x32_bf16 v[52:55], v[164:167], v[180:183], v[52:55]
	v_mfma_f32_16x16x32_bf16 v[44:47], v[172:175], v[180:183], v[44:47]
	v_mfma_f32_16x16x32_bf16 v[36:39], v[164:167], v[196:199], v[36:39]
	v_mfma_f32_16x16x32_bf16 v[28:31], v[172:175], v[196:199], v[28:31]
	v_mfma_f32_16x16x32_bf16 v[20:23], v[164:167], v[204:207], v[20:23]
	v_mfma_f32_16x16x32_bf16 v[12:15], v[172:175], v[204:207], v[12:15]
	v_mfma_f32_16x16x32_bf16 v[4:7], v[164:167], v[222:225], v[4:7]
	s_barrier
	v_mfma_f32_16x16x32_bf16 v[0:3], v[172:175], v[222:225], v[0:3]
	s_setprio 0
	s_add_i32 s62, s62, 2
	s_add_u32 s2, s2, 0x100
	s_addc_u32 s3, s3, 0
	s_cmp_gt_u32 s62, 13
	s_cbranch_scc0 .LBB0_702

; #define PG8_STAGE(bufoff, gbase, voff) do { _Pragma("unroll") for (int _i = 0; _i < 2; ++_i) \
;         __builtin_amdgcn_global_load_lds((const unsigned*)((const char*)(gbase) + (voff)[_i]), (PG8_LAS unsigned*)(lds + (bufoff) + ldsw + _i * 8192), 16, 0, 0); } while (0)
; #define PG8_LDA(dst, b, h) do { _Pragma("unroll") for (int m = 0; m < 4; ++m) _Pragma("unroll") for (int k = 0; k < 2; ++k) dst[m][k] = *(const PG8_LAS bf16x8*)(lds + PG8_SA(b, h) + aoff + m * 2048 + k * 1024); } while (0)
; #define PG8_LDB(dst, b, h) do { _Pragma("unroll") for (int n = 0; n < 2; ++n) _Pragma("unroll") for (int k = 0; k < 2; ++k) dst[n][k] = *(const PG8_LAS bf16x8*)(lds + PG8_SB(b, h) + boff + n * 2048 + k * 1024); } while (0)
; #define PG8_MMA(ai, bj, At, Bt) do { __builtin_amdgcn_s_setprio(1); _Pragma("unroll") for (int m = 0; m < 4; ++m) _Pragma("unroll") for (int n = 0; n < 2; ++n) _Pragma("unroll") for (int k = 0; k < 2; ++k) \
;         acc[ai][bj][m][n] = __builtin_amdgcn_mfma_f32_16x16x32_bf16(Bt[n][k], At[m][k], acc[ai][bj][m][n], 0, 0, 0); __builtin_amdgcn_s_setprio(0); } while (0)
; #define PG8_WAIT_V(n) asm volatile("s_waitcnt vmcnt(" #n ")" ::: "memory")
; #define PG8_WAIT_L(n) asm volatile("s_waitcnt lgkmcnt(" #n ")" ::: "memory")
; #define PG8_BAR __builtin_amdgcn_s_barrier()
; #define PG8_SCHED __builtin_amdgcn_sched_barrier(0)
;     ...
;             PG8_LDB(B0, 0, 0); PG8_LDB(B1, 0, 1); PG8_SCHED; PG8_LDA(At, 0, 0); PG8_STAGE(PG8_SA(1, 1), a1 + hstepA, voffA);
;             PG8_WAIT_V(8); PG8_WAIT_L(0); PG8_BAR; PG8_MMA(0, 0, At, B0); PG8_MMA(0, 1, At, B1); PG8_BAR; PG8_SCHED;
;             PG8_LDA(At, 0, 1); PG8_STAGE(PG8_SB(0, 0), b2, voffB); PG8_STAGE(PG8_SB(0, 1), b2 + hstepB, voffB); PG8_STAGE(PG8_SA(0, 0), a2, voffA);
;             PG8_WAIT_V(8); PG8_WAIT_L(0); PG8_BAR; PG8_MMA(1, 0, At, B0); PG8_MMA(1, 1, At, B1); PG8_BAR; PG8_SCHED;
;             PG8_LDB(B0, 1, 0); PG8_LDB(B1, 1, 1); PG8_SCHED; PG8_LDA(At, 1, 0); PG8_STAGE(PG8_SA(0, 1), a2 + hstepA, voffA);
;             PG8_WAIT_V(8); PG8_WAIT_L(0); PG8_BAR; PG8_MMA(0, 0, At, B0); PG8_MMA(0, 1, At, B1); PG8_BAR; PG8_SCHED;
;             PG8_LDA(At, 1, 1); PG8_STAGE(PG8_SB(1, 0), b3, voffB); PG8_STAGE(PG8_SB(1, 1), b3 + hstepB, voffB); PG8_STAGE(PG8_SA(1, 0), a3, voffA);
;             PG8_WAIT_V(8); PG8_WAIT_L(0); PG8_BAR; PG8_MMA(1, 0, At, B0); PG8_MMA(1, 1, At, B1); PG8_BAR; PG8_SCHED;
.Lpeel_785:
	s_add_u32 s24, s9, s14
	s_addc_u32 s25, s47, 0
	s_xor_b32 s15, s14, 0x100
	s_add_u32 s15, s9, s15
	s_addc_u32 s20, s47, 0
	s_and_b64 s[18:19], s[16:17], exec
	s_cselect_b32 s21, s49, s20
	s_cselect_b32 s20, s48, s15
	s_add_u32 s15, s52, s14
	s_addc_u32 s18, s53, 0
	s_add_u32 s15, s15, 0x100
	s_addc_u32 s22, s18, 0
	s_and_b64 s[18:19], s[16:17], exec
	s_cselect_b32 s23, s46, s22
	s_cselect_b32 s22, s45, s15
	s_addk_i32 s14, 0x180
	s_and_b32 s14, s14, 0x180
	s_add_u32 s18, s9, s14
	s_addc_u32 s19, s47, 0
	s_and_b64 s[14:15], s[16:17], exec
	s_cselect_b32 s14, s50, s18
	s_cselect_b32 s15, s51, s19
	s_add_i32 s17, 0, 0x10000
	s_add_i32 s62, 0, 0x14000
	s_add_u32 s26, s24, 0x10080
	s_addc_u32 s27, s25, 0
	s_add_i32 s61, s17, s30
	s_add_i32 m0, s31, 0xc000
	s_add_i32 s64, s31, 0xe000
	s_add_i32 s58, s61, 0x2000
	v_add_u32_e32 v140, s17, v159
	s_add_u32 s24, s22, 0x10000
	ds_read_b128 v[162:165], v140
	ds_read_b128 v[166:169], v140 offset:1024
	ds_read_b128 v[170:173], v140 offset:2048
	ds_read_b128 v[174:177], v140 offset:3072
	v_add_u32_e32 v140, s62, v159
	s_addc_u32 s25, s23, 0
	s_add_i32 s60, s62, s30
	ds_read_b128 v[178:181], v140
	ds_read_b128 v[182:185], v140 offset:1024
	ds_read_b128 v[186:189], v140 offset:2048
	ds_read_b128 v[190:193], v140 offset:3072
	s_add_i32 s59, s60, 0x2000
	s_add_i32 s57, 0, 0x18000
	s_add_i32 s56, 0, 0x1c000
	s_add_u32 s18, s20, 0x10000
	s_addc_u32 s19, s21, 0
	s_add_i32 s55, s57, s30
	s_add_i32 s54, s55, 0x2000
	s_add_u32 s16, s22, 0x10080
	s_addc_u32 s17, s23, 0
	s_add_i32 s63, s56, s30
	s_add_i32 s62, s63, 0x2000
	v_lshl_add_u64 v[140:141], s[26:27], 0, v[128:129]
	ds_read_b128 v[194:197], v160
	ds_read_b128 v[198:201], v160 offset:1024
	ds_read_b128 v[202:205], v160 offset:2048
	ds_read_b128 v[218:221], v160 offset:3072
	ds_read_b128 v[222:225], v160 offset:4096
	ds_read_b128 v[238:241], v160 offset:5120
	ds_read_b128 v[242:245], v160 offset:6144
	ds_read_b128 v[246:249], v160 offset:7168
	global_load_lds_dwordx4 v[140:141], off
	v_lshl_add_u64 v[140:141], s[26:27], 0, v[130:131]
	s_mov_b32 m0, s64
	s_nop 0
	global_load_lds_dwordx4 v[140:141], off
	s_waitcnt vmcnt(8)
	s_waitcnt lgkmcnt(0)
	s_barrier
	s_setprio 1
	s_waitcnt lgkmcnt(0)
	v_mfma_f32_16x16x32_bf16 v[124:127], v[162:165], v[194:197], 0
	v_mfma_f32_16x16x32_bf16 v[120:123], v[170:173], v[194:197], 0
	v_mfma_f32_16x16x32_bf16 v[116:119], v[162:165], v[202:205], 0
	v_mfma_f32_16x16x32_bf16 v[108:111], v[170:173], v[202:205], 0
	v_mfma_f32_16x16x32_bf16 v[100:103], v[162:165], v[222:225], 0
	v_mfma_f32_16x16x32_bf16 v[92:95], v[170:173], v[222:225], 0
	v_mfma_f32_16x16x32_bf16 v[84:87], v[162:165], v[242:245], 0
	v_mfma_f32_16x16x32_bf16 v[76:79], v[170:173], v[242:245], 0
	v_mfma_f32_16x16x32_bf16 v[124:127], v[166:169], v[198:201], v[124:127]
	v_mfma_f32_16x16x32_bf16 v[120:123], v[174:177], v[198:201], v[120:123]
	v_mfma_f32_16x16x32_bf16 v[116:119], v[166:169], v[218:221], v[116:119]
	v_mfma_f32_16x16x32_bf16 v[108:111], v[174:177], v[218:221], v[108:111]
	v_mfma_f32_16x16x32_bf16 v[100:103], v[166:169], v[238:241], v[100:103]
	v_mfma_f32_16x16x32_bf16 v[92:95], v[174:177], v[238:241], v[92:95]
	v_mfma_f32_16x16x32_bf16 v[84:87], v[166:169], v[246:249], v[84:87]
	v_mfma_f32_16x16x32_bf16 v[76:79], v[174:177], v[246:249], v[76:79]
	s_setprio 0
	s_setprio 1
	v_mfma_f32_16x16x32_bf16 v[112:115], v[178:181], v[194:197], 0
	v_mfma_f32_16x16x32_bf16 v[104:107], v[186:189], v[194:197], 0
	v_mfma_f32_16x16x32_bf16 v[96:99], v[178:181], v[202:205], 0
	v_mfma_f32_16x16x32_bf16 v[88:91], v[186:189], v[202:205], 0
	v_mfma_f32_16x16x32_bf16 v[80:83], v[178:181], v[222:225], 0
	v_mfma_f32_16x16x32_bf16 v[72:75], v[186:189], v[222:225], 0
	v_mfma_f32_16x16x32_bf16 v[68:71], v[178:181], v[242:245], 0
	v_mfma_f32_16x16x32_bf16 v[64:67], v[186:189], v[242:245], 0
	v_mfma_f32_16x16x32_bf16 v[112:115], v[182:185], v[198:201], v[112:115]
	v_mfma_f32_16x16x32_bf16 v[104:107], v[190:193], v[198:201], v[104:107]
	v_mfma_f32_16x16x32_bf16 v[96:99], v[182:185], v[218:221], v[96:99]
	v_mfma_f32_16x16x32_bf16 v[88:91], v[190:193], v[218:221], v[88:91]
	v_mfma_f32_16x16x32_bf16 v[80:83], v[182:185], v[238:241], v[80:83]
	v_mfma_f32_16x16x32_bf16 v[72:75], v[190:193], v[238:241], v[72:75]
	v_mfma_f32_16x16x32_bf16 v[68:71], v[182:185], v[246:249], v[68:71]
	s_barrier
	v_mfma_f32_16x16x32_bf16 v[64:67], v[190:193], v[246:249], v[64:67]
	s_setprio 0
	s_mov_b32 m0, s61
	v_lshl_add_u64 v[140:141], s[22:23], 0, v[134:135]
	ds_read_b128 v[194:197], v160 offset:16384
	ds_read_b128 v[198:201], v160 offset:17408
	ds_read_b128 v[202:205], v160 offset:18432
	ds_read_b128 v[218:221], v160 offset:19456
	ds_read_b128 v[222:225], v160 offset:20480
	ds_read_b128 v[238:241], v160 offset:21504
	ds_read_b128 v[242:245], v160 offset:22528
	ds_read_b128 v[246:249], v160 offset:23552
	global_load_lds_dwordx4 v[140:141], off
	v_lshl_add_u64 v[206:207], s[22:23], 0, v[132:133]
	s_mov_b32 m0, s58
	v_lshl_add_u64 v[250:251], s[24:25], 0, v[134:135]
	global_load_lds_dwordx4 v[206:207], off
	s_mov_b32 m0, s60
	s_nop 0
	global_load_lds_dwordx4 v[250:251], off
	v_lshl_add_u64 v[250:251], s[24:25], 0, v[132:133]
	s_mov_b32 m0, s59
	s_nop 0
	global_load_lds_dwordx4 v[250:251], off
	v_lshl_add_u64 v[250:251], s[20:21], 0, v[128:129]
	s_mov_b32 m0, s31
	s_nop 0
	global_load_lds_dwordx4 v[250:251], off
	v_lshl_add_u64 v[250:251], s[20:21], 0, v[130:131]
	s_mov_b32 m0, s35
	s_nop 0
	global_load_lds_dwordx4 v[250:251], off
	s_waitcnt vmcnt(8)
	s_waitcnt lgkmcnt(0)
	s_barrier
; #define PG8_STAGE(bufoff, gbase, voff) do { _Pragma("unroll") for (int _i = 0; _i < 2; ++_i) \
;         __builtin_amdgcn_global_load_lds((const unsigned*)((const char*)(gbase) + (voff)[_i]), (PG8_LAS unsigned*)(lds + (bufoff) + ldsw + _i * 8192), 16, 0, 0); } while (0)
; #define PG8_LDA(dst, b, h) do { _Pragma("unroll") for (int m = 0; m < 4; ++m) _Pragma("unroll") for (int k = 0; k < 2; ++k) dst[m][k] = *(const PG8_LAS bf16x8*)(lds + PG8_SA(b, h) + aoff + m * 2048 + k * 1024); } while (0)
; #define PG8_LDB(dst, b, h) do { _Pragma("unroll") for (int n = 0; n < 2; ++n) _Pragma("unroll") for (int k = 0; k < 2; ++k) dst[n][k] = *(const PG8_LAS bf16x8*)(lds + PG8_SB(b, h) + boff + n * 2048 + k * 1024); } while (0)
; #define PG8_MMA(ai, bj, At, Bt) do { __builtin_amdgcn_s_setprio(1); _Pragma("unroll") for (int m = 0; m < 4; ++m) _Pragma("unroll") for (int n = 0; n < 2; ++n) _Pragma("unroll") for (int k = 0; k < 2; ++k) \
;         acc[ai][bj][m][n] = __builtin_amdgcn_mfma_f32_16x16x32_bf16(Bt[n][k], At[m][k], acc[ai][bj][m][n], 0, 0, 0); __builtin_amdgcn_s_setprio(0); } while (0)
; #define PG8_WAIT_V(n) asm volatile("s_waitcnt vmcnt(" #n ")" ::: "memory")
; #define PG8_WAIT_L(n) asm volatile("s_waitcnt lgkmcnt(" #n ")" ::: "memory")
; #define PG8_BAR __builtin_amdgcn_s_barrier()
; #define PG8_SCHED __builtin_amdgcn_sched_barrier(0)
;     ...
;             PG8_LDB(B0, 0, 0); PG8_LDB(B1, 0, 1); PG8_SCHED; PG8_LDA(At, 0, 0); PG8_STAGE(PG8_SA(1, 1), a1 + hstepA, voffA);
;             PG8_WAIT_V(8); PG8_WAIT_L(0); PG8_BAR; PG8_MMA(0, 0, At, B0); PG8_MMA(0, 1, At, B1); PG8_BAR; PG8_SCHED;
;             PG8_LDA(At, 0, 1); PG8_STAGE(PG8_SB(0, 0), b2, voffB); PG8_STAGE(PG8_SB(0, 1), b2 + hstepB, voffB); PG8_STAGE(PG8_SA(0, 0), a2, voffA);
;             PG8_WAIT_V(8); PG8_WAIT_L(0); PG8_BAR; PG8_MMA(1, 0, At, B0); PG8_MMA(1, 1, At, B1); PG8_BAR; PG8_SCHED;
;             PG8_LDB(B0, 1, 0); PG8_LDB(B1, 1, 1); PG8_SCHED; PG8_LDA(At, 1, 0); PG8_STAGE(PG8_SA(0, 1), a2 + hstepA, voffA);
;             PG8_WAIT_V(8); PG8_WAIT_L(0); PG8_BAR; PG8_MMA(0, 0, At, B0); PG8_MMA(0, 1, At, B1); PG8_BAR; PG8_SCHED;
;             PG8_LDA(At, 1, 1); PG8_STAGE(PG8_SB(1, 0), b3, voffB); PG8_STAGE(PG8_SB(1, 1), b3 + hstepB, voffB); PG8_STAGE(PG8_SA(1, 0), a3, voffA);
;             PG8_WAIT_V(8); PG8_WAIT_L(0); PG8_BAR; PG8_MMA(1, 0, At, B0); PG8_MMA(1, 1, At, B1); PG8_BAR; PG8_SCHED;
	s_setprio 1
	s_waitcnt lgkmcnt(0)
	v_mfma_f32_16x16x32_bf16 v[60:63], v[162:165], v[194:197], 0
	v_mfma_f32_16x16x32_bf16 v[56:59], v[170:173], v[194:197], 0
	v_mfma_f32_16x16x32_bf16 v[52:55], v[162:165], v[202:205], 0
	v_mfma_f32_16x16x32_bf16 v[44:47], v[170:173], v[202:205], 0
	v_mfma_f32_16x16x32_bf16 v[36:39], v[162:165], v[222:225], 0
	v_mfma_f32_16x16x32_bf16 v[28:31], v[170:173], v[222:225], 0
	v_mfma_f32_16x16x32_bf16 v[20:23], v[162:165], v[242:245], 0
	v_mfma_f32_16x16x32_bf16 v[12:15], v[170:173], v[242:245], 0
	v_mfma_f32_16x16x32_bf16 v[60:63], v[166:169], v[198:201], v[60:63]
	v_mfma_f32_16x16x32_bf16 v[56:59], v[174:177], v[198:201], v[56:59]
	v_mfma_f32_16x16x32_bf16 v[52:55], v[166:169], v[218:221], v[52:55]
	v_mfma_f32_16x16x32_bf16 v[44:47], v[174:177], v[218:221], v[44:47]
	v_mfma_f32_16x16x32_bf16 v[36:39], v[166:169], v[238:241], v[36:39]
	v_mfma_f32_16x16x32_bf16 v[28:31], v[174:177], v[238:241], v[28:31]
	v_mfma_f32_16x16x32_bf16 v[20:23], v[166:169], v[246:249], v[20:23]
	v_mfma_f32_16x16x32_bf16 v[12:15], v[174:177], v[246:249], v[12:15]
	s_setprio 0
	s_setprio 1
	v_mfma_f32_16x16x32_bf16 v[48:51], v[178:181], v[194:197], 0
	v_mfma_f32_16x16x32_bf16 v[40:43], v[186:189], v[194:197], 0
	v_mfma_f32_16x16x32_bf16 v[32:35], v[178:181], v[202:205], 0
	v_mfma_f32_16x16x32_bf16 v[24:27], v[186:189], v[202:205], 0
	v_mfma_f32_16x16x32_bf16 v[16:19], v[178:181], v[222:225], 0
	v_mfma_f32_16x16x32_bf16 v[8:11], v[186:189], v[222:225], 0
	v_mfma_f32_16x16x32_bf16 v[4:7], v[178:181], v[242:245], 0
	v_mfma_f32_16x16x32_bf16 v[0:3], v[186:189], v[242:245], 0
	v_mfma_f32_16x16x32_bf16 v[48:51], v[182:185], v[198:201], v[48:51]
	v_mfma_f32_16x16x32_bf16 v[40:43], v[190:193], v[198:201], v[40:43]
	v_mfma_f32_16x16x32_bf16 v[32:35], v[182:185], v[218:221], v[32:35]
	v_mfma_f32_16x16x32_bf16 v[24:27], v[190:193], v[218:221], v[24:27]
	v_mfma_f32_16x16x32_bf16 v[16:19], v[182:185], v[238:241], v[16:19]
	v_mfma_f32_16x16x32_bf16 v[8:11], v[190:193], v[238:241], v[8:11]
	v_mfma_f32_16x16x32_bf16 v[4:7], v[182:185], v[246:249], v[4:7]
	s_barrier
	v_mfma_f32_16x16x32_bf16 v[0:3], v[190:193], v[246:249], v[0:3]
	s_setprio 0
	v_add_u32_e32 v161, s57, v159
	ds_read_b128 v[162:165], v161
	ds_read_b128 v[166:169], v161 offset:1024
	ds_read_b128 v[170:173], v161 offset:2048
	ds_read_b128 v[174:177], v161 offset:3072
	v_add_u32_e32 v161, s56, v159
	ds_read_b128 v[178:181], v161
	ds_read_b128 v[182:185], v161 offset:1024
	ds_read_b128 v[186:189], v161 offset:2048
	ds_read_b128 v[190:193], v161 offset:3072
	s_mov_b32 m0, s36
	v_lshl_add_u64 v[250:251], s[18:19], 0, v[128:129]
	ds_read_b128 v[194:197], v160 offset:32768
	ds_read_b128 v[198:201], v160 offset:33792
	ds_read_b128 v[202:205], v160 offset:34816
	ds_read_b128 v[218:221], v160 offset:35840
	ds_read_b128 v[222:225], v160 offset:36864
	ds_read_b128 v[238:241], v160 offset:37888
	ds_read_b128 v[242:245], v160 offset:38912
	ds_read_b128 v[246:249], v160 offset:39936
	global_load_lds_dwordx4 v[250:251], off
	v_lshl_add_u64 v[250:251], s[18:19], 0, v[130:131]
	s_mov_b32 m0, s37
	s_nop 0
	global_load_lds_dwordx4 v[250:251], off
	s_waitcnt vmcnt(8)
	s_waitcnt lgkmcnt(0)
	s_barrier
	s_setprio 1
	s_waitcnt lgkmcnt(0)
	v_mfma_f32_16x16x32_bf16 v[124:127], v[162:165], v[194:197], v[124:127]
	v_mfma_f32_16x16x32_bf16 v[120:123], v[170:173], v[194:197], v[120:123]
	v_mfma_f32_16x16x32_bf16 v[116:119], v[162:165], v[202:205], v[116:119]
	v_mfma_f32_16x16x32_bf16 v[108:111], v[170:173], v[202:205], v[108:111]
	v_mfma_f32_16x16x32_bf16 v[100:103], v[162:165], v[222:225], v[100:103]
	v_mfma_f32_16x16x32_bf16 v[92:95], v[170:173], v[222:225], v[92:95]
	v_mfma_f32_16x16x32_bf16 v[84:87], v[162:165], v[242:245], v[84:87]
	v_mfma_f32_16x16x32_bf16 v[76:79], v[170:173], v[242:245], v[76:79]
	v_mfma_f32_16x16x32_bf16 v[124:127], v[166:169], v[198:201], v[124:127]
	v_mfma_f32_16x16x32_bf16 v[120:123], v[174:177], v[198:201], v[120:123]
	v_mfma_f32_16x16x32_bf16 v[116:119], v[166:169], v[218:221], v[116:119]
	v_mfma_f32_16x16x32_bf16 v[108:111], v[174:177], v[218:221], v[108:111]
	v_mfma_f32_16x16x32_bf16 v[100:103], v[166:169], v[238:241], v[100:103]
	v_mfma_f32_16x16x32_bf16 v[92:95], v[174:177], v[238:241], v[92:95]
	v_mfma_f32_16x16x32_bf16 v[84:87], v[166:169], v[246:249], v[84:87]
	v_mfma_f32_16x16x32_bf16 v[76:79], v[174:177], v[246:249], v[76:79]
	s_setprio 0
	s_setprio 1
	v_mfma_f32_16x16x32_bf16 v[112:115], v[178:181], v[194:197], v[112:115]
	v_mfma_f32_16x16x32_bf16 v[104:107], v[186:189], v[194:197], v[104:107]
	v_mfma_f32_16x16x32_bf16 v[96:99], v[178:181], v[202:205], v[96:99]
	v_mfma_f32_16x16x32_bf16 v[88:91], v[186:189], v[202:205], v[88:91]
	v_mfma_f32_16x16x32_bf16 v[80:83], v[178:181], v[222:225], v[80:83]
	v_mfma_f32_16x16x32_bf16 v[72:75], v[186:189], v[222:225], v[72:75]
	v_mfma_f32_16x16x32_bf16 v[68:71], v[178:181], v[242:245], v[68:71]
	v_mfma_f32_16x16x32_bf16 v[64:67], v[186:189], v[242:245], v[64:67]
	v_mfma_f32_16x16x32_bf16 v[112:115], v[182:185], v[198:201], v[112:115]
	v_mfma_f32_16x16x32_bf16 v[104:107], v[190:193], v[198:201], v[104:107]
	v_mfma_f32_16x16x32_bf16 v[96:99], v[182:185], v[218:221], v[96:99]
	v_mfma_f32_16x16x32_bf16 v[88:91], v[190:193], v[218:221], v[88:91]
	v_mfma_f32_16x16x32_bf16 v[80:83], v[182:185], v[238:241], v[80:83]
	v_mfma_f32_16x16x32_bf16 v[72:75], v[190:193], v[238:241], v[72:75]
	v_mfma_f32_16x16x32_bf16 v[68:71], v[182:185], v[246:249], v[68:71]
	s_barrier
; #define PG8_STAGE(bufoff, gbase, voff) do { _Pragma("unroll") for (int _i = 0; _i < 2; ++_i) \
;         __builtin_amdgcn_global_load_lds((const unsigned*)((const char*)(gbase) + (voff)[_i]), (PG8_LAS unsigned*)(lds + (bufoff) + ldsw + _i * 8192), 16, 0, 0); } while (0)
; #define PG8_LDA(dst, b, h) do { _Pragma("unroll") for (int m = 0; m < 4; ++m) _Pragma("unroll") for (int k = 0; k < 2; ++k) dst[m][k] = *(const PG8_LAS bf16x8*)(lds + PG8_SA(b, h) + aoff + m * 2048 + k * 1024); } while (0)
; #define PG8_LDB(dst, b, h) do { _Pragma("unroll") for (int n = 0; n < 2; ++n) _Pragma("unroll") for (int k = 0; k < 2; ++k) dst[n][k] = *(const PG8_LAS bf16x8*)(lds + PG8_SB(b, h) + boff + n * 2048 + k * 1024); } while (0)
; #define PG8_MMA(ai, bj, At, Bt) do { __builtin_amdgcn_s_setprio(1); _Pragma("unroll") for (int m = 0; m < 4; ++m) _Pragma("unroll") for (int n = 0; n < 2; ++n) _Pragma("unroll") for (int k = 0; k < 2; ++k) \
;         acc[ai][bj][m][n] = __builtin_amdgcn_mfma_f32_16x16x32_bf16(Bt[n][k], At[m][k], acc[ai][bj][m][n], 0, 0, 0); __builtin_amdgcn_s_setprio(0); } while (0)
; #define PG8_WAIT_V(n) asm volatile("s_waitcnt vmcnt(" #n ")" ::: "memory")
; #define PG8_WAIT_L(n) asm volatile("s_waitcnt lgkmcnt(" #n ")" ::: "memory")
; #define PG8_BAR __builtin_amdgcn_s_barrier()
; #define PG8_SCHED __builtin_amdgcn_sched_barrier(0)
;     ...
;             PG8_LDB(B0, 0, 0); PG8_LDB(B1, 0, 1); PG8_SCHED; PG8_LDA(At, 0, 0); PG8_STAGE(PG8_SA(1, 1), a1 + hstepA, voffA);
;             PG8_WAIT_V(8); PG8_WAIT_L(0); PG8_BAR; PG8_MMA(0, 0, At, B0); PG8_MMA(0, 1, At, B1); PG8_BAR; PG8_SCHED;
;             PG8_LDA(At, 0, 1); PG8_STAGE(PG8_SB(0, 0), b2, voffB); PG8_STAGE(PG8_SB(0, 1), b2 + hstepB, voffB); PG8_STAGE(PG8_SA(0, 0), a2, voffA);
;             PG8_WAIT_V(8); PG8_WAIT_L(0); PG8_BAR; PG8_MMA(1, 0, At, B0); PG8_MMA(1, 1, At, B1); PG8_BAR; PG8_SCHED;
;             PG8_LDB(B0, 1, 0); PG8_LDB(B1, 1, 1); PG8_SCHED; PG8_LDA(At, 1, 0); PG8_STAGE(PG8_SA(0, 1), a2 + hstepA, voffA);
;             PG8_WAIT_V(8); PG8_WAIT_L(0); PG8_BAR; PG8_MMA(0, 0, At, B0); PG8_MMA(0, 1, At, B1); PG8_BAR; PG8_SCHED;
;             PG8_LDA(At, 1, 1); PG8_STAGE(PG8_SB(1, 0), b3, voffB); PG8_STAGE(PG8_SB(1, 1), b3 + hstepB, voffB); PG8_STAGE(PG8_SA(1, 0), a3, voffA);
;             PG8_WAIT_V(8); PG8_WAIT_L(0); PG8_BAR; PG8_MMA(1, 0, At, B0); PG8_MMA(1, 1, At, B1); PG8_BAR; PG8_SCHED;
	v_mfma_f32_16x16x32_bf16 v[64:67], v[190:193], v[246:249], v[64:67]
	s_setprio 0
	s_mov_b32 m0, s55
	v_lshl_add_u64 v[140:141], v[140:141], 0, s[66:67]
	ds_read_b128 v[194:197], v160 offset:49152
	ds_read_b128 v[198:201], v160 offset:50176
	ds_read_b128 v[202:205], v160 offset:51200
	ds_read_b128 v[218:221], v160 offset:52224
	ds_read_b128 v[222:225], v160 offset:53248
	ds_read_b128 v[238:241], v160 offset:54272
	ds_read_b128 v[242:245], v160 offset:55296
	ds_read_b128 v[246:249], v160 offset:56320
	global_load_lds_dwordx4 v[140:141], off
	v_lshl_add_u64 v[140:141], v[206:207], 0, s[66:67]
	s_mov_b32 m0, s54
	s_nop 0
	global_load_lds_dwordx4 v[140:141], off
	v_lshl_add_u64 v[140:141], s[16:17], 0, v[134:135]
	s_mov_b32 m0, s63
	s_nop 0
	global_load_lds_dwordx4 v[140:141], off
	v_lshl_add_u64 v[140:141], s[16:17], 0, v[132:133]
	s_mov_b32 m0, s62
	s_nop 0
	global_load_lds_dwordx4 v[140:141], off
	v_lshl_add_u64 v[140:141], s[14:15], 0, v[128:129]
	s_mov_b32 m0, s40
	s_nop 0
	global_load_lds_dwordx4 v[140:141], off
	v_lshl_add_u64 v[140:141], s[14:15], 0, v[130:131]
	s_mov_b32 m0, s41
	s_nop 0
	global_load_lds_dwordx4 v[140:141], off
	s_waitcnt vmcnt(8)
	s_waitcnt lgkmcnt(0)
	s_barrier
	s_setprio 1
	s_waitcnt lgkmcnt(0)
	v_mfma_f32_16x16x32_bf16 v[60:63], v[162:165], v[194:197], v[60:63]
	v_mfma_f32_16x16x32_bf16 v[56:59], v[170:173], v[194:197], v[56:59]
	v_mfma_f32_16x16x32_bf16 v[52:55], v[162:165], v[202:205], v[52:55]
	v_mfma_f32_16x16x32_bf16 v[44:47], v[170:173], v[202:205], v[44:47]
	v_mfma_f32_16x16x32_bf16 v[36:39], v[162:165], v[222:225], v[36:39]
	v_mfma_f32_16x16x32_bf16 v[28:31], v[170:173], v[222:225], v[28:31]
	v_mfma_f32_16x16x32_bf16 v[20:23], v[162:165], v[242:245], v[20:23]
	v_mfma_f32_16x16x32_bf16 v[12:15], v[170:173], v[242:245], v[12:15]
	v_mfma_f32_16x16x32_bf16 v[60:63], v[166:169], v[198:201], v[60:63]
	v_mfma_f32_16x16x32_bf16 v[56:59], v[174:177], v[198:201], v[56:59]
	v_mfma_f32_16x16x32_bf16 v[52:55], v[166:169], v[218:221], v[52:55]
	v_mfma_f32_16x16x32_bf16 v[44:47], v[174:177], v[218:221], v[44:47]
	v_mfma_f32_16x16x32_bf16 v[36:39], v[166:169], v[238:241], v[36:39]
	v_mfma_f32_16x16x32_bf16 v[28:31], v[174:177], v[238:241], v[28:31]
	v_mfma_f32_16x16x32_bf16 v[20:23], v[166:169], v[246:249], v[20:23]
	v_mfma_f32_16x16x32_bf16 v[12:15], v[174:177], v[246:249], v[12:15]
	s_setprio 0
	s_setprio 1
	v_mfma_f32_16x16x32_bf16 v[48:51], v[178:181], v[194:197], v[48:51]
	v_mfma_f32_16x16x32_bf16 v[40:43], v[186:189], v[194:197], v[40:43]
	v_mfma_f32_16x16x32_bf16 v[32:35], v[178:181], v[202:205], v[32:35]
	v_mfma_f32_16x16x32_bf16 v[24:27], v[186:189], v[202:205], v[24:27]
	v_mfma_f32_16x16x32_bf16 v[16:19], v[178:181], v[222:225], v[16:19]
	v_mfma_f32_16x16x32_bf16 v[8:11], v[186:189], v[222:225], v[8:11]
	v_mfma_f32_16x16x32_bf16 v[4:7], v[178:181], v[242:245], v[4:7]
	v_mfma_f32_16x16x32_bf16 v[0:3], v[186:189], v[242:245], v[0:3]
	v_mfma_f32_16x16x32_bf16 v[48:51], v[182:185], v[198:201], v[48:51]
	v_mfma_f32_16x16x32_bf16 v[40:43], v[190:193], v[198:201], v[40:43]
	v_mfma_f32_16x16x32_bf16 v[32:35], v[182:185], v[218:221], v[32:35]
	v_mfma_f32_16x16x32_bf16 v[24:27], v[190:193], v[218:221], v[24:27]
	v_mfma_f32_16x16x32_bf16 v[16:19], v[182:185], v[238:241], v[16:19]
	v_mfma_f32_16x16x32_bf16 v[8:11], v[190:193], v[238:241], v[8:11]
	v_mfma_f32_16x16x32_bf16 v[4:7], v[182:185], v[246:249], v[4:7]
	s_barrier
	v_mfma_f32_16x16x32_bf16 v[0:3], v[190:193], v[246:249], v[0:3]
	s_setprio 0
	s_andn2_b64 vcc, exec, s[12:13]
	s_mov_b64 s[16:17], -1
	s_mov_b64 s[12:13], 0
	s_movk_i32 s14, 0x100
	s_cbranch_vccz .LBB0_785
	s_branch .Lpeel_exit_785
.LBB0_785:
	s_add_u32 s24, s9, s14
	s_addc_u32 s25, s47, 0
	s_xor_b32 s15, s14, 0x100
	s_add_u32 s15, s9, s15
	s_addc_u32 s20, s47, 0
	s_and_b64 s[18:19], s[16:17], exec
	s_cselect_b32 s21, s49, s20
	s_cselect_b32 s20, s48, s15
	s_add_u32 s15, s52, s14
	s_addc_u32 s18, s53, 0
	s_add_u32 s15, s15, 0x100
	s_addc_u32 s22, s18, 0
	s_and_b64 s[18:19], s[16:17], exec
	s_cselect_b32 s23, s46, s22
	s_cselect_b32 s22, s45, s15
	s_addk_i32 s14, 0x180
	s_and_b32 s14, s14, 0x180
	s_add_u32 s18, s9, s14
	s_addc_u32 s19, s47, 0
	s_and_b64 s[14:15], s[16:17], exec
	s_cselect_b32 s14, s50, s18
	s_cselect_b32 s15, s51, s19
	s_add_i32 s17, 0, 0x10000
	s_add_i32 s62, 0, 0x14000
	s_add_u32 s26, s24, 0x10080
	s_addc_u32 s27, s25, 0
	s_add_i32 s61, s17, s30
	s_add_i32 m0, s31, 0xc000
	s_add_i32 s64, s31, 0xe000
	s_add_i32 s58, s61, 0x2000
	v_add_u32_e32 v140, s17, v159
	s_add_u32 s24, s22, 0x10000
	ds_read_b128 v[162:165], v140
	ds_read_b128 v[166:169], v140 offset:1024
	ds_read_b128 v[170:173], v140 offset:2048
	ds_read_b128 v[174:177], v140 offset:3072
	v_add_u32_e32 v140, s62, v159
	s_addc_u32 s25, s23, 0
	s_add_i32 s60, s62, s30
	ds_read_b128 v[178:181], v140
	ds_read_b128 v[182:185], v140 offset:1024
	ds_read_b128 v[186:189], v140 offset:2048
	ds_read_b128 v[190:193], v140 offset:3072
	s_add_i32 s59, s60, 0x2000
	s_add_i32 s57, 0, 0x18000
	s_add_i32 s56, 0, 0x1c000
	s_add_u32 s18, s20, 0x10000
	s_addc_u32 s19, s21, 0
	s_add_i32 s55, s57, s30
	s_add_i32 s54, s55, 0x2000
	s_add_u32 s16, s22, 0x10080
	s_addc_u32 s17, s23, 0
	s_add_i32 s63, s56, s30
	s_add_i32 s62, s63, 0x2000
	v_lshl_add_u64 v[140:141], s[26:27], 0, v[128:129]
	ds_read_b128 v[194:197], v160
	ds_read_b128 v[198:201], v160 offset:1024
	ds_read_b128 v[202:205], v160 offset:2048
	ds_read_b128 v[218:221], v160 offset:3072
	ds_read_b128 v[222:225], v160 offset:4096
	ds_read_b128 v[238:241], v160 offset:5120
	ds_read_b128 v[242:245], v160 offset:6144
	ds_read_b128 v[246:249], v160 offset:7168
	global_load_lds_dwordx4 v[140:141], off
	v_lshl_add_u64 v[140:141], s[26:27], 0, v[130:131]
	s_mov_b32 m0, s64
	s_nop 0
	global_load_lds_dwordx4 v[140:141], off
	s_waitcnt vmcnt(8)
	s_waitcnt lgkmcnt(0)
	s_barrier
; #define PG8_STAGE(bufoff, gbase, voff) do { _Pragma("unroll") for (int _i = 0; _i < 2; ++_i) \
;         __builtin_amdgcn_global_load_lds((const unsigned*)((const char*)(gbase) + (voff)[_i]), (PG8_LAS unsigned*)(lds + (bufoff) + ldsw + _i * 8192), 16, 0, 0); } while (0)
; #define PG8_LDA(dst, b, h) do { _Pragma("unroll") for (int m = 0; m < 4; ++m) _Pragma("unroll") for (int k = 0; k < 2; ++k) dst[m][k] = *(const PG8_LAS bf16x8*)(lds + PG8_SA(b, h) + aoff + m * 2048 + k * 1024); } while (0)
; #define PG8_LDB(dst, b, h) do { _Pragma("unroll") for (int n = 0; n < 2; ++n) _Pragma("unroll") for (int k = 0; k < 2; ++k) dst[n][k] = *(const PG8_LAS bf16x8*)(lds + PG8_SB(b, h) + boff + n * 2048 + k * 1024); } while (0)
; #define PG8_MMA(ai, bj, At, Bt) do { __builtin_amdgcn_s_setprio(1); _Pragma("unroll") for (int m = 0; m < 4; ++m) _Pragma("unroll") for (int n = 0; n < 2; ++n) _Pragma("unroll") for (int k = 0; k < 2; ++k) \
;         acc[ai][bj][m][n] = __builtin_amdgcn_mfma_f32_16x16x32_bf16(Bt[n][k], At[m][k], acc[ai][bj][m][n], 0, 0, 0); __builtin_amdgcn_s_setprio(0); } while (0)
; #define PG8_WAIT_V(n) asm volatile("s_waitcnt vmcnt(" #n ")" ::: "memory")
; #define PG8_WAIT_L(n) asm volatile("s_waitcnt lgkmcnt(" #n ")" ::: "memory")
; #define PG8_BAR __builtin_amdgcn_s_barrier()
; #define PG8_SCHED __builtin_amdgcn_sched_barrier(0)
;     ...
;             PG8_LDB(B0, 0, 0); PG8_LDB(B1, 0, 1); PG8_SCHED; PG8_LDA(At, 0, 0); PG8_STAGE(PG8_SA(1, 1), a1 + hstepA, voffA);
;             PG8_WAIT_V(8); PG8_WAIT_L(0); PG8_BAR; PG8_MMA(0, 0, At, B0); PG8_MMA(0, 1, At, B1); PG8_BAR; PG8_SCHED;
;             PG8_LDA(At, 0, 1); PG8_STAGE(PG8_SB(0, 0), b2, voffB); PG8_STAGE(PG8_SB(0, 1), b2 + hstepB, voffB); PG8_STAGE(PG8_SA(0, 0), a2, voffA);
;             PG8_WAIT_V(8); PG8_WAIT_L(0); PG8_BAR; PG8_MMA(1, 0, At, B0); PG8_MMA(1, 1, At, B1); PG8_BAR; PG8_SCHED;
;             PG8_LDB(B0, 1, 0); PG8_LDB(B1, 1, 1); PG8_SCHED; PG8_LDA(At, 1, 0); PG8_STAGE(PG8_SA(0, 1), a2 + hstepA, voffA);
;             PG8_WAIT_V(8); PG8_WAIT_L(0); PG8_BAR; PG8_MMA(0, 0, At, B0); PG8_MMA(0, 1, At, B1); PG8_BAR; PG8_SCHED;
;             PG8_LDA(At, 1, 1); PG8_STAGE(PG8_SB(1, 0), b3, voffB); PG8_STAGE(PG8_SB(1, 1), b3 + hstepB, voffB); PG8_STAGE(PG8_SA(1, 0), a3, voffA);
;             PG8_WAIT_V(8); PG8_WAIT_L(0); PG8_BAR; PG8_MMA(1, 0, At, B0); PG8_MMA(1, 1, At, B1); PG8_BAR; PG8_SCHED;
	s_setprio 1
	s_waitcnt lgkmcnt(0)
	v_mfma_f32_16x16x32_bf16 v[124:127], v[162:165], v[194:197], v[124:127]
	v_mfma_f32_16x16x32_bf16 v[120:123], v[170:173], v[194:197], v[120:123]
	v_mfma_f32_16x16x32_bf16 v[116:119], v[162:165], v[202:205], v[116:119]
	v_mfma_f32_16x16x32_bf16 v[108:111], v[170:173], v[202:205], v[108:111]
	v_mfma_f32_16x16x32_bf16 v[100:103], v[162:165], v[222:225], v[100:103]
	v_mfma_f32_16x16x32_bf16 v[92:95], v[170:173], v[222:225], v[92:95]
	v_mfma_f32_16x16x32_bf16 v[84:87], v[162:165], v[242:245], v[84:87]
	v_mfma_f32_16x16x32_bf16 v[76:79], v[170:173], v[242:245], v[76:79]
	v_mfma_f32_16x16x32_bf16 v[124:127], v[166:169], v[198:201], v[124:127]
	v_mfma_f32_16x16x32_bf16 v[120:123], v[174:177], v[198:201], v[120:123]
	v_mfma_f32_16x16x32_bf16 v[116:119], v[166:169], v[218:221], v[116:119]
	v_mfma_f32_16x16x32_bf16 v[108:111], v[174:177], v[218:221], v[108:111]
	v_mfma_f32_16x16x32_bf16 v[100:103], v[166:169], v[238:241], v[100:103]
	v_mfma_f32_16x16x32_bf16 v[92:95], v[174:177], v[238:241], v[92:95]
	v_mfma_f32_16x16x32_bf16 v[84:87], v[166:169], v[246:249], v[84:87]
	v_mfma_f32_16x16x32_bf16 v[76:79], v[174:177], v[246:249], v[76:79]
	s_setprio 0
	s_setprio 1
	v_mfma_f32_16x16x32_bf16 v[112:115], v[178:181], v[194:197], v[112:115]
	v_mfma_f32_16x16x32_bf16 v[104:107], v[186:189], v[194:197], v[104:107]
	v_mfma_f32_16x16x32_bf16 v[96:99], v[178:181], v[202:205], v[96:99]
	v_mfma_f32_16x16x32_bf16 v[88:91], v[186:189], v[202:205], v[88:91]
	v_mfma_f32_16x16x32_bf16 v[80:83], v[178:181], v[222:225], v[80:83]
	v_mfma_f32_16x16x32_bf16 v[72:75], v[186:189], v[222:225], v[72:75]
	v_mfma_f32_16x16x32_bf16 v[68:71], v[178:181], v[242:245], v[68:71]
	v_mfma_f32_16x16x32_bf16 v[64:67], v[186:189], v[242:245], v[64:67]
	v_mfma_f32_16x16x32_bf16 v[112:115], v[182:185], v[198:201], v[112:115]
	v_mfma_f32_16x16x32_bf16 v[104:107], v[190:193], v[198:201], v[104:107]
	v_mfma_f32_16x16x32_bf16 v[96:99], v[182:185], v[218:221], v[96:99]
	v_mfma_f32_16x16x32_bf16 v[88:91], v[190:193], v[218:221], v[88:91]
	v_mfma_f32_16x16x32_bf16 v[80:83], v[182:185], v[238:241], v[80:83]
	v_mfma_f32_16x16x32_bf16 v[72:75], v[190:193], v[238:241], v[72:75]
	v_mfma_f32_16x16x32_bf16 v[68:71], v[182:185], v[246:249], v[68:71]
	s_barrier
	v_mfma_f32_16x16x32_bf16 v[64:67], v[190:193], v[246:249], v[64:67]
	s_setprio 0
	s_mov_b32 m0, s61
	v_lshl_add_u64 v[140:141], s[22:23], 0, v[134:135]
	ds_read_b128 v[194:197], v160 offset:16384
	ds_read_b128 v[198:201], v160 offset:17408
	ds_read_b128 v[202:205], v160 offset:18432
	ds_read_b128 v[218:221], v160 offset:19456
	ds_read_b128 v[222:225], v160 offset:20480
	ds_read_b128 v[238:241], v160 offset:21504
	ds_read_b128 v[242:245], v160 offset:22528
	ds_read_b128 v[246:249], v160 offset:23552
	global_load_lds_dwordx4 v[140:141], off
	v_lshl_add_u64 v[206:207], s[22:23], 0, v[132:133]
	s_mov_b32 m0, s58
	v_lshl_add_u64 v[250:251], s[24:25], 0, v[134:135]
	global_load_lds_dwordx4 v[206:207], off
	s_mov_b32 m0, s60
	s_nop 0
	global_load_lds_dwordx4 v[250:251], off
	v_lshl_add_u64 v[250:251], s[24:25], 0, v[132:133]
	s_mov_b32 m0, s59
	s_nop 0
	global_load_lds_dwordx4 v[250:251], off
	v_lshl_add_u64 v[250:251], s[20:21], 0, v[128:129]
	s_mov_b32 m0, s31
	s_nop 0
	global_load_lds_dwordx4 v[250:251], off
	v_lshl_add_u64 v[250:251], s[20:21], 0, v[130:131]
	s_mov_b32 m0, s35
	s_nop 0
	global_load_lds_dwordx4 v[250:251], off
	s_waitcnt vmcnt(8)
	s_waitcnt lgkmcnt(0)
	s_barrier
	s_setprio 1
	s_waitcnt lgkmcnt(0)
	v_mfma_f32_16x16x32_bf16 v[60:63], v[162:165], v[194:197], v[60:63]
	v_mfma_f32_16x16x32_bf16 v[56:59], v[170:173], v[194:197], v[56:59]
	v_mfma_f32_16x16x32_bf16 v[52:55], v[162:165], v[202:205], v[52:55]
	v_mfma_f32_16x16x32_bf16 v[44:47], v[170:173], v[202:205], v[44:47]
	v_mfma_f32_16x16x32_bf16 v[36:39], v[162:165], v[222:225], v[36:39]
	v_mfma_f32_16x16x32_bf16 v[28:31], v[170:173], v[222:225], v[28:31]
	v_mfma_f32_16x16x32_bf16 v[20:23], v[162:165], v[242:245], v[20:23]
	v_mfma_f32_16x16x32_bf16 v[12:15], v[170:173], v[242:245], v[12:15]
	v_mfma_f32_16x16x32_bf16 v[60:63], v[166:169], v[198:201], v[60:63]
	v_mfma_f32_16x16x32_bf16 v[56:59], v[174:177], v[198:201], v[56:59]
	v_mfma_f32_16x16x32_bf16 v[52:55], v[166:169], v[218:221], v[52:55]
	v_mfma_f32_16x16x32_bf16 v[44:47], v[174:177], v[218:221], v[44:47]
	v_mfma_f32_16x16x32_bf16 v[36:39], v[166:169], v[238:241], v[36:39]
	v_mfma_f32_16x16x32_bf16 v[28:31], v[174:177], v[238:241], v[28:31]
	v_mfma_f32_16x16x32_bf16 v[20:23], v[166:169], v[246:249], v[20:23]
	v_mfma_f32_16x16x32_bf16 v[12:15], v[174:177], v[246:249], v[12:15]
	s_setprio 0
	s_setprio 1
	v_mfma_f32_16x16x32_bf16 v[48:51], v[178:181], v[194:197], v[48:51]
	v_mfma_f32_16x16x32_bf16 v[40:43], v[186:189], v[194:197], v[40:43]
	v_mfma_f32_16x16x32_bf16 v[32:35], v[178:181], v[202:205], v[32:35]
	v_mfma_f32_16x16x32_bf16 v[24:27], v[186:189], v[202:205], v[24:27]
	v_mfma_f32_16x16x32_bf16 v[16:19], v[178:181], v[222:225], v[16:19]
	v_mfma_f32_16x16x32_bf16 v[8:11], v[186:189], v[222:225], v[8:11]
	v_mfma_f32_16x16x32_bf16 v[4:7], v[178:181], v[242:245], v[4:7]
	v_mfma_f32_16x16x32_bf16 v[0:3], v[186:189], v[242:245], v[0:3]
	v_mfma_f32_16x16x32_bf16 v[48:51], v[182:185], v[198:201], v[48:51]
	v_mfma_f32_16x16x32_bf16 v[40:43], v[190:193], v[198:201], v[40:43]
	v_mfma_f32_16x16x32_bf16 v[32:35], v[182:185], v[218:221], v[32:35]
	v_mfma_f32_16x16x32_bf16 v[24:27], v[190:193], v[218:221], v[24:27]
	v_mfma_f32_16x16x32_bf16 v[16:19], v[182:185], v[238:241], v[16:19]
	v_mfma_f32_16x16x32_bf16 v[8:11], v[190:193], v[238:241], v[8:11]
	v_mfma_f32_16x16x32_bf16 v[4:7], v[182:185], v[246:249], v[4:7]
	s_barrier
; #define PG8_STAGE(bufoff, gbase, voff) do { _Pragma("unroll") for (int _i = 0; _i < 2; ++_i) \
;         __builtin_amdgcn_global_load_lds((const unsigned*)((const char*)(gbase) + (voff)[_i]), (PG8_LAS unsigned*)(lds + (bufoff) + ldsw + _i * 8192), 16, 0, 0); } while (0)
; #define PG8_LDA(dst, b, h) do { _Pragma("unroll") for (int m = 0; m < 4; ++m) _Pragma("unroll") for (int k = 0; k < 2; ++k) dst[m][k] = *(const PG8_LAS bf16x8*)(lds + PG8_SA(b, h) + aoff + m * 2048 + k * 1024); } while (0)
; #define PG8_LDB(dst, b, h) do { _Pragma("unroll") for (int n = 0; n < 2; ++n) _Pragma("unroll") for (int k = 0; k < 2; ++k) dst[n][k] = *(const PG8_LAS bf16x8*)(lds + PG8_SB(b, h) + boff + n * 2048 + k * 1024); } while (0)
; #define PG8_MMA(ai, bj, At, Bt) do { __builtin_amdgcn_s_setprio(1); _Pragma("unroll") for (int m = 0; m < 4; ++m) _Pragma("unroll") for (int n = 0; n < 2; ++n) _Pragma("unroll") for (int k = 0; k < 2; ++k) \
;         acc[ai][bj][m][n] = __builtin_amdgcn_mfma_f32_16x16x32_bf16(Bt[n][k], At[m][k], acc[ai][bj][m][n], 0, 0, 0); __builtin_amdgcn_s_setprio(0); } while (0)
; #define PG8_WAIT_V(n) asm volatile("s_waitcnt vmcnt(" #n ")" ::: "memory")
; #define PG8_WAIT_L(n) asm volatile("s_waitcnt lgkmcnt(" #n ")" ::: "memory")
; #define PG8_BAR __builtin_amdgcn_s_barrier()
; #define PG8_SCHED __builtin_amdgcn_sched_barrier(0)
;     ...
;             PG8_LDB(B0, 0, 0); PG8_LDB(B1, 0, 1); PG8_SCHED; PG8_LDA(At, 0, 0); PG8_STAGE(PG8_SA(1, 1), a1 + hstepA, voffA);
;             PG8_WAIT_V(8); PG8_WAIT_L(0); PG8_BAR; PG8_MMA(0, 0, At, B0); PG8_MMA(0, 1, At, B1); PG8_BAR; PG8_SCHED;
;             PG8_LDA(At, 0, 1); PG8_STAGE(PG8_SB(0, 0), b2, voffB); PG8_STAGE(PG8_SB(0, 1), b2 + hstepB, voffB); PG8_STAGE(PG8_SA(0, 0), a2, voffA);
;             PG8_WAIT_V(8); PG8_WAIT_L(0); PG8_BAR; PG8_MMA(1, 0, At, B0); PG8_MMA(1, 1, At, B1); PG8_BAR; PG8_SCHED;
;             PG8_LDB(B0, 1, 0); PG8_LDB(B1, 1, 1); PG8_SCHED; PG8_LDA(At, 1, 0); PG8_STAGE(PG8_SA(0, 1), a2 + hstepA, voffA);
;             PG8_WAIT_V(8); PG8_WAIT_L(0); PG8_BAR; PG8_MMA(0, 0, At, B0); PG8_MMA(0, 1, At, B1); PG8_BAR; PG8_SCHED;
;             PG8_LDA(At, 1, 1); PG8_STAGE(PG8_SB(1, 0), b3, voffB); PG8_STAGE(PG8_SB(1, 1), b3 + hstepB, voffB); PG8_STAGE(PG8_SA(1, 0), a3, voffA);
;             PG8_WAIT_V(8); PG8_WAIT_L(0); PG8_BAR; PG8_MMA(1, 0, At, B0); PG8_MMA(1, 1, At, B1); PG8_BAR; PG8_SCHED;
	v_mfma_f32_16x16x32_bf16 v[0:3], v[190:193], v[246:249], v[0:3]
	s_setprio 0
	v_add_u32_e32 v161, s57, v159
	ds_read_b128 v[162:165], v161
	ds_read_b128 v[166:169], v161 offset:1024
	ds_read_b128 v[170:173], v161 offset:2048
	ds_read_b128 v[174:177], v161 offset:3072
	v_add_u32_e32 v161, s56, v159
	ds_read_b128 v[178:181], v161
	ds_read_b128 v[182:185], v161 offset:1024
	ds_read_b128 v[186:189], v161 offset:2048
	ds_read_b128 v[190:193], v161 offset:3072
	s_mov_b32 m0, s36
	v_lshl_add_u64 v[250:251], s[18:19], 0, v[128:129]
	ds_read_b128 v[194:197], v160 offset:32768
	ds_read_b128 v[198:201], v160 offset:33792
	ds_read_b128 v[202:205], v160 offset:34816
	ds_read_b128 v[218:221], v160 offset:35840
	ds_read_b128 v[222:225], v160 offset:36864
	ds_read_b128 v[238:241], v160 offset:37888
	ds_read_b128 v[242:245], v160 offset:38912
	ds_read_b128 v[246:249], v160 offset:39936
	global_load_lds_dwordx4 v[250:251], off
	v_lshl_add_u64 v[250:251], s[18:19], 0, v[130:131]
	s_mov_b32 m0, s37
	s_nop 0
	global_load_lds_dwordx4 v[250:251], off
	s_waitcnt vmcnt(8)
	s_waitcnt lgkmcnt(0)
	s_barrier
	s_setprio 1
	s_waitcnt lgkmcnt(0)
	v_mfma_f32_16x16x32_bf16 v[124:127], v[162:165], v[194:197], v[124:127]
	v_mfma_f32_16x16x32_bf16 v[120:123], v[170:173], v[194:197], v[120:123]
	v_mfma_f32_16x16x32_bf16 v[116:119], v[162:165], v[202:205], v[116:119]
	v_mfma_f32_16x16x32_bf16 v[108:111], v[170:173], v[202:205], v[108:111]
	v_mfma_f32_16x16x32_bf16 v[100:103], v[162:165], v[222:225], v[100:103]
	v_mfma_f32_16x16x32_bf16 v[92:95], v[170:173], v[222:225], v[92:95]
	v_mfma_f32_16x16x32_bf16 v[84:87], v[162:165], v[242:245], v[84:87]
	v_mfma_f32_16x16x32_bf16 v[76:79], v[170:173], v[242:245], v[76:79]
	v_mfma_f32_16x16x32_bf16 v[124:127], v[166:169], v[198:201], v[124:127]
	v_mfma_f32_16x16x32_bf16 v[120:123], v[174:177], v[198:201], v[120:123]
	v_mfma_f32_16x16x32_bf16 v[116:119], v[166:169], v[218:221], v[116:119]
	v_mfma_f32_16x16x32_bf16 v[108:111], v[174:177], v[218:221], v[108:111]
	v_mfma_f32_16x16x32_bf16 v[100:103], v[166:169], v[238:241], v[100:103]
	v_mfma_f32_16x16x32_bf16 v[92:95], v[174:177], v[238:241], v[92:95]
	v_mfma_f32_16x16x32_bf16 v[84:87], v[166:169], v[246:249], v[84:87]
	v_mfma_f32_16x16x32_bf16 v[76:79], v[174:177], v[246:249], v[76:79]
	s_setprio 0
	s_setprio 1
	v_mfma_f32_16x16x32_bf16 v[112:115], v[178:181], v[194:197], v[112:115]
	v_mfma_f32_16x16x32_bf16 v[104:107], v[186:189], v[194:197], v[104:107]
	v_mfma_f32_16x16x32_bf16 v[96:99], v[178:181], v[202:205], v[96:99]
	v_mfma_f32_16x16x32_bf16 v[88:91], v[186:189], v[202:205], v[88:91]
	v_mfma_f32_16x16x32_bf16 v[80:83], v[178:181], v[222:225], v[80:83]
	v_mfma_f32_16x16x32_bf16 v[72:75], v[186:189], v[222:225], v[72:75]
	v_mfma_f32_16x16x32_bf16 v[68:71], v[178:181], v[242:245], v[68:71]
	v_mfma_f32_16x16x32_bf16 v[64:67], v[186:189], v[242:245], v[64:67]
	v_mfma_f32_16x16x32_bf16 v[112:115], v[182:185], v[198:201], v[112:115]
	v_mfma_f32_16x16x32_bf16 v[104:107], v[190:193], v[198:201], v[104:107]
	v_mfma_f32_16x16x32_bf16 v[96:99], v[182:185], v[218:221], v[96:99]
	v_mfma_f32_16x16x32_bf16 v[88:91], v[190:193], v[218:221], v[88:91]
	v_mfma_f32_16x16x32_bf16 v[80:83], v[182:185], v[238:241], v[80:83]
	v_mfma_f32_16x16x32_bf16 v[72:75], v[190:193], v[238:241], v[72:75]
	v_mfma_f32_16x16x32_bf16 v[68:71], v[182:185], v[246:249], v[68:71]
	s_barrier
	v_mfma_f32_16x16x32_bf16 v[64:67], v[190:193], v[246:249], v[64:67]
	s_setprio 0
	s_mov_b32 m0, s55
	v_lshl_add_u64 v[140:141], v[140:141], 0, s[66:67]
	ds_read_b128 v[194:197], v160 offset:49152
	ds_read_b128 v[198:201], v160 offset:50176
	ds_read_b128 v[202:205], v160 offset:51200
	ds_read_b128 v[218:221], v160 offset:52224
	ds_read_b128 v[222:225], v160 offset:53248
	ds_read_b128 v[238:241], v160 offset:54272
	ds_read_b128 v[242:245], v160 offset:55296
	ds_read_b128 v[246:249], v160 offset:56320
	global_load_lds_dwordx4 v[140:141], off
	v_lshl_add_u64 v[140:141], v[206:207], 0, s[66:67]
	s_mov_b32 m0, s54
	s_nop 0
	global_load_lds_dwordx4 v[140:141], off
	v_lshl_add_u64 v[140:141], s[16:17], 0, v[134:135]
	s_mov_b32 m0, s63
	s_nop 0
	global_load_lds_dwordx4 v[140:141], off
	v_lshl_add_u64 v[140:141], s[16:17], 0, v[132:133]
	s_mov_b32 m0, s62
	s_nop 0
	global_load_lds_dwordx4 v[140:141], off
	v_lshl_add_u64 v[140:141], s[14:15], 0, v[128:129]
	s_mov_b32 m0, s40
	s_nop 0
	global_load_lds_dwordx4 v[140:141], off
	v_lshl_add_u64 v[140:141], s[14:15], 0, v[130:131]
	s_mov_b32 m0, s41
	s_nop 0
	global_load_lds_dwordx4 v[140:141], off
	s_waitcnt vmcnt(8)
	s_waitcnt lgkmcnt(0)
	s_barrier
	s_setprio 1
	s_waitcnt lgkmcnt(0)
	v_mfma_f32_16x16x32_bf16 v[60:63], v[162:165], v[194:197], v[60:63]
	v_mfma_f32_16x16x32_bf16 v[56:59], v[170:173], v[194:197], v[56:59]
	v_mfma_f32_16x16x32_bf16 v[52:55], v[162:165], v[202:205], v[52:55]
	v_mfma_f32_16x16x32_bf16 v[44:47], v[170:173], v[202:205], v[44:47]
	v_mfma_f32_16x16x32_bf16 v[36:39], v[162:165], v[222:225], v[36:39]
	v_mfma_f32_16x16x32_bf16 v[28:31], v[170:173], v[222:225], v[28:31]
	v_mfma_f32_16x16x32_bf16 v[20:23], v[162:165], v[242:245], v[20:23]
	v_mfma_f32_16x16x32_bf16 v[12:15], v[170:173], v[242:245], v[12:15]
	v_mfma_f32_16x16x32_bf16 v[60:63], v[166:169], v[198:201], v[60:63]
	v_mfma_f32_16x16x32_bf16 v[56:59], v[174:177], v[198:201], v[56:59]
	v_mfma_f32_16x16x32_bf16 v[52:55], v[166:169], v[218:221], v[52:55]
	v_mfma_f32_16x16x32_bf16 v[44:47], v[174:177], v[218:221], v[44:47]
	v_mfma_f32_16x16x32_bf16 v[36:39], v[166:169], v[238:241], v[36:39]
	v_mfma_f32_16x16x32_bf16 v[28:31], v[174:177], v[238:241], v[28:31]
	v_mfma_f32_16x16x32_bf16 v[20:23], v[166:169], v[246:249], v[20:23]
	v_mfma_f32_16x16x32_bf16 v[12:15], v[174:177], v[246:249], v[12:15]
	s_setprio 0
	s_setprio 1
	v_mfma_f32_16x16x32_bf16 v[48:51], v[178:181], v[194:197], v[48:51]
	v_mfma_f32_16x16x32_bf16 v[40:43], v[186:189], v[194:197], v[40:43]
	v_mfma_f32_16x16x32_bf16 v[32:35], v[178:181], v[202:205], v[32:35]
	v_mfma_f32_16x16x32_bf16 v[24:27], v[186:189], v[202:205], v[24:27]
	v_mfma_f32_16x16x32_bf16 v[16:19], v[178:181], v[222:225], v[16:19]
	v_mfma_f32_16x16x32_bf16 v[8:11], v[186:189], v[222:225], v[8:11]
	v_mfma_f32_16x16x32_bf16 v[4:7], v[178:181], v[242:245], v[4:7]
	v_mfma_f32_16x16x32_bf16 v[0:3], v[186:189], v[242:245], v[0:3]
	v_mfma_f32_16x16x32_bf16 v[48:51], v[182:185], v[198:201], v[48:51]
	v_mfma_f32_16x16x32_bf16 v[40:43], v[190:193], v[198:201], v[40:43]
	v_mfma_f32_16x16x32_bf16 v[32:35], v[182:185], v[218:221], v[32:35]
	v_mfma_f32_16x16x32_bf16 v[24:27], v[190:193], v[218:221], v[24:27]
	v_mfma_f32_16x16x32_bf16 v[16:19], v[182:185], v[238:241], v[16:19]
	v_mfma_f32_16x16x32_bf16 v[8:11], v[190:193], v[238:241], v[8:11]
	v_mfma_f32_16x16x32_bf16 v[4:7], v[182:185], v[246:249], v[4:7]
	s_barrier
	v_mfma_f32_16x16x32_bf16 v[0:3], v[190:193], v[246:249], v[0:3]
	s_setprio 0
	s_andn2_b64 vcc, exec, s[12:13]
	s_mov_b64 s[16:17], -1
	s_mov_b64 s[12:13], 0
	s_movk_i32 s14, 0x100
	s_cbranch_vccz .LBB0_785

;     __device__ __forceinline__ size_t hstep() const { return (size_t)HALF * K * 2; }
;     __device__ __forceinline__ const char* tile(const Unit& u, int t) const { return A + (size_t)u.pm * 2 * hstep() + (size_t)t * (BK * 2); }
;     __device__ __forceinline__ size_t hstep() const { return (size_t)HALF * 512; }
; #define PG8_STAGE(bufoff, gbase, voff) do { _Pragma("unroll") for (int _i = 0; _i < 2; ++_i) \
;         __builtin_amdgcn_global_load_lds((const unsigned*)((const char*)(gbase) + (voff)[_i]), (PG8_LAS unsigned*)(lds + (bufoff) + ldsw + _i * 8192), 16, 0, 0); } while (0)
; #define PG8_LDA(dst, b, h) do { _Pragma("unroll") for (int m = 0; m < 4; ++m) _Pragma("unroll") for (int k = 0; k < 2; ++k) dst[m][k] = *(const PG8_LAS bf16x8*)(lds + PG8_SA(b, h) + aoff + m * 2048 + k * 1024); } while (0)
; #define PG8_LDB(dst, b, h) do { _Pragma("unroll") for (int n = 0; n < 2; ++n) _Pragma("unroll") for (int k = 0; k < 2; ++k) dst[n][k] = *(const PG8_LAS bf16x8*)(lds + PG8_SB(b, h) + boff + n * 2048 + k * 1024); } while (0)
; #define PG8_WAIT_V(n) asm volatile("s_waitcnt vmcnt(" #n ")" ::: "memory")
; #define PG8_BAR __builtin_amdgcn_s_barrier()
;     __device__ __forceinline__ const char* tile(const Unit& u, int t) const { return U + (long)(t >> 2) * xoff + (size_t)u.pn * (1024 * 512) + (size_t)u.pm * 2 * hstep() + (size_t)(t & 3) * (BK * 2); }
;     ...
;             PG8_LDB(B0, 0, 0); PG8_LDB(B1, 0, 1); PG8_SCHED; PG8_LDA(At, 0, 0); PG8_STAGE(PG8_SA(1, 1), a1 + hstepA, voffA);
;             PG8_WAIT_V(8); PG8_WAIT_L(0); PG8_BAR; PG8_MMA(0, 0, At, B0); PG8_MMA(0, 1, At, B1); PG8_BAR; PG8_SCHED;
;             PG8_LDA(At, 0, 1); PG8_STAGE(PG8_SB(0, 0), b2, voffB); PG8_STAGE(PG8_SB(0, 1), b2 + hstepB, voffB); PG8_STAGE(PG8_SA(0, 0), a2, voffA);
;             PG8_WAIT_V(8); PG8_WAIT_L(0); PG8_BAR; PG8_MMA(1, 0, At, B0); PG8_MMA(1, 1, At, B1); PG8_BAR; PG8_SCHED;
;             PG8_LDB(B0, 1, 0); PG8_LDB(B1, 1, 1); PG8_SCHED; PG8_LDA(At, 1, 0); PG8_STAGE(PG8_SA(0, 1), a2 + hstepA, voffA);
;             PG8_WAIT_V(8); PG8_WAIT_L(0); PG8_BAR; PG8_MMA(0, 0, At, B0); PG8_MMA(0, 1, At, B1); PG8_BAR; PG8_SCHED;
;             PG8_LDA(At, 1, 1); PG8_STAGE(PG8_SB(1, 0), b3, voffB); PG8_STAGE(PG8_SB(1, 1), b3 + hstepB, voffB); PG8_STAGE(PG8_SA(1, 0), a3, voffA);
;             PG8_WAIT_V(8); PG8_WAIT_L(0); PG8_BAR; PG8_MMA(1, 0, At, B0); PG8_MMA(1, 1, At, B1); PG8_BAR; PG8_SCHED;
.LBB0_833:
	s_add_u32 s47, s44, s16
	s_addc_u32 s48, s45, s17
	s_and_b64 s[20:21], exec, s[20:21]
	s_cselect_b32 s21, s43, s48
	s_cselect_b32 s20, s42, s47
	s_add_i32 s47, s46, -3
	s_lshr_b32 s48, s47, 2
	s_mul_i32 s48, s48, 0x6000000
	s_add_u32 s48, s1, s48
	s_addc_u32 s49, s3, 0
	s_and_b32 s50, s16, 0x100
	s_add_u32 s48, s48, s50
	s_addc_u32 s49, s49, 0
	s_add_i32 s50, 0, 0x10000
	v_add_u32_e32 v137, s50, v144
	s_add_i32 s51, 0, 0x14000
	ds_read_b128 v[148:151], v137
	ds_read_b128 v[152:155], v137 offset:1024
	ds_read_b128 v[156:159], v137 offset:2048
	ds_read_b128 v[160:163], v137 offset:3072
	v_add_u32_e32 v137, s51, v144
	ds_read_b128 v[164:167], v137
	ds_read_b128 v[168:171], v137 offset:1024
	ds_read_b128 v[172:175], v137 offset:2048
	ds_read_b128 v[176:179], v137 offset:3072
	s_add_u32 s48, s48, 0x10080
	s_addc_u32 s49, s49, 0
	v_lshl_add_u64 v[140:141], s[48:49], 0, v[128:129]
	s_add_i32 m0, s27, 0xc000
	ds_read_b128 v[180:183], v142
	ds_read_b128 v[184:187], v142 offset:1024
	ds_read_b128 v[188:191], v142 offset:2048
	ds_read_b128 v[192:195], v142 offset:3072
	ds_read_b128 v[196:199], v142 offset:4096
	ds_read_b128 v[200:203], v142 offset:5120
	ds_read_b128 v[204:207], v142 offset:6144
	ds_read_b128 v[218:221], v142 offset:7168
	global_load_lds_dwordx4 v[140:141], off
	v_lshl_add_u64 v[140:141], s[48:49], 0, v[130:131]
	s_add_i32 m0, s27, 0xe000
	s_nop 0
	global_load_lds_dwordx4 v[140:141], off
	s_waitcnt vmcnt(8)
	s_waitcnt lgkmcnt(0)
	s_barrier
	s_setprio 1
	s_waitcnt lgkmcnt(0)
	v_mfma_f32_16x16x32_bf16 v[124:127], v[148:151], v[180:183], v[124:127]
	v_mfma_f32_16x16x32_bf16 v[120:123], v[156:159], v[180:183], v[120:123]
	v_mfma_f32_16x16x32_bf16 v[108:111], v[148:151], v[188:191], v[108:111]
	v_mfma_f32_16x16x32_bf16 v[104:107], v[156:159], v[188:191], v[104:107]
	v_mfma_f32_16x16x32_bf16 v[92:95], v[148:151], v[196:199], v[92:95]
	v_mfma_f32_16x16x32_bf16 v[88:91], v[156:159], v[196:199], v[88:91]
	v_mfma_f32_16x16x32_bf16 v[76:79], v[148:151], v[204:207], v[76:79]
	v_mfma_f32_16x16x32_bf16 v[72:75], v[156:159], v[204:207], v[72:75]
	v_mfma_f32_16x16x32_bf16 v[124:127], v[152:155], v[184:187], v[124:127]
	v_mfma_f32_16x16x32_bf16 v[120:123], v[160:163], v[184:187], v[120:123]
	v_mfma_f32_16x16x32_bf16 v[108:111], v[152:155], v[192:195], v[108:111]
	v_mfma_f32_16x16x32_bf16 v[104:107], v[160:163], v[192:195], v[104:107]
	v_mfma_f32_16x16x32_bf16 v[92:95], v[152:155], v[200:203], v[92:95]
	v_mfma_f32_16x16x32_bf16 v[88:91], v[160:163], v[200:203], v[88:91]
	v_mfma_f32_16x16x32_bf16 v[76:79], v[152:155], v[218:221], v[76:79]
	v_mfma_f32_16x16x32_bf16 v[72:75], v[160:163], v[218:221], v[72:75]
	s_setprio 0
	s_setprio 1
	v_mfma_f32_16x16x32_bf16 v[116:119], v[164:167], v[180:183], v[116:119]
	v_mfma_f32_16x16x32_bf16 v[112:115], v[172:175], v[180:183], v[112:115]
	v_mfma_f32_16x16x32_bf16 v[100:103], v[164:167], v[188:191], v[100:103]
	v_mfma_f32_16x16x32_bf16 v[96:99], v[172:175], v[188:191], v[96:99]
	v_mfma_f32_16x16x32_bf16 v[84:87], v[164:167], v[196:199], v[84:87]
	v_mfma_f32_16x16x32_bf16 v[80:83], v[172:175], v[196:199], v[80:83]
	v_mfma_f32_16x16x32_bf16 v[68:71], v[164:167], v[204:207], v[68:71]
	v_mfma_f32_16x16x32_bf16 v[64:67], v[172:175], v[204:207], v[64:67]
	v_mfma_f32_16x16x32_bf16 v[116:119], v[168:171], v[184:187], v[116:119]
	v_mfma_f32_16x16x32_bf16 v[112:115], v[176:179], v[184:187], v[112:115]
	v_mfma_f32_16x16x32_bf16 v[100:103], v[168:171], v[192:195], v[100:103]
	v_mfma_f32_16x16x32_bf16 v[96:99], v[176:179], v[192:195], v[96:99]
	v_mfma_f32_16x16x32_bf16 v[84:87], v[168:171], v[200:203], v[84:87]
	v_mfma_f32_16x16x32_bf16 v[80:83], v[176:179], v[200:203], v[80:83]
	v_mfma_f32_16x16x32_bf16 v[68:71], v[168:171], v[218:221], v[68:71]
	s_barrier
	v_mfma_f32_16x16x32_bf16 v[64:67], v[176:179], v[218:221], v[64:67]
	s_setprio 0
	s_add_i32 s48, s50, s26
	v_lshl_add_u64 v[140:141], s[20:21], 0, v[134:135]
	s_mov_b32 m0, s48
	ds_read_b128 v[180:183], v142 offset:16384
	ds_read_b128 v[184:187], v142 offset:17408
	ds_read_b128 v[188:191], v142 offset:18432
	ds_read_b128 v[192:195], v142 offset:19456
	ds_read_b128 v[196:199], v142 offset:20480
	ds_read_b128 v[200:203], v142 offset:21504
	ds_read_b128 v[204:207], v142 offset:22528
	ds_read_b128 v[218:221], v142 offset:23552
	global_load_lds_dwordx4 v[140:141], off
	s_add_i32 m0, s48, 0x2000
	s_add_u32 s48, s20, 0x20000
	v_lshl_add_u64 v[222:223], s[20:21], 0, v[132:133]
	s_addc_u32 s49, s21, 0
	s_add_i32 s50, s51, s26
	global_load_lds_dwordx4 v[222:223], off
	v_lshl_add_u64 v[224:225], s[48:49], 0, v[134:135]
	s_mov_b32 m0, s50
	s_nop 0
	global_load_lds_dwordx4 v[224:225], off
	v_lshl_add_u64 v[224:225], s[48:49], 0, v[132:133]
	s_add_i32 m0, s50, 0x2000
	s_nop 0
	global_load_lds_dwordx4 v[224:225], off
	v_lshl_add_u64 v[224:225], s[22:23], 0, v[128:129]
	s_mov_b32 m0, s27
	s_nop 0
	global_load_lds_dwordx4 v[224:225], off
	v_lshl_add_u64 v[224:225], s[22:23], 0, v[130:131]
	s_mov_b32 m0, s28
	s_nop 0
	global_load_lds_dwordx4 v[224:225], off
	s_waitcnt vmcnt(8)
	s_waitcnt lgkmcnt(0)
	s_barrier
; #define PG8_STAGE(bufoff, gbase, voff) do { _Pragma("unroll") for (int _i = 0; _i < 2; ++_i) \
;         __builtin_amdgcn_global_load_lds((const unsigned*)((const char*)(gbase) + (voff)[_i]), (PG8_LAS unsigned*)(lds + (bufoff) + ldsw + _i * 8192), 16, 0, 0); } while (0)
; #define PG8_LDA(dst, b, h) do { _Pragma("unroll") for (int m = 0; m < 4; ++m) _Pragma("unroll") for (int k = 0; k < 2; ++k) dst[m][k] = *(const PG8_LAS bf16x8*)(lds + PG8_SA(b, h) + aoff + m * 2048 + k * 1024); } while (0)
; #define PG8_LDB(dst, b, h) do { _Pragma("unroll") for (int n = 0; n < 2; ++n) _Pragma("unroll") for (int k = 0; k < 2; ++k) dst[n][k] = *(const PG8_LAS bf16x8*)(lds + PG8_SB(b, h) + boff + n * 2048 + k * 1024); } while (0)
; #define PG8_MMA(ai, bj, At, Bt) do { __builtin_amdgcn_s_setprio(1); _Pragma("unroll") for (int m = 0; m < 4; ++m) _Pragma("unroll") for (int n = 0; n < 2; ++n) _Pragma("unroll") for (int k = 0; k < 2; ++k) \
;         acc[ai][bj][m][n] = __builtin_amdgcn_mfma_f32_16x16x32_bf16(Bt[n][k], At[m][k], acc[ai][bj][m][n], 0, 0, 0); __builtin_amdgcn_s_setprio(0); } while (0)
; #define PG8_WAIT_V(n) asm volatile("s_waitcnt vmcnt(" #n ")" ::: "memory")
; #define PG8_WAIT_L(n) asm volatile("s_waitcnt lgkmcnt(" #n ")" ::: "memory")
; #define PG8_BAR __builtin_amdgcn_s_barrier()
; #define PG8_SCHED __builtin_amdgcn_sched_barrier(0)
;     ...
;             PG8_LDB(B0, 0, 0); PG8_LDB(B1, 0, 1); PG8_SCHED; PG8_LDA(At, 0, 0); PG8_STAGE(PG8_SA(1, 1), a1 + hstepA, voffA);
;             PG8_WAIT_V(8); PG8_WAIT_L(0); PG8_BAR; PG8_MMA(0, 0, At, B0); PG8_MMA(0, 1, At, B1); PG8_BAR; PG8_SCHED;
;             PG8_LDA(At, 0, 1); PG8_STAGE(PG8_SB(0, 0), b2, voffB); PG8_STAGE(PG8_SB(0, 1), b2 + hstepB, voffB); PG8_STAGE(PG8_SA(0, 0), a2, voffA);
;             PG8_WAIT_V(8); PG8_WAIT_L(0); PG8_BAR; PG8_MMA(1, 0, At, B0); PG8_MMA(1, 1, At, B1); PG8_BAR; PG8_SCHED;
;             PG8_LDB(B0, 1, 0); PG8_LDB(B1, 1, 1); PG8_SCHED; PG8_LDA(At, 1, 0); PG8_STAGE(PG8_SA(0, 1), a2 + hstepA, voffA);
;             PG8_WAIT_V(8); PG8_WAIT_L(0); PG8_BAR; PG8_MMA(0, 0, At, B0); PG8_MMA(0, 1, At, B1); PG8_BAR; PG8_SCHED;
;             PG8_LDA(At, 1, 1); PG8_STAGE(PG8_SB(1, 0), b3, voffB); PG8_STAGE(PG8_SB(1, 1), b3 + hstepB, voffB); PG8_STAGE(PG8_SA(1, 0), a3, voffA);
;             PG8_WAIT_V(8); PG8_WAIT_L(0); PG8_BAR; PG8_MMA(1, 0, At, B0); PG8_MMA(1, 1, At, B1); PG8_BAR; PG8_SCHED;
	s_setprio 1
	s_waitcnt lgkmcnt(0)
	v_mfma_f32_16x16x32_bf16 v[60:63], v[148:151], v[180:183], v[60:63]
	v_mfma_f32_16x16x32_bf16 v[56:59], v[156:159], v[180:183], v[56:59]
	v_mfma_f32_16x16x32_bf16 v[44:47], v[148:151], v[188:191], v[44:47]
	v_mfma_f32_16x16x32_bf16 v[40:43], v[156:159], v[188:191], v[40:43]
	v_mfma_f32_16x16x32_bf16 v[28:31], v[148:151], v[196:199], v[28:31]
	v_mfma_f32_16x16x32_bf16 v[24:27], v[156:159], v[196:199], v[24:27]
	v_mfma_f32_16x16x32_bf16 v[12:15], v[148:151], v[204:207], v[12:15]
	v_mfma_f32_16x16x32_bf16 v[8:11], v[156:159], v[204:207], v[8:11]
	v_mfma_f32_16x16x32_bf16 v[60:63], v[152:155], v[184:187], v[60:63]
	v_mfma_f32_16x16x32_bf16 v[56:59], v[160:163], v[184:187], v[56:59]
	v_mfma_f32_16x16x32_bf16 v[44:47], v[152:155], v[192:195], v[44:47]
	v_mfma_f32_16x16x32_bf16 v[40:43], v[160:163], v[192:195], v[40:43]
	v_mfma_f32_16x16x32_bf16 v[28:31], v[152:155], v[200:203], v[28:31]
	v_mfma_f32_16x16x32_bf16 v[24:27], v[160:163], v[200:203], v[24:27]
	v_mfma_f32_16x16x32_bf16 v[12:15], v[152:155], v[218:221], v[12:15]
	v_mfma_f32_16x16x32_bf16 v[8:11], v[160:163], v[218:221], v[8:11]
	s_setprio 0
	s_setprio 1
	v_mfma_f32_16x16x32_bf16 v[52:55], v[164:167], v[180:183], v[52:55]
	v_mfma_f32_16x16x32_bf16 v[48:51], v[172:175], v[180:183], v[48:51]
	v_mfma_f32_16x16x32_bf16 v[36:39], v[164:167], v[188:191], v[36:39]
	v_mfma_f32_16x16x32_bf16 v[32:35], v[172:175], v[188:191], v[32:35]
	v_mfma_f32_16x16x32_bf16 v[20:23], v[164:167], v[196:199], v[20:23]
	v_mfma_f32_16x16x32_bf16 v[16:19], v[172:175], v[196:199], v[16:19]
	v_mfma_f32_16x16x32_bf16 v[4:7], v[164:167], v[204:207], v[4:7]
	v_mfma_f32_16x16x32_bf16 v[0:3], v[172:175], v[204:207], v[0:3]
	v_mfma_f32_16x16x32_bf16 v[52:55], v[168:171], v[184:187], v[52:55]
	v_mfma_f32_16x16x32_bf16 v[48:51], v[176:179], v[184:187], v[48:51]
	v_mfma_f32_16x16x32_bf16 v[36:39], v[168:171], v[192:195], v[36:39]
	v_mfma_f32_16x16x32_bf16 v[32:35], v[176:179], v[192:195], v[32:35]
	v_mfma_f32_16x16x32_bf16 v[20:23], v[168:171], v[200:203], v[20:23]
	v_mfma_f32_16x16x32_bf16 v[16:19], v[176:179], v[200:203], v[16:19]
	v_mfma_f32_16x16x32_bf16 v[4:7], v[168:171], v[218:221], v[4:7]
	s_barrier
	v_mfma_f32_16x16x32_bf16 v[0:3], v[176:179], v[218:221], v[0:3]
	s_setprio 0
	s_add_i32 s48, 0, 0x18000
	v_add_u32_e32 v137, s48, v144
	s_add_i32 s49, 0, 0x1c000
	ds_read_b128 v[148:151], v137
	ds_read_b128 v[152:155], v137 offset:1024
	ds_read_b128 v[156:159], v137 offset:2048
	ds_read_b128 v[160:163], v137 offset:3072
	v_add_u32_e32 v137, s49, v144
	ds_read_b128 v[164:167], v137
	ds_read_b128 v[168:171], v137 offset:1024
	ds_read_b128 v[172:175], v137 offset:2048
	ds_read_b128 v[176:179], v137 offset:3072
	s_add_u32 s22, s22, 0x10000
	s_addc_u32 s23, s23, 0
	s_mov_b32 m0, s29
	v_lshl_add_u64 v[224:225], s[22:23], 0, v[128:129]
	ds_read_b128 v[180:183], v142 offset:32768
	ds_read_b128 v[184:187], v142 offset:33792
	ds_read_b128 v[188:191], v142 offset:34816
	ds_read_b128 v[192:195], v142 offset:35840
	ds_read_b128 v[196:199], v142 offset:36864
	ds_read_b128 v[200:203], v142 offset:37888
	ds_read_b128 v[204:207], v142 offset:38912
	ds_read_b128 v[218:221], v142 offset:39936
	global_load_lds_dwordx4 v[224:225], off
	v_lshl_add_u64 v[224:225], s[22:23], 0, v[130:131]
	s_mov_b32 m0, s30
	s_nop 0
	global_load_lds_dwordx4 v[224:225], off
	s_waitcnt vmcnt(8)
	s_waitcnt lgkmcnt(0)
	s_barrier
	s_setprio 1
	s_waitcnt lgkmcnt(0)
	v_mfma_f32_16x16x32_bf16 v[124:127], v[148:151], v[180:183], v[124:127]
	v_mfma_f32_16x16x32_bf16 v[120:123], v[156:159], v[180:183], v[120:123]
	v_mfma_f32_16x16x32_bf16 v[108:111], v[148:151], v[188:191], v[108:111]
	v_mfma_f32_16x16x32_bf16 v[104:107], v[156:159], v[188:191], v[104:107]
	v_mfma_f32_16x16x32_bf16 v[92:95], v[148:151], v[196:199], v[92:95]
	v_mfma_f32_16x16x32_bf16 v[88:91], v[156:159], v[196:199], v[88:91]
	v_mfma_f32_16x16x32_bf16 v[76:79], v[148:151], v[204:207], v[76:79]
	v_mfma_f32_16x16x32_bf16 v[72:75], v[156:159], v[204:207], v[72:75]
	v_mfma_f32_16x16x32_bf16 v[124:127], v[152:155], v[184:187], v[124:127]
	v_mfma_f32_16x16x32_bf16 v[120:123], v[160:163], v[184:187], v[120:123]
	v_mfma_f32_16x16x32_bf16 v[108:111], v[152:155], v[192:195], v[108:111]
	v_mfma_f32_16x16x32_bf16 v[104:107], v[160:163], v[192:195], v[104:107]
	v_mfma_f32_16x16x32_bf16 v[92:95], v[152:155], v[200:203], v[92:95]
	v_mfma_f32_16x16x32_bf16 v[88:91], v[160:163], v[200:203], v[88:91]
	v_mfma_f32_16x16x32_bf16 v[76:79], v[152:155], v[218:221], v[76:79]
	v_mfma_f32_16x16x32_bf16 v[72:75], v[160:163], v[218:221], v[72:75]
	s_setprio 0
	s_setprio 1
	v_mfma_f32_16x16x32_bf16 v[116:119], v[164:167], v[180:183], v[116:119]
	v_mfma_f32_16x16x32_bf16 v[112:115], v[172:175], v[180:183], v[112:115]
	v_mfma_f32_16x16x32_bf16 v[100:103], v[164:167], v[188:191], v[100:103]
	v_mfma_f32_16x16x32_bf16 v[96:99], v[172:175], v[188:191], v[96:99]
	v_mfma_f32_16x16x32_bf16 v[84:87], v[164:167], v[196:199], v[84:87]
	v_mfma_f32_16x16x32_bf16 v[80:83], v[172:175], v[196:199], v[80:83]
	v_mfma_f32_16x16x32_bf16 v[68:71], v[164:167], v[204:207], v[68:71]
	v_mfma_f32_16x16x32_bf16 v[64:67], v[172:175], v[204:207], v[64:67]
	v_mfma_f32_16x16x32_bf16 v[116:119], v[168:171], v[184:187], v[116:119]
	v_mfma_f32_16x16x32_bf16 v[112:115], v[176:179], v[184:187], v[112:115]
	v_mfma_f32_16x16x32_bf16 v[100:103], v[168:171], v[192:195], v[100:103]
	v_mfma_f32_16x16x32_bf16 v[96:99], v[176:179], v[192:195], v[96:99]
	v_mfma_f32_16x16x32_bf16 v[84:87], v[168:171], v[200:203], v[84:87]
	v_mfma_f32_16x16x32_bf16 v[80:83], v[176:179], v[200:203], v[80:83]
	v_mfma_f32_16x16x32_bf16 v[68:71], v[168:171], v[218:221], v[68:71]
	s_barrier
; #define PG8_STAGE(bufoff, gbase, voff) do { _Pragma("unroll") for (int _i = 0; _i < 2; ++_i) \
;         __builtin_amdgcn_global_load_lds((const unsigned*)((const char*)(gbase) + (voff)[_i]), (PG8_LAS unsigned*)(lds + (bufoff) + ldsw + _i * 8192), 16, 0, 0); } while (0)
; #define PG8_LDA(dst, b, h) do { _Pragma("unroll") for (int m = 0; m < 4; ++m) _Pragma("unroll") for (int k = 0; k < 2; ++k) dst[m][k] = *(const PG8_LAS bf16x8*)(lds + PG8_SA(b, h) + aoff + m * 2048 + k * 1024); } while (0)
; #define PG8_LDB(dst, b, h) do { _Pragma("unroll") for (int n = 0; n < 2; ++n) _Pragma("unroll") for (int k = 0; k < 2; ++k) dst[n][k] = *(const PG8_LAS bf16x8*)(lds + PG8_SB(b, h) + boff + n * 2048 + k * 1024); } while (0)
; #define PG8_MMA(ai, bj, At, Bt) do { __builtin_amdgcn_s_setprio(1); _Pragma("unroll") for (int m = 0; m < 4; ++m) _Pragma("unroll") for (int n = 0; n < 2; ++n) _Pragma("unroll") for (int k = 0; k < 2; ++k) \
;         acc[ai][bj][m][n] = __builtin_amdgcn_mfma_f32_16x16x32_bf16(Bt[n][k], At[m][k], acc[ai][bj][m][n], 0, 0, 0); __builtin_amdgcn_s_setprio(0); } while (0)
; #define PG8_WAIT_V(n) asm volatile("s_waitcnt vmcnt(" #n ")" ::: "memory")
; #define PG8_WAIT_L(n) asm volatile("s_waitcnt lgkmcnt(" #n ")" ::: "memory")
; #define PG8_BAR __builtin_amdgcn_s_barrier()
; #define PG8_SCHED __builtin_amdgcn_sched_barrier(0)
;     ...
;             PG8_LDB(B0, 0, 0); PG8_LDB(B1, 0, 1); PG8_SCHED; PG8_LDA(At, 0, 0); PG8_STAGE(PG8_SA(1, 1), a1 + hstepA, voffA);
;             PG8_WAIT_V(8); PG8_WAIT_L(0); PG8_BAR; PG8_MMA(0, 0, At, B0); PG8_MMA(0, 1, At, B1); PG8_BAR; PG8_SCHED;
;             PG8_LDA(At, 0, 1); PG8_STAGE(PG8_SB(0, 0), b2, voffB); PG8_STAGE(PG8_SB(0, 1), b2 + hstepB, voffB); PG8_STAGE(PG8_SA(0, 0), a2, voffA);
;             PG8_WAIT_V(8); PG8_WAIT_L(0); PG8_BAR; PG8_MMA(1, 0, At, B0); PG8_MMA(1, 1, At, B1); PG8_BAR; PG8_SCHED;
;             PG8_LDB(B0, 1, 0); PG8_LDB(B1, 1, 1); PG8_SCHED; PG8_LDA(At, 1, 0); PG8_STAGE(PG8_SA(0, 1), a2 + hstepA, voffA);
;             PG8_WAIT_V(8); PG8_WAIT_L(0); PG8_BAR; PG8_MMA(0, 0, At, B0); PG8_MMA(0, 1, At, B1); PG8_BAR; PG8_SCHED;
;             PG8_LDA(At, 1, 1); PG8_STAGE(PG8_SB(1, 0), b3, voffB); PG8_STAGE(PG8_SB(1, 1), b3 + hstepB, voffB); PG8_STAGE(PG8_SA(1, 0), a3, voffA);
;             PG8_WAIT_V(8); PG8_WAIT_L(0); PG8_BAR; PG8_MMA(1, 0, At, B0); PG8_MMA(1, 1, At, B1); PG8_BAR; PG8_SCHED;
	v_mfma_f32_16x16x32_bf16 v[64:67], v[176:179], v[218:221], v[64:67]
	s_setprio 0
	s_mov_b64 s[50:51], 0x80
	s_add_i32 s22, s48, s26
	v_lshl_add_u64 v[140:141], v[140:141], 0, s[50:51]
	s_mov_b32 m0, s22
	ds_read_b128 v[180:183], v142 offset:49152
	ds_read_b128 v[184:187], v142 offset:50176
	ds_read_b128 v[188:191], v142 offset:51200
	ds_read_b128 v[192:195], v142 offset:52224
	ds_read_b128 v[196:199], v142 offset:53248
	ds_read_b128 v[200:203], v142 offset:54272
	ds_read_b128 v[204:207], v142 offset:55296
	ds_read_b128 v[218:221], v142 offset:56320
	global_load_lds_dwordx4 v[140:141], off
	s_add_i32 m0, s22, 0x2000
	s_add_u32 s20, s20, 0x20080
	v_lshl_add_u64 v[140:141], v[222:223], 0, s[50:51]
	s_addc_u32 s21, s21, 0
	s_add_i32 s22, s49, s26
	global_load_lds_dwordx4 v[140:141], off
	v_lshl_add_u64 v[140:141], s[20:21], 0, v[134:135]
	s_mov_b32 m0, s22
	s_nop 0
	global_load_lds_dwordx4 v[140:141], off
	v_lshl_add_u64 v[140:141], s[20:21], 0, v[132:133]
	s_add_i32 m0, s22, 0x2000
	s_nop 0
	global_load_lds_dwordx4 v[140:141], off
	v_lshl_add_u64 v[140:141], s[18:19], 0, v[128:129]
	s_mov_b32 m0, s31
	s_nop 0
	global_load_lds_dwordx4 v[140:141], off
	v_lshl_add_u64 v[140:141], s[18:19], 0, v[130:131]
	s_mov_b32 m0, s34
	s_nop 0
	global_load_lds_dwordx4 v[140:141], off
	s_waitcnt vmcnt(8)
	s_waitcnt lgkmcnt(0)
	s_barrier
	s_setprio 1
	s_waitcnt lgkmcnt(0)
	v_mfma_f32_16x16x32_bf16 v[60:63], v[148:151], v[180:183], v[60:63]
	v_mfma_f32_16x16x32_bf16 v[56:59], v[156:159], v[180:183], v[56:59]
	v_mfma_f32_16x16x32_bf16 v[44:47], v[148:151], v[188:191], v[44:47]
	v_mfma_f32_16x16x32_bf16 v[40:43], v[156:159], v[188:191], v[40:43]
	v_mfma_f32_16x16x32_bf16 v[28:31], v[148:151], v[196:199], v[28:31]
	v_mfma_f32_16x16x32_bf16 v[24:27], v[156:159], v[196:199], v[24:27]
	v_mfma_f32_16x16x32_bf16 v[12:15], v[148:151], v[204:207], v[12:15]
	v_mfma_f32_16x16x32_bf16 v[8:11], v[156:159], v[204:207], v[8:11]
	v_mfma_f32_16x16x32_bf16 v[60:63], v[152:155], v[184:187], v[60:63]
	v_mfma_f32_16x16x32_bf16 v[56:59], v[160:163], v[184:187], v[56:59]
	v_mfma_f32_16x16x32_bf16 v[44:47], v[152:155], v[192:195], v[44:47]
	v_mfma_f32_16x16x32_bf16 v[40:43], v[160:163], v[192:195], v[40:43]
	v_mfma_f32_16x16x32_bf16 v[28:31], v[152:155], v[200:203], v[28:31]
	v_mfma_f32_16x16x32_bf16 v[24:27], v[160:163], v[200:203], v[24:27]
	v_mfma_f32_16x16x32_bf16 v[12:15], v[152:155], v[218:221], v[12:15]
	v_mfma_f32_16x16x32_bf16 v[8:11], v[160:163], v[218:221], v[8:11]
	s_setprio 0
	s_setprio 1
	v_mfma_f32_16x16x32_bf16 v[52:55], v[164:167], v[180:183], v[52:55]
	v_mfma_f32_16x16x32_bf16 v[48:51], v[172:175], v[180:183], v[48:51]
	v_mfma_f32_16x16x32_bf16 v[36:39], v[164:167], v[188:191], v[36:39]
	v_mfma_f32_16x16x32_bf16 v[32:35], v[172:175], v[188:191], v[32:35]
	v_mfma_f32_16x16x32_bf16 v[20:23], v[164:167], v[196:199], v[20:23]
	v_mfma_f32_16x16x32_bf16 v[16:19], v[172:175], v[196:199], v[16:19]
	v_mfma_f32_16x16x32_bf16 v[4:7], v[164:167], v[204:207], v[4:7]
	v_mfma_f32_16x16x32_bf16 v[0:3], v[172:175], v[204:207], v[0:3]
	v_mfma_f32_16x16x32_bf16 v[52:55], v[168:171], v[184:187], v[52:55]
	v_mfma_f32_16x16x32_bf16 v[48:51], v[176:179], v[184:187], v[48:51]
	v_mfma_f32_16x16x32_bf16 v[36:39], v[168:171], v[192:195], v[36:39]
	v_mfma_f32_16x16x32_bf16 v[32:35], v[176:179], v[192:195], v[32:35]
	v_mfma_f32_16x16x32_bf16 v[20:23], v[168:171], v[200:203], v[20:23]
	v_mfma_f32_16x16x32_bf16 v[16:19], v[176:179], v[200:203], v[16:19]
	v_mfma_f32_16x16x32_bf16 v[4:7], v[168:171], v[218:221], v[4:7]
	s_barrier
	v_mfma_f32_16x16x32_bf16 v[0:3], v[176:179], v[218:221], v[0:3]
	s_setprio 0
	s_add_u32 s16, s16, 0x100
	s_addc_u32 s17, s17, 0
	s_add_i32 s46, s46, 2
	s_cmp_gt_u32 s47, 5
	s_cbranch_scc1 .LBB0_838
